# phase-0 cache/state/adaLN items with loads in flight; GEMM k-loops: ds_writes spread over odd MFMA slots; retention-state item loads issued a step ahead; rope per-block store waits dropped
# speedup vs baseline: 1.1423x; 1.0224x over previous
.LBB0_47:
	s_andn2_b64 vcc, exec, s[4:5]
	s_cbranch_vccnz .LBB0_49
	s_add_i32 s4, s91, 0xfffffcbf
	s_bfe_u32 s13, s4, 0x20003
	s_lshr_b32 s18, s4, 5
	s_and_b32 s6, s4, 3
	s_bfe_u32 s7, s4, 0x10002
	s_lshl_b32 s4, s13, 2
	s_lshl_b32 s5, s18, 1
	s_add_i32 s4, s4, s5
	s_load_dwordx16 s[36:51], s[86:87], 0x0
	s_or_b32 s4, s4, s7
	s_lshl_b32 s4, s4, 2
	s_or_b32 s34, s4, s6
	s_lshl_b64 s[4:5], s[34:35], 16
	s_waitcnt lgkmcnt(0)
	s_add_u32 s4, s40, s4
	s_addc_u32 s5, s41, s5
	s_mov_b64 s[98:99], s[4:5]
	s_lshl_b32 s4, s18, 3
	s_lshl_b32 s5, s13, 1
	s_or_b32 s4, s5, s4
	s_or_b32 s4, s4, s7
	s_lshl_b32 s4, s4, 2
	s_or_b32 s34, s4, s6
	s_lshl_b64 s[4:5], s[34:35], 15
	v_readlane_b32 s0, v250, 5
	s_nop 1
	s_add_u32 s4, s0, s4
	v_readlane_b32 s0, v250, 6
	s_nop 1
	s_addc_u32 s5, s0, s5
	v_and_b32_e32 v7, 0x7f, v74
	v_ashrrev_i32_e32 v6, 1, v74
	v_and_b32_e32 v2, 0xffffffc0, v6
	v_lshlrev_b32_e32 v0, 9, v2
	v_lshl_add_u32 v0, v7, 2, v0
	v_lshlrev_b32_e32 v1, 1, v2
	v_lshl_add_u32 v1, v7, 8, v1
	s_waitcnt vmcnt(0)
	v_mov_b32_e32 v8, v0
	global_load_dword v132, v8, s[98:99]
	global_load_dword v133, v8, s[98:99] offset:512
	global_load_dword v134, v8, s[98:99] offset:1024
	global_load_dword v135, v8, s[98:99] offset:1536
	global_load_dword v136, v8, s[98:99] offset:2048
	global_load_dword v137, v8, s[98:99] offset:2560
	global_load_dword v138, v8, s[98:99] offset:3072
	global_load_dword v139, v8, s[98:99] offset:3584
	v_add_u32_e32 v9, 0x1000, v0
	global_load_dword v140, v9, s[98:99]
	global_load_dword v141, v9, s[98:99] offset:512
	global_load_dword v142, v9, s[98:99] offset:1024
	global_load_dword v143, v9, s[98:99] offset:1536
	global_load_dword v144, v9, s[98:99] offset:2048
	global_load_dword v145, v9, s[98:99] offset:2560
	global_load_dword v146, v9, s[98:99] offset:3072
	global_load_dword v147, v9, s[98:99] offset:3584
	v_add_u32_e32 v10, 0x2000, v0
	global_load_dword v148, v10, s[98:99]
	global_load_dword v149, v10, s[98:99] offset:512
	global_load_dword v150, v10, s[98:99] offset:1024
	global_load_dword v151, v10, s[98:99] offset:1536
	global_load_dword v152, v10, s[98:99] offset:2048
	global_load_dword v153, v10, s[98:99] offset:2560
	global_load_dword v154, v10, s[98:99] offset:3072
	global_load_dword v155, v10, s[98:99] offset:3584
	v_add_u32_e32 v11, 0x3000, v0
	global_load_dword v156, v11, s[98:99]
	global_load_dword v157, v11, s[98:99] offset:512
	global_load_dword v158, v11, s[98:99] offset:1024
	global_load_dword v159, v11, s[98:99] offset:1536
	global_load_dword v160, v11, s[98:99] offset:2048
	global_load_dword v161, v11, s[98:99] offset:2560
	global_load_dword v162, v11, s[98:99] offset:3072
	global_load_dword v163, v11, s[98:99] offset:3584
	v_add_u32_e32 v8, 0x4000, v0
	global_load_dword v164, v8, s[98:99]
	global_load_dword v165, v8, s[98:99] offset:512
	global_load_dword v166, v8, s[98:99] offset:1024
	global_load_dword v167, v8, s[98:99] offset:1536
	global_load_dword v168, v8, s[98:99] offset:2048
	global_load_dword v169, v8, s[98:99] offset:2560
	global_load_dword v170, v8, s[98:99] offset:3072
	global_load_dword v171, v8, s[98:99] offset:3584
	v_add_u32_e32 v9, 0x5000, v0
	global_load_dword v172, v9, s[98:99]
	global_load_dword v173, v9, s[98:99] offset:512
	global_load_dword v174, v9, s[98:99] offset:1024
	global_load_dword v175, v9, s[98:99] offset:1536
	global_load_dword v176, v9, s[98:99] offset:2048
	global_load_dword v177, v9, s[98:99] offset:2560
	global_load_dword v178, v9, s[98:99] offset:3072
	global_load_dword v179, v9, s[98:99] offset:3584
	v_add_u32_e32 v10, 0x6000, v0
	global_load_dword v180, v10, s[98:99]
	global_load_dword v181, v10, s[98:99] offset:512
	global_load_dword v182, v10, s[98:99] offset:1024
	global_load_dword v183, v10, s[98:99] offset:1536
	global_load_dword v184, v10, s[98:99] offset:2048
	global_load_dword v185, v10, s[98:99] offset:2560
	global_load_dword v186, v10, s[98:99] offset:3072
	global_load_dword v187, v10, s[98:99] offset:3584
	s_waitcnt vmcnt(48)
	v_cvt_pk_bf16_f32 v12, v132, v133
	v_cvt_pk_bf16_f32 v13, v134, v135
	v_cvt_pk_bf16_f32 v14, v136, v137
	v_cvt_pk_bf16_f32 v15, v138, v139
	global_store_dwordx4 v1, v[12:15], s[4:5]
	v_add_u32_e32 v11, 0x7000, v0
	global_load_dword v132, v11, s[98:99]
	global_load_dword v133, v11, s[98:99] offset:512
	global_load_dword v134, v11, s[98:99] offset:1024
	global_load_dword v135, v11, s[98:99] offset:1536
	global_load_dword v136, v11, s[98:99] offset:2048
	global_load_dword v137, v11, s[98:99] offset:2560
	global_load_dword v138, v11, s[98:99] offset:3072
	global_load_dword v139, v11, s[98:99] offset:3584
	s_waitcnt vmcnt(49)
	v_cvt_pk_bf16_f32 v16, v140, v141
	v_cvt_pk_bf16_f32 v17, v142, v143
	v_cvt_pk_bf16_f32 v18, v144, v145
	v_cvt_pk_bf16_f32 v19, v146, v147
	global_store_dwordx4 v1, v[16:19], s[4:5] offset:16
	s_waitcnt vmcnt(42)
	v_cvt_pk_bf16_f32 v12, v148, v149
	v_cvt_pk_bf16_f32 v13, v150, v151
	v_cvt_pk_bf16_f32 v14, v152, v153
	v_cvt_pk_bf16_f32 v15, v154, v155
	global_store_dwordx4 v1, v[12:15], s[4:5] offset:32
	s_waitcnt vmcnt(35)
	v_cvt_pk_bf16_f32 v16, v156, v157
	v_cvt_pk_bf16_f32 v17, v158, v159
	v_cvt_pk_bf16_f32 v18, v160, v161
	v_cvt_pk_bf16_f32 v19, v162, v163
	global_store_dwordx4 v1, v[16:19], s[4:5] offset:48
	s_waitcnt vmcnt(28)
	v_cvt_pk_bf16_f32 v12, v164, v165
	v_cvt_pk_bf16_f32 v13, v166, v167
	v_cvt_pk_bf16_f32 v14, v168, v169
	v_cvt_pk_bf16_f32 v15, v170, v171
	global_store_dwordx4 v1, v[12:15], s[4:5] offset:64
	s_waitcnt vmcnt(21)
	v_cvt_pk_bf16_f32 v16, v172, v173
	v_cvt_pk_bf16_f32 v17, v174, v175
	v_cvt_pk_bf16_f32 v18, v176, v177
	v_cvt_pk_bf16_f32 v19, v178, v179
	global_store_dwordx4 v1, v[16:19], s[4:5] offset:80
	s_waitcnt vmcnt(14)
	v_cvt_pk_bf16_f32 v12, v180, v181
	v_cvt_pk_bf16_f32 v13, v182, v183
	v_cvt_pk_bf16_f32 v14, v184, v185
	v_cvt_pk_bf16_f32 v15, v186, v187
	global_store_dwordx4 v1, v[12:15], s[4:5] offset:96
	s_waitcnt vmcnt(6)
	v_cvt_pk_bf16_f32 v16, v132, v133
	v_cvt_pk_bf16_f32 v17, v134, v135
	v_cvt_pk_bf16_f32 v18, v136, v137
	v_cvt_pk_bf16_f32 v19, v138, v139
	global_store_dwordx4 v1, v[16:19], s[4:5] offset:112

.LBB0_53:
	s_waitcnt vmcnt(0)
	s_mov_b64 s[52:53], 0x1000
	s_mov_b64 s[6:7], 0x800
	global_load_dwordx4 v[132:135], v[2:3], off offset:-8
	v_lshl_add_u64 v[2:3], v[2:3], 0, s[52:53]
	global_load_dwordx4 v[136:139], v[2:3], off offset:-8
	v_lshl_add_u64 v[2:3], v[2:3], 0, s[52:53]
	global_load_dwordx4 v[140:143], v[2:3], off offset:-8
	v_lshl_add_u64 v[2:3], v[2:3], 0, s[52:53]
	global_load_dwordx4 v[144:147], v[2:3], off offset:-8
	v_lshl_add_u64 v[2:3], v[2:3], 0, s[52:53]
	global_load_dwordx4 v[148:151], v[2:3], off offset:-8
	v_lshl_add_u64 v[2:3], v[2:3], 0, s[52:53]
	global_load_dwordx4 v[152:155], v[2:3], off offset:-8
	v_lshl_add_u64 v[2:3], v[2:3], 0, s[52:53]
	global_load_dwordx4 v[156:159], v[2:3], off offset:-8
	v_lshl_add_u64 v[2:3], v[2:3], 0, s[52:53]
	global_load_dwordx4 v[160:163], v[2:3], off offset:-8
	v_lshl_add_u64 v[2:3], v[2:3], 0, s[52:53]
	global_load_dwordx4 v[164:167], v[2:3], off offset:-8
	v_lshl_add_u64 v[2:3], v[2:3], 0, s[52:53]
	global_load_dwordx4 v[168:171], v[2:3], off offset:-8
	v_lshl_add_u64 v[2:3], v[2:3], 0, s[52:53]
	global_load_dwordx4 v[172:175], v[2:3], off offset:-8
	v_lshl_add_u64 v[2:3], v[2:3], 0, s[52:53]
	global_load_dwordx4 v[176:179], v[2:3], off offset:-8
	v_lshl_add_u64 v[2:3], v[2:3], 0, s[52:53]
	global_load_dwordx4 v[180:183], v[2:3], off offset:-8
	v_lshl_add_u64 v[2:3], v[2:3], 0, s[52:53]
	global_load_dwordx4 v[184:187], v[2:3], off offset:-8
	v_lshl_add_u64 v[2:3], v[2:3], 0, s[52:53]
	global_load_dwordx4 v[188:191], v[2:3], off offset:-8
	v_lshl_add_u64 v[2:3], v[2:3], 0, s[52:53]
	global_load_dwordx4 v[192:195], v[2:3], off offset:-8
	v_lshl_add_u64 v[2:3], v[2:3], 0, s[52:53]
	s_waitcnt vmcnt(15)
	v_cvt_pk_bf16_f32 v6, v132, v133
	v_cvt_pk_bf16_f32 v7, v134, v135
	global_store_dwordx2 v[0:1], v[6:7], off offset:-4
	v_lshl_add_u64 v[0:1], v[0:1], 0, s[6:7]
	global_load_dwordx4 v[132:135], v[2:3], off offset:-8
	v_lshl_add_u64 v[2:3], v[2:3], 0, s[52:53]
	s_waitcnt vmcnt(16)
	v_cvt_pk_bf16_f32 v8, v136, v137
	v_cvt_pk_bf16_f32 v9, v138, v139
	global_store_dwordx2 v[0:1], v[8:9], off offset:-4
	v_lshl_add_u64 v[0:1], v[0:1], 0, s[6:7]
	global_load_dwordx4 v[136:139], v[2:3], off offset:-8
	v_lshl_add_u64 v[2:3], v[2:3], 0, s[52:53]
	s_waitcnt vmcnt(17)
	v_cvt_pk_bf16_f32 v6, v140, v141
	v_cvt_pk_bf16_f32 v7, v142, v143
	global_store_dwordx2 v[0:1], v[6:7], off offset:-4
	v_lshl_add_u64 v[0:1], v[0:1], 0, s[6:7]
	global_load_dwordx4 v[140:143], v[2:3], off offset:-8
	v_lshl_add_u64 v[2:3], v[2:3], 0, s[52:53]
	s_waitcnt vmcnt(18)
	v_cvt_pk_bf16_f32 v8, v144, v145
	v_cvt_pk_bf16_f32 v9, v146, v147
	global_store_dwordx2 v[0:1], v[8:9], off offset:-4
	v_lshl_add_u64 v[0:1], v[0:1], 0, s[6:7]
	global_load_dwordx4 v[144:147], v[2:3], off offset:-8
	v_lshl_add_u64 v[2:3], v[2:3], 0, s[52:53]
	s_waitcnt vmcnt(19)
	v_cvt_pk_bf16_f32 v6, v148, v149
	v_cvt_pk_bf16_f32 v7, v150, v151
	global_store_dwordx2 v[0:1], v[6:7], off offset:-4
	v_lshl_add_u64 v[0:1], v[0:1], 0, s[6:7]
	global_load_dwordx4 v[148:151], v[2:3], off offset:-8
	v_lshl_add_u64 v[2:3], v[2:3], 0, s[52:53]
	s_waitcnt vmcnt(20)
	v_cvt_pk_bf16_f32 v8, v152, v153
	v_cvt_pk_bf16_f32 v9, v154, v155
	global_store_dwordx2 v[0:1], v[8:9], off offset:-4
	v_lshl_add_u64 v[0:1], v[0:1], 0, s[6:7]
	global_load_dwordx4 v[152:155], v[2:3], off offset:-8
	v_lshl_add_u64 v[2:3], v[2:3], 0, s[52:53]
	s_waitcnt vmcnt(21)
	v_cvt_pk_bf16_f32 v6, v156, v157
	v_cvt_pk_bf16_f32 v7, v158, v159
	global_store_dwordx2 v[0:1], v[6:7], off offset:-4
	v_lshl_add_u64 v[0:1], v[0:1], 0, s[6:7]
	global_load_dwordx4 v[156:159], v[2:3], off offset:-8
	v_lshl_add_u64 v[2:3], v[2:3], 0, s[52:53]
	s_waitcnt vmcnt(22)
	v_cvt_pk_bf16_f32 v8, v160, v161
	v_cvt_pk_bf16_f32 v9, v162, v163
	global_store_dwordx2 v[0:1], v[8:9], off offset:-4
	v_lshl_add_u64 v[0:1], v[0:1], 0, s[6:7]
	global_load_dwordx4 v[160:163], v[2:3], off offset:-8
	v_lshl_add_u64 v[2:3], v[2:3], 0, s[52:53]
	s_waitcnt vmcnt(23)
	v_cvt_pk_bf16_f32 v6, v164, v165
	v_cvt_pk_bf16_f32 v7, v166, v167
	global_store_dwordx2 v[0:1], v[6:7], off offset:-4
	v_lshl_add_u64 v[0:1], v[0:1], 0, s[6:7]
	global_load_dwordx4 v[164:167], v[2:3], off offset:-8
	v_lshl_add_u64 v[2:3], v[2:3], 0, s[52:53]
	s_waitcnt vmcnt(24)
	v_cvt_pk_bf16_f32 v8, v168, v169
	v_cvt_pk_bf16_f32 v9, v170, v171
	global_store_dwordx2 v[0:1], v[8:9], off offset:-4
	v_lshl_add_u64 v[0:1], v[0:1], 0, s[6:7]
	global_load_dwordx4 v[168:171], v[2:3], off offset:-8
	v_lshl_add_u64 v[2:3], v[2:3], 0, s[52:53]
	s_waitcnt vmcnt(25)
	v_cvt_pk_bf16_f32 v6, v172, v173
	v_cvt_pk_bf16_f32 v7, v174, v175
	global_store_dwordx2 v[0:1], v[6:7], off offset:-4
	v_lshl_add_u64 v[0:1], v[0:1], 0, s[6:7]
	global_load_dwordx4 v[172:175], v[2:3], off offset:-8
	v_lshl_add_u64 v[2:3], v[2:3], 0, s[52:53]
	s_waitcnt vmcnt(26)
	v_cvt_pk_bf16_f32 v8, v176, v177
	v_cvt_pk_bf16_f32 v9, v178, v179
	global_store_dwordx2 v[0:1], v[8:9], off offset:-4
	v_lshl_add_u64 v[0:1], v[0:1], 0, s[6:7]
	global_load_dwordx4 v[176:179], v[2:3], off offset:-8
	v_lshl_add_u64 v[2:3], v[2:3], 0, s[52:53]
	s_waitcnt vmcnt(27)
	v_cvt_pk_bf16_f32 v6, v180, v181
	v_cvt_pk_bf16_f32 v7, v182, v183
	global_store_dwordx2 v[0:1], v[6:7], off offset:-4
	v_lshl_add_u64 v[0:1], v[0:1], 0, s[6:7]
	global_load_dwordx4 v[180:183], v[2:3], off offset:-8
	v_lshl_add_u64 v[2:3], v[2:3], 0, s[52:53]
	s_waitcnt vmcnt(28)
	v_cvt_pk_bf16_f32 v8, v184, v185
	v_cvt_pk_bf16_f32 v9, v186, v187
	global_store_dwordx2 v[0:1], v[8:9], off offset:-4
	v_lshl_add_u64 v[0:1], v[0:1], 0, s[6:7]
	global_load_dwordx4 v[184:187], v[2:3], off offset:-8
	v_lshl_add_u64 v[2:3], v[2:3], 0, s[52:53]
	s_waitcnt vmcnt(29)
	v_cvt_pk_bf16_f32 v6, v188, v189
	v_cvt_pk_bf16_f32 v7, v190, v191
	global_store_dwordx2 v[0:1], v[6:7], off offset:-4
	v_lshl_add_u64 v[0:1], v[0:1], 0, s[6:7]
	global_load_dwordx4 v[188:191], v[2:3], off offset:-8
	v_lshl_add_u64 v[2:3], v[2:3], 0, s[52:53]
	s_waitcnt vmcnt(30)
	v_cvt_pk_bf16_f32 v8, v192, v193
	v_cvt_pk_bf16_f32 v9, v194, v195
	global_store_dwordx2 v[0:1], v[8:9], off offset:-4
	v_lshl_add_u64 v[0:1], v[0:1], 0, s[6:7]
	global_load_dwordx4 v[192:195], v[2:3], off offset:-8
	v_lshl_add_u64 v[2:3], v[2:3], 0, s[52:53]
	s_waitcnt vmcnt(30)
	v_cvt_pk_bf16_f32 v6, v132, v133
	v_cvt_pk_bf16_f32 v7, v134, v135
	global_store_dwordx2 v[0:1], v[6:7], off offset:-4
	v_lshl_add_u64 v[0:1], v[0:1], 0, s[6:7]
	s_waitcnt vmcnt(29)
	v_cvt_pk_bf16_f32 v8, v136, v137
	v_cvt_pk_bf16_f32 v9, v138, v139
	global_store_dwordx2 v[0:1], v[8:9], off offset:-4
	v_lshl_add_u64 v[0:1], v[0:1], 0, s[6:7]
	s_waitcnt vmcnt(28)
	v_cvt_pk_bf16_f32 v6, v140, v141
	v_cvt_pk_bf16_f32 v7, v142, v143
	global_store_dwordx2 v[0:1], v[6:7], off offset:-4
	v_lshl_add_u64 v[0:1], v[0:1], 0, s[6:7]
	s_waitcnt vmcnt(27)
	v_cvt_pk_bf16_f32 v8, v144, v145
	v_cvt_pk_bf16_f32 v9, v146, v147
	global_store_dwordx2 v[0:1], v[8:9], off offset:-4
	v_lshl_add_u64 v[0:1], v[0:1], 0, s[6:7]
	s_waitcnt vmcnt(26)
	v_cvt_pk_bf16_f32 v6, v148, v149
	v_cvt_pk_bf16_f32 v7, v150, v151
	global_store_dwordx2 v[0:1], v[6:7], off offset:-4
	v_lshl_add_u64 v[0:1], v[0:1], 0, s[6:7]
	s_waitcnt vmcnt(25)
	v_cvt_pk_bf16_f32 v8, v152, v153
	v_cvt_pk_bf16_f32 v9, v154, v155
	global_store_dwordx2 v[0:1], v[8:9], off offset:-4
	v_lshl_add_u64 v[0:1], v[0:1], 0, s[6:7]
	s_waitcnt vmcnt(24)
	v_cvt_pk_bf16_f32 v6, v156, v157
	v_cvt_pk_bf16_f32 v7, v158, v159
	global_store_dwordx2 v[0:1], v[6:7], off offset:-4
	v_lshl_add_u64 v[0:1], v[0:1], 0, s[6:7]
	s_waitcnt vmcnt(23)
	v_cvt_pk_bf16_f32 v8, v160, v161
	v_cvt_pk_bf16_f32 v9, v162, v163
	global_store_dwordx2 v[0:1], v[8:9], off offset:-4
	v_lshl_add_u64 v[0:1], v[0:1], 0, s[6:7]
	s_waitcnt vmcnt(22)
	v_cvt_pk_bf16_f32 v6, v164, v165
	v_cvt_pk_bf16_f32 v7, v166, v167
	global_store_dwordx2 v[0:1], v[6:7], off offset:-4
	v_lshl_add_u64 v[0:1], v[0:1], 0, s[6:7]
	s_waitcnt vmcnt(21)
	v_cvt_pk_bf16_f32 v8, v168, v169
	v_cvt_pk_bf16_f32 v9, v170, v171
	global_store_dwordx2 v[0:1], v[8:9], off offset:-4
	v_lshl_add_u64 v[0:1], v[0:1], 0, s[6:7]
	s_waitcnt vmcnt(20)
	v_cvt_pk_bf16_f32 v6, v172, v173
	v_cvt_pk_bf16_f32 v7, v174, v175
	global_store_dwordx2 v[0:1], v[6:7], off offset:-4
	v_lshl_add_u64 v[0:1], v[0:1], 0, s[6:7]
	s_waitcnt vmcnt(19)
	v_cvt_pk_bf16_f32 v8, v176, v177
	v_cvt_pk_bf16_f32 v9, v178, v179
	global_store_dwordx2 v[0:1], v[8:9], off offset:-4
	v_lshl_add_u64 v[0:1], v[0:1], 0, s[6:7]
	s_waitcnt vmcnt(18)
	v_cvt_pk_bf16_f32 v6, v180, v181
	v_cvt_pk_bf16_f32 v7, v182, v183
	global_store_dwordx2 v[0:1], v[6:7], off offset:-4
	v_lshl_add_u64 v[0:1], v[0:1], 0, s[6:7]
	s_waitcnt vmcnt(17)
	v_cvt_pk_bf16_f32 v8, v184, v185
	v_cvt_pk_bf16_f32 v9, v186, v187
	global_store_dwordx2 v[0:1], v[8:9], off offset:-4
	v_lshl_add_u64 v[0:1], v[0:1], 0, s[6:7]
	s_waitcnt vmcnt(16)
	v_cvt_pk_bf16_f32 v6, v188, v189
	v_cvt_pk_bf16_f32 v7, v190, v191
	global_store_dwordx2 v[0:1], v[6:7], off offset:-4
	v_lshl_add_u64 v[0:1], v[0:1], 0, s[6:7]
	s_waitcnt vmcnt(15)
	v_cvt_pk_bf16_f32 v8, v192, v193
	v_cvt_pk_bf16_f32 v9, v194, v195
	global_store_dwordx2 v[0:1], v[8:9], off offset:-4
	v_lshl_add_u64 v[0:1], v[0:1], 0, s[6:7]

.LBB0_55:
	v_mov_b32_e32 v4, v74
	v_lshlrev_b32_e32 v6, 2, v4
	v_mov_b32_e32 v0, v4
	v_mov_b32_e32 v1, 0
	v_lshl_add_u64 v[0:1], s[52:53], 0, v[0:1]
	v_lshlrev_b64 v[0:1], 10, v[0:1]
	v_lshl_add_u64 v[0:1], s[54:55], 0, v[0:1]
	v_add_u32_e32 v5, 256, v74
	v_lshlrev_b32_e32 v7, 2, v5
	v_mov_b32_e32 v2, v5
	v_mov_b32_e32 v3, 0
	v_lshl_add_u64 v[2:3], s[52:53], 0, v[2:3]
	v_lshlrev_b64 v[2:3], 10, v[2:3]
	v_lshl_add_u64 v[2:3], s[54:55], 0, v[2:3]
	v_mov_b32_e32 v8, v6
	global_load_dword v132, v8, s[6:7]
	global_load_dword v133, v8, s[6:7] offset:2048
	v_add_u32_e32 v9, 0x1000, v6
	global_load_dword v134, v9, s[6:7]
	global_load_dword v135, v9, s[6:7] offset:2048
	v_add_u32_e32 v10, 0x2000, v6
	global_load_dword v136, v10, s[6:7]
	global_load_dword v137, v10, s[6:7] offset:2048
	v_add_u32_e32 v11, 0x3000, v6
	global_load_dword v138, v11, s[6:7]
	global_load_dword v139, v11, s[6:7] offset:2048
	v_add_u32_e32 v8, 0x4000, v6
	global_load_dword v140, v8, s[6:7]
	global_load_dword v141, v8, s[6:7] offset:2048
	v_add_u32_e32 v9, 0x5000, v6
	global_load_dword v142, v9, s[6:7]
	global_load_dword v143, v9, s[6:7] offset:2048
	v_add_u32_e32 v10, 0x6000, v6
	global_load_dword v144, v10, s[6:7]
	global_load_dword v145, v10, s[6:7] offset:2048
	v_add_u32_e32 v11, 0x7000, v6
	global_load_dword v146, v11, s[6:7]
	global_load_dword v147, v11, s[6:7] offset:2048
	v_add_u32_e32 v8, 0x8000, v6
	global_load_dword v148, v8, s[6:7]
	global_load_dword v149, v8, s[6:7] offset:2048
	v_add_u32_e32 v9, 0x9000, v6
	global_load_dword v150, v9, s[6:7]
	global_load_dword v151, v9, s[6:7] offset:2048
	v_add_u32_e32 v10, 0xa000, v6
	global_load_dword v152, v10, s[6:7]
	global_load_dword v153, v10, s[6:7] offset:2048
	v_add_u32_e32 v11, 0xb000, v6
	global_load_dword v154, v11, s[6:7]
	global_load_dword v155, v11, s[6:7] offset:2048
	v_add_u32_e32 v8, 0xc000, v6
	global_load_dword v156, v8, s[6:7]
	global_load_dword v157, v8, s[6:7] offset:2048
	v_add_u32_e32 v9, 0xd000, v6
	global_load_dword v158, v9, s[6:7]
	global_load_dword v159, v9, s[6:7] offset:2048
	v_add_u32_e32 v10, 0xe000, v6
	global_load_dword v160, v10, s[6:7]
	global_load_dword v161, v10, s[6:7] offset:2048
	v_add_u32_e32 v11, 0xf000, v6
	global_load_dword v162, v11, s[6:7]
	global_load_dword v163, v11, s[6:7] offset:2048
	v_add_u32_e32 v8, 0x10000, v6
	global_load_dword v164, v8, s[6:7]
	global_load_dword v165, v8, s[6:7] offset:2048
	v_add_u32_e32 v9, 0x11000, v6
	global_load_dword v166, v9, s[6:7]
	global_load_dword v167, v9, s[6:7] offset:2048
	v_add_u32_e32 v10, 0x12000, v6
	global_load_dword v168, v10, s[6:7]
	global_load_dword v169, v10, s[6:7] offset:2048
	v_add_u32_e32 v11, 0x13000, v6
	global_load_dword v170, v11, s[6:7]
	global_load_dword v171, v11, s[6:7] offset:2048
	v_add_u32_e32 v8, 0x14000, v6
	global_load_dword v172, v8, s[6:7]
	global_load_dword v173, v8, s[6:7] offset:2048
	v_add_u32_e32 v9, 0x15000, v6
	global_load_dword v174, v9, s[6:7]
	global_load_dword v175, v9, s[6:7] offset:2048
	v_add_u32_e32 v10, 0x16000, v6
	global_load_dword v176, v10, s[6:7]
	global_load_dword v177, v10, s[6:7] offset:2048
	v_add_u32_e32 v11, 0x17000, v6
	global_load_dword v178, v11, s[6:7]
	global_load_dword v179, v11, s[6:7] offset:2048
	v_add_u32_e32 v8, 0x18000, v6
	global_load_dword v180, v8, s[6:7]
	global_load_dword v181, v8, s[6:7] offset:2048
	v_add_u32_e32 v9, 0x19000, v6
	global_load_dword v182, v9, s[6:7]
	global_load_dword v183, v9, s[6:7] offset:2048
	v_add_u32_e32 v10, 0x1a000, v6
	global_load_dword v184, v10, s[6:7]
	global_load_dword v185, v10, s[6:7] offset:2048
	v_add_u32_e32 v11, 0x1b000, v6
	global_load_dword v186, v11, s[6:7]
	global_load_dword v187, v11, s[6:7] offset:2048
	s_waitcnt vmcnt(48)
	v_cvt_pk_bf16_f32 v12, v132, v133
	v_cvt_pk_bf16_f32 v13, v134, v135
	v_cvt_pk_bf16_f32 v14, v136, v137
	v_cvt_pk_bf16_f32 v15, v138, v139
	global_store_dwordx4 v[0:1], v[12:15], off
	v_add_u32_e32 v8, 0x1c000, v6
	global_load_dword v132, v8, s[6:7]
	global_load_dword v133, v8, s[6:7] offset:2048
	v_add_u32_e32 v9, 0x1d000, v6
	global_load_dword v134, v9, s[6:7]
	global_load_dword v135, v9, s[6:7] offset:2048
	v_add_u32_e32 v10, 0x1e000, v6
	global_load_dword v136, v10, s[6:7]
	global_load_dword v137, v10, s[6:7] offset:2048
	v_add_u32_e32 v11, 0x1f000, v6
	global_load_dword v138, v11, s[6:7]
	global_load_dword v139, v11, s[6:7] offset:2048
	s_waitcnt vmcnt(49)
	v_cvt_pk_bf16_f32 v16, v140, v141
	v_cvt_pk_bf16_f32 v17, v142, v143
	v_cvt_pk_bf16_f32 v18, v144, v145
	v_cvt_pk_bf16_f32 v19, v146, v147
	global_store_dwordx4 v[0:1], v[16:19], off offset:16
	v_mov_b32_e32 v8, v7
	global_load_dword v140, v8, s[6:7]
	global_load_dword v141, v8, s[6:7] offset:2048
	v_add_u32_e32 v9, 0x1000, v7
	global_load_dword v142, v9, s[6:7]
	global_load_dword v143, v9, s[6:7] offset:2048
	v_add_u32_e32 v10, 0x2000, v7
	global_load_dword v144, v10, s[6:7]
	global_load_dword v145, v10, s[6:7] offset:2048
	v_add_u32_e32 v11, 0x3000, v7
	global_load_dword v146, v11, s[6:7]
	global_load_dword v147, v11, s[6:7] offset:2048
	s_waitcnt vmcnt(50)
	v_cvt_pk_bf16_f32 v12, v148, v149
	v_cvt_pk_bf16_f32 v13, v150, v151
	v_cvt_pk_bf16_f32 v14, v152, v153
	v_cvt_pk_bf16_f32 v15, v154, v155
	global_store_dwordx4 v[0:1], v[12:15], off offset:32
	v_add_u32_e32 v8, 0x4000, v7
	global_load_dword v148, v8, s[6:7]
	global_load_dword v149, v8, s[6:7] offset:2048
	v_add_u32_e32 v9, 0x5000, v7
	global_load_dword v150, v9, s[6:7]
	global_load_dword v151, v9, s[6:7] offset:2048
	v_add_u32_e32 v10, 0x6000, v7
	global_load_dword v152, v10, s[6:7]
	global_load_dword v153, v10, s[6:7] offset:2048
	v_add_u32_e32 v11, 0x7000, v7
	global_load_dword v154, v11, s[6:7]
	global_load_dword v155, v11, s[6:7] offset:2048
	s_waitcnt vmcnt(51)
	v_cvt_pk_bf16_f32 v16, v156, v157
	v_cvt_pk_bf16_f32 v17, v158, v159
	v_cvt_pk_bf16_f32 v18, v160, v161
	v_cvt_pk_bf16_f32 v19, v162, v163
	global_store_dwordx4 v[0:1], v[16:19], off offset:48
	v_add_u32_e32 v8, 0x8000, v7
	global_load_dword v156, v8, s[6:7]
	global_load_dword v157, v8, s[6:7] offset:2048
	v_add_u32_e32 v9, 0x9000, v7
	global_load_dword v158, v9, s[6:7]
	global_load_dword v159, v9, s[6:7] offset:2048
	v_add_u32_e32 v10, 0xa000, v7
	global_load_dword v160, v10, s[6:7]
	global_load_dword v161, v10, s[6:7] offset:2048
	v_add_u32_e32 v11, 0xb000, v7
	global_load_dword v162, v11, s[6:7]
	global_load_dword v163, v11, s[6:7] offset:2048
	s_waitcnt vmcnt(52)
	v_cvt_pk_bf16_f32 v12, v164, v165
	v_cvt_pk_bf16_f32 v13, v166, v167
	v_cvt_pk_bf16_f32 v14, v168, v169
	v_cvt_pk_bf16_f32 v15, v170, v171
	global_store_dwordx4 v[0:1], v[12:15], off offset:64
	v_add_u32_e32 v8, 0xc000, v7
	global_load_dword v164, v8, s[6:7]
	global_load_dword v165, v8, s[6:7] offset:2048
	v_add_u32_e32 v9, 0xd000, v7
	global_load_dword v166, v9, s[6:7]
	global_load_dword v167, v9, s[6:7] offset:2048
	v_add_u32_e32 v10, 0xe000, v7
	global_load_dword v168, v10, s[6:7]
	global_load_dword v169, v10, s[6:7] offset:2048
	v_add_u32_e32 v11, 0xf000, v7
	global_load_dword v170, v11, s[6:7]
	global_load_dword v171, v11, s[6:7] offset:2048
	s_waitcnt vmcnt(53)
	v_cvt_pk_bf16_f32 v16, v172, v173
	v_cvt_pk_bf16_f32 v17, v174, v175
	v_cvt_pk_bf16_f32 v18, v176, v177
	v_cvt_pk_bf16_f32 v19, v178, v179
	global_store_dwordx4 v[0:1], v[16:19], off offset:80
	v_add_u32_e32 v8, 0x10000, v7
	global_load_dword v172, v8, s[6:7]
	global_load_dword v173, v8, s[6:7] offset:2048
	v_add_u32_e32 v9, 0x11000, v7
	global_load_dword v174, v9, s[6:7]
	global_load_dword v175, v9, s[6:7] offset:2048
	v_add_u32_e32 v10, 0x12000, v7
	global_load_dword v176, v10, s[6:7]
	global_load_dword v177, v10, s[6:7] offset:2048
	v_add_u32_e32 v11, 0x13000, v7
	global_load_dword v178, v11, s[6:7]
	global_load_dword v179, v11, s[6:7] offset:2048
	s_waitcnt vmcnt(54)
	v_cvt_pk_bf16_f32 v12, v180, v181
	v_cvt_pk_bf16_f32 v13, v182, v183
	v_cvt_pk_bf16_f32 v14, v184, v185
	v_cvt_pk_bf16_f32 v15, v186, v187
	global_store_dwordx4 v[0:1], v[12:15], off offset:96
	v_add_u32_e32 v8, 0x14000, v7
	global_load_dword v180, v8, s[6:7]
	global_load_dword v181, v8, s[6:7] offset:2048
	v_add_u32_e32 v9, 0x15000, v7
	global_load_dword v182, v9, s[6:7]
	global_load_dword v183, v9, s[6:7] offset:2048
	v_add_u32_e32 v10, 0x16000, v7
	global_load_dword v184, v10, s[6:7]
	global_load_dword v185, v10, s[6:7] offset:2048
	v_add_u32_e32 v11, 0x17000, v7
	global_load_dword v186, v11, s[6:7]
	global_load_dword v187, v11, s[6:7] offset:2048
	s_waitcnt vmcnt(54)
	v_cvt_pk_bf16_f32 v16, v132, v133
	v_cvt_pk_bf16_f32 v17, v134, v135
	v_cvt_pk_bf16_f32 v18, v136, v137
	v_cvt_pk_bf16_f32 v19, v138, v139
	global_store_dwordx4 v[0:1], v[16:19], off offset:112
	v_add_u32_e32 v8, 0x18000, v7
	global_load_dword v132, v8, s[6:7]
	global_load_dword v133, v8, s[6:7] offset:2048
	v_add_u32_e32 v9, 0x19000, v7
	global_load_dword v134, v9, s[6:7]
	global_load_dword v135, v9, s[6:7] offset:2048
	v_add_u32_e32 v10, 0x1a000, v7
	global_load_dword v136, v10, s[6:7]
	global_load_dword v137, v10, s[6:7] offset:2048
	v_add_u32_e32 v11, 0x1b000, v7
	global_load_dword v138, v11, s[6:7]
	global_load_dword v139, v11, s[6:7] offset:2048
	s_waitcnt vmcnt(54)
	v_cvt_pk_bf16_f32 v12, v140, v141
	v_cvt_pk_bf16_f32 v13, v142, v143
	v_cvt_pk_bf16_f32 v14, v144, v145
	v_cvt_pk_bf16_f32 v15, v146, v147
	global_store_dwordx4 v[2:3], v[12:15], off
	v_add_u32_e32 v8, 0x1c000, v7
	global_load_dword v140, v8, s[6:7]
	global_load_dword v141, v8, s[6:7] offset:2048
	v_add_u32_e32 v9, 0x1d000, v7
	global_load_dword v142, v9, s[6:7]
	global_load_dword v143, v9, s[6:7] offset:2048
	v_add_u32_e32 v10, 0x1e000, v7
	global_load_dword v144, v10, s[6:7]
	global_load_dword v145, v10, s[6:7] offset:2048
	v_add_u32_e32 v11, 0x1f000, v7
	global_load_dword v146, v11, s[6:7]
	global_load_dword v147, v11, s[6:7] offset:2048
	s_waitcnt vmcnt(54)
	v_cvt_pk_bf16_f32 v16, v148, v149
	v_cvt_pk_bf16_f32 v17, v150, v151
	v_cvt_pk_bf16_f32 v18, v152, v153
	v_cvt_pk_bf16_f32 v19, v154, v155
	global_store_dwordx4 v[2:3], v[16:19], off offset:16
	s_waitcnt vmcnt(46)
	v_cvt_pk_bf16_f32 v12, v156, v157
	v_cvt_pk_bf16_f32 v13, v158, v159
	v_cvt_pk_bf16_f32 v14, v160, v161
	v_cvt_pk_bf16_f32 v15, v162, v163
	global_store_dwordx4 v[2:3], v[12:15], off offset:32
	s_waitcnt vmcnt(38)
	v_cvt_pk_bf16_f32 v16, v164, v165
	v_cvt_pk_bf16_f32 v17, v166, v167
	v_cvt_pk_bf16_f32 v18, v168, v169
	v_cvt_pk_bf16_f32 v19, v170, v171
	global_store_dwordx4 v[2:3], v[16:19], off offset:48
	s_waitcnt vmcnt(30)
	v_cvt_pk_bf16_f32 v12, v172, v173
	v_cvt_pk_bf16_f32 v13, v174, v175
	v_cvt_pk_bf16_f32 v14, v176, v177
	v_cvt_pk_bf16_f32 v15, v178, v179
	global_store_dwordx4 v[2:3], v[12:15], off offset:64
	s_waitcnt vmcnt(22)
	v_cvt_pk_bf16_f32 v16, v180, v181
	v_cvt_pk_bf16_f32 v17, v182, v183
	v_cvt_pk_bf16_f32 v18, v184, v185
	v_cvt_pk_bf16_f32 v19, v186, v187
	global_store_dwordx4 v[2:3], v[16:19], off offset:80
	s_waitcnt vmcnt(14)
	v_cvt_pk_bf16_f32 v12, v132, v133
	v_cvt_pk_bf16_f32 v13, v134, v135
	v_cvt_pk_bf16_f32 v14, v136, v137
	v_cvt_pk_bf16_f32 v15, v138, v139
	global_store_dwordx4 v[2:3], v[12:15], off offset:96
	s_waitcnt vmcnt(6)
	v_cvt_pk_bf16_f32 v16, v140, v141
	v_cvt_pk_bf16_f32 v17, v142, v143
	v_cvt_pk_bf16_f32 v18, v144, v145
	v_cvt_pk_bf16_f32 v19, v146, v147
	global_store_dwordx4 v[2:3], v[16:19], off offset:112
	s_mov_b64 s[56:57], 0
	s_movk_i32 s4, 0x100

.LBB0_76:
	global_load_dword v198, v[0:1], off
	v_add_u32_e32 v6, 0x400, v2
	v_ashrrev_i32_e32 v7, 31, v6
	v_lshl_add_u64 v[6:7], v[6:7], 2, s[48:49]
	global_load_dword v199, v[6:7], off
	v_add_u32_e32 v6, 0x800, v2
	v_ashrrev_i32_e32 v7, 31, v6
	v_lshl_add_u64 v[6:7], v[6:7], 2, s[48:49]
	global_load_dword v200, v[6:7], off
	v_add_u32_e32 v6, 0xc00, v2
	v_ashrrev_i32_e32 v7, 31, v6
	v_lshl_add_u64 v[6:7], v[6:7], 2, s[48:49]
	global_load_dword v201, v[6:7], off
	v_add_u32_e32 v6, 0x1000, v2
	v_ashrrev_i32_e32 v7, 31, v6
	v_lshl_add_u64 v[6:7], v[6:7], 2, s[48:49]
	global_load_dword v202, v[6:7], off
	s_waitcnt vmcnt(4)
	v_mul_f32_e32 v6, 0xbfb8aa3b, v198
	v_exp_f32_e32 v6, v6
	s_nop 0
	v_add_f32_e32 v6, 1.0, v6
	v_rcp_f32_e32 v6, v6
	s_nop 0
	v_mul_f32_e32 v5, v198, v6
	v_add_u32_e32 v7, 0x20, v21
	ds_write_b32 v7, v5
	s_waitcnt vmcnt(3)
	v_mul_f32_e32 v6, 0xbfb8aa3b, v199
	v_exp_f32_e32 v6, v6
	s_nop 0
	v_add_f32_e32 v6, 1.0, v6
	v_rcp_f32_e32 v6, v6
	s_nop 0
	v_mul_f32_e32 v5, v199, v6
	v_add_u32_e32 v7, 0x420, v21
	ds_write_b32 v7, v5
	s_waitcnt vmcnt(2)
	v_mul_f32_e32 v6, 0xbfb8aa3b, v200
	v_exp_f32_e32 v6, v6
	s_nop 0
	v_add_f32_e32 v6, 1.0, v6
	v_rcp_f32_e32 v6, v6
	s_nop 0
	v_mul_f32_e32 v5, v200, v6
	v_add_u32_e32 v7, 0x820, v21
	ds_write_b32 v7, v5
	s_waitcnt vmcnt(1)
	v_mul_f32_e32 v6, 0xbfb8aa3b, v201
	v_exp_f32_e32 v6, v6
	s_nop 0
	v_add_f32_e32 v6, 1.0, v6
	v_rcp_f32_e32 v6, v6
	s_nop 0
	v_mul_f32_e32 v5, v201, v6
	v_add_u32_e32 v7, 0xc20, v21
	ds_write_b32 v7, v5
	s_waitcnt vmcnt(0)
	v_mul_f32_e32 v6, 0xbfb8aa3b, v202
	v_exp_f32_e32 v6, v6
	s_nop 0
	v_add_f32_e32 v6, 1.0, v6
	v_rcp_f32_e32 v6, v6
	s_nop 0
	v_mul_f32_e32 v5, v202, v6
	v_add_u32_e32 v7, 0x1020, v21
	ds_write_b32 v7, v5
	s_or_b64 exec, exec, s[6:7]
.LBB0_78:
	s_or_b64 exec, exec, s[4:5]
	s_ashr_i32 s4, s91, 2
	s_mul_hi_i32 s5, s4, 0x2aaaaaab
	s_lshr_b32 s6, s5, 31
	s_lshr_b32 s5, s5, 4
	s_add_i32 s5, s5, s6
	s_mulk_i32 s5, 0x60
	s_sub_i32 s4, s4, s5
	s_mul_hi_i32 s5, s91, 0x2aaaaaab
	s_lshr_b32 s6, s5, 31
	s_ashr_i32 s18, s5, 6
	s_add_i32 s18, s18, s6
	s_and_b32 s6, s2, 3
	v_and_b32_e32 v0, -16, v74
	s_load_dwordx16 s[48:63], s[86:87], 0x40
	v_lshl_add_u32 v33, v0, 2, 32
	v_lshl_add_u32 v0, s6, 8, v0
	s_lshl_b32 s4, s4, 6
	v_mad_i64_i32 v[0:1], s[6:7], v0, s94, 0
	s_ashr_i32 s5, s4, 31
	v_mad_i64_i32 v[0:1], s[6:7], s18, v86, v[0:1]
	s_lshl_b64 s[6:7], s[4:5], 2
	v_and_b32_e32 v2, 15, v74
	s_waitcnt lgkmcnt(0)
	s_add_u32 s52, s48, s6
	v_lshl_or_b32 v0, v2, 4, v0
	s_addc_u32 s53, s49, s7
	v_mov_b32_e32 v4, 0
	v_lshl_add_u64 v[76:77], s[52:53], 0, v[0:1]
	s_mov_b64 s[52:53], 0
	v_mov_b32_e32 v5, v4
	v_mov_b32_e32 v6, v4
	v_mov_b32_e32 v7, v4
	v_mov_b32_e32 v16, v4
	v_mov_b32_e32 v17, v4
	v_mov_b32_e32 v18, v4
	v_mov_b32_e32 v19, v4
	v_mov_b32_e32 v12, v4
	v_mov_b32_e32 v13, v4
	v_mov_b32_e32 v14, v4
	v_mov_b32_e32 v15, v4
	v_mov_b32_e32 v8, v4
	v_mov_b32_e32 v9, v4
	v_mov_b32_e32 v10, v4
	v_mov_b32_e32 v11, v4
	v_mov_b32_e32 v0, v4
	v_mov_b32_e32 v1, v4
	v_mov_b32_e32 v2, v4
	v_mov_b32_e32 v3, v4
	s_mov_b64 s[98:99], 0x6000
	v_mov_b64_e32 v[196:197], v[76:77]
	global_load_dwordx4 v[132:135], v[196:197], off
	v_lshl_add_u64 v[196:197], v[196:197], 0, s[98:99]
	global_load_dwordx4 v[136:139], v[196:197], off
	v_lshl_add_u64 v[196:197], v[196:197], 0, s[98:99]
	global_load_dwordx4 v[140:143], v[196:197], off
	v_lshl_add_u64 v[196:197], v[196:197], 0, s[98:99]
	global_load_dwordx4 v[144:147], v[196:197], off
	v_lshl_add_u64 v[196:197], v[196:197], 0, s[98:99]
	global_load_dwordx4 v[148:151], v[196:197], off
	v_lshl_add_u64 v[196:197], v[196:197], 0, s[98:99]
	global_load_dwordx4 v[152:155], v[196:197], off
	v_lshl_add_u64 v[196:197], v[196:197], 0, s[98:99]
	global_load_dwordx4 v[156:159], v[196:197], off
	v_lshl_add_u64 v[196:197], v[196:197], 0, s[98:99]
	global_load_dwordx4 v[160:163], v[196:197], off
	v_lshl_add_u64 v[196:197], v[196:197], 0, s[98:99]
	global_load_dwordx4 v[164:167], v[196:197], off
	v_lshl_add_u64 v[196:197], v[196:197], 0, s[98:99]
	global_load_dwordx4 v[168:171], v[196:197], off
	v_lshl_add_u64 v[196:197], v[196:197], 0, s[98:99]
	global_load_dwordx4 v[172:175], v[196:197], off
	v_lshl_add_u64 v[196:197], v[196:197], 0, s[98:99]
	global_load_dwordx4 v[176:179], v[196:197], off
	v_lshl_add_u64 v[196:197], v[196:197], 0, s[98:99]
	global_load_dwordx4 v[180:183], v[196:197], off
	v_lshl_add_u64 v[196:197], v[196:197], 0, s[98:99]
	global_load_dwordx4 v[184:187], v[196:197], off
	v_lshl_add_u64 v[196:197], v[196:197], 0, s[98:99]
	global_load_dwordx4 v[188:191], v[196:197], off
	v_lshl_add_u64 v[196:197], v[196:197], 0, s[98:99]
	global_load_dwordx4 v[192:195], v[196:197], off
	s_barrier
.LBB0_79:
	ds_read_b128 v[104:107], v33
	ds_read_b128 v[108:111], v33 offset:1024
	ds_read_b128 v[112:115], v33 offset:2048
	ds_read_b128 v[116:119], v33 offset:3072
	ds_read_b128 v[120:123], v33 offset:4096
	s_waitcnt lgkmcnt(4)
	v_mov_b32_e32 v78, v107
	s_waitcnt lgkmcnt(3)
	v_mov_b32_e32 v124, v111
	s_waitcnt lgkmcnt(2)
	v_mov_b32_e32 v126, v115
	s_waitcnt lgkmcnt(1)
	v_mov_b32_e32 v128, v119
	s_waitcnt lgkmcnt(0)
	v_mov_b32_e32 v130, v123
	v_add_u32_e32 v33, 16, v33
	s_waitcnt vmcnt(15)
	v_pk_fma_f32 v[4:5], v[132:133], v[104:105], v[4:5] op_sel_hi:[1,0,1]
	v_pk_fma_f32 v[6:7], v[134:135], v[104:105], v[6:7] op_sel_hi:[1,0,1]
	v_pk_fma_f32 v[16:17], v[132:133], v[108:109], v[16:17] op_sel_hi:[1,0,1]
	v_pk_fma_f32 v[18:19], v[134:135], v[108:109], v[18:19] op_sel_hi:[1,0,1]
	v_pk_fma_f32 v[12:13], v[132:133], v[112:113], v[12:13] op_sel_hi:[1,0,1]
	v_pk_fma_f32 v[14:15], v[134:135], v[112:113], v[14:15] op_sel_hi:[1,0,1]
	v_pk_fma_f32 v[8:9], v[132:133], v[116:117], v[8:9] op_sel_hi:[1,0,1]
	v_pk_fma_f32 v[10:11], v[134:135], v[116:117], v[10:11] op_sel_hi:[1,0,1]
	v_pk_fma_f32 v[0:1], v[132:133], v[120:121], v[0:1] op_sel_hi:[1,0,1]
	v_pk_fma_f32 v[2:3], v[134:135], v[120:121], v[2:3] op_sel_hi:[1,0,1]
	s_waitcnt vmcnt(14)
	v_pk_fma_f32 v[4:5], v[136:137], v[104:105], v[4:5] op_sel:[0,1,0]
	v_pk_fma_f32 v[6:7], v[138:139], v[104:105], v[6:7] op_sel:[0,1,0]
	v_pk_fma_f32 v[16:17], v[136:137], v[108:109], v[16:17] op_sel:[0,1,0]
	v_pk_fma_f32 v[18:19], v[138:139], v[108:109], v[18:19] op_sel:[0,1,0]
	v_pk_fma_f32 v[12:13], v[136:137], v[112:113], v[12:13] op_sel:[0,1,0]
	v_pk_fma_f32 v[14:15], v[138:139], v[112:113], v[14:15] op_sel:[0,1,0]
	v_pk_fma_f32 v[8:9], v[136:137], v[116:117], v[8:9] op_sel:[0,1,0]
	v_pk_fma_f32 v[10:11], v[138:139], v[116:117], v[10:11] op_sel:[0,1,0]
	v_pk_fma_f32 v[0:1], v[136:137], v[120:121], v[0:1] op_sel:[0,1,0]
	v_pk_fma_f32 v[2:3], v[138:139], v[120:121], v[2:3] op_sel:[0,1,0]
	s_waitcnt vmcnt(13)
	v_pk_fma_f32 v[4:5], v[140:141], v[106:107], v[4:5] op_sel_hi:[1,0,1]
	v_pk_fma_f32 v[6:7], v[142:143], v[106:107], v[6:7] op_sel_hi:[1,0,1]
	v_pk_fma_f32 v[16:17], v[140:141], v[110:111], v[16:17] op_sel_hi:[1,0,1]
	v_pk_fma_f32 v[18:19], v[142:143], v[110:111], v[18:19] op_sel_hi:[1,0,1]
	v_pk_fma_f32 v[12:13], v[140:141], v[114:115], v[12:13] op_sel_hi:[1,0,1]
	v_pk_fma_f32 v[14:15], v[142:143], v[114:115], v[14:15] op_sel_hi:[1,0,1]
	v_pk_fma_f32 v[8:9], v[140:141], v[118:119], v[8:9] op_sel_hi:[1,0,1]
	v_pk_fma_f32 v[10:11], v[142:143], v[118:119], v[10:11] op_sel_hi:[1,0,1]
	v_pk_fma_f32 v[0:1], v[140:141], v[122:123], v[0:1] op_sel_hi:[1,0,1]
	v_pk_fma_f32 v[2:3], v[142:143], v[122:123], v[2:3] op_sel_hi:[1,0,1]
	s_waitcnt vmcnt(12)
	v_pk_fma_f32 v[4:5], v[144:145], v[78:79], v[4:5] op_sel_hi:[1,0,1]
	v_pk_fma_f32 v[6:7], v[146:147], v[78:79], v[6:7] op_sel_hi:[1,0,1]
	v_pk_fma_f32 v[16:17], v[144:145], v[124:125], v[16:17] op_sel_hi:[1,0,1]
	v_pk_fma_f32 v[18:19], v[146:147], v[124:125], v[18:19] op_sel_hi:[1,0,1]
	v_pk_fma_f32 v[12:13], v[144:145], v[126:127], v[12:13] op_sel_hi:[1,0,1]
	v_pk_fma_f32 v[14:15], v[146:147], v[126:127], v[14:15] op_sel_hi:[1,0,1]
	v_pk_fma_f32 v[8:9], v[144:145], v[128:129], v[8:9] op_sel_hi:[1,0,1]
	v_pk_fma_f32 v[10:11], v[146:147], v[128:129], v[10:11] op_sel_hi:[1,0,1]
	v_pk_fma_f32 v[0:1], v[144:145], v[130:131], v[0:1] op_sel_hi:[1,0,1]
	v_pk_fma_f32 v[2:3], v[146:147], v[130:131], v[2:3] op_sel_hi:[1,0,1]
	ds_read_b128 v[104:107], v33
	ds_read_b128 v[108:111], v33 offset:1024
	ds_read_b128 v[112:115], v33 offset:2048
	ds_read_b128 v[116:119], v33 offset:3072
	ds_read_b128 v[120:123], v33 offset:4096
	s_waitcnt lgkmcnt(4)
	v_mov_b32_e32 v78, v107
	s_waitcnt lgkmcnt(3)
	v_mov_b32_e32 v124, v111
	s_waitcnt lgkmcnt(2)
	v_mov_b32_e32 v126, v115
	s_waitcnt lgkmcnt(1)
	v_mov_b32_e32 v128, v119
	s_waitcnt lgkmcnt(0)
	v_mov_b32_e32 v130, v123
	v_add_u32_e32 v33, 16, v33
	s_waitcnt vmcnt(11)
	v_pk_fma_f32 v[4:5], v[148:149], v[104:105], v[4:5] op_sel_hi:[1,0,1]
	v_pk_fma_f32 v[6:7], v[150:151], v[104:105], v[6:7] op_sel_hi:[1,0,1]
	v_pk_fma_f32 v[16:17], v[148:149], v[108:109], v[16:17] op_sel_hi:[1,0,1]
	v_pk_fma_f32 v[18:19], v[150:151], v[108:109], v[18:19] op_sel_hi:[1,0,1]
	v_pk_fma_f32 v[12:13], v[148:149], v[112:113], v[12:13] op_sel_hi:[1,0,1]
	v_pk_fma_f32 v[14:15], v[150:151], v[112:113], v[14:15] op_sel_hi:[1,0,1]
	v_pk_fma_f32 v[8:9], v[148:149], v[116:117], v[8:9] op_sel_hi:[1,0,1]
	v_pk_fma_f32 v[10:11], v[150:151], v[116:117], v[10:11] op_sel_hi:[1,0,1]
	v_pk_fma_f32 v[0:1], v[148:149], v[120:121], v[0:1] op_sel_hi:[1,0,1]
	v_pk_fma_f32 v[2:3], v[150:151], v[120:121], v[2:3] op_sel_hi:[1,0,1]
	s_waitcnt vmcnt(10)
	v_pk_fma_f32 v[4:5], v[152:153], v[104:105], v[4:5] op_sel:[0,1,0]
	v_pk_fma_f32 v[6:7], v[154:155], v[104:105], v[6:7] op_sel:[0,1,0]
	v_pk_fma_f32 v[16:17], v[152:153], v[108:109], v[16:17] op_sel:[0,1,0]
	v_pk_fma_f32 v[18:19], v[154:155], v[108:109], v[18:19] op_sel:[0,1,0]
	v_pk_fma_f32 v[12:13], v[152:153], v[112:113], v[12:13] op_sel:[0,1,0]
	v_pk_fma_f32 v[14:15], v[154:155], v[112:113], v[14:15] op_sel:[0,1,0]
	v_pk_fma_f32 v[8:9], v[152:153], v[116:117], v[8:9] op_sel:[0,1,0]
	v_pk_fma_f32 v[10:11], v[154:155], v[116:117], v[10:11] op_sel:[0,1,0]
	v_pk_fma_f32 v[0:1], v[152:153], v[120:121], v[0:1] op_sel:[0,1,0]
	v_pk_fma_f32 v[2:3], v[154:155], v[120:121], v[2:3] op_sel:[0,1,0]
	s_waitcnt vmcnt(9)
	v_pk_fma_f32 v[4:5], v[156:157], v[106:107], v[4:5] op_sel_hi:[1,0,1]
	v_pk_fma_f32 v[6:7], v[158:159], v[106:107], v[6:7] op_sel_hi:[1,0,1]
	v_pk_fma_f32 v[16:17], v[156:157], v[110:111], v[16:17] op_sel_hi:[1,0,1]
	v_pk_fma_f32 v[18:19], v[158:159], v[110:111], v[18:19] op_sel_hi:[1,0,1]
	v_pk_fma_f32 v[12:13], v[156:157], v[114:115], v[12:13] op_sel_hi:[1,0,1]
	v_pk_fma_f32 v[14:15], v[158:159], v[114:115], v[14:15] op_sel_hi:[1,0,1]
	v_pk_fma_f32 v[8:9], v[156:157], v[118:119], v[8:9] op_sel_hi:[1,0,1]
	v_pk_fma_f32 v[10:11], v[158:159], v[118:119], v[10:11] op_sel_hi:[1,0,1]
	v_pk_fma_f32 v[0:1], v[156:157], v[122:123], v[0:1] op_sel_hi:[1,0,1]
	v_pk_fma_f32 v[2:3], v[158:159], v[122:123], v[2:3] op_sel_hi:[1,0,1]
	s_waitcnt vmcnt(8)
	v_pk_fma_f32 v[4:5], v[160:161], v[78:79], v[4:5] op_sel_hi:[1,0,1]
	v_pk_fma_f32 v[6:7], v[162:163], v[78:79], v[6:7] op_sel_hi:[1,0,1]
	v_pk_fma_f32 v[16:17], v[160:161], v[124:125], v[16:17] op_sel_hi:[1,0,1]
	v_pk_fma_f32 v[18:19], v[162:163], v[124:125], v[18:19] op_sel_hi:[1,0,1]
	v_pk_fma_f32 v[12:13], v[160:161], v[126:127], v[12:13] op_sel_hi:[1,0,1]
	v_pk_fma_f32 v[14:15], v[162:163], v[126:127], v[14:15] op_sel_hi:[1,0,1]
	v_pk_fma_f32 v[8:9], v[160:161], v[128:129], v[8:9] op_sel_hi:[1,0,1]
	v_pk_fma_f32 v[10:11], v[162:163], v[128:129], v[10:11] op_sel_hi:[1,0,1]
	v_pk_fma_f32 v[0:1], v[160:161], v[130:131], v[0:1] op_sel_hi:[1,0,1]
	v_pk_fma_f32 v[2:3], v[162:163], v[130:131], v[2:3] op_sel_hi:[1,0,1]
	ds_read_b128 v[104:107], v33
	ds_read_b128 v[108:111], v33 offset:1024
	ds_read_b128 v[112:115], v33 offset:2048
	ds_read_b128 v[116:119], v33 offset:3072
	ds_read_b128 v[120:123], v33 offset:4096
	s_waitcnt lgkmcnt(4)
	v_mov_b32_e32 v78, v107
	s_waitcnt lgkmcnt(3)
	v_mov_b32_e32 v124, v111
	s_waitcnt lgkmcnt(2)
	v_mov_b32_e32 v126, v115
	s_waitcnt lgkmcnt(1)
	v_mov_b32_e32 v128, v119
	s_waitcnt lgkmcnt(0)
	v_mov_b32_e32 v130, v123
	v_add_u32_e32 v33, 16, v33
	s_waitcnt vmcnt(7)
	v_pk_fma_f32 v[4:5], v[164:165], v[104:105], v[4:5] op_sel_hi:[1,0,1]
	v_pk_fma_f32 v[6:7], v[166:167], v[104:105], v[6:7] op_sel_hi:[1,0,1]
	v_pk_fma_f32 v[16:17], v[164:165], v[108:109], v[16:17] op_sel_hi:[1,0,1]
	v_pk_fma_f32 v[18:19], v[166:167], v[108:109], v[18:19] op_sel_hi:[1,0,1]
	v_pk_fma_f32 v[12:13], v[164:165], v[112:113], v[12:13] op_sel_hi:[1,0,1]
	v_pk_fma_f32 v[14:15], v[166:167], v[112:113], v[14:15] op_sel_hi:[1,0,1]
	v_pk_fma_f32 v[8:9], v[164:165], v[116:117], v[8:9] op_sel_hi:[1,0,1]
	v_pk_fma_f32 v[10:11], v[166:167], v[116:117], v[10:11] op_sel_hi:[1,0,1]
	v_pk_fma_f32 v[0:1], v[164:165], v[120:121], v[0:1] op_sel_hi:[1,0,1]
	v_pk_fma_f32 v[2:3], v[166:167], v[120:121], v[2:3] op_sel_hi:[1,0,1]
	s_waitcnt vmcnt(6)
	v_pk_fma_f32 v[4:5], v[168:169], v[104:105], v[4:5] op_sel:[0,1,0]
	v_pk_fma_f32 v[6:7], v[170:171], v[104:105], v[6:7] op_sel:[0,1,0]
	v_pk_fma_f32 v[16:17], v[168:169], v[108:109], v[16:17] op_sel:[0,1,0]
	v_pk_fma_f32 v[18:19], v[170:171], v[108:109], v[18:19] op_sel:[0,1,0]
	v_pk_fma_f32 v[12:13], v[168:169], v[112:113], v[12:13] op_sel:[0,1,0]
	v_pk_fma_f32 v[14:15], v[170:171], v[112:113], v[14:15] op_sel:[0,1,0]
	v_pk_fma_f32 v[8:9], v[168:169], v[116:117], v[8:9] op_sel:[0,1,0]
	v_pk_fma_f32 v[10:11], v[170:171], v[116:117], v[10:11] op_sel:[0,1,0]
	v_pk_fma_f32 v[0:1], v[168:169], v[120:121], v[0:1] op_sel:[0,1,0]
	v_pk_fma_f32 v[2:3], v[170:171], v[120:121], v[2:3] op_sel:[0,1,0]
	s_waitcnt vmcnt(5)
	v_pk_fma_f32 v[4:5], v[172:173], v[106:107], v[4:5] op_sel_hi:[1,0,1]
	v_pk_fma_f32 v[6:7], v[174:175], v[106:107], v[6:7] op_sel_hi:[1,0,1]
	v_pk_fma_f32 v[16:17], v[172:173], v[110:111], v[16:17] op_sel_hi:[1,0,1]
	v_pk_fma_f32 v[18:19], v[174:175], v[110:111], v[18:19] op_sel_hi:[1,0,1]
	v_pk_fma_f32 v[12:13], v[172:173], v[114:115], v[12:13] op_sel_hi:[1,0,1]
	v_pk_fma_f32 v[14:15], v[174:175], v[114:115], v[14:15] op_sel_hi:[1,0,1]
	v_pk_fma_f32 v[8:9], v[172:173], v[118:119], v[8:9] op_sel_hi:[1,0,1]
	v_pk_fma_f32 v[10:11], v[174:175], v[118:119], v[10:11] op_sel_hi:[1,0,1]
	v_pk_fma_f32 v[0:1], v[172:173], v[122:123], v[0:1] op_sel_hi:[1,0,1]
	v_pk_fma_f32 v[2:3], v[174:175], v[122:123], v[2:3] op_sel_hi:[1,0,1]
	s_waitcnt vmcnt(4)
	v_pk_fma_f32 v[4:5], v[176:177], v[78:79], v[4:5] op_sel_hi:[1,0,1]
	v_pk_fma_f32 v[6:7], v[178:179], v[78:79], v[6:7] op_sel_hi:[1,0,1]
	v_pk_fma_f32 v[16:17], v[176:177], v[124:125], v[16:17] op_sel_hi:[1,0,1]
	v_pk_fma_f32 v[18:19], v[178:179], v[124:125], v[18:19] op_sel_hi:[1,0,1]
	v_pk_fma_f32 v[12:13], v[176:177], v[126:127], v[12:13] op_sel_hi:[1,0,1]
	v_pk_fma_f32 v[14:15], v[178:179], v[126:127], v[14:15] op_sel_hi:[1,0,1]
	v_pk_fma_f32 v[8:9], v[176:177], v[128:129], v[8:9] op_sel_hi:[1,0,1]
	v_pk_fma_f32 v[10:11], v[178:179], v[128:129], v[10:11] op_sel_hi:[1,0,1]
	v_pk_fma_f32 v[0:1], v[176:177], v[130:131], v[0:1] op_sel_hi:[1,0,1]
	v_pk_fma_f32 v[2:3], v[178:179], v[130:131], v[2:3] op_sel_hi:[1,0,1]
	ds_read_b128 v[104:107], v33
	ds_read_b128 v[108:111], v33 offset:1024
	ds_read_b128 v[112:115], v33 offset:2048
	ds_read_b128 v[116:119], v33 offset:3072
	ds_read_b128 v[120:123], v33 offset:4096
	s_waitcnt lgkmcnt(4)
	v_mov_b32_e32 v78, v107
	s_waitcnt lgkmcnt(3)
	v_mov_b32_e32 v124, v111
	s_waitcnt lgkmcnt(2)
	v_mov_b32_e32 v126, v115
	s_waitcnt lgkmcnt(1)
	v_mov_b32_e32 v128, v119
	s_waitcnt lgkmcnt(0)
	v_mov_b32_e32 v130, v123
	v_add_u32_e32 v33, 16, v33
	s_waitcnt vmcnt(3)
	v_pk_fma_f32 v[4:5], v[180:181], v[104:105], v[4:5] op_sel_hi:[1,0,1]
	v_pk_fma_f32 v[6:7], v[182:183], v[104:105], v[6:7] op_sel_hi:[1,0,1]
	v_pk_fma_f32 v[16:17], v[180:181], v[108:109], v[16:17] op_sel_hi:[1,0,1]
	v_pk_fma_f32 v[18:19], v[182:183], v[108:109], v[18:19] op_sel_hi:[1,0,1]
	v_pk_fma_f32 v[12:13], v[180:181], v[112:113], v[12:13] op_sel_hi:[1,0,1]
	v_pk_fma_f32 v[14:15], v[182:183], v[112:113], v[14:15] op_sel_hi:[1,0,1]
	v_pk_fma_f32 v[8:9], v[180:181], v[116:117], v[8:9] op_sel_hi:[1,0,1]
	v_pk_fma_f32 v[10:11], v[182:183], v[116:117], v[10:11] op_sel_hi:[1,0,1]
	v_pk_fma_f32 v[0:1], v[180:181], v[120:121], v[0:1] op_sel_hi:[1,0,1]
	v_pk_fma_f32 v[2:3], v[182:183], v[120:121], v[2:3] op_sel_hi:[1,0,1]
	s_waitcnt vmcnt(2)
	v_pk_fma_f32 v[4:5], v[184:185], v[104:105], v[4:5] op_sel:[0,1,0]
	v_pk_fma_f32 v[6:7], v[186:187], v[104:105], v[6:7] op_sel:[0,1,0]
	v_pk_fma_f32 v[16:17], v[184:185], v[108:109], v[16:17] op_sel:[0,1,0]
	v_pk_fma_f32 v[18:19], v[186:187], v[108:109], v[18:19] op_sel:[0,1,0]
	v_pk_fma_f32 v[12:13], v[184:185], v[112:113], v[12:13] op_sel:[0,1,0]
	v_pk_fma_f32 v[14:15], v[186:187], v[112:113], v[14:15] op_sel:[0,1,0]
	v_pk_fma_f32 v[8:9], v[184:185], v[116:117], v[8:9] op_sel:[0,1,0]
	v_pk_fma_f32 v[10:11], v[186:187], v[116:117], v[10:11] op_sel:[0,1,0]
	v_pk_fma_f32 v[0:1], v[184:185], v[120:121], v[0:1] op_sel:[0,1,0]
	v_pk_fma_f32 v[2:3], v[186:187], v[120:121], v[2:3] op_sel:[0,1,0]
	s_waitcnt vmcnt(1)
	v_pk_fma_f32 v[4:5], v[188:189], v[106:107], v[4:5] op_sel_hi:[1,0,1]
	v_pk_fma_f32 v[6:7], v[190:191], v[106:107], v[6:7] op_sel_hi:[1,0,1]
	v_pk_fma_f32 v[16:17], v[188:189], v[110:111], v[16:17] op_sel_hi:[1,0,1]
	v_pk_fma_f32 v[18:19], v[190:191], v[110:111], v[18:19] op_sel_hi:[1,0,1]
	v_pk_fma_f32 v[12:13], v[188:189], v[114:115], v[12:13] op_sel_hi:[1,0,1]
	v_pk_fma_f32 v[14:15], v[190:191], v[114:115], v[14:15] op_sel_hi:[1,0,1]
	v_pk_fma_f32 v[8:9], v[188:189], v[118:119], v[8:9] op_sel_hi:[1,0,1]
	v_pk_fma_f32 v[10:11], v[190:191], v[118:119], v[10:11] op_sel_hi:[1,0,1]
	v_pk_fma_f32 v[0:1], v[188:189], v[122:123], v[0:1] op_sel_hi:[1,0,1]
	v_pk_fma_f32 v[2:3], v[190:191], v[122:123], v[2:3] op_sel_hi:[1,0,1]
	s_waitcnt vmcnt(0)
	v_pk_fma_f32 v[4:5], v[192:193], v[78:79], v[4:5] op_sel_hi:[1,0,1]
	v_pk_fma_f32 v[6:7], v[194:195], v[78:79], v[6:7] op_sel_hi:[1,0,1]
	v_pk_fma_f32 v[16:17], v[192:193], v[124:125], v[16:17] op_sel_hi:[1,0,1]
	v_pk_fma_f32 v[18:19], v[194:195], v[124:125], v[18:19] op_sel_hi:[1,0,1]
	v_pk_fma_f32 v[12:13], v[192:193], v[126:127], v[12:13] op_sel_hi:[1,0,1]
	v_pk_fma_f32 v[14:15], v[194:195], v[126:127], v[14:15] op_sel_hi:[1,0,1]
	v_pk_fma_f32 v[8:9], v[192:193], v[128:129], v[8:9] op_sel_hi:[1,0,1]
	v_pk_fma_f32 v[10:11], v[194:195], v[128:129], v[10:11] op_sel_hi:[1,0,1]
	v_pk_fma_f32 v[0:1], v[192:193], v[130:131], v[0:1] op_sel_hi:[1,0,1]
	v_pk_fma_f32 v[2:3], v[194:195], v[130:131], v[2:3] op_sel_hi:[1,0,1]
	v_and_b32_e32 v21, 60, v21
	v_lshrrev_b32_e32 v33, 4, v74
	s_movk_i32 s5, 0x500
	v_lshlrev_b32_e32 v21, 2, v21
	v_mul_lo_u32 v33, v33, s5
	s_movk_i32 s5, 0x140
	v_add3_u32 v21, 32, v21, v33
	v_cmp_gt_i32_e32 vcc, s5, v74
	ds_write_b128 v21, v[4:7] offset:5120
	ds_write_b128 v21, v[16:19] offset:5376
	ds_write_b128 v21, v[12:15] offset:5632
	ds_write_b128 v21, v[8:11] offset:5888
	ds_write_b128 v21, v[0:3] offset:6144
	s_waitcnt lgkmcnt(0)
	s_barrier
	s_and_saveexec_b64 s[52:53], vcc
	s_cbranch_execz .LBB0_22
	s_load_dwordx16 s[36:51], s[86:87], 0x40
	s_cmp_eq_u32 s13, 0
	s_mul_i32 s5, s18, 0x1800
	s_cselect_b64 s[54:55], -1, 0
	s_add_i32 s4, s4, s5
	v_and_b32_e32 v1, 63, v74
	v_or_b32_e32 v2, s4, v1
	s_add_u32 s4, s30, s6
	v_lshlrev_b32_e32 v0, 2, v1
	v_ashrrev_i32_e32 v3, 31, v2
	s_addc_u32 s5, s31, s7
	v_mov_b32_e32 v1, v20
	s_mul_i32 s18, s18, 5
	v_add_u32_e32 v4, 32, v0
	v_lshl_add_u64 v[0:1], s[4:5], 0, v[0:1]
	s_waitcnt lgkmcnt(0)
	v_lshl_add_u64 v[2:3], v[2:3], 2, s[38:39]
	s_mov_b64 s[4:5], 0
	s_branch .LBB0_83

.LBB0_198:
	s_setprio 1
	ds_read_b128 v[140:143], v103
	ds_read_b128 v[144:147], v104 offset:36864
	ds_read_b128 v[148:151], v103 offset:32
	ds_read_b128 v[152:155], v104 offset:36896
	ds_read_b128 v[156:159], v104 offset:41472
	ds_read_b128 v[160:163], v104 offset:41504
	s_waitcnt lgkmcnt(4)
	v_mfma_f32_32x32x16_bf16 v[48:63], v[140:143], v[144:147], v[48:63]
	global_load_dwordx4 v[108:111], v168, s[98:99] offset:3840
	global_load_dwordx4 v[112:115], v170, s[98:99] offset:3840
	s_waitcnt vmcnt(9)
	ds_write_b128 v105, v[68:71] offset:18432
	s_waitcnt lgkmcnt(2)
	v_mfma_f32_32x32x16_bf16 v[32:47], v[140:143], v[156:159], v[32:47]
	global_load_dwordx4 v[116:119], v172, s[98:99] offset:3840
	global_load_dwordx4 v[120:123], v174, s[98:99] offset:3840
	ds_read_b128 v[140:143], v103 offset:4608
	ds_read_b128 v[164:167], v103 offset:4640
	s_waitcnt lgkmcnt(1)
	v_mfma_f32_32x32x16_bf16 v[16:31], v[140:143], v[144:147], v[16:31]
	global_load_dwordx4 v[124:127], v176, s[98:99] offset:3840
	global_load_dwordx4 v[128:131], v178, s[98:99] offset:3840
	s_waitcnt vmcnt(11)
	ds_write_b128 v105, v[84:87] offset:23040
	v_mfma_f32_32x32x16_bf16 v[0:15], v[140:143], v[156:159], v[0:15]
	global_load_dwordx4 v[132:135], v180, s[98:99] offset:3840
	global_load_dwordx4 v[136:139], v182, s[98:99] offset:3840
	v_mfma_f32_32x32x16_bf16 v[48:63], v[148:151], v[152:155], v[48:63]
	s_waitcnt vmcnt(12)
	ds_write_b128 v105, v[88:91] offset:27648
	v_mfma_f32_32x32x16_bf16 v[32:47], v[148:151], v[160:163], v[32:47]
	s_waitcnt lgkmcnt(2)
	v_mfma_f32_32x32x16_bf16 v[16:31], v[164:167], v[152:155], v[16:31]
	s_waitcnt vmcnt(11)
	ds_write_b128 v105, v[92:95] offset:32256
	ds_read_b128 v[140:143], v103 offset:64
	ds_read_b128 v[144:147], v104 offset:36928
	ds_read_b128 v[148:151], v103 offset:96
	ds_read_b128 v[152:155], v104 offset:36960
	v_mfma_f32_32x32x16_bf16 v[0:15], v[164:167], v[160:163], v[0:15]
	ds_read_b128 v[156:159], v104 offset:41536
	ds_read_b128 v[160:163], v104 offset:41568
	s_waitcnt lgkmcnt(4)
	v_mfma_f32_32x32x16_bf16 v[48:63], v[140:143], v[144:147], v[48:63]
	ds_write_b128 v105, v[64:67] offset:55296
	s_waitcnt lgkmcnt(2)
	v_mfma_f32_32x32x16_bf16 v[32:47], v[140:143], v[156:159], v[32:47]
	ds_read_b128 v[140:143], v103 offset:4672
	ds_read_b128 v[164:167], v103 offset:4704
	s_waitcnt lgkmcnt(1)
	v_mfma_f32_32x32x16_bf16 v[16:31], v[140:143], v[144:147], v[16:31]
	s_waitcnt vmcnt(10)
	ds_write_b128 v105, v[72:75] offset:59904
	v_mfma_f32_32x32x16_bf16 v[0:15], v[140:143], v[156:159], v[0:15]
	v_mfma_f32_32x32x16_bf16 v[48:63], v[148:151], v[152:155], v[48:63]
	s_waitcnt vmcnt(9)
	ds_write_b128 v105, v[76:79] offset:64512
	v_mfma_f32_32x32x16_bf16 v[32:47], v[148:151], v[160:163], v[32:47]
	s_waitcnt lgkmcnt(2)
	v_mfma_f32_32x32x16_bf16 v[16:31], v[164:167], v[152:155], v[16:31]
	s_waitcnt vmcnt(8)
	ds_write_b128 v106, v[80:83] offset:13824
	v_mfma_f32_32x32x16_bf16 v[0:15], v[164:167], v[160:163], v[0:15]
	s_setprio 0
	s_waitcnt lgkmcnt(0)
	s_barrier
	s_setprio 1
	ds_read_b128 v[140:143], v103 offset:18432
	ds_read_b128 v[144:147], v104 offset:55296
	ds_read_b128 v[148:151], v103 offset:18464
	ds_read_b128 v[152:155], v104 offset:55328
	ds_read_b128 v[156:159], v104 offset:59904
	ds_read_b128 v[160:163], v104 offset:59936
	s_waitcnt lgkmcnt(4)
	v_mfma_f32_32x32x16_bf16 v[48:63], v[140:143], v[144:147], v[48:63]
	global_load_dwordx4 v[68:71], v168, s[98:99] offset:3968
	global_load_dwordx4 v[84:87], v170, s[98:99] offset:3968
	s_waitcnt vmcnt(9)
	ds_write_b128 v105, v[108:111]
	s_waitcnt lgkmcnt(2)
	v_mfma_f32_32x32x16_bf16 v[32:47], v[140:143], v[156:159], v[32:47]
	global_load_dwordx4 v[88:91], v172, s[98:99] offset:3968
	global_load_dwordx4 v[92:95], v174, s[98:99] offset:3968
	ds_read_b128 v[140:143], v103 offset:23040
	ds_read_b128 v[164:167], v103 offset:23072
	s_waitcnt lgkmcnt(1)
	v_mfma_f32_32x32x16_bf16 v[16:31], v[140:143], v[144:147], v[16:31]
	global_load_dwordx4 v[64:67], v176, s[98:99] offset:3968
	global_load_dwordx4 v[72:75], v178, s[98:99] offset:3968
	s_waitcnt vmcnt(12)
	ds_write_b128 v105, v[112:115] offset:4608
	v_mfma_f32_32x32x16_bf16 v[0:15], v[140:143], v[156:159], v[0:15]
	global_load_dwordx4 v[76:79], v180, s[98:99] offset:3968
	global_load_dwordx4 v[80:83], v182, s[98:99] offset:3968
	v_mfma_f32_32x32x16_bf16 v[48:63], v[148:151], v[152:155], v[48:63]
	s_add_u32 s98, s98, 0x100
	s_addc_u32 s99, s99, 0
	s_add_i32 s6, s6, 2
	s_cmp_lt_u32 s6, 11
	s_waitcnt vmcnt(13)
	ds_write_b128 v105, v[116:119] offset:9216
	v_mfma_f32_32x32x16_bf16 v[32:47], v[148:151], v[160:163], v[32:47]
	s_waitcnt lgkmcnt(2)
	v_mfma_f32_32x32x16_bf16 v[16:31], v[164:167], v[152:155], v[16:31]
	s_waitcnt vmcnt(12)
	ds_write_b128 v105, v[120:123] offset:13824
	ds_read_b128 v[140:143], v103 offset:18496
	ds_read_b128 v[144:147], v104 offset:55360
	ds_read_b128 v[148:151], v103 offset:18528
	ds_read_b128 v[152:155], v104 offset:55392
	v_mfma_f32_32x32x16_bf16 v[0:15], v[164:167], v[160:163], v[0:15]
	ds_read_b128 v[156:159], v104 offset:59968
	ds_read_b128 v[160:163], v104 offset:60000
	s_waitcnt lgkmcnt(4)
	v_mfma_f32_32x32x16_bf16 v[48:63], v[140:143], v[144:147], v[48:63]
	s_waitcnt vmcnt(11)
	ds_write_b128 v105, v[124:127] offset:36864
	s_waitcnt lgkmcnt(2)
	v_mfma_f32_32x32x16_bf16 v[32:47], v[140:143], v[156:159], v[32:47]
	ds_read_b128 v[140:143], v103 offset:23104
	ds_read_b128 v[164:167], v103 offset:23136
	s_waitcnt lgkmcnt(1)
	v_mfma_f32_32x32x16_bf16 v[16:31], v[140:143], v[144:147], v[16:31]
	s_waitcnt vmcnt(10)
	ds_write_b128 v105, v[128:131] offset:41472
	v_mfma_f32_32x32x16_bf16 v[0:15], v[140:143], v[156:159], v[0:15]
	v_mfma_f32_32x32x16_bf16 v[48:63], v[148:151], v[152:155], v[48:63]
	s_waitcnt vmcnt(9)
	ds_write_b128 v105, v[132:135] offset:46080
	v_mfma_f32_32x32x16_bf16 v[32:47], v[148:151], v[160:163], v[32:47]
	s_waitcnt lgkmcnt(2)
	v_mfma_f32_32x32x16_bf16 v[16:31], v[164:167], v[152:155], v[16:31]
	s_waitcnt vmcnt(8)
	ds_write_b128 v105, v[136:139] offset:50688
	v_mfma_f32_32x32x16_bf16 v[0:15], v[164:167], v[160:163], v[0:15]
	s_setprio 0
	s_waitcnt lgkmcnt(0)
	s_barrier
	s_cbranch_scc1 .LBB0_198
	s_setprio 1
	ds_read_b128 v[98:101], v103
	ds_read_b128 v[108:111], v104 offset:36864
	ds_read_b128 v[112:115], v103 offset:32
	ds_read_b128 v[116:119], v104 offset:36896
	ds_read_b128 v[120:123], v104 offset:41472
	ds_read_b128 v[124:127], v104 offset:41504
	s_waitcnt lgkmcnt(4)
	v_mfma_f32_32x32x16_bf16 v[48:63], v[98:101], v[108:111], v[48:63]
	s_waitcnt vmcnt(7)
	ds_write_b128 v105, v[68:71] offset:18432
	s_waitcnt lgkmcnt(2)
	v_mfma_f32_32x32x16_bf16 v[32:47], v[98:101], v[120:123], v[32:47]
	ds_read_b128 v[98:101], v103 offset:4608
	ds_read_b128 v[128:131], v103 offset:4640
	s_waitcnt lgkmcnt(1)
	v_mfma_f32_32x32x16_bf16 v[16:31], v[98:101], v[108:111], v[16:31]
	s_waitcnt vmcnt(6)
	ds_write_b128 v105, v[84:87] offset:23040
	v_mfma_f32_32x32x16_bf16 v[0:15], v[98:101], v[120:123], v[0:15]
	v_mfma_f32_32x32x16_bf16 v[48:63], v[112:115], v[116:119], v[48:63]
	s_waitcnt vmcnt(5)
	ds_write_b128 v105, v[88:91] offset:27648
	v_mfma_f32_32x32x16_bf16 v[32:47], v[112:115], v[124:127], v[32:47]
	s_waitcnt lgkmcnt(2)
	v_mfma_f32_32x32x16_bf16 v[16:31], v[128:131], v[116:119], v[16:31]
	s_waitcnt vmcnt(4)
	ds_write_b128 v105, v[92:95] offset:32256
	ds_read_b128 v[98:101], v103 offset:64
	ds_read_b128 v[108:111], v104 offset:36928
	ds_read_b128 v[112:115], v103 offset:96
	ds_read_b128 v[116:119], v104 offset:36960
	v_mfma_f32_32x32x16_bf16 v[0:15], v[128:131], v[124:127], v[0:15]
	ds_read_b128 v[120:123], v104 offset:41536
	ds_read_b128 v[124:127], v104 offset:41568
	s_waitcnt lgkmcnt(4)
	v_mfma_f32_32x32x16_bf16 v[48:63], v[98:101], v[108:111], v[48:63]
	s_waitcnt vmcnt(3)
	ds_write_b128 v105, v[64:67] offset:55296
	s_waitcnt lgkmcnt(2)
	v_mfma_f32_32x32x16_bf16 v[32:47], v[98:101], v[120:123], v[32:47]
	ds_read_b128 v[98:101], v103 offset:4672
	ds_read_b128 v[128:131], v103 offset:4704
	s_waitcnt lgkmcnt(1)
	v_mfma_f32_32x32x16_bf16 v[16:31], v[98:101], v[108:111], v[16:31]
	s_waitcnt vmcnt(2)
	ds_write_b128 v105, v[72:75] offset:59904
	v_mfma_f32_32x32x16_bf16 v[0:15], v[98:101], v[120:123], v[0:15]
	v_mfma_f32_32x32x16_bf16 v[48:63], v[112:115], v[116:119], v[48:63]
	s_waitcnt vmcnt(1)
	ds_write_b128 v105, v[76:79] offset:64512
	v_mfma_f32_32x32x16_bf16 v[32:47], v[112:115], v[124:127], v[32:47]
	s_waitcnt lgkmcnt(2)
	v_mfma_f32_32x32x16_bf16 v[16:31], v[128:131], v[116:119], v[16:31]
	s_waitcnt vmcnt(0)
	ds_write_b128 v106, v[80:83] offset:13824
	v_mfma_f32_32x32x16_bf16 v[0:15], v[128:131], v[124:127], v[0:15]
	s_setprio 0
	s_waitcnt lgkmcnt(0)
	s_barrier
	s_setprio 1
	ds_read_b128 v[64:67], v103 offset:18432
	ds_read_b128 v[68:71], v104 offset:55296
	ds_read_b128 v[72:75], v103 offset:18464
	ds_read_b128 v[76:79], v104 offset:55328
	ds_read_b128 v[80:83], v104 offset:59904
	ds_read_b128 v[84:87], v104 offset:59936
	s_waitcnt lgkmcnt(4)
	v_mfma_f32_32x32x16_bf16 v[48:63], v[64:67], v[68:71], v[48:63]
	s_waitcnt lgkmcnt(1)
	v_mfma_f32_32x32x16_bf16 v[32:47], v[64:67], v[80:83], v[32:47]
	ds_read_b128 v[64:67], v103 offset:23040
	ds_read_b128 v[88:91], v103 offset:23072
	s_waitcnt lgkmcnt(1)
	v_mfma_f32_32x32x16_bf16 v[16:31], v[64:67], v[68:71], v[16:31]
	v_mfma_f32_32x32x16_bf16 v[0:15], v[64:67], v[80:83], v[0:15]
	v_mfma_f32_32x32x16_bf16 v[48:63], v[72:75], v[76:79], v[48:63]
	v_mfma_f32_32x32x16_bf16 v[32:47], v[72:75], v[84:87], v[32:47]
	s_waitcnt lgkmcnt(0)
	v_mfma_f32_32x32x16_bf16 v[16:31], v[88:91], v[76:79], v[16:31]
	ds_read_b128 v[64:67], v103 offset:18496
	ds_read_b128 v[68:71], v104 offset:55360
	ds_read_b128 v[72:75], v103 offset:18528
	ds_read_b128 v[76:79], v104 offset:55392
	v_mfma_f32_32x32x16_bf16 v[0:15], v[88:91], v[84:87], v[0:15]
	ds_read_b128 v[80:83], v104 offset:59968
	ds_read_b128 v[84:87], v104 offset:60000
	s_waitcnt lgkmcnt(4)
	v_mfma_f32_32x32x16_bf16 v[48:63], v[64:67], v[68:71], v[48:63]
	s_waitcnt lgkmcnt(1)
	v_mfma_f32_32x32x16_bf16 v[32:47], v[64:67], v[80:83], v[32:47]
	ds_read_b128 v[64:67], v103 offset:23104
	ds_read_b128 v[88:91], v103 offset:23136
	s_waitcnt lgkmcnt(1)
	v_mfma_f32_32x32x16_bf16 v[16:31], v[64:67], v[68:71], v[16:31]
	v_mfma_f32_32x32x16_bf16 v[0:15], v[64:67], v[80:83], v[0:15]
	v_mfma_f32_32x32x16_bf16 v[48:63], v[72:75], v[76:79], v[48:63]
	v_mfma_f32_32x32x16_bf16 v[32:47], v[72:75], v[84:87], v[32:47]
	s_waitcnt lgkmcnt(0)
	v_mfma_f32_32x32x16_bf16 v[16:31], v[88:91], v[76:79], v[16:31]
	v_mfma_f32_32x32x16_bf16 v[0:15], v[88:91], v[84:87], v[0:15]
	s_setprio 0
	s_cmpk_gt_u32 s24, 0xfff
	s_cselect_b64 s[12:13], -1, 0
	s_cmpk_lt_u32 s24, 0x1000
	s_cselect_b64 s[48:49], -1, 0
	s_ashr_i32 s76, s2, 2
	s_cmp_lt_i32 s76, 7
	s_barrier
	s_cbranch_scc1 .LBB0_201
	s_cmp_lg_u32 s76, 7
	s_cselect_b64 s[6:7], -1, 0
	s_cbranch_execz .LBB0_202
	s_branch .LBB0_203

.LBB0_218:
	v_ashrrev_i32_e32 v66, 1, v102
	v_lshrrev_b32_e32 v64, 3, v102
	v_and_b32_e32 v72, 4, v64
	v_add_u32_e32 v64, s75, v66
	v_bfe_u32 v73, v64, 6, 4
	v_lshlrev_b32_e32 v64, 1, v102
	v_and_b32_e32 v74, 62, v64
	v_cndmask_b32_e64 v64, 0, 1, s[12:13]
	s_and_b64 vcc, exec, s[10:11]
	v_cmp_ne_u32_e64 s[10:11], 1, v64
	s_cbranch_vccz .LBB0_223
	s_and_b64 vcc, exec, s[10:11]
	s_cbranch_vccnz .LBB0_221
	v_lshlrev_b32_e32 v175, 2, v74
	v_mov_b32_e32 v174, v72
	v_cndmask_b32_e64 v174, v174, v73, s[8:9]
	v_lshl_or_b32 v174, v174, 8, v175
	global_load_dwordx2 v[110:111], v174, s[22:23]
	v_or_b32_e32 v174, 1, v72
	v_cndmask_b32_e64 v174, v174, v73, s[8:9]
	v_lshl_or_b32 v174, v174, 8, v175
	global_load_dwordx2 v[112:113], v174, s[22:23]
	v_or_b32_e32 v174, 2, v72
	v_cndmask_b32_e64 v174, v174, v73, s[8:9]
	v_lshl_or_b32 v174, v174, 8, v175
	global_load_dwordx2 v[114:115], v174, s[22:23]
	v_or_b32_e32 v174, 3, v72
	v_cndmask_b32_e64 v174, v174, v73, s[8:9]
	v_lshl_or_b32 v174, v174, 8, v175
	global_load_dwordx2 v[116:117], v174, s[22:23]
	v_or_b32_e32 v174, 8, v72
	v_cndmask_b32_e64 v174, v174, v73, s[8:9]
	v_lshl_or_b32 v174, v174, 8, v175
	global_load_dwordx2 v[118:119], v174, s[22:23]
	v_or_b32_e32 v174, 9, v72
	v_cndmask_b32_e64 v174, v174, v73, s[8:9]
	v_lshl_or_b32 v174, v174, 8, v175
	global_load_dwordx2 v[120:121], v174, s[22:23]
	v_or_b32_e32 v174, 10, v72
	v_cndmask_b32_e64 v174, v174, v73, s[8:9]
	v_lshl_or_b32 v174, v174, 8, v175
	global_load_dwordx2 v[122:123], v174, s[22:23]
	v_or_b32_e32 v174, 11, v72
	v_cndmask_b32_e64 v174, v174, v73, s[8:9]
	v_lshl_or_b32 v174, v174, 8, v175
	global_load_dwordx2 v[124:125], v174, s[22:23]
	v_or_b32_e32 v174, 16, v72
	v_cndmask_b32_e64 v174, v174, v73, s[8:9]
	v_lshl_or_b32 v174, v174, 8, v175
	global_load_dwordx2 v[126:127], v174, s[22:23]
	v_or_b32_e32 v174, 17, v72
	v_cndmask_b32_e64 v174, v174, v73, s[8:9]
	v_lshl_or_b32 v174, v174, 8, v175
	global_load_dwordx2 v[128:129], v174, s[22:23]
	v_or_b32_e32 v174, 18, v72
	v_cndmask_b32_e64 v174, v174, v73, s[8:9]
	v_lshl_or_b32 v174, v174, 8, v175
	global_load_dwordx2 v[130:131], v174, s[22:23]
	v_or_b32_e32 v174, 19, v72
	v_cndmask_b32_e64 v174, v174, v73, s[8:9]
	v_lshl_or_b32 v174, v174, 8, v175
	global_load_dwordx2 v[132:133], v174, s[22:23]
	v_or_b32_e32 v174, 24, v72
	v_cndmask_b32_e64 v174, v174, v73, s[8:9]
	v_lshl_or_b32 v174, v174, 8, v175
	global_load_dwordx2 v[134:135], v174, s[22:23]
	v_or_b32_e32 v174, 25, v72
	v_cndmask_b32_e64 v174, v174, v73, s[8:9]
	v_lshl_or_b32 v174, v174, 8, v175
	global_load_dwordx2 v[136:137], v174, s[22:23]
	v_or_b32_e32 v174, 26, v72
	v_cndmask_b32_e64 v174, v174, v73, s[8:9]
	v_lshl_or_b32 v174, v174, 8, v175
	global_load_dwordx2 v[138:139], v174, s[22:23]
	v_or_b32_e32 v174, 27, v72
	v_cndmask_b32_e64 v174, v174, v73, s[8:9]
	v_lshl_or_b32 v174, v174, 8, v175
	global_load_dwordx2 v[140:141], v174, s[22:23]
	v_or_b32_e32 v174, 32, v72
	v_cndmask_b32_e64 v174, v174, v73, s[8:9]
	v_lshl_or_b32 v174, v174, 8, v175
	global_load_dwordx2 v[142:143], v174, s[22:23]
	v_or_b32_e32 v174, 33, v72
	v_cndmask_b32_e64 v174, v174, v73, s[8:9]
	v_lshl_or_b32 v174, v174, 8, v175
	global_load_dwordx2 v[144:145], v174, s[22:23]
	v_or_b32_e32 v174, 34, v72
	v_cndmask_b32_e64 v174, v174, v73, s[8:9]
	v_lshl_or_b32 v174, v174, 8, v175
	global_load_dwordx2 v[146:147], v174, s[22:23]
	v_or_b32_e32 v174, 35, v72
	v_cndmask_b32_e64 v174, v174, v73, s[8:9]
	v_lshl_or_b32 v174, v174, 8, v175
	global_load_dwordx2 v[148:149], v174, s[22:23]
	v_or_b32_e32 v174, 40, v72
	v_cndmask_b32_e64 v174, v174, v73, s[8:9]
	v_lshl_or_b32 v174, v174, 8, v175
	global_load_dwordx2 v[150:151], v174, s[22:23]
	v_or_b32_e32 v174, 41, v72
	v_cndmask_b32_e64 v174, v174, v73, s[8:9]
	v_lshl_or_b32 v174, v174, 8, v175
	global_load_dwordx2 v[152:153], v174, s[22:23]
	v_or_b32_e32 v174, 42, v72
	v_cndmask_b32_e64 v174, v174, v73, s[8:9]
	v_lshl_or_b32 v174, v174, 8, v175
	global_load_dwordx2 v[154:155], v174, s[22:23]
	v_or_b32_e32 v174, 43, v72
	v_cndmask_b32_e64 v174, v174, v73, s[8:9]
	v_lshl_or_b32 v174, v174, 8, v175
	global_load_dwordx2 v[156:157], v174, s[22:23]
	v_or_b32_e32 v174, 48, v72
	v_cndmask_b32_e64 v174, v174, v73, s[8:9]
	v_lshl_or_b32 v174, v174, 8, v175
	global_load_dwordx2 v[158:159], v174, s[22:23]
	v_or_b32_e32 v174, 49, v72
	v_cndmask_b32_e64 v174, v174, v73, s[8:9]
	v_lshl_or_b32 v174, v174, 8, v175
	global_load_dwordx2 v[160:161], v174, s[22:23]
	v_or_b32_e32 v174, 50, v72
	v_cndmask_b32_e64 v174, v174, v73, s[8:9]
	v_lshl_or_b32 v174, v174, 8, v175
	global_load_dwordx2 v[162:163], v174, s[22:23]
	v_or_b32_e32 v174, 51, v72
	v_cndmask_b32_e64 v174, v174, v73, s[8:9]
	v_lshl_or_b32 v174, v174, 8, v175
	global_load_dwordx2 v[164:165], v174, s[22:23]
	v_or_b32_e32 v174, 56, v72
	v_cndmask_b32_e64 v174, v174, v73, s[8:9]
	v_lshl_or_b32 v174, v174, 8, v175
	global_load_dwordx2 v[166:167], v174, s[22:23]
	v_or_b32_e32 v174, 57, v72
	v_cndmask_b32_e64 v174, v174, v73, s[8:9]
	v_lshl_or_b32 v174, v174, 8, v175
	global_load_dwordx2 v[168:169], v174, s[22:23]
	v_or_b32_e32 v174, 58, v72
	v_cndmask_b32_e64 v174, v174, v73, s[8:9]
	v_lshl_or_b32 v174, v174, 8, v175
	global_load_dwordx2 v[170:171], v174, s[22:23]
	v_or_b32_e32 v174, 59, v72
	v_cndmask_b32_e64 v174, v174, v73, s[8:9]
	v_lshl_or_b32 v174, v174, 8, v175
	global_load_dwordx2 v[172:173], v174, s[22:23]
	s_waitcnt vmcnt(0)
	v_mov_b64_e32 v[64:65], v[110:111]
	v_pk_mul_f32 v[70:71], v[32:33], v[64:65] op_sel:[0,1] op_sel_hi:[0,0]
	v_pk_mul_f32 v[68:69], v[48:49], v[64:65]
	v_pk_fma_f32 v[64:65], v[48:49], v[64:65], v[70:71] op_sel_hi:[0,1,1]
	v_sub_f32_e32 v64, v68, v70
	s_branch .LBB0_222

.LBB0_239:
	s_and_b64 vcc, exec, s[16:17]
	s_cbranch_vccz .LBB0_247
	s_and_b64 vcc, exec, s[10:11]
	s_cbranch_vccnz .LBB0_249
	v_mov_b64_e32 v[70:71], v[112:113]
	v_pk_mul_f32 v[78:79], v[32:33], v[70:71] op_sel:[1,1] op_sel_hi:[1,0]
	v_pk_mul_f32 v[76:77], v[48:49], v[70:71] op_sel:[1,0]
	v_pk_fma_f32 v[70:71], v[48:49], v[70:71], v[78:79] op_sel:[1,0,0]
	s_nop 0
	v_sub_f32_e32 v70, v76, v78
	s_branch .LBB0_250

.LBB0_265:
	s_and_b64 vcc, exec, s[16:17]
	s_cbranch_vccz .LBB0_273
	s_and_b64 vcc, exec, s[10:11]
	s_cbranch_vccnz .LBB0_275
	v_mov_b64_e32 v[32:33], v[114:115]
	v_pk_mul_f32 v[76:77], v[34:35], v[32:33] op_sel:[0,1] op_sel_hi:[0,0]
	v_pk_mul_f32 v[48:49], v[50:51], v[32:33]
	v_pk_fma_f32 v[32:33], v[50:51], v[32:33], v[76:77] op_sel_hi:[0,1,1]
	v_sub_f32_e32 v32, v48, v76
	s_branch .LBB0_276

.LBB0_291:
	s_and_b64 vcc, exec, s[16:17]
	s_cbranch_vccz .LBB0_299
	s_and_b64 vcc, exec, s[10:11]
	s_cbranch_vccnz .LBB0_301
	v_mov_b64_e32 v[48:49], v[116:117]
	v_mov_b32_e32 v50, v35
	v_mov_b32_e32 v34, v51
	v_pk_mul_f32 v[78:79], v[50:51], v[48:49] op_sel:[0,1] op_sel_hi:[0,0]
	v_pk_mul_f32 v[76:77], v[34:35], v[48:49] op_sel_hi:[0,1]
	v_pk_fma_f32 v[48:49], v[34:35], v[48:49], v[78:79] op_sel_hi:[0,1,1]
	v_sub_f32_e32 v48, v76, v78
	s_branch .LBB0_302

.LBB0_311:
	s_and_b64 vcc, exec, s[34:35]
	s_cbranch_vccz .LBB0_327
	s_and_b64 vcc, exec, s[10:11]
	s_cbranch_vccnz .LBB0_329
	v_mov_b64_e32 v[32:33], v[118:119]
	v_pk_mul_f32 v[48:49], v[36:37], v[32:33] op_sel:[0,1] op_sel_hi:[0,0]
	v_pk_mul_f32 v[34:35], v[52:53], v[32:33]
	v_pk_fma_f32 v[32:33], v[52:53], v[32:33], v[48:49] op_sel_hi:[0,1,1]
	v_sub_f32_e32 v32, v34, v48
	s_branch .LBB0_330

.LBB0_345:
	s_and_b64 vcc, exec, s[34:35]
	s_cbranch_vccz .LBB0_353
	s_and_b64 vcc, exec, s[10:11]
	s_cbranch_vccnz .LBB0_355
	v_mov_b64_e32 v[34:35], v[120:121]
	v_mov_b32_e32 v48, v37
	v_mov_b32_e32 v36, v53
	v_pk_mul_f32 v[48:49], v[48:49], v[34:35] op_sel:[0,1] op_sel_hi:[0,0]
	v_pk_mul_f32 v[68:69], v[36:37], v[34:35] op_sel_hi:[0,1]
	v_pk_fma_f32 v[34:35], v[36:37], v[34:35], v[48:49] op_sel_hi:[0,1,1]
	v_sub_f32_e32 v34, v68, v48
	s_branch .LBB0_356

.LBB0_371:
	s_and_b64 vcc, exec, s[34:35]
	s_cbranch_vccz .LBB0_379
	s_and_b64 vcc, exec, s[10:11]
	s_cbranch_vccnz .LBB0_381
	v_mov_b64_e32 v[36:37], v[122:123]
	v_pk_mul_f32 v[52:53], v[38:39], v[36:37] op_sel:[0,1] op_sel_hi:[0,0]
	v_pk_mul_f32 v[48:49], v[54:55], v[36:37]
	v_pk_fma_f32 v[36:37], v[54:55], v[36:37], v[52:53] op_sel_hi:[0,1,1]
	v_sub_f32_e32 v36, v48, v52
	s_branch .LBB0_382

.LBB0_397:
	s_and_b64 vcc, exec, s[34:35]
	s_cbranch_vccz .LBB0_405
	s_and_b64 vcc, exec, s[10:11]
	s_cbranch_vccnz .LBB0_407
	v_mov_b64_e32 v[48:49], v[124:125]
	v_mov_b32_e32 v52, v39
	v_mov_b32_e32 v38, v55
	v_pk_mul_f32 v[52:53], v[52:53], v[48:49] op_sel:[0,1] op_sel_hi:[0,0]
	v_pk_mul_f32 v[68:69], v[38:39], v[48:49] op_sel_hi:[0,1]
	v_pk_fma_f32 v[48:49], v[38:39], v[48:49], v[52:53] op_sel_hi:[0,1,1]
	v_sub_f32_e32 v48, v68, v52
	s_branch .LBB0_408

.LBB0_415:
	s_and_b64 vcc, exec, s[34:35]
	s_cbranch_vccz .LBB0_433
	s_and_b64 vcc, exec, s[10:11]
	s_cbranch_vccnz .LBB0_435
	v_mov_b64_e32 v[32:33], v[126:127]
	v_pk_mul_f32 v[36:37], v[40:41], v[32:33] op_sel:[0,1] op_sel_hi:[0,0]
	v_pk_mul_f32 v[34:35], v[56:57], v[32:33]
	v_pk_fma_f32 v[32:33], v[56:57], v[32:33], v[36:37] op_sel_hi:[0,1,1]
	v_sub_f32_e32 v32, v34, v36
	s_branch .LBB0_436

.LBB0_451:
	s_and_b64 vcc, exec, s[34:35]
	s_cbranch_vccz .LBB0_459
	s_and_b64 vcc, exec, s[10:11]
	s_cbranch_vccnz .LBB0_461
	v_mov_b64_e32 v[34:35], v[128:129]
	v_mov_b32_e32 v38, v41
	v_mov_b32_e32 v36, v57
	v_pk_mul_f32 v[38:39], v[38:39], v[34:35] op_sel:[0,1] op_sel_hi:[0,0]
	v_pk_mul_f32 v[48:49], v[36:37], v[34:35] op_sel_hi:[0,1]
	v_pk_fma_f32 v[34:35], v[36:37], v[34:35], v[38:39] op_sel_hi:[0,1,1]
	v_sub_f32_e32 v34, v48, v38
	s_branch .LBB0_462

.LBB0_477:
	s_and_b64 vcc, exec, s[34:35]
	s_cbranch_vccz .LBB0_485
	s_and_b64 vcc, exec, s[10:11]
	s_cbranch_vccnz .LBB0_487
	v_mov_b64_e32 v[36:37], v[130:131]
	v_pk_mul_f32 v[40:41], v[42:43], v[36:37] op_sel:[0,1] op_sel_hi:[0,0]
	v_pk_mul_f32 v[38:39], v[58:59], v[36:37]
	v_pk_fma_f32 v[36:37], v[58:59], v[36:37], v[40:41] op_sel_hi:[0,1,1]
	v_sub_f32_e32 v36, v38, v40
	s_branch .LBB0_488

.LBB0_503:
	s_and_b64 vcc, exec, s[34:35]
	s_cbranch_vccz .LBB0_511
	s_and_b64 vcc, exec, s[10:11]
	s_cbranch_vccnz .LBB0_513
	v_mov_b64_e32 v[38:39], v[132:133]
	v_mov_b32_e32 v42, v43
	v_mov_b32_e32 v40, v59
	v_pk_mul_f32 v[52:53], v[42:43], v[38:39] op_sel:[0,1] op_sel_hi:[0,0]
	v_pk_mul_f32 v[48:49], v[40:41], v[38:39] op_sel_hi:[0,1]
	v_pk_fma_f32 v[38:39], v[40:41], v[38:39], v[52:53] op_sel_hi:[0,1,1]
	v_sub_f32_e32 v38, v48, v52
	s_branch .LBB0_514

.LBB0_521:
	s_and_b64 vcc, exec, s[34:35]
	s_cbranch_vccz .LBB0_539
	s_and_b64 vcc, exec, s[10:11]
	s_cbranch_vccnz .LBB0_541
	v_mov_b64_e32 v[32:33], v[134:135]
	v_pk_mul_f32 v[36:37], v[44:45], v[32:33] op_sel:[0,1] op_sel_hi:[0,0]
	v_pk_mul_f32 v[34:35], v[60:61], v[32:33]
	v_pk_fma_f32 v[32:33], v[60:61], v[32:33], v[36:37] op_sel_hi:[0,1,1]
	v_sub_f32_e32 v32, v34, v36
	s_branch .LBB0_542

.LBB0_557:
	s_and_b64 vcc, exec, s[34:35]
	s_cbranch_vccz .LBB0_565
	s_and_b64 vcc, exec, s[10:11]
	s_cbranch_vccnz .LBB0_567
	v_mov_b64_e32 v[34:35], v[136:137]
	v_mov_b32_e32 v38, v45
	v_mov_b32_e32 v36, v61
	v_pk_mul_f32 v[38:39], v[38:39], v[34:35] op_sel:[0,1] op_sel_hi:[0,0]
	v_pk_mul_f32 v[40:41], v[36:37], v[34:35] op_sel_hi:[0,1]
	v_pk_fma_f32 v[34:35], v[36:37], v[34:35], v[38:39] op_sel_hi:[0,1,1]
	v_sub_f32_e32 v34, v40, v38
	s_branch .LBB0_568

.LBB0_583:
	s_and_b64 vcc, exec, s[34:35]
	s_cbranch_vccz .LBB0_591
	s_and_b64 vcc, exec, s[10:11]
	s_cbranch_vccnz .LBB0_593
	v_mov_b64_e32 v[36:37], v[138:139]
	v_pk_mul_f32 v[40:41], v[46:47], v[36:37] op_sel:[0,1] op_sel_hi:[0,0]
	v_pk_mul_f32 v[38:39], v[62:63], v[36:37]
	v_pk_fma_f32 v[36:37], v[62:63], v[36:37], v[40:41] op_sel_hi:[0,1,1]
	v_sub_f32_e32 v36, v38, v40
	s_branch .LBB0_594

.LBB0_609:
	s_and_b64 vcc, exec, s[34:35]
	s_cbranch_vccz .LBB0_617
	s_and_b64 vcc, exec, s[10:11]
	s_cbranch_vccnz .LBB0_619
	v_mov_b64_e32 v[38:39], v[140:141]
	v_mov_b32_e32 v42, v47
	v_mov_b32_e32 v40, v63
	v_pk_mul_f32 v[42:43], v[42:43], v[38:39] op_sel:[0,1] op_sel_hi:[0,0]
	v_pk_mul_f32 v[44:45], v[40:41], v[38:39] op_sel_hi:[0,1]
	v_pk_fma_f32 v[38:39], v[40:41], v[38:39], v[42:43] op_sel_hi:[0,1,1]
	v_sub_f32_e32 v38, v44, v42
	s_branch .LBB0_620

.LBB0_627:
	s_and_b64 vcc, exec, s[34:35]
	s_cbranch_vccz .LBB0_645
	s_and_b64 vcc, exec, s[10:11]
	s_cbranch_vccnz .LBB0_647
	v_mov_b64_e32 v[32:33], v[142:143]
	v_pk_mul_f32 v[36:37], v[0:1], v[32:33] op_sel:[0,1] op_sel_hi:[0,0]
	v_pk_mul_f32 v[34:35], v[16:17], v[32:33]
	v_pk_fma_f32 v[32:33], v[16:17], v[32:33], v[36:37] op_sel_hi:[0,1,1]
	v_sub_f32_e32 v32, v34, v36
	s_branch .LBB0_648

.LBB0_663:
	s_and_b64 vcc, exec, s[34:35]
	s_cbranch_vccz .LBB0_671
	s_and_b64 vcc, exec, s[10:11]
	s_cbranch_vccnz .LBB0_673
	v_mov_b64_e32 v[34:35], v[144:145]
	v_pk_mul_f32 v[38:39], v[0:1], v[34:35] op_sel:[1,1] op_sel_hi:[1,0]
	v_pk_mul_f32 v[36:37], v[16:17], v[34:35] op_sel:[1,0]
	v_pk_fma_f32 v[34:35], v[16:17], v[34:35], v[38:39] op_sel:[1,0,0]
	s_nop 0
	v_sub_f32_e32 v34, v36, v38
	s_branch .LBB0_674

.LBB0_689:
	s_and_b64 vcc, exec, s[34:35]
	s_cbranch_vccz .LBB0_697
	s_and_b64 vcc, exec, s[10:11]
	s_cbranch_vccnz .LBB0_699
	v_mov_b64_e32 v[0:1], v[146:147]
	v_pk_mul_f32 v[36:37], v[2:3], v[0:1] op_sel:[0,1] op_sel_hi:[0,0]
	v_pk_mul_f32 v[16:17], v[18:19], v[0:1]
	v_pk_fma_f32 v[0:1], v[18:19], v[0:1], v[36:37] op_sel_hi:[0,1,1]
	v_sub_f32_e32 v0, v16, v36
	s_branch .LBB0_700

.LBB0_715:
	s_and_b64 vcc, exec, s[34:35]
	s_cbranch_vccz .LBB0_723
	s_and_b64 vcc, exec, s[10:11]
	s_cbranch_vccnz .LBB0_725
	v_mov_b64_e32 v[16:17], v[148:149]
	v_mov_b32_e32 v18, v3
	v_mov_b32_e32 v2, v19
	v_pk_mul_f32 v[38:39], v[18:19], v[16:17] op_sel:[0,1] op_sel_hi:[0,0]
	v_pk_mul_f32 v[36:37], v[2:3], v[16:17] op_sel_hi:[0,1]
	v_pk_fma_f32 v[16:17], v[2:3], v[16:17], v[38:39] op_sel_hi:[0,1,1]
	v_sub_f32_e32 v16, v36, v38
	s_branch .LBB0_726

.LBB0_733:
	s_and_b64 vcc, exec, s[34:35]
	s_cbranch_vccz .LBB0_751
	s_and_b64 vcc, exec, s[10:11]
	s_cbranch_vccnz .LBB0_753
	v_mov_b64_e32 v[0:1], v[150:151]
	v_pk_mul_f32 v[16:17], v[4:5], v[0:1] op_sel:[0,1] op_sel_hi:[0,0]
	v_pk_mul_f32 v[2:3], v[20:21], v[0:1]
	v_pk_fma_f32 v[0:1], v[20:21], v[0:1], v[16:17] op_sel_hi:[0,1,1]
	v_sub_f32_e32 v0, v2, v16
	s_branch .LBB0_754

.LBB0_769:
	s_and_b64 vcc, exec, s[34:35]
	s_cbranch_vccz .LBB0_777
	s_and_b64 vcc, exec, s[10:11]
	s_cbranch_vccnz .LBB0_779
	v_mov_b64_e32 v[2:3], v[152:153]
	v_mov_b32_e32 v16, v5
	v_mov_b32_e32 v4, v21
	v_pk_mul_f32 v[16:17], v[16:17], v[2:3] op_sel:[0,1] op_sel_hi:[0,0]
	v_pk_mul_f32 v[18:19], v[4:5], v[2:3] op_sel_hi:[0,1]
	v_pk_fma_f32 v[2:3], v[4:5], v[2:3], v[16:17] op_sel_hi:[0,1,1]
	v_sub_f32_e32 v2, v18, v16
	s_branch .LBB0_780

.LBB0_795:
	s_and_b64 vcc, exec, s[34:35]
	s_cbranch_vccz .LBB0_803
	s_and_b64 vcc, exec, s[10:11]
	s_cbranch_vccnz .LBB0_805
	v_mov_b64_e32 v[4:5], v[154:155]
	v_pk_mul_f32 v[18:19], v[6:7], v[4:5] op_sel:[0,1] op_sel_hi:[0,0]
	v_pk_mul_f32 v[16:17], v[22:23], v[4:5]
	v_pk_fma_f32 v[4:5], v[22:23], v[4:5], v[18:19] op_sel_hi:[0,1,1]
	v_sub_f32_e32 v4, v16, v18
	s_branch .LBB0_806

.LBB0_821:
	s_and_b64 vcc, exec, s[34:35]
	s_cbranch_vccz .LBB0_829
	s_and_b64 vcc, exec, s[10:11]
	s_cbranch_vccnz .LBB0_831
	v_mov_b64_e32 v[16:17], v[156:157]
	v_mov_b32_e32 v18, v7
	v_mov_b32_e32 v6, v23
	v_pk_mul_f32 v[18:19], v[18:19], v[16:17] op_sel:[0,1] op_sel_hi:[0,0]
	v_pk_mul_f32 v[20:21], v[6:7], v[16:17] op_sel_hi:[0,1]
	v_pk_fma_f32 v[16:17], v[6:7], v[16:17], v[18:19] op_sel_hi:[0,1,1]
	v_sub_f32_e32 v16, v20, v18
	s_branch .LBB0_832

.LBB0_839:
	s_and_b64 vcc, exec, s[34:35]
	s_cbranch_vccz .LBB0_857
	s_and_b64 vcc, exec, s[10:11]
	s_cbranch_vccnz .LBB0_859
	v_mov_b64_e32 v[0:1], v[158:159]
	v_pk_mul_f32 v[4:5], v[8:9], v[0:1] op_sel:[0,1] op_sel_hi:[0,0]
	v_pk_mul_f32 v[2:3], v[24:25], v[0:1]
	v_pk_fma_f32 v[0:1], v[24:25], v[0:1], v[4:5] op_sel_hi:[0,1,1]
	v_sub_f32_e32 v0, v2, v4
	s_branch .LBB0_860

.LBB0_875:
	s_and_b64 vcc, exec, s[34:35]
	s_cbranch_vccz .LBB0_883
	s_and_b64 vcc, exec, s[10:11]
	s_cbranch_vccnz .LBB0_885
	v_mov_b64_e32 v[2:3], v[160:161]
	v_mov_b32_e32 v6, v9
	v_mov_b32_e32 v4, v25
	v_pk_mul_f32 v[6:7], v[6:7], v[2:3] op_sel:[0,1] op_sel_hi:[0,0]
	v_pk_mul_f32 v[16:17], v[4:5], v[2:3] op_sel_hi:[0,1]
	v_pk_fma_f32 v[2:3], v[4:5], v[2:3], v[6:7] op_sel_hi:[0,1,1]
	v_sub_f32_e32 v2, v16, v6
	s_branch .LBB0_886

.LBB0_901:
	s_and_b64 vcc, exec, s[34:35]
	s_cbranch_vccz .LBB0_909
	s_and_b64 vcc, exec, s[10:11]
	s_cbranch_vccnz .LBB0_911
	v_mov_b64_e32 v[4:5], v[162:163]
	v_pk_mul_f32 v[8:9], v[10:11], v[4:5] op_sel:[0,1] op_sel_hi:[0,0]
	v_pk_mul_f32 v[6:7], v[26:27], v[4:5]
	v_pk_fma_f32 v[4:5], v[26:27], v[4:5], v[8:9] op_sel_hi:[0,1,1]
	v_sub_f32_e32 v4, v6, v8
	s_branch .LBB0_912

.LBB0_927:
	s_and_b64 vcc, exec, s[34:35]
	s_cbranch_vccz .LBB0_935
	s_and_b64 vcc, exec, s[10:11]
	s_cbranch_vccnz .LBB0_937
	v_mov_b64_e32 v[6:7], v[164:165]
	v_mov_b32_e32 v10, v11
	v_mov_b32_e32 v8, v27
	v_pk_mul_f32 v[18:19], v[10:11], v[6:7] op_sel:[0,1] op_sel_hi:[0,0]
	v_pk_mul_f32 v[16:17], v[8:9], v[6:7] op_sel_hi:[0,1]
	v_pk_fma_f32 v[6:7], v[8:9], v[6:7], v[18:19] op_sel_hi:[0,1,1]
	v_sub_f32_e32 v6, v16, v18
	s_branch .LBB0_938

.LBB0_945:
	s_and_b64 vcc, exec, s[34:35]
	s_cbranch_vccz .LBB0_963
	s_and_b64 vcc, exec, s[10:11]
	s_cbranch_vccnz .LBB0_965
	v_mov_b64_e32 v[0:1], v[166:167]
	v_pk_mul_f32 v[4:5], v[12:13], v[0:1] op_sel:[0,1] op_sel_hi:[0,0]
	v_pk_mul_f32 v[2:3], v[28:29], v[0:1]
	v_pk_fma_f32 v[0:1], v[28:29], v[0:1], v[4:5] op_sel_hi:[0,1,1]
	v_sub_f32_e32 v0, v2, v4
	s_branch .LBB0_966

.LBB0_981:
	s_and_b64 vcc, exec, s[34:35]
	s_cbranch_vccz .LBB0_989
	s_and_b64 vcc, exec, s[10:11]
	s_cbranch_vccnz .LBB0_991
	v_mov_b64_e32 v[2:3], v[168:169]
	v_mov_b32_e32 v6, v13
	v_mov_b32_e32 v4, v29
	v_pk_mul_f32 v[6:7], v[6:7], v[2:3] op_sel:[0,1] op_sel_hi:[0,0]
	v_pk_mul_f32 v[8:9], v[4:5], v[2:3] op_sel_hi:[0,1]
	v_pk_fma_f32 v[2:3], v[4:5], v[2:3], v[6:7] op_sel_hi:[0,1,1]
	v_sub_f32_e32 v2, v8, v6
	s_branch .LBB0_992

.LBB0_1007:
	s_and_b64 vcc, exec, s[34:35]
	s_cbranch_vccz .LBB0_1015
	s_and_b64 vcc, exec, s[10:11]
	s_cbranch_vccnz .LBB0_1017
	v_mov_b64_e32 v[4:5], v[170:171]
	v_pk_mul_f32 v[8:9], v[14:15], v[4:5] op_sel:[0,1] op_sel_hi:[0,0]
	v_pk_mul_f32 v[6:7], v[30:31], v[4:5]
	v_pk_fma_f32 v[4:5], v[30:31], v[4:5], v[8:9] op_sel_hi:[0,1,1]
	v_sub_f32_e32 v4, v6, v8
	s_branch .LBB0_1018

.LBB0_1033:
	s_and_b64 vcc, exec, s[14:15]
	s_cbranch_vccz .LBB0_1041
	s_and_b64 vcc, exec, s[10:11]
	s_cbranch_vccnz .LBB0_1043
	v_mov_b64_e32 v[6:7], v[172:173]
	v_mov_b32_e32 v10, v15
	v_mov_b32_e32 v8, v31
	v_pk_mul_f32 v[10:11], v[10:11], v[6:7] op_sel:[0,1] op_sel_hi:[0,0]
	v_pk_mul_f32 v[12:13], v[8:9], v[6:7] op_sel_hi:[0,1]
	v_pk_fma_f32 v[6:7], v[8:9], v[6:7], v[10:11] op_sel_hi:[0,1,1]
	v_sub_f32_e32 v6, v12, v10
	s_branch .LBB0_1044

.LBB0_1183:
	v_lshl_add_u64 v[0:1], v[74:75], 0, s[4:5]
	s_mov_b32 s0, 0xab93000
	v_add_co_u32_e64 v82, s[0:1], s0, v0
	s_nop 1
	v_addc_co_u32_e64 v83, s[0:1], 0, v1, s[0:1]
	v_lshl_add_u64 v[0:1], v[76:77], 0, s[4:5]
	s_mov_b32 s0, 0xdf93000
	v_add_co_u32_e64 v78, s[0:1], s0, v0
	s_nop 1
	v_addc_co_u32_e64 v79, s[0:1], 0, v1, s[0:1]
	s_mov_b32 s0, 0xdf97000
	v_add_co_u32_e64 v80, s[0:1], s0, v0
	s_nop 1
	v_addc_co_u32_e64 v81, s[0:1], 0, v1, s[0:1]
	s_mov_b32 s0, 0xdf9b000
	v_add_co_u32_e64 v90, s[0:1], s0, v0
	s_nop 1
	v_addc_co_u32_e64 v91, s[0:1], 0, v1, s[0:1]
	s_mov_b32 s0, 0xdf9f000
	v_add_co_u32_e64 v92, s[0:1], s0, v0
	s_nop 1
	v_addc_co_u32_e64 v93, s[0:1], 0, v1, s[0:1]
	global_load_dwordx4 v[112:115], v[82:83], off offset:3584
	global_load_dwordx4 v[116:119], v[82:83], off offset:3616
	global_load_dwordx4 v[120:123], v[78:79], off offset:3584
	global_load_dwordx4 v[124:127], v[80:81], off offset:3584
	global_load_dwordx4 v[128:131], v[90:91], off offset:3584
	global_load_dwordx4 v[132:135], v[92:93], off offset:3584
	global_load_dwordx4 v[136:139], v[78:79], off offset:3616
	global_load_dwordx4 v[140:143], v[80:81], off offset:3616
	global_load_dwordx4 v[144:147], v[90:91], off offset:3616
	global_load_dwordx4 v[148:151], v[92:93], off offset:3616
	global_load_dwordx4 v[152:155], v[82:83], off offset:3648
	global_load_dwordx4 v[156:159], v[82:83], off offset:3680
	global_load_dwordx4 v[160:163], v[78:79], off offset:3648
	global_load_dwordx4 v[168:171], v[80:81], off offset:3648
	global_load_dwordx4 v[172:175], v[90:91], off offset:3648
	global_load_dwordx4 v[176:179], v[92:93], off offset:3648
	global_load_dwordx4 v[180:183], v[78:79], off offset:3680
	global_load_dwordx4 v[184:187], v[80:81], off offset:3680
	global_load_dwordx4 v[188:191], v[90:91], off offset:3680
	global_load_dwordx4 v[192:195], v[92:93], off offset:3680
	v_add_u32_e32 v70, 0xfffffff0, v89
	v_add_u32_e32 v72, 0xff, v88
	v_add_u32_e32 v71, 0xfffffff1, v89
	v_cndmask_b32_e32 v70, v70, v72, vcc
	v_add_u32_e32 v72, 0xfe, v88
	v_cndmask_b32_e32 v71, v71, v72, vcc
	v_cvt_f32_u32_e32 v70, v70
	v_cvt_f32_u32_e32 v71, v71
	v_mul_f32_e32 v70, v87, v70
	v_mul_f32_e32 v71, v87, v71
	v_exp_f32_e32 v70, v70
	v_exp_f32_e32 v71, v71
	s_waitcnt vmcnt(19)
	v_lshlrev_b32_e32 v72, 16, v112
	v_and_b32_e32 v73, 0xffff0000, v112
	v_pk_mul_f32 v[70:71], v[70:71], v[72:73]
	s_nop 0
	v_cvt_pk_bf16_f32 v112, v70, v71
	v_add_u32_e32 v70, 0xfffffff2, v89
	v_add_u32_e32 v72, 0xfd, v88
	v_add_u32_e32 v71, 0xfffffff3, v89
	v_cndmask_b32_e32 v70, v70, v72, vcc
	v_add_u32_e32 v72, 0xfc, v88
	v_cndmask_b32_e32 v71, v71, v72, vcc
	v_cvt_f32_u32_e32 v70, v70
	v_cvt_f32_u32_e32 v71, v71
	v_mul_f32_e32 v70, v87, v70
	v_mul_f32_e32 v71, v87, v71
	v_exp_f32_e32 v70, v70
	v_exp_f32_e32 v71, v71
	v_lshlrev_b32_e32 v72, 16, v113
	v_and_b32_e32 v73, 0xffff0000, v113
	v_pk_mul_f32 v[70:71], v[70:71], v[72:73]
	s_nop 0
	v_cvt_pk_bf16_f32 v113, v70, v71
	v_add_u32_e32 v70, 0xfffffff4, v89
	v_add_u32_e32 v72, 0xfb, v88
	v_add_u32_e32 v71, 0xfffffff5, v89
	v_cndmask_b32_e32 v70, v70, v72, vcc
	v_add_u32_e32 v72, 0xfa, v88
	v_cndmask_b32_e32 v71, v71, v72, vcc
	v_cvt_f32_u32_e32 v70, v70
	v_cvt_f32_u32_e32 v71, v71
	v_mul_f32_e32 v70, v87, v70
	v_mul_f32_e32 v71, v87, v71
	v_exp_f32_e32 v70, v70
	v_exp_f32_e32 v71, v71
	v_lshlrev_b32_e32 v72, 16, v114
	v_and_b32_e32 v73, 0xffff0000, v114
	v_pk_mul_f32 v[70:71], v[70:71], v[72:73]
	s_nop 0
	v_cvt_pk_bf16_f32 v114, v70, v71
	v_add_u32_e32 v70, 0xfffffff6, v89
	v_add_u32_e32 v72, 0xf9, v88
	v_add_u32_e32 v71, 0xfffffff7, v89
	v_cndmask_b32_e32 v70, v70, v72, vcc
	v_add_u32_e32 v72, 0xf8, v88
	v_cndmask_b32_e32 v71, v71, v72, vcc
	v_cvt_f32_u32_e32 v70, v70
	v_cvt_f32_u32_e32 v71, v71
	v_mul_f32_e32 v70, v87, v70
	v_mul_f32_e32 v71, v87, v71
	v_exp_f32_e32 v70, v70
	v_exp_f32_e32 v71, v71
	v_lshlrev_b32_e32 v72, 16, v115
	v_and_b32_e32 v73, 0xffff0000, v115
	v_pk_mul_f32 v[70:71], v[70:71], v[72:73]
	s_nop 0
	v_cvt_pk_bf16_f32 v115, v70, v71
	s_waitcnt vmcnt(17)
	v_mfma_f32_32x32x16_bf16 v[54:69], v[112:115], v[120:123], v[54:69]
	s_waitcnt vmcnt(16)
	v_mfma_f32_32x32x16_bf16 v[38:53], v[112:115], v[124:127], v[38:53]
	s_waitcnt vmcnt(15)
	v_mfma_f32_32x32x16_bf16 v[22:37], v[112:115], v[128:131], v[22:37]
	s_waitcnt vmcnt(14)
	v_mfma_f32_32x32x16_bf16 v[6:21], v[112:115], v[132:135], v[6:21]
	v_add_u32_e32 v70, 0x0, v89
	v_add_u32_e32 v72, 0xef, v88
	v_add_u32_e32 v71, 0x1, v89
	v_cndmask_b32_e32 v70, v70, v72, vcc
	v_add_u32_e32 v72, 0xee, v88
	v_cndmask_b32_e32 v71, v71, v72, vcc
	v_cvt_f32_u32_e32 v70, v70
	v_cvt_f32_u32_e32 v71, v71
	v_mul_f32_e32 v70, v87, v70
	v_mul_f32_e32 v71, v87, v71
	v_exp_f32_e32 v70, v70
	v_exp_f32_e32 v71, v71
	v_lshlrev_b32_e32 v72, 16, v116
	v_and_b32_e32 v73, 0xffff0000, v116
	v_pk_mul_f32 v[70:71], v[70:71], v[72:73]
	s_nop 0
	v_cvt_pk_bf16_f32 v116, v70, v71
	v_add_u32_e32 v70, 0x2, v89
	v_add_u32_e32 v72, 0xed, v88
	v_add_u32_e32 v71, 0x3, v89
	v_cndmask_b32_e32 v70, v70, v72, vcc
	v_add_u32_e32 v72, 0xec, v88
	v_cndmask_b32_e32 v71, v71, v72, vcc
	v_cvt_f32_u32_e32 v70, v70
	v_cvt_f32_u32_e32 v71, v71
	v_mul_f32_e32 v70, v87, v70
	v_mul_f32_e32 v71, v87, v71
	v_exp_f32_e32 v70, v70
	v_exp_f32_e32 v71, v71
	v_lshlrev_b32_e32 v72, 16, v117
	v_and_b32_e32 v73, 0xffff0000, v117
	v_pk_mul_f32 v[70:71], v[70:71], v[72:73]
	s_nop 0
	v_cvt_pk_bf16_f32 v117, v70, v71
	v_add_u32_e32 v70, 0x4, v89
	v_add_u32_e32 v72, 0xeb, v88
	v_add_u32_e32 v71, 0x5, v89
	v_cndmask_b32_e32 v70, v70, v72, vcc
	v_add_u32_e32 v72, 0xea, v88
	v_cndmask_b32_e32 v71, v71, v72, vcc
	v_cvt_f32_u32_e32 v70, v70
	v_cvt_f32_u32_e32 v71, v71
	v_mul_f32_e32 v70, v87, v70
	v_mul_f32_e32 v71, v87, v71
	v_exp_f32_e32 v70, v70
	v_exp_f32_e32 v71, v71
	v_lshlrev_b32_e32 v72, 16, v118
	v_and_b32_e32 v73, 0xffff0000, v118
	v_pk_mul_f32 v[70:71], v[70:71], v[72:73]
	s_nop 0
	v_cvt_pk_bf16_f32 v118, v70, v71
	v_add_u32_e32 v70, 0x6, v89
	v_add_u32_e32 v72, 0xe9, v88
	v_add_u32_e32 v71, 0x7, v89
	v_cndmask_b32_e32 v70, v70, v72, vcc
	v_add_u32_e32 v72, 0xe8, v88
	v_cndmask_b32_e32 v71, v71, v72, vcc
	v_cvt_f32_u32_e32 v70, v70
	v_cvt_f32_u32_e32 v71, v71
	v_mul_f32_e32 v70, v87, v70
	v_mul_f32_e32 v71, v87, v71
	v_exp_f32_e32 v70, v70
	v_exp_f32_e32 v71, v71
	v_lshlrev_b32_e32 v72, 16, v119
	v_and_b32_e32 v73, 0xffff0000, v119
	v_pk_mul_f32 v[70:71], v[70:71], v[72:73]
	s_nop 0
	v_cvt_pk_bf16_f32 v119, v70, v71
	s_waitcnt vmcnt(13)
	v_mfma_f32_32x32x16_bf16 v[54:69], v[116:119], v[136:139], v[54:69]
	s_waitcnt vmcnt(11)
	v_mfma_f32_32x32x16_bf16 v[22:37], v[116:119], v[144:147], v[22:37]
	v_mfma_f32_32x32x16_bf16 v[38:53], v[116:119], v[140:143], v[38:53]
	s_waitcnt vmcnt(10)
	v_mfma_f32_32x32x16_bf16 v[6:21], v[116:119], v[148:151], v[6:21]
	global_load_dwordx4 v[112:115], v[82:83], off offset:3712
	global_load_dwordx4 v[116:119], v[82:83], off offset:3744
	global_load_dwordx4 v[120:123], v[78:79], off offset:3712
	global_load_dwordx4 v[124:127], v[80:81], off offset:3712
	global_load_dwordx4 v[128:131], v[90:91], off offset:3712
	global_load_dwordx4 v[132:135], v[92:93], off offset:3712
	global_load_dwordx4 v[136:139], v[78:79], off offset:3744
	global_load_dwordx4 v[140:143], v[80:81], off offset:3744
	global_load_dwordx4 v[144:147], v[90:91], off offset:3744
	global_load_dwordx4 v[148:151], v[92:93], off offset:3744
	v_add_u32_e32 v70, 0x10, v89
	v_add_u32_e32 v72, 0xdf, v88
	v_add_u32_e32 v71, 0x11, v89
	v_cndmask_b32_e32 v70, v70, v72, vcc
	v_add_u32_e32 v72, 0xde, v88
	v_cndmask_b32_e32 v71, v71, v72, vcc
	v_cvt_f32_u32_e32 v70, v70
	v_cvt_f32_u32_e32 v71, v71
	v_mul_f32_e32 v70, v87, v70
	v_mul_f32_e32 v71, v87, v71
	v_exp_f32_e32 v70, v70
	v_exp_f32_e32 v71, v71
	s_waitcnt vmcnt(19)
	v_lshlrev_b32_e32 v72, 16, v152
	v_and_b32_e32 v73, 0xffff0000, v152
	v_pk_mul_f32 v[70:71], v[70:71], v[72:73]
	s_nop 0
	v_cvt_pk_bf16_f32 v152, v70, v71
	v_add_u32_e32 v70, 0x12, v89
	v_add_u32_e32 v72, 0xdd, v88
	v_add_u32_e32 v71, 0x13, v89
	v_cndmask_b32_e32 v70, v70, v72, vcc
	v_add_u32_e32 v72, 0xdc, v88
	v_cndmask_b32_e32 v71, v71, v72, vcc
	v_cvt_f32_u32_e32 v70, v70
	v_cvt_f32_u32_e32 v71, v71
	v_mul_f32_e32 v70, v87, v70
	v_mul_f32_e32 v71, v87, v71
	v_exp_f32_e32 v70, v70
	v_exp_f32_e32 v71, v71
	v_lshlrev_b32_e32 v72, 16, v153
	v_and_b32_e32 v73, 0xffff0000, v153
	v_pk_mul_f32 v[70:71], v[70:71], v[72:73]
	s_nop 0
	v_cvt_pk_bf16_f32 v153, v70, v71
	v_add_u32_e32 v70, 0x14, v89
	v_add_u32_e32 v72, 0xdb, v88
	v_add_u32_e32 v71, 0x15, v89
	v_cndmask_b32_e32 v70, v70, v72, vcc
	v_add_u32_e32 v72, 0xda, v88
	v_cndmask_b32_e32 v71, v71, v72, vcc
	v_cvt_f32_u32_e32 v70, v70
	v_cvt_f32_u32_e32 v71, v71
	v_mul_f32_e32 v70, v87, v70
	v_mul_f32_e32 v71, v87, v71
	v_exp_f32_e32 v70, v70
	v_exp_f32_e32 v71, v71
	v_lshlrev_b32_e32 v72, 16, v154
	v_and_b32_e32 v73, 0xffff0000, v154
	v_pk_mul_f32 v[70:71], v[70:71], v[72:73]
	s_nop 0
	v_cvt_pk_bf16_f32 v154, v70, v71
	v_add_u32_e32 v70, 0x16, v89
	v_add_u32_e32 v72, 0xd9, v88
	v_add_u32_e32 v71, 0x17, v89
	v_cndmask_b32_e32 v70, v70, v72, vcc
	v_add_u32_e32 v72, 0xd8, v88
	v_cndmask_b32_e32 v71, v71, v72, vcc
	v_cvt_f32_u32_e32 v70, v70
	v_cvt_f32_u32_e32 v71, v71
	v_mul_f32_e32 v70, v87, v70
	v_mul_f32_e32 v71, v87, v71
	v_exp_f32_e32 v70, v70
	v_exp_f32_e32 v71, v71
	v_lshlrev_b32_e32 v72, 16, v155
	v_and_b32_e32 v73, 0xffff0000, v155
	v_pk_mul_f32 v[70:71], v[70:71], v[72:73]
	s_nop 0
	v_cvt_pk_bf16_f32 v155, v70, v71
	s_waitcnt vmcnt(17)
	v_mfma_f32_32x32x16_bf16 v[54:69], v[152:155], v[160:163], v[54:69]
	s_waitcnt vmcnt(16)
	v_mfma_f32_32x32x16_bf16 v[38:53], v[152:155], v[168:171], v[38:53]
	s_waitcnt vmcnt(15)
	v_mfma_f32_32x32x16_bf16 v[22:37], v[152:155], v[172:175], v[22:37]
	s_waitcnt vmcnt(14)
	v_mfma_f32_32x32x16_bf16 v[6:21], v[152:155], v[176:179], v[6:21]
	v_add_u32_e32 v70, 0x20, v89
	v_add_u32_e32 v72, 0xcf, v88
	v_add_u32_e32 v71, 0x21, v89
	v_cndmask_b32_e32 v70, v70, v72, vcc
	v_add_u32_e32 v72, 0xce, v88
	v_cndmask_b32_e32 v71, v71, v72, vcc
	v_cvt_f32_u32_e32 v70, v70
	v_cvt_f32_u32_e32 v71, v71
	v_mul_f32_e32 v70, v87, v70
	v_mul_f32_e32 v71, v87, v71
	v_exp_f32_e32 v70, v70
	v_exp_f32_e32 v71, v71
	v_lshlrev_b32_e32 v72, 16, v156
	v_and_b32_e32 v73, 0xffff0000, v156
	v_pk_mul_f32 v[70:71], v[70:71], v[72:73]
	s_nop 0
	v_cvt_pk_bf16_f32 v156, v70, v71
	v_add_u32_e32 v70, 0x22, v89
	v_add_u32_e32 v72, 0xcd, v88
	v_add_u32_e32 v71, 0x23, v89
	v_cndmask_b32_e32 v70, v70, v72, vcc
	v_add_u32_e32 v72, 0xcc, v88
	v_cndmask_b32_e32 v71, v71, v72, vcc
	v_cvt_f32_u32_e32 v70, v70
	v_cvt_f32_u32_e32 v71, v71
	v_mul_f32_e32 v70, v87, v70
	v_mul_f32_e32 v71, v87, v71
	v_exp_f32_e32 v70, v70
	v_exp_f32_e32 v71, v71
	v_lshlrev_b32_e32 v72, 16, v157
	v_and_b32_e32 v73, 0xffff0000, v157
	v_pk_mul_f32 v[70:71], v[70:71], v[72:73]
	s_nop 0
	v_cvt_pk_bf16_f32 v157, v70, v71
	v_add_u32_e32 v70, 0x24, v89
	v_add_u32_e32 v72, 0xcb, v88
	v_add_u32_e32 v71, 0x25, v89
	v_cndmask_b32_e32 v70, v70, v72, vcc
	v_add_u32_e32 v72, 0xca, v88
	v_cndmask_b32_e32 v71, v71, v72, vcc
	v_cvt_f32_u32_e32 v70, v70
	v_cvt_f32_u32_e32 v71, v71
	v_mul_f32_e32 v70, v87, v70
	v_mul_f32_e32 v71, v87, v71
	v_exp_f32_e32 v70, v70
	v_exp_f32_e32 v71, v71
	v_lshlrev_b32_e32 v72, 16, v158
	v_and_b32_e32 v73, 0xffff0000, v158
	v_pk_mul_f32 v[70:71], v[70:71], v[72:73]
	s_nop 0
	v_cvt_pk_bf16_f32 v158, v70, v71
	v_add_u32_e32 v70, 0x26, v89
	v_add_u32_e32 v72, 0xc9, v88
	v_add_u32_e32 v71, 0x27, v89
	v_cndmask_b32_e32 v70, v70, v72, vcc
	v_add_u32_e32 v72, 0xc8, v88
	v_cndmask_b32_e32 v71, v71, v72, vcc
	v_cvt_f32_u32_e32 v70, v70
	v_cvt_f32_u32_e32 v71, v71
	v_mul_f32_e32 v70, v87, v70
	v_mul_f32_e32 v71, v87, v71
	v_exp_f32_e32 v70, v70
	v_exp_f32_e32 v71, v71
	v_lshlrev_b32_e32 v72, 16, v159
	v_and_b32_e32 v73, 0xffff0000, v159
	v_pk_mul_f32 v[70:71], v[70:71], v[72:73]
	s_nop 0
	v_cvt_pk_bf16_f32 v159, v70, v71
	s_waitcnt vmcnt(13)
	v_mfma_f32_32x32x16_bf16 v[54:69], v[156:159], v[180:183], v[54:69]
	s_waitcnt vmcnt(11)
	v_mfma_f32_32x32x16_bf16 v[22:37], v[156:159], v[188:191], v[22:37]
	v_mfma_f32_32x32x16_bf16 v[38:53], v[156:159], v[184:187], v[38:53]
	s_waitcnt vmcnt(10)
	v_mfma_f32_32x32x16_bf16 v[6:21], v[156:159], v[192:195], v[6:21]
	global_load_dwordx4 v[152:155], v[82:83], off offset:3776
	global_load_dwordx4 v[156:159], v[82:83], off offset:3808
	global_load_dwordx4 v[160:163], v[78:79], off offset:3776
	global_load_dwordx4 v[168:171], v[80:81], off offset:3776
	global_load_dwordx4 v[172:175], v[90:91], off offset:3776
	global_load_dwordx4 v[176:179], v[92:93], off offset:3776
	global_load_dwordx4 v[180:183], v[78:79], off offset:3808
	global_load_dwordx4 v[184:187], v[80:81], off offset:3808
	global_load_dwordx4 v[188:191], v[90:91], off offset:3808
	global_load_dwordx4 v[192:195], v[92:93], off offset:3808
	v_add_u32_e32 v70, 0x30, v89
	v_add_u32_e32 v72, 0xbf, v88
	v_add_u32_e32 v71, 0x31, v89
	v_cndmask_b32_e32 v70, v70, v72, vcc
	v_add_u32_e32 v72, 0xbe, v88
	v_cndmask_b32_e32 v71, v71, v72, vcc
	v_cvt_f32_u32_e32 v70, v70
	v_cvt_f32_u32_e32 v71, v71
	v_mul_f32_e32 v70, v87, v70
	v_mul_f32_e32 v71, v87, v71
	v_exp_f32_e32 v70, v70
	v_exp_f32_e32 v71, v71
	s_waitcnt vmcnt(19)
	v_lshlrev_b32_e32 v72, 16, v112
	v_and_b32_e32 v73, 0xffff0000, v112
	v_pk_mul_f32 v[70:71], v[70:71], v[72:73]
	s_nop 0
	v_cvt_pk_bf16_f32 v112, v70, v71
	v_add_u32_e32 v70, 0x32, v89
	v_add_u32_e32 v72, 0xbd, v88
	v_add_u32_e32 v71, 0x33, v89
	v_cndmask_b32_e32 v70, v70, v72, vcc
	v_add_u32_e32 v72, 0xbc, v88
	v_cndmask_b32_e32 v71, v71, v72, vcc
	v_cvt_f32_u32_e32 v70, v70
	v_cvt_f32_u32_e32 v71, v71
	v_mul_f32_e32 v70, v87, v70
	v_mul_f32_e32 v71, v87, v71
	v_exp_f32_e32 v70, v70
	v_exp_f32_e32 v71, v71
	v_lshlrev_b32_e32 v72, 16, v113
	v_and_b32_e32 v73, 0xffff0000, v113
	v_pk_mul_f32 v[70:71], v[70:71], v[72:73]
	s_nop 0
	v_cvt_pk_bf16_f32 v113, v70, v71
	v_add_u32_e32 v70, 0x34, v89
	v_add_u32_e32 v72, 0xbb, v88
	v_add_u32_e32 v71, 0x35, v89
	v_cndmask_b32_e32 v70, v70, v72, vcc
	v_add_u32_e32 v72, 0xba, v88
	v_cndmask_b32_e32 v71, v71, v72, vcc
	v_cvt_f32_u32_e32 v70, v70
	v_cvt_f32_u32_e32 v71, v71
	v_mul_f32_e32 v70, v87, v70
	v_mul_f32_e32 v71, v87, v71
	v_exp_f32_e32 v70, v70
	v_exp_f32_e32 v71, v71
	v_lshlrev_b32_e32 v72, 16, v114
	v_and_b32_e32 v73, 0xffff0000, v114
	v_pk_mul_f32 v[70:71], v[70:71], v[72:73]
	s_nop 0
	v_cvt_pk_bf16_f32 v114, v70, v71
	v_add_u32_e32 v70, 0x36, v89
	v_add_u32_e32 v72, 0xb9, v88
	v_add_u32_e32 v71, 0x37, v89
	v_cndmask_b32_e32 v70, v70, v72, vcc
	v_add_u32_e32 v72, 0xb8, v88
	v_cndmask_b32_e32 v71, v71, v72, vcc
	v_cvt_f32_u32_e32 v70, v70
	v_cvt_f32_u32_e32 v71, v71
	v_mul_f32_e32 v70, v87, v70
	v_mul_f32_e32 v71, v87, v71
	v_exp_f32_e32 v70, v70
	v_exp_f32_e32 v71, v71
	v_lshlrev_b32_e32 v72, 16, v115
	v_and_b32_e32 v73, 0xffff0000, v115
	v_pk_mul_f32 v[70:71], v[70:71], v[72:73]
	s_nop 0
	v_cvt_pk_bf16_f32 v115, v70, v71
	s_waitcnt vmcnt(17)
	v_mfma_f32_32x32x16_bf16 v[54:69], v[112:115], v[120:123], v[54:69]
	s_waitcnt vmcnt(16)
	v_mfma_f32_32x32x16_bf16 v[38:53], v[112:115], v[124:127], v[38:53]
	s_waitcnt vmcnt(15)
	v_mfma_f32_32x32x16_bf16 v[22:37], v[112:115], v[128:131], v[22:37]
	s_waitcnt vmcnt(14)
	v_mfma_f32_32x32x16_bf16 v[6:21], v[112:115], v[132:135], v[6:21]
	v_add_u32_e32 v70, 0x40, v89
	v_add_u32_e32 v72, 0xaf, v88
	v_add_u32_e32 v71, 0x41, v89
	v_cndmask_b32_e32 v70, v70, v72, vcc
	v_add_u32_e32 v72, 0xae, v88
	v_cndmask_b32_e32 v71, v71, v72, vcc
	v_cvt_f32_u32_e32 v70, v70
	v_cvt_f32_u32_e32 v71, v71
	v_mul_f32_e32 v70, v87, v70
	v_mul_f32_e32 v71, v87, v71
	v_exp_f32_e32 v70, v70
	v_exp_f32_e32 v71, v71
	v_lshlrev_b32_e32 v72, 16, v116
	v_and_b32_e32 v73, 0xffff0000, v116
	v_pk_mul_f32 v[70:71], v[70:71], v[72:73]
	s_nop 0
	v_cvt_pk_bf16_f32 v116, v70, v71
	v_add_u32_e32 v70, 0x42, v89
	v_add_u32_e32 v72, 0xad, v88
	v_add_u32_e32 v71, 0x43, v89
	v_cndmask_b32_e32 v70, v70, v72, vcc
	v_add_u32_e32 v72, 0xac, v88
	v_cndmask_b32_e32 v71, v71, v72, vcc
	v_cvt_f32_u32_e32 v70, v70
	v_cvt_f32_u32_e32 v71, v71
	v_mul_f32_e32 v70, v87, v70
	v_mul_f32_e32 v71, v87, v71
	v_exp_f32_e32 v70, v70
	v_exp_f32_e32 v71, v71
	v_lshlrev_b32_e32 v72, 16, v117
	v_and_b32_e32 v73, 0xffff0000, v117
	v_pk_mul_f32 v[70:71], v[70:71], v[72:73]
	s_nop 0
	v_cvt_pk_bf16_f32 v117, v70, v71
	v_add_u32_e32 v70, 0x44, v89
	v_add_u32_e32 v72, 0xab, v88
	v_add_u32_e32 v71, 0x45, v89
	v_cndmask_b32_e32 v70, v70, v72, vcc
	v_add_u32_e32 v72, 0xaa, v88
	v_cndmask_b32_e32 v71, v71, v72, vcc
	v_cvt_f32_u32_e32 v70, v70
	v_cvt_f32_u32_e32 v71, v71
	v_mul_f32_e32 v70, v87, v70
	v_mul_f32_e32 v71, v87, v71
	v_exp_f32_e32 v70, v70
	v_exp_f32_e32 v71, v71
	v_lshlrev_b32_e32 v72, 16, v118
	v_and_b32_e32 v73, 0xffff0000, v118
	v_pk_mul_f32 v[70:71], v[70:71], v[72:73]
	s_nop 0
	v_cvt_pk_bf16_f32 v118, v70, v71
	v_add_u32_e32 v70, 0x46, v89
	v_add_u32_e32 v72, 0xa9, v88
	v_add_u32_e32 v71, 0x47, v89
	v_cndmask_b32_e32 v70, v70, v72, vcc
	v_add_u32_e32 v72, 0xa8, v88
	v_cndmask_b32_e32 v71, v71, v72, vcc
	v_cvt_f32_u32_e32 v70, v70
	v_cvt_f32_u32_e32 v71, v71
	v_mul_f32_e32 v70, v87, v70
	v_mul_f32_e32 v71, v87, v71
	v_exp_f32_e32 v70, v70
	v_exp_f32_e32 v71, v71
	v_lshlrev_b32_e32 v72, 16, v119
	v_and_b32_e32 v73, 0xffff0000, v119
	v_pk_mul_f32 v[70:71], v[70:71], v[72:73]
	s_nop 0
	v_cvt_pk_bf16_f32 v119, v70, v71
	s_waitcnt vmcnt(13)
	v_mfma_f32_32x32x16_bf16 v[54:69], v[116:119], v[136:139], v[54:69]
	s_waitcnt vmcnt(11)
	v_mfma_f32_32x32x16_bf16 v[22:37], v[116:119], v[144:147], v[22:37]
	v_mfma_f32_32x32x16_bf16 v[38:53], v[116:119], v[140:143], v[38:53]
	s_waitcnt vmcnt(10)
	v_mfma_f32_32x32x16_bf16 v[6:21], v[116:119], v[148:151], v[6:21]
	global_load_dwordx4 v[112:115], v[82:83], off offset:3840
	global_load_dwordx4 v[116:119], v[82:83], off offset:3872
	global_load_dwordx4 v[120:123], v[78:79], off offset:3840
	global_load_dwordx4 v[124:127], v[80:81], off offset:3840
	global_load_dwordx4 v[128:131], v[90:91], off offset:3840
	global_load_dwordx4 v[132:135], v[92:93], off offset:3840
	global_load_dwordx4 v[136:139], v[78:79], off offset:3872
	global_load_dwordx4 v[140:143], v[80:81], off offset:3872
	global_load_dwordx4 v[144:147], v[90:91], off offset:3872
	global_load_dwordx4 v[148:151], v[92:93], off offset:3872
	v_add_u32_e32 v70, 0x50, v89
	v_add_u32_e32 v72, 0x9f, v88
	v_add_u32_e32 v71, 0x51, v89
	v_cndmask_b32_e32 v70, v70, v72, vcc
	v_add_u32_e32 v72, 0x9e, v88
	v_cndmask_b32_e32 v71, v71, v72, vcc
	v_cvt_f32_u32_e32 v70, v70
	v_cvt_f32_u32_e32 v71, v71
	v_mul_f32_e32 v70, v87, v70
	v_mul_f32_e32 v71, v87, v71
	v_exp_f32_e32 v70, v70
	v_exp_f32_e32 v71, v71
	s_waitcnt vmcnt(19)
	v_lshlrev_b32_e32 v72, 16, v152
	v_and_b32_e32 v73, 0xffff0000, v152
	v_pk_mul_f32 v[70:71], v[70:71], v[72:73]
	s_nop 0
	v_cvt_pk_bf16_f32 v152, v70, v71
	v_add_u32_e32 v70, 0x52, v89
	v_add_u32_e32 v72, 0x9d, v88
	v_add_u32_e32 v71, 0x53, v89
	v_cndmask_b32_e32 v70, v70, v72, vcc
	v_add_u32_e32 v72, 0x9c, v88
	v_cndmask_b32_e32 v71, v71, v72, vcc
	v_cvt_f32_u32_e32 v70, v70
	v_cvt_f32_u32_e32 v71, v71
	v_mul_f32_e32 v70, v87, v70
	v_mul_f32_e32 v71, v87, v71
	v_exp_f32_e32 v70, v70
	v_exp_f32_e32 v71, v71
	v_lshlrev_b32_e32 v72, 16, v153
	v_and_b32_e32 v73, 0xffff0000, v153
	v_pk_mul_f32 v[70:71], v[70:71], v[72:73]
	s_nop 0
	v_cvt_pk_bf16_f32 v153, v70, v71
	v_add_u32_e32 v70, 0x54, v89
	v_add_u32_e32 v72, 0x9b, v88
	v_add_u32_e32 v71, 0x55, v89
	v_cndmask_b32_e32 v70, v70, v72, vcc
	v_add_u32_e32 v72, 0x9a, v88
	v_cndmask_b32_e32 v71, v71, v72, vcc
	v_cvt_f32_u32_e32 v70, v70
	v_cvt_f32_u32_e32 v71, v71
	v_mul_f32_e32 v70, v87, v70
	v_mul_f32_e32 v71, v87, v71
	v_exp_f32_e32 v70, v70
	v_exp_f32_e32 v71, v71
	v_lshlrev_b32_e32 v72, 16, v154
	v_and_b32_e32 v73, 0xffff0000, v154
	v_pk_mul_f32 v[70:71], v[70:71], v[72:73]
	s_nop 0
	v_cvt_pk_bf16_f32 v154, v70, v71
	v_add_u32_e32 v70, 0x56, v89
	v_add_u32_e32 v72, 0x99, v88
	v_add_u32_e32 v71, 0x57, v89
	v_cndmask_b32_e32 v70, v70, v72, vcc
	v_add_u32_e32 v72, 0x98, v88
	v_cndmask_b32_e32 v71, v71, v72, vcc
	v_cvt_f32_u32_e32 v70, v70
	v_cvt_f32_u32_e32 v71, v71
	v_mul_f32_e32 v70, v87, v70
	v_mul_f32_e32 v71, v87, v71
	v_exp_f32_e32 v70, v70
	v_exp_f32_e32 v71, v71
	v_lshlrev_b32_e32 v72, 16, v155
	v_and_b32_e32 v73, 0xffff0000, v155
	v_pk_mul_f32 v[70:71], v[70:71], v[72:73]
	s_nop 0
	v_cvt_pk_bf16_f32 v155, v70, v71
	s_waitcnt vmcnt(17)
	v_mfma_f32_32x32x16_bf16 v[54:69], v[152:155], v[160:163], v[54:69]
	s_waitcnt vmcnt(16)
	v_mfma_f32_32x32x16_bf16 v[38:53], v[152:155], v[168:171], v[38:53]
	s_waitcnt vmcnt(15)
	v_mfma_f32_32x32x16_bf16 v[22:37], v[152:155], v[172:175], v[22:37]
	s_waitcnt vmcnt(14)
	v_mfma_f32_32x32x16_bf16 v[6:21], v[152:155], v[176:179], v[6:21]
	v_add_u32_e32 v70, 0x60, v89
	v_add_u32_e32 v72, 0x8f, v88
	v_add_u32_e32 v71, 0x61, v89
	v_cndmask_b32_e32 v70, v70, v72, vcc
	v_add_u32_e32 v72, 0x8e, v88
	v_cndmask_b32_e32 v71, v71, v72, vcc
	v_cvt_f32_u32_e32 v70, v70
	v_cvt_f32_u32_e32 v71, v71
	v_mul_f32_e32 v70, v87, v70
	v_mul_f32_e32 v71, v87, v71
	v_exp_f32_e32 v70, v70
	v_exp_f32_e32 v71, v71
	v_lshlrev_b32_e32 v72, 16, v156
	v_and_b32_e32 v73, 0xffff0000, v156
	v_pk_mul_f32 v[70:71], v[70:71], v[72:73]
	s_nop 0
	v_cvt_pk_bf16_f32 v156, v70, v71
	v_add_u32_e32 v70, 0x62, v89
	v_add_u32_e32 v72, 0x8d, v88
	v_add_u32_e32 v71, 0x63, v89
	v_cndmask_b32_e32 v70, v70, v72, vcc
	v_add_u32_e32 v72, 0x8c, v88
	v_cndmask_b32_e32 v71, v71, v72, vcc
	v_cvt_f32_u32_e32 v70, v70
	v_cvt_f32_u32_e32 v71, v71
	v_mul_f32_e32 v70, v87, v70
	v_mul_f32_e32 v71, v87, v71
	v_exp_f32_e32 v70, v70
	v_exp_f32_e32 v71, v71
	v_lshlrev_b32_e32 v72, 16, v157
	v_and_b32_e32 v73, 0xffff0000, v157
	v_pk_mul_f32 v[70:71], v[70:71], v[72:73]
	s_nop 0
	v_cvt_pk_bf16_f32 v157, v70, v71
	v_add_u32_e32 v70, 0x64, v89
	v_add_u32_e32 v72, 0x8b, v88
	v_add_u32_e32 v71, 0x65, v89
	v_cndmask_b32_e32 v70, v70, v72, vcc
	v_add_u32_e32 v72, 0x8a, v88
	v_cndmask_b32_e32 v71, v71, v72, vcc
	v_cvt_f32_u32_e32 v70, v70
	v_cvt_f32_u32_e32 v71, v71
	v_mul_f32_e32 v70, v87, v70
	v_mul_f32_e32 v71, v87, v71
	v_exp_f32_e32 v70, v70
	v_exp_f32_e32 v71, v71
	v_lshlrev_b32_e32 v72, 16, v158
	v_and_b32_e32 v73, 0xffff0000, v158
	v_pk_mul_f32 v[70:71], v[70:71], v[72:73]
	s_nop 0
	v_cvt_pk_bf16_f32 v158, v70, v71
	v_add_u32_e32 v70, 0x66, v89
	v_add_u32_e32 v72, 0x89, v88
	v_add_u32_e32 v71, 0x67, v89
	v_cndmask_b32_e32 v70, v70, v72, vcc
	v_add_u32_e32 v72, 0x88, v88
	v_cndmask_b32_e32 v71, v71, v72, vcc
	v_cvt_f32_u32_e32 v70, v70
	v_cvt_f32_u32_e32 v71, v71
	v_mul_f32_e32 v70, v87, v70
	v_mul_f32_e32 v71, v87, v71
	v_exp_f32_e32 v70, v70
	v_exp_f32_e32 v71, v71
	v_lshlrev_b32_e32 v72, 16, v159
	v_and_b32_e32 v73, 0xffff0000, v159
	v_pk_mul_f32 v[70:71], v[70:71], v[72:73]
	s_nop 0
	v_cvt_pk_bf16_f32 v159, v70, v71
	s_waitcnt vmcnt(13)
	v_mfma_f32_32x32x16_bf16 v[54:69], v[156:159], v[180:183], v[54:69]
	s_waitcnt vmcnt(11)
	v_mfma_f32_32x32x16_bf16 v[22:37], v[156:159], v[188:191], v[22:37]
	v_mfma_f32_32x32x16_bf16 v[38:53], v[156:159], v[184:187], v[38:53]
	s_waitcnt vmcnt(10)
	v_mfma_f32_32x32x16_bf16 v[6:21], v[156:159], v[192:195], v[6:21]
	global_load_dwordx4 v[152:155], v[82:83], off offset:3904
	global_load_dwordx4 v[156:159], v[82:83], off offset:3936
	global_load_dwordx4 v[160:163], v[78:79], off offset:3904
	global_load_dwordx4 v[168:171], v[80:81], off offset:3904
	global_load_dwordx4 v[172:175], v[90:91], off offset:3904
	global_load_dwordx4 v[176:179], v[92:93], off offset:3904
	global_load_dwordx4 v[180:183], v[78:79], off offset:3936
	global_load_dwordx4 v[184:187], v[80:81], off offset:3936
	global_load_dwordx4 v[188:191], v[90:91], off offset:3936
	global_load_dwordx4 v[192:195], v[92:93], off offset:3936
	v_add_u32_e32 v70, 0x70, v89
	v_add_u32_e32 v72, 0x7f, v88
	v_add_u32_e32 v71, 0x71, v89
	v_cndmask_b32_e32 v70, v70, v72, vcc
	v_add_u32_e32 v72, 0x7e, v88
	v_cndmask_b32_e32 v71, v71, v72, vcc
	v_cvt_f32_u32_e32 v70, v70
	v_cvt_f32_u32_e32 v71, v71
	v_mul_f32_e32 v70, v87, v70
	v_mul_f32_e32 v71, v87, v71
	v_exp_f32_e32 v70, v70
	v_exp_f32_e32 v71, v71
	s_waitcnt vmcnt(19)
	v_lshlrev_b32_e32 v72, 16, v112
	v_and_b32_e32 v73, 0xffff0000, v112
	v_pk_mul_f32 v[70:71], v[70:71], v[72:73]
	s_nop 0
	v_cvt_pk_bf16_f32 v112, v70, v71
	v_add_u32_e32 v70, 0x72, v89
	v_add_u32_e32 v72, 0x7d, v88
	v_add_u32_e32 v71, 0x73, v89
	v_cndmask_b32_e32 v70, v70, v72, vcc
	v_add_u32_e32 v72, 0x7c, v88
	v_cndmask_b32_e32 v71, v71, v72, vcc
	v_cvt_f32_u32_e32 v70, v70
	v_cvt_f32_u32_e32 v71, v71
	v_mul_f32_e32 v70, v87, v70
	v_mul_f32_e32 v71, v87, v71
	v_exp_f32_e32 v70, v70
	v_exp_f32_e32 v71, v71
	v_lshlrev_b32_e32 v72, 16, v113
	v_and_b32_e32 v73, 0xffff0000, v113
	v_pk_mul_f32 v[70:71], v[70:71], v[72:73]
	s_nop 0
	v_cvt_pk_bf16_f32 v113, v70, v71
	v_add_u32_e32 v70, 0x74, v89
	v_add_u32_e32 v72, 0x7b, v88
	v_add_u32_e32 v71, 0x75, v89
	v_cndmask_b32_e32 v70, v70, v72, vcc
	v_add_u32_e32 v72, 0x7a, v88
	v_cndmask_b32_e32 v71, v71, v72, vcc
	v_cvt_f32_u32_e32 v70, v70
	v_cvt_f32_u32_e32 v71, v71
	v_mul_f32_e32 v70, v87, v70
	v_mul_f32_e32 v71, v87, v71
	v_exp_f32_e32 v70, v70
	v_exp_f32_e32 v71, v71
	v_lshlrev_b32_e32 v72, 16, v114
	v_and_b32_e32 v73, 0xffff0000, v114
	v_pk_mul_f32 v[70:71], v[70:71], v[72:73]
	s_nop 0
	v_cvt_pk_bf16_f32 v114, v70, v71
	v_add_u32_e32 v70, 0x76, v89
	v_add_u32_e32 v72, 0x79, v88
	v_add_u32_e32 v71, 0x77, v89
	v_cndmask_b32_e32 v70, v70, v72, vcc
	v_add_u32_e32 v72, 0x78, v88
	v_cndmask_b32_e32 v71, v71, v72, vcc
	v_cvt_f32_u32_e32 v70, v70
	v_cvt_f32_u32_e32 v71, v71
	v_mul_f32_e32 v70, v87, v70
	v_mul_f32_e32 v71, v87, v71
	v_exp_f32_e32 v70, v70
	v_exp_f32_e32 v71, v71
	v_lshlrev_b32_e32 v72, 16, v115
	v_and_b32_e32 v73, 0xffff0000, v115
	v_pk_mul_f32 v[70:71], v[70:71], v[72:73]
	s_nop 0
	v_cvt_pk_bf16_f32 v115, v70, v71
	s_waitcnt vmcnt(17)
	v_mfma_f32_32x32x16_bf16 v[54:69], v[112:115], v[120:123], v[54:69]
	s_waitcnt vmcnt(16)
	v_mfma_f32_32x32x16_bf16 v[38:53], v[112:115], v[124:127], v[38:53]
	s_waitcnt vmcnt(15)
	v_mfma_f32_32x32x16_bf16 v[22:37], v[112:115], v[128:131], v[22:37]
	s_waitcnt vmcnt(14)
	v_mfma_f32_32x32x16_bf16 v[6:21], v[112:115], v[132:135], v[6:21]
	v_add_u32_e32 v70, 0x80, v89
	v_add_u32_e32 v72, 0x6f, v88
	v_add_u32_e32 v71, 0x81, v89
	v_cndmask_b32_e32 v70, v70, v72, vcc
	v_add_u32_e32 v72, 0x6e, v88
	v_cndmask_b32_e32 v71, v71, v72, vcc
	v_cvt_f32_u32_e32 v70, v70
	v_cvt_f32_u32_e32 v71, v71
	v_mul_f32_e32 v70, v87, v70
	v_mul_f32_e32 v71, v87, v71
	v_exp_f32_e32 v70, v70
	v_exp_f32_e32 v71, v71
	v_lshlrev_b32_e32 v72, 16, v116
	v_and_b32_e32 v73, 0xffff0000, v116
	v_pk_mul_f32 v[70:71], v[70:71], v[72:73]
	s_nop 0
	v_cvt_pk_bf16_f32 v116, v70, v71
	v_add_u32_e32 v70, 0x82, v89
	v_add_u32_e32 v72, 0x6d, v88
	v_add_u32_e32 v71, 0x83, v89
	v_cndmask_b32_e32 v70, v70, v72, vcc
	v_add_u32_e32 v72, 0x6c, v88
	v_cndmask_b32_e32 v71, v71, v72, vcc
	v_cvt_f32_u32_e32 v70, v70
	v_cvt_f32_u32_e32 v71, v71
	v_mul_f32_e32 v70, v87, v70
	v_mul_f32_e32 v71, v87, v71
	v_exp_f32_e32 v70, v70
	v_exp_f32_e32 v71, v71
	v_lshlrev_b32_e32 v72, 16, v117
	v_and_b32_e32 v73, 0xffff0000, v117
	v_pk_mul_f32 v[70:71], v[70:71], v[72:73]
	s_nop 0
	v_cvt_pk_bf16_f32 v117, v70, v71
	v_add_u32_e32 v70, 0x84, v89
	v_add_u32_e32 v72, 0x6b, v88
	v_add_u32_e32 v71, 0x85, v89
	v_cndmask_b32_e32 v70, v70, v72, vcc
	v_add_u32_e32 v72, 0x6a, v88
	v_cndmask_b32_e32 v71, v71, v72, vcc
	v_cvt_f32_u32_e32 v70, v70
	v_cvt_f32_u32_e32 v71, v71
	v_mul_f32_e32 v70, v87, v70
	v_mul_f32_e32 v71, v87, v71
	v_exp_f32_e32 v70, v70
	v_exp_f32_e32 v71, v71
	v_lshlrev_b32_e32 v72, 16, v118
	v_and_b32_e32 v73, 0xffff0000, v118
	v_pk_mul_f32 v[70:71], v[70:71], v[72:73]
	s_nop 0
	v_cvt_pk_bf16_f32 v118, v70, v71
	v_add_u32_e32 v70, 0x86, v89
	v_add_u32_e32 v72, 0x69, v88
	v_add_u32_e32 v71, 0x87, v89
	v_cndmask_b32_e32 v70, v70, v72, vcc
	v_add_u32_e32 v72, 0x68, v88
	v_cndmask_b32_e32 v71, v71, v72, vcc
	v_cvt_f32_u32_e32 v70, v70
	v_cvt_f32_u32_e32 v71, v71
	v_mul_f32_e32 v70, v87, v70
	v_mul_f32_e32 v71, v87, v71
	v_exp_f32_e32 v70, v70
	v_exp_f32_e32 v71, v71
	v_lshlrev_b32_e32 v72, 16, v119
	v_and_b32_e32 v73, 0xffff0000, v119
	v_pk_mul_f32 v[70:71], v[70:71], v[72:73]
	s_nop 0
	v_cvt_pk_bf16_f32 v119, v70, v71
	s_waitcnt vmcnt(13)
	v_mfma_f32_32x32x16_bf16 v[54:69], v[116:119], v[136:139], v[54:69]
	s_waitcnt vmcnt(11)
	v_mfma_f32_32x32x16_bf16 v[22:37], v[116:119], v[144:147], v[22:37]
	v_mfma_f32_32x32x16_bf16 v[38:53], v[116:119], v[140:143], v[38:53]
	s_waitcnt vmcnt(10)
	v_mfma_f32_32x32x16_bf16 v[6:21], v[116:119], v[148:151], v[6:21]
	global_load_dwordx4 v[112:115], v[82:83], off offset:3968
	global_load_dwordx4 v[116:119], v[82:83], off offset:4000
	global_load_dwordx4 v[120:123], v[78:79], off offset:3968
	global_load_dwordx4 v[124:127], v[80:81], off offset:3968
	global_load_dwordx4 v[128:131], v[90:91], off offset:3968
	global_load_dwordx4 v[132:135], v[92:93], off offset:3968
	global_load_dwordx4 v[136:139], v[78:79], off offset:4000
	global_load_dwordx4 v[140:143], v[80:81], off offset:4000
	global_load_dwordx4 v[144:147], v[90:91], off offset:4000
	global_load_dwordx4 v[148:151], v[92:93], off offset:4000
	v_add_u32_e32 v70, 0x90, v89
	v_add_u32_e32 v72, 0x5f, v88
	v_add_u32_e32 v71, 0x91, v89
	v_cndmask_b32_e32 v70, v70, v72, vcc
	v_add_u32_e32 v72, 0x5e, v88
	v_cndmask_b32_e32 v71, v71, v72, vcc
	v_cvt_f32_u32_e32 v70, v70
	v_cvt_f32_u32_e32 v71, v71
	v_mul_f32_e32 v70, v87, v70
	v_mul_f32_e32 v71, v87, v71
	v_exp_f32_e32 v70, v70
	v_exp_f32_e32 v71, v71
	s_waitcnt vmcnt(19)
	v_lshlrev_b32_e32 v72, 16, v152
	v_and_b32_e32 v73, 0xffff0000, v152
	v_pk_mul_f32 v[70:71], v[70:71], v[72:73]
	s_nop 0
	v_cvt_pk_bf16_f32 v152, v70, v71
	v_add_u32_e32 v70, 0x92, v89
	v_add_u32_e32 v72, 0x5d, v88
	v_add_u32_e32 v71, 0x93, v89
	v_cndmask_b32_e32 v70, v70, v72, vcc
	v_add_u32_e32 v72, 0x5c, v88
	v_cndmask_b32_e32 v71, v71, v72, vcc
	v_cvt_f32_u32_e32 v70, v70
	v_cvt_f32_u32_e32 v71, v71
	v_mul_f32_e32 v70, v87, v70
	v_mul_f32_e32 v71, v87, v71
	v_exp_f32_e32 v70, v70
	v_exp_f32_e32 v71, v71
	v_lshlrev_b32_e32 v72, 16, v153
	v_and_b32_e32 v73, 0xffff0000, v153
	v_pk_mul_f32 v[70:71], v[70:71], v[72:73]
	s_nop 0
	v_cvt_pk_bf16_f32 v153, v70, v71
	v_add_u32_e32 v70, 0x94, v89
	v_add_u32_e32 v72, 0x5b, v88
	v_add_u32_e32 v71, 0x95, v89
	v_cndmask_b32_e32 v70, v70, v72, vcc
	v_add_u32_e32 v72, 0x5a, v88
	v_cndmask_b32_e32 v71, v71, v72, vcc
	v_cvt_f32_u32_e32 v70, v70
	v_cvt_f32_u32_e32 v71, v71
	v_mul_f32_e32 v70, v87, v70
	v_mul_f32_e32 v71, v87, v71
	v_exp_f32_e32 v70, v70
	v_exp_f32_e32 v71, v71
	v_lshlrev_b32_e32 v72, 16, v154
	v_and_b32_e32 v73, 0xffff0000, v154
	v_pk_mul_f32 v[70:71], v[70:71], v[72:73]
	s_nop 0
	v_cvt_pk_bf16_f32 v154, v70, v71
	v_add_u32_e32 v70, 0x96, v89
	v_add_u32_e32 v72, 0x59, v88
	v_add_u32_e32 v71, 0x97, v89
	v_cndmask_b32_e32 v70, v70, v72, vcc
	v_add_u32_e32 v72, 0x58, v88
	v_cndmask_b32_e32 v71, v71, v72, vcc
	v_cvt_f32_u32_e32 v70, v70
	v_cvt_f32_u32_e32 v71, v71
	v_mul_f32_e32 v70, v87, v70
	v_mul_f32_e32 v71, v87, v71
	v_exp_f32_e32 v70, v70
	v_exp_f32_e32 v71, v71
	v_lshlrev_b32_e32 v72, 16, v155
	v_and_b32_e32 v73, 0xffff0000, v155
	v_pk_mul_f32 v[70:71], v[70:71], v[72:73]
	s_nop 0
	v_cvt_pk_bf16_f32 v155, v70, v71
	s_waitcnt vmcnt(17)
	v_mfma_f32_32x32x16_bf16 v[54:69], v[152:155], v[160:163], v[54:69]
	s_waitcnt vmcnt(16)
	v_mfma_f32_32x32x16_bf16 v[38:53], v[152:155], v[168:171], v[38:53]
	s_waitcnt vmcnt(15)
	v_mfma_f32_32x32x16_bf16 v[22:37], v[152:155], v[172:175], v[22:37]
	s_waitcnt vmcnt(14)
	v_mfma_f32_32x32x16_bf16 v[6:21], v[152:155], v[176:179], v[6:21]
	v_add_u32_e32 v70, 0xa0, v89
	v_add_u32_e32 v72, 0x4f, v88
	v_add_u32_e32 v71, 0xa1, v89
	v_cndmask_b32_e32 v70, v70, v72, vcc
	v_add_u32_e32 v72, 0x4e, v88
	v_cndmask_b32_e32 v71, v71, v72, vcc
	v_cvt_f32_u32_e32 v70, v70
	v_cvt_f32_u32_e32 v71, v71
	v_mul_f32_e32 v70, v87, v70
	v_mul_f32_e32 v71, v87, v71
	v_exp_f32_e32 v70, v70
	v_exp_f32_e32 v71, v71
	v_lshlrev_b32_e32 v72, 16, v156
	v_and_b32_e32 v73, 0xffff0000, v156
	v_pk_mul_f32 v[70:71], v[70:71], v[72:73]
	s_nop 0
	v_cvt_pk_bf16_f32 v156, v70, v71
	v_add_u32_e32 v70, 0xa2, v89
	v_add_u32_e32 v72, 0x4d, v88
	v_add_u32_e32 v71, 0xa3, v89
	v_cndmask_b32_e32 v70, v70, v72, vcc
	v_add_u32_e32 v72, 0x4c, v88
	v_cndmask_b32_e32 v71, v71, v72, vcc
	v_cvt_f32_u32_e32 v70, v70
	v_cvt_f32_u32_e32 v71, v71
	v_mul_f32_e32 v70, v87, v70
	v_mul_f32_e32 v71, v87, v71
	v_exp_f32_e32 v70, v70
	v_exp_f32_e32 v71, v71
	v_lshlrev_b32_e32 v72, 16, v157
	v_and_b32_e32 v73, 0xffff0000, v157
	v_pk_mul_f32 v[70:71], v[70:71], v[72:73]
	s_nop 0
	v_cvt_pk_bf16_f32 v157, v70, v71
	v_add_u32_e32 v70, 0xa4, v89
	v_add_u32_e32 v72, 0x4b, v88
	v_add_u32_e32 v71, 0xa5, v89
	v_cndmask_b32_e32 v70, v70, v72, vcc
	v_add_u32_e32 v72, 0x4a, v88
	v_cndmask_b32_e32 v71, v71, v72, vcc
	v_cvt_f32_u32_e32 v70, v70
	v_cvt_f32_u32_e32 v71, v71
	v_mul_f32_e32 v70, v87, v70
	v_mul_f32_e32 v71, v87, v71
	v_exp_f32_e32 v70, v70
	v_exp_f32_e32 v71, v71
	v_lshlrev_b32_e32 v72, 16, v158
	v_and_b32_e32 v73, 0xffff0000, v158
	v_pk_mul_f32 v[70:71], v[70:71], v[72:73]
	s_nop 0
	v_cvt_pk_bf16_f32 v158, v70, v71
	v_add_u32_e32 v70, 0xa6, v89
	v_add_u32_e32 v72, 0x49, v88
	v_add_u32_e32 v71, 0xa7, v89
	v_cndmask_b32_e32 v70, v70, v72, vcc
	v_add_u32_e32 v72, 0x48, v88
	v_cndmask_b32_e32 v71, v71, v72, vcc
	v_cvt_f32_u32_e32 v70, v70
	v_cvt_f32_u32_e32 v71, v71
	v_mul_f32_e32 v70, v87, v70
	v_mul_f32_e32 v71, v87, v71
	v_exp_f32_e32 v70, v70
	v_exp_f32_e32 v71, v71
	v_lshlrev_b32_e32 v72, 16, v159
	v_and_b32_e32 v73, 0xffff0000, v159
	v_pk_mul_f32 v[70:71], v[70:71], v[72:73]
	s_nop 0
	v_cvt_pk_bf16_f32 v159, v70, v71
	s_waitcnt vmcnt(13)
	v_mfma_f32_32x32x16_bf16 v[54:69], v[156:159], v[180:183], v[54:69]
	s_waitcnt vmcnt(11)
	v_mfma_f32_32x32x16_bf16 v[22:37], v[156:159], v[188:191], v[22:37]
	v_mfma_f32_32x32x16_bf16 v[38:53], v[156:159], v[184:187], v[38:53]
	s_waitcnt vmcnt(10)
	v_mfma_f32_32x32x16_bf16 v[6:21], v[156:159], v[192:195], v[6:21]
	global_load_dwordx4 v[152:155], v[82:83], off offset:4032
	global_load_dwordx4 v[156:159], v[82:83], off offset:4064
	global_load_dwordx4 v[160:163], v[78:79], off offset:4032
	global_load_dwordx4 v[168:171], v[80:81], off offset:4032
	global_load_dwordx4 v[172:175], v[90:91], off offset:4032
	global_load_dwordx4 v[176:179], v[92:93], off offset:4032
	global_load_dwordx4 v[180:183], v[78:79], off offset:4064
	global_load_dwordx4 v[184:187], v[80:81], off offset:4064
	global_load_dwordx4 v[188:191], v[90:91], off offset:4064
	global_load_dwordx4 v[192:195], v[92:93], off offset:4064
	v_add_u32_e32 v70, 0xb0, v89
	v_add_u32_e32 v72, 0x3f, v88
	v_add_u32_e32 v71, 0xb1, v89
	v_cndmask_b32_e32 v70, v70, v72, vcc
	v_add_u32_e32 v72, 0x3e, v88
	v_cndmask_b32_e32 v71, v71, v72, vcc
	v_cvt_f32_u32_e32 v70, v70
	v_cvt_f32_u32_e32 v71, v71
	v_mul_f32_e32 v70, v87, v70
	v_mul_f32_e32 v71, v87, v71
	v_exp_f32_e32 v70, v70
	v_exp_f32_e32 v71, v71
	s_waitcnt vmcnt(19)
	v_lshlrev_b32_e32 v72, 16, v112
	v_and_b32_e32 v73, 0xffff0000, v112
	v_pk_mul_f32 v[70:71], v[70:71], v[72:73]
	s_nop 0
	v_cvt_pk_bf16_f32 v112, v70, v71
	v_add_u32_e32 v70, 0xb2, v89
	v_add_u32_e32 v72, 0x3d, v88
	v_add_u32_e32 v71, 0xb3, v89
	v_cndmask_b32_e32 v70, v70, v72, vcc
	v_add_u32_e32 v72, 0x3c, v88
	v_cndmask_b32_e32 v71, v71, v72, vcc
	v_cvt_f32_u32_e32 v70, v70
	v_cvt_f32_u32_e32 v71, v71
	v_mul_f32_e32 v70, v87, v70
	v_mul_f32_e32 v71, v87, v71
	v_exp_f32_e32 v70, v70
	v_exp_f32_e32 v71, v71
	v_lshlrev_b32_e32 v72, 16, v113
	v_and_b32_e32 v73, 0xffff0000, v113
	v_pk_mul_f32 v[70:71], v[70:71], v[72:73]
	s_nop 0
	v_cvt_pk_bf16_f32 v113, v70, v71
	v_add_u32_e32 v70, 0xb4, v89
	v_add_u32_e32 v72, 0x3b, v88
	v_add_u32_e32 v71, 0xb5, v89
	v_cndmask_b32_e32 v70, v70, v72, vcc
	v_add_u32_e32 v72, 0x3a, v88
	v_cndmask_b32_e32 v71, v71, v72, vcc
	v_cvt_f32_u32_e32 v70, v70
	v_cvt_f32_u32_e32 v71, v71
	v_mul_f32_e32 v70, v87, v70
	v_mul_f32_e32 v71, v87, v71
	v_exp_f32_e32 v70, v70
	v_exp_f32_e32 v71, v71
	v_lshlrev_b32_e32 v72, 16, v114
	v_and_b32_e32 v73, 0xffff0000, v114
	v_pk_mul_f32 v[70:71], v[70:71], v[72:73]
	s_nop 0
	v_cvt_pk_bf16_f32 v114, v70, v71
	v_add_u32_e32 v70, 0xb6, v89
	v_add_u32_e32 v72, 0x39, v88
	v_add_u32_e32 v71, 0xb7, v89
	v_cndmask_b32_e32 v70, v70, v72, vcc
	v_add_u32_e32 v72, 0x38, v88
	v_cndmask_b32_e32 v71, v71, v72, vcc
	v_cvt_f32_u32_e32 v70, v70
	v_cvt_f32_u32_e32 v71, v71
	v_mul_f32_e32 v70, v87, v70
	v_mul_f32_e32 v71, v87, v71
	v_exp_f32_e32 v70, v70
	v_exp_f32_e32 v71, v71
	v_lshlrev_b32_e32 v72, 16, v115
	v_and_b32_e32 v73, 0xffff0000, v115
	v_pk_mul_f32 v[70:71], v[70:71], v[72:73]
	s_nop 0
	v_cvt_pk_bf16_f32 v115, v70, v71
	s_waitcnt vmcnt(17)
	v_mfma_f32_32x32x16_bf16 v[54:69], v[112:115], v[120:123], v[54:69]
	s_waitcnt vmcnt(16)
	v_mfma_f32_32x32x16_bf16 v[38:53], v[112:115], v[124:127], v[38:53]
	s_waitcnt vmcnt(15)
	v_mfma_f32_32x32x16_bf16 v[22:37], v[112:115], v[128:131], v[22:37]
	s_waitcnt vmcnt(14)
	v_mfma_f32_32x32x16_bf16 v[6:21], v[112:115], v[132:135], v[6:21]
	v_add_u32_e32 v70, 0xc0, v89
	v_add_u32_e32 v72, 0x2f, v88
	v_add_u32_e32 v71, 0xc1, v89
	v_cndmask_b32_e32 v70, v70, v72, vcc
	v_add_u32_e32 v72, 0x2e, v88
	v_cndmask_b32_e32 v71, v71, v72, vcc
	v_cvt_f32_u32_e32 v70, v70
	v_cvt_f32_u32_e32 v71, v71
	v_mul_f32_e32 v70, v87, v70
	v_mul_f32_e32 v71, v87, v71
	v_exp_f32_e32 v70, v70
	v_exp_f32_e32 v71, v71
	v_lshlrev_b32_e32 v72, 16, v116
	v_and_b32_e32 v73, 0xffff0000, v116
	v_pk_mul_f32 v[70:71], v[70:71], v[72:73]
	s_nop 0
	v_cvt_pk_bf16_f32 v116, v70, v71
	v_add_u32_e32 v70, 0xc2, v89
	v_add_u32_e32 v72, 0x2d, v88
	v_add_u32_e32 v71, 0xc3, v89
	v_cndmask_b32_e32 v70, v70, v72, vcc
	v_add_u32_e32 v72, 0x2c, v88
	v_cndmask_b32_e32 v71, v71, v72, vcc
	v_cvt_f32_u32_e32 v70, v70
	v_cvt_f32_u32_e32 v71, v71
	v_mul_f32_e32 v70, v87, v70
	v_mul_f32_e32 v71, v87, v71
	v_exp_f32_e32 v70, v70
	v_exp_f32_e32 v71, v71
	v_lshlrev_b32_e32 v72, 16, v117
	v_and_b32_e32 v73, 0xffff0000, v117
	v_pk_mul_f32 v[70:71], v[70:71], v[72:73]
	s_nop 0
	v_cvt_pk_bf16_f32 v117, v70, v71
	v_add_u32_e32 v70, 0xc4, v89
	v_add_u32_e32 v72, 0x2b, v88
	v_add_u32_e32 v71, 0xc5, v89
	v_cndmask_b32_e32 v70, v70, v72, vcc
	v_add_u32_e32 v72, 0x2a, v88
	v_cndmask_b32_e32 v71, v71, v72, vcc
	v_cvt_f32_u32_e32 v70, v70
	v_cvt_f32_u32_e32 v71, v71
	v_mul_f32_e32 v70, v87, v70
	v_mul_f32_e32 v71, v87, v71
	v_exp_f32_e32 v70, v70
	v_exp_f32_e32 v71, v71
	v_lshlrev_b32_e32 v72, 16, v118
	v_and_b32_e32 v73, 0xffff0000, v118
	v_pk_mul_f32 v[70:71], v[70:71], v[72:73]
	s_nop 0
	v_cvt_pk_bf16_f32 v118, v70, v71
	v_add_u32_e32 v70, 0xc6, v89
	v_add_u32_e32 v72, 0x29, v88
	v_add_u32_e32 v71, 0xc7, v89
	v_cndmask_b32_e32 v70, v70, v72, vcc
	v_add_u32_e32 v72, 0x28, v88
	v_cndmask_b32_e32 v71, v71, v72, vcc
	v_cvt_f32_u32_e32 v70, v70
	v_cvt_f32_u32_e32 v71, v71
	v_mul_f32_e32 v70, v87, v70
	v_mul_f32_e32 v71, v87, v71
	v_exp_f32_e32 v70, v70
	v_exp_f32_e32 v71, v71
	v_lshlrev_b32_e32 v72, 16, v119
	v_and_b32_e32 v73, 0xffff0000, v119
	v_pk_mul_f32 v[70:71], v[70:71], v[72:73]
	s_nop 0
	v_cvt_pk_bf16_f32 v119, v70, v71
	s_waitcnt vmcnt(13)
	v_mfma_f32_32x32x16_bf16 v[54:69], v[116:119], v[136:139], v[54:69]
	s_waitcnt vmcnt(11)
	v_mfma_f32_32x32x16_bf16 v[22:37], v[116:119], v[144:147], v[22:37]
	v_mfma_f32_32x32x16_bf16 v[38:53], v[116:119], v[140:143], v[38:53]
	s_waitcnt vmcnt(10)
	v_mfma_f32_32x32x16_bf16 v[6:21], v[116:119], v[148:151], v[6:21]
	v_add_u32_e32 v70, 0xd0, v89
	v_add_u32_e32 v72, 0x1f, v88
	v_add_u32_e32 v71, 0xd1, v89
	v_cndmask_b32_e32 v70, v70, v72, vcc
	v_add_u32_e32 v72, 0x1e, v88
	v_cndmask_b32_e32 v71, v71, v72, vcc
	v_cvt_f32_u32_e32 v70, v70
	v_cvt_f32_u32_e32 v71, v71
	v_mul_f32_e32 v70, v87, v70
	v_mul_f32_e32 v71, v87, v71
	v_exp_f32_e32 v70, v70
	v_exp_f32_e32 v71, v71
	s_waitcnt vmcnt(9)
	v_lshlrev_b32_e32 v72, 16, v152
	v_and_b32_e32 v73, 0xffff0000, v152
	v_pk_mul_f32 v[70:71], v[70:71], v[72:73]
	s_nop 0
	v_cvt_pk_bf16_f32 v152, v70, v71
	v_add_u32_e32 v70, 0xd2, v89
	v_add_u32_e32 v72, 0x1d, v88
	v_add_u32_e32 v71, 0xd3, v89
	v_cndmask_b32_e32 v70, v70, v72, vcc
	v_add_u32_e32 v72, 0x1c, v88
	v_cndmask_b32_e32 v71, v71, v72, vcc
	v_cvt_f32_u32_e32 v70, v70
	v_cvt_f32_u32_e32 v71, v71
	v_mul_f32_e32 v70, v87, v70
	v_mul_f32_e32 v71, v87, v71
	v_exp_f32_e32 v70, v70
	v_exp_f32_e32 v71, v71
	v_lshlrev_b32_e32 v72, 16, v153
	v_and_b32_e32 v73, 0xffff0000, v153
	v_pk_mul_f32 v[70:71], v[70:71], v[72:73]
	s_nop 0
	v_cvt_pk_bf16_f32 v153, v70, v71
	v_add_u32_e32 v70, 0xd4, v89
	v_add_u32_e32 v72, 0x1b, v88
	v_add_u32_e32 v71, 0xd5, v89
	v_cndmask_b32_e32 v70, v70, v72, vcc
	v_add_u32_e32 v72, 0x1a, v88
	v_cndmask_b32_e32 v71, v71, v72, vcc
	v_cvt_f32_u32_e32 v70, v70
	v_cvt_f32_u32_e32 v71, v71
	v_mul_f32_e32 v70, v87, v70
	v_mul_f32_e32 v71, v87, v71
	v_exp_f32_e32 v70, v70
	v_exp_f32_e32 v71, v71
	v_lshlrev_b32_e32 v72, 16, v154
	v_and_b32_e32 v73, 0xffff0000, v154
	v_pk_mul_f32 v[70:71], v[70:71], v[72:73]
	s_nop 0
	v_cvt_pk_bf16_f32 v154, v70, v71
	v_add_u32_e32 v70, 0xd6, v89
	v_add_u32_e32 v72, 0x19, v88
	v_add_u32_e32 v71, 0xd7, v89
	v_cndmask_b32_e32 v70, v70, v72, vcc
	v_add_u32_e32 v72, 0x18, v88
	v_cndmask_b32_e32 v71, v71, v72, vcc
	v_cvt_f32_u32_e32 v70, v70
	v_cvt_f32_u32_e32 v71, v71
	v_mul_f32_e32 v70, v87, v70
	v_mul_f32_e32 v71, v87, v71
	v_exp_f32_e32 v70, v70
	v_exp_f32_e32 v71, v71
	v_lshlrev_b32_e32 v72, 16, v155
	v_and_b32_e32 v73, 0xffff0000, v155
	v_pk_mul_f32 v[70:71], v[70:71], v[72:73]
	s_nop 0
	v_cvt_pk_bf16_f32 v155, v70, v71
	s_waitcnt vmcnt(7)
	v_mfma_f32_32x32x16_bf16 v[54:69], v[152:155], v[160:163], v[54:69]
	s_waitcnt vmcnt(6)
	v_mfma_f32_32x32x16_bf16 v[38:53], v[152:155], v[168:171], v[38:53]
	s_waitcnt vmcnt(5)
	v_mfma_f32_32x32x16_bf16 v[22:37], v[152:155], v[172:175], v[22:37]
	s_waitcnt vmcnt(4)
	v_mfma_f32_32x32x16_bf16 v[6:21], v[152:155], v[176:179], v[6:21]
	v_add_u32_e32 v70, 0xe0, v89
	v_add_u32_e32 v72, 0xf, v88
	v_add_u32_e32 v71, 0xe1, v89
	v_cndmask_b32_e32 v70, v70, v72, vcc
	v_add_u32_e32 v72, 0xe, v88
	v_cndmask_b32_e32 v71, v71, v72, vcc
	v_cvt_f32_u32_e32 v70, v70
	v_cvt_f32_u32_e32 v71, v71
	v_mul_f32_e32 v70, v87, v70
	v_mul_f32_e32 v71, v87, v71
	v_exp_f32_e32 v70, v70
	v_exp_f32_e32 v71, v71
	v_lshlrev_b32_e32 v72, 16, v156
	v_and_b32_e32 v73, 0xffff0000, v156
	v_pk_mul_f32 v[70:71], v[70:71], v[72:73]
	s_nop 0
	v_cvt_pk_bf16_f32 v156, v70, v71
	v_add_u32_e32 v70, 0xe2, v89
	v_add_u32_e32 v72, 0xd, v88
	v_add_u32_e32 v71, 0xe3, v89
	v_cndmask_b32_e32 v70, v70, v72, vcc
	v_add_u32_e32 v72, 0xc, v88
	v_cndmask_b32_e32 v71, v71, v72, vcc
	v_cvt_f32_u32_e32 v70, v70
	v_cvt_f32_u32_e32 v71, v71
	v_mul_f32_e32 v70, v87, v70
	v_mul_f32_e32 v71, v87, v71
	v_exp_f32_e32 v70, v70
	v_exp_f32_e32 v71, v71
	v_lshlrev_b32_e32 v72, 16, v157
	v_and_b32_e32 v73, 0xffff0000, v157
	v_pk_mul_f32 v[70:71], v[70:71], v[72:73]
	s_nop 0
	v_cvt_pk_bf16_f32 v157, v70, v71
	v_add_u32_e32 v70, 0xe4, v89
	v_add_u32_e32 v72, 0xb, v88
	v_add_u32_e32 v71, 0xe5, v89
	v_cndmask_b32_e32 v70, v70, v72, vcc
	v_add_u32_e32 v72, 0xa, v88
	v_cndmask_b32_e32 v71, v71, v72, vcc
	v_cvt_f32_u32_e32 v70, v70
	v_cvt_f32_u32_e32 v71, v71
	v_mul_f32_e32 v70, v87, v70
	v_mul_f32_e32 v71, v87, v71
	v_exp_f32_e32 v70, v70
	v_exp_f32_e32 v71, v71
	v_lshlrev_b32_e32 v72, 16, v158
	v_and_b32_e32 v73, 0xffff0000, v158
	v_pk_mul_f32 v[70:71], v[70:71], v[72:73]
	s_nop 0
	v_cvt_pk_bf16_f32 v158, v70, v71
	v_add_u32_e32 v70, 0xe6, v89
	v_add_u32_e32 v72, 0x9, v88
	v_add_u32_e32 v71, 0xe7, v89
	v_cndmask_b32_e32 v70, v70, v72, vcc
	v_add_u32_e32 v72, 0x8, v88
	v_cndmask_b32_e32 v71, v71, v72, vcc
	v_cvt_f32_u32_e32 v70, v70
	v_cvt_f32_u32_e32 v71, v71
	v_mul_f32_e32 v70, v87, v70
	v_mul_f32_e32 v71, v87, v71
	v_exp_f32_e32 v70, v70
	v_exp_f32_e32 v71, v71
	v_lshlrev_b32_e32 v72, 16, v159
	v_and_b32_e32 v73, 0xffff0000, v159
	v_pk_mul_f32 v[70:71], v[70:71], v[72:73]
	s_nop 0
	v_cvt_pk_bf16_f32 v159, v70, v71
	s_waitcnt vmcnt(3)
	v_mfma_f32_32x32x16_bf16 v[54:69], v[156:159], v[180:183], v[54:69]
	s_waitcnt vmcnt(1)
	v_mfma_f32_32x32x16_bf16 v[22:37], v[156:159], v[188:191], v[22:37]
	v_mfma_f32_32x32x16_bf16 v[38:53], v[156:159], v[184:187], v[38:53]
	s_waitcnt vmcnt(0)
	v_mfma_f32_32x32x16_bf16 v[6:21], v[156:159], v[192:195], v[6:21]
	v_add_u32_e32 v89, 0x100, v89
	s_movk_i32 s8, 0xff00
	s_lshl_b32 s0, s7, 18
	s_lshl_b32 s1, s6, 16
	s_or_b32 s0, s0, s1
	s_lshl_b32 s1, s2, 14
	s_or_b32 s46, s0, s1
	s_lshl_b64 s[0:1], s[46:47], 2
	v_readlane_b32 s2, v250, 34
	s_add_u32 s0, s2, s0
	v_readlane_b32 s2, v250, 35
	v_lshl_or_b32 v2, v84, 2, v86
	s_addc_u32 s1, s2, s1
	v_lshlrev_b32_e32 v4, 2, v85
	v_ashrrev_i32_e32 v3, 31, v2
	v_or_b32_e32 v72, 1, v2
	v_lshl_add_u64 v[0:1], s[0:1], 0, v[4:5]
	v_lshlrev_b64 v[70:71], 9, v[2:3]
	v_ashrrev_i32_e32 v73, 31, v72
	v_lshl_add_u64 v[70:71], v[0:1], 0, v[70:71]
	v_lshlrev_b64 v[72:73], 9, v[72:73]
	global_store_dword v[70:71], v54, off
	v_lshl_add_u64 v[72:73], v[0:1], 0, v[72:73]
	v_or_b32_e32 v54, 2, v2
	global_store_dword v[72:73], v55, off
	v_ashrrev_i32_e32 v55, 31, v54
	v_or_b32_e32 v74, 3, v2
	v_lshlrev_b64 v[54:55], 9, v[54:55]
	v_ashrrev_i32_e32 v75, 31, v74
	v_lshl_add_u64 v[54:55], v[0:1], 0, v[54:55]
	v_lshlrev_b64 v[74:75], 9, v[74:75]
	global_store_dword v[54:55], v56, off
	v_lshl_add_u64 v[74:75], v[0:1], 0, v[74:75]
	v_or_b32_e32 v56, 8, v2
	global_store_dword v[74:75], v57, off
	v_ashrrev_i32_e32 v57, 31, v56
	v_or_b32_e32 v76, 9, v2
	v_lshlrev_b64 v[56:57], 9, v[56:57]
	v_ashrrev_i32_e32 v77, 31, v76
	v_lshl_add_u64 v[56:57], v[0:1], 0, v[56:57]
	v_lshlrev_b64 v[76:77], 9, v[76:77]
	global_store_dword v[56:57], v58, off
	v_lshl_add_u64 v[76:77], v[0:1], 0, v[76:77]
	v_or_b32_e32 v58, 10, v2
	global_store_dword v[76:77], v59, off
	v_ashrrev_i32_e32 v59, 31, v58
	v_or_b32_e32 v78, 11, v2
	v_lshlrev_b64 v[58:59], 9, v[58:59]
	v_ashrrev_i32_e32 v79, 31, v78
	v_lshl_add_u64 v[58:59], v[0:1], 0, v[58:59]
	v_lshlrev_b64 v[78:79], 9, v[78:79]
	global_store_dword v[58:59], v60, off
	v_lshl_add_u64 v[78:79], v[0:1], 0, v[78:79]
	v_or_b32_e32 v60, 16, v2
	global_store_dword v[78:79], v61, off
	v_ashrrev_i32_e32 v61, 31, v60
	v_or_b32_e32 v80, 17, v2
	v_lshlrev_b64 v[60:61], 9, v[60:61]
	v_ashrrev_i32_e32 v81, 31, v80
	v_lshl_add_u64 v[60:61], v[0:1], 0, v[60:61]
	v_lshlrev_b64 v[80:81], 9, v[80:81]
	global_store_dword v[60:61], v62, off
	v_lshl_add_u64 v[80:81], v[0:1], 0, v[80:81]
	v_or_b32_e32 v62, 18, v2
	global_store_dword v[80:81], v63, off
	v_ashrrev_i32_e32 v63, 31, v62
	v_or_b32_e32 v82, 19, v2
	v_lshlrev_b64 v[62:63], 9, v[62:63]
	v_ashrrev_i32_e32 v83, 31, v82
	v_lshl_add_u64 v[62:63], v[0:1], 0, v[62:63]
	v_lshlrev_b64 v[82:83], 9, v[82:83]
	global_store_dword v[62:63], v64, off
	v_lshl_add_u64 v[82:83], v[0:1], 0, v[82:83]
	v_or_b32_e32 v64, 24, v2
	global_store_dword v[82:83], v65, off
	v_ashrrev_i32_e32 v65, 31, v64
	v_or_b32_e32 v84, 25, v2
	v_lshlrev_b64 v[64:65], 9, v[64:65]
	v_ashrrev_i32_e32 v85, 31, v84
	v_lshl_add_u64 v[64:65], v[0:1], 0, v[64:65]
	v_lshlrev_b64 v[84:85], 9, v[84:85]
	global_store_dword v[64:65], v66, off
	v_lshl_add_u64 v[84:85], v[0:1], 0, v[84:85]
	v_or_b32_e32 v66, 26, v2
	v_or_b32_e32 v2, 27, v2
	global_store_dword v[84:85], v67, off
	v_ashrrev_i32_e32 v67, 31, v66
	v_ashrrev_i32_e32 v3, 31, v2
	v_lshlrev_b64 v[66:67], 9, v[66:67]
	v_lshlrev_b64 v[2:3], 9, v[2:3]
	v_lshl_add_u64 v[66:67], v[0:1], 0, v[66:67]
	v_lshl_add_u64 v[0:1], v[0:1], 0, v[2:3]
	global_store_dword v[66:67], v68, off
	global_store_dword v[0:1], v69, off
	global_store_dword v[70:71], v38, off offset:128
	global_store_dword v[72:73], v39, off offset:128
	global_store_dword v[54:55], v40, off offset:128
	global_store_dword v[74:75], v41, off offset:128
	global_store_dword v[56:57], v42, off offset:128
	global_store_dword v[76:77], v43, off offset:128
	global_store_dword v[58:59], v44, off offset:128
	global_store_dword v[78:79], v45, off offset:128
	global_store_dword v[60:61], v46, off offset:128
	global_store_dword v[80:81], v47, off offset:128
	global_store_dword v[62:63], v48, off offset:128
	global_store_dword v[82:83], v49, off offset:128
	global_store_dword v[64:65], v50, off offset:128
	global_store_dword v[84:85], v51, off offset:128
	global_store_dword v[66:67], v52, off offset:128
	global_store_dword v[0:1], v53, off offset:128
	global_store_dword v[70:71], v22, off offset:256
	global_store_dword v[72:73], v23, off offset:256
	global_store_dword v[54:55], v24, off offset:256
	global_store_dword v[74:75], v25, off offset:256
	global_store_dword v[56:57], v26, off offset:256
	global_store_dword v[76:77], v27, off offset:256
	global_store_dword v[58:59], v28, off offset:256
	global_store_dword v[78:79], v29, off offset:256
	global_store_dword v[60:61], v30, off offset:256
	global_store_dword v[80:81], v31, off offset:256
	global_store_dword v[62:63], v32, off offset:256
	global_store_dword v[82:83], v33, off offset:256
	global_store_dword v[64:65], v34, off offset:256
	global_store_dword v[84:85], v35, off offset:256
	global_store_dword v[66:67], v36, off offset:256
	global_store_dword v[0:1], v37, off offset:256
	global_store_dword v[70:71], v6, off offset:384
	global_store_dword v[72:73], v7, off offset:384
	global_store_dword v[54:55], v8, off offset:384
	global_store_dword v[74:75], v9, off offset:384
	global_store_dword v[56:57], v10, off offset:384
	global_store_dword v[76:77], v11, off offset:384
	global_store_dword v[58:59], v12, off offset:384
	global_store_dword v[78:79], v13, off offset:384
	global_store_dword v[60:61], v14, off offset:384
	global_store_dword v[80:81], v15, off offset:384
	global_store_dword v[62:63], v16, off offset:384
	global_store_dword v[82:83], v17, off offset:384
	global_store_dword v[64:65], v18, off offset:384
	global_store_dword v[84:85], v19, off offset:384
	global_store_dword v[66:67], v20, off offset:384
	global_store_dword v[0:1], v21, off offset:384
	s_mov_b64 s[0:1], 0

.LBB0_1745:
	s_setprio 1
	ds_read_b128 v[148:151], v144
	ds_read_b128 v[152:155], v145 offset:36864
	ds_read_b128 v[156:159], v145 offset:41472
	s_waitcnt lgkmcnt(1)
	v_mfma_f32_32x32x16_bf16 v[48:63], v[148:151], v[152:155], v[48:63]
	global_load_dwordx4 v[96:99], v160, s[98:99] offset:256
	global_load_dwordx4 v[100:103], v164, s[98:99] offset:256
	s_waitcnt vmcnt(9)
	ds_write_b128 v146, v[64:67] offset:18432
	s_waitcnt lgkmcnt(1)
	v_mfma_f32_32x32x16_bf16 v[32:47], v[148:151], v[156:159], v[32:47]
	global_load_dwordx4 v[104:107], v166, s[98:99] offset:256
	global_load_dwordx4 v[108:111], v168, s[98:99] offset:256
	ds_read_b128 v[148:151], v144 offset:4608
	s_waitcnt lgkmcnt(0)
	v_mfma_f32_32x32x16_bf16 v[16:31], v[148:151], v[152:155], v[16:31]
	global_load_dwordx4 v[112:115], v162, s[98:99]
	global_load_dwordx4 v[116:119], v130, s[98:99]
	s_waitcnt vmcnt(12)
	ds_write_b128 v146, v[68:71] offset:23040
	v_mfma_f32_32x32x16_bf16 v[0:15], v[148:151], v[156:159], v[0:15]
	global_load_dwordx4 v[120:123], v170, s[98:99]
	global_load_dwordx4 v[124:127], v172, s[98:99] offset:-128
	ds_read_b128 v[148:151], v144 offset:32
	ds_read_b128 v[152:155], v145 offset:36896
	ds_read_b128 v[156:159], v145 offset:41504
	s_waitcnt lgkmcnt(1)
	v_mfma_f32_32x32x16_bf16 v[48:63], v[148:151], v[152:155], v[48:63]
	s_waitcnt vmcnt(13)
	ds_write_b128 v146, v[72:75] offset:27648
	s_waitcnt lgkmcnt(1)
	v_mfma_f32_32x32x16_bf16 v[32:47], v[148:151], v[156:159], v[32:47]
	ds_read_b128 v[148:151], v144 offset:4640
	s_waitcnt lgkmcnt(0)
	v_mfma_f32_32x32x16_bf16 v[16:31], v[148:151], v[152:155], v[16:31]
	s_waitcnt vmcnt(12)
	ds_write_b128 v146, v[76:79] offset:32256
	v_mfma_f32_32x32x16_bf16 v[0:15], v[148:151], v[156:159], v[0:15]
	ds_read_b128 v[148:151], v144 offset:64
	ds_read_b128 v[152:155], v145 offset:36928
	ds_read_b128 v[156:159], v145 offset:41536
	s_waitcnt lgkmcnt(1)
	v_mfma_f32_32x32x16_bf16 v[48:63], v[148:151], v[152:155], v[48:63]
	s_waitcnt vmcnt(11)
	ds_write_b128 v146, v[80:83] offset:55296
	s_waitcnt lgkmcnt(1)
	v_mfma_f32_32x32x16_bf16 v[32:47], v[148:151], v[156:159], v[32:47]
	ds_read_b128 v[148:151], v144 offset:4672
	s_waitcnt lgkmcnt(0)
	v_mfma_f32_32x32x16_bf16 v[16:31], v[148:151], v[152:155], v[16:31]
	s_waitcnt vmcnt(10)
	ds_write_b128 v146, v[84:87] offset:59904
	v_mfma_f32_32x32x16_bf16 v[0:15], v[148:151], v[156:159], v[0:15]
	ds_read_b128 v[148:151], v144 offset:96
	ds_read_b128 v[152:155], v145 offset:36960
	ds_read_b128 v[156:159], v145 offset:41568
	s_waitcnt lgkmcnt(1)
	v_mfma_f32_32x32x16_bf16 v[48:63], v[148:151], v[152:155], v[48:63]
	s_waitcnt vmcnt(9)
	ds_write_b128 v146, v[88:91] offset:64512
	s_waitcnt lgkmcnt(1)
	v_mfma_f32_32x32x16_bf16 v[32:47], v[148:151], v[156:159], v[32:47]
	ds_read_b128 v[148:151], v144 offset:4704
	s_waitcnt lgkmcnt(0)
	v_mfma_f32_32x32x16_bf16 v[16:31], v[148:151], v[152:155], v[16:31]
	s_waitcnt vmcnt(8)
	ds_write_b128 v147, v[92:95] offset:13824
	v_mfma_f32_32x32x16_bf16 v[0:15], v[148:151], v[156:159], v[0:15]
	s_setprio 0
	s_waitcnt lgkmcnt(0)
	s_barrier
	s_setprio 1
	ds_read_b128 v[148:151], v144 offset:18432
	ds_read_b128 v[152:155], v145 offset:55296
	ds_read_b128 v[156:159], v145 offset:59904
	s_waitcnt lgkmcnt(1)
	v_mfma_f32_32x32x16_bf16 v[48:63], v[148:151], v[152:155], v[48:63]
	global_load_dwordx4 v[64:67], v160, s[98:99] offset:384
	global_load_dwordx4 v[68:71], v164, s[98:99] offset:384
	s_waitcnt vmcnt(9)
	ds_write_b128 v146, v[96:99]
	s_waitcnt lgkmcnt(1)
	v_mfma_f32_32x32x16_bf16 v[32:47], v[148:151], v[156:159], v[32:47]
	global_load_dwordx4 v[72:75], v166, s[98:99] offset:384
	global_load_dwordx4 v[76:79], v168, s[98:99] offset:384
	ds_read_b128 v[148:151], v144 offset:23040
	s_waitcnt lgkmcnt(0)
	v_mfma_f32_32x32x16_bf16 v[16:31], v[148:151], v[152:155], v[16:31]
	global_load_dwordx4 v[80:83], v162, s[98:99] offset:128
	global_load_dwordx4 v[84:87], v131, s[98:99]
	s_waitcnt vmcnt(12)
	ds_write_b128 v146, v[100:103] offset:4608
	v_mfma_f32_32x32x16_bf16 v[0:15], v[148:151], v[156:159], v[0:15]
	global_load_dwordx4 v[88:91], v170, s[98:99] offset:128
	global_load_dwordx4 v[92:95], v172, s[98:99]
	ds_read_b128 v[148:151], v144 offset:18464
	ds_read_b128 v[152:155], v145 offset:55328
	ds_read_b128 v[156:159], v145 offset:59936
	s_waitcnt lgkmcnt(1)
	v_mfma_f32_32x32x16_bf16 v[48:63], v[148:151], v[152:155], v[48:63]
	s_add_u32 s98, s98, 0x100
	s_addc_u32 s99, s99, 0
	s_add_i32 s0, s0, 2
	s_cmp_lt_u32 s0, 3
	s_waitcnt vmcnt(13)
	ds_write_b128 v146, v[104:107] offset:9216
	s_waitcnt lgkmcnt(1)
	v_mfma_f32_32x32x16_bf16 v[32:47], v[148:151], v[156:159], v[32:47]
	ds_read_b128 v[148:151], v144 offset:23072
	s_waitcnt lgkmcnt(0)
	v_mfma_f32_32x32x16_bf16 v[16:31], v[148:151], v[152:155], v[16:31]
	s_waitcnt vmcnt(12)
	ds_write_b128 v146, v[108:111] offset:13824
	v_mfma_f32_32x32x16_bf16 v[0:15], v[148:151], v[156:159], v[0:15]
	ds_read_b128 v[148:151], v144 offset:18496
	ds_read_b128 v[152:155], v145 offset:55360
	ds_read_b128 v[156:159], v145 offset:59968
	s_waitcnt lgkmcnt(1)
	v_mfma_f32_32x32x16_bf16 v[48:63], v[148:151], v[152:155], v[48:63]
	s_waitcnt vmcnt(11)
	ds_write_b128 v146, v[112:115] offset:36864
	s_waitcnt lgkmcnt(1)
	v_mfma_f32_32x32x16_bf16 v[32:47], v[148:151], v[156:159], v[32:47]
	ds_read_b128 v[148:151], v144 offset:23104
	s_waitcnt lgkmcnt(0)
	v_mfma_f32_32x32x16_bf16 v[16:31], v[148:151], v[152:155], v[16:31]
	s_waitcnt vmcnt(10)
	ds_write_b128 v146, v[116:119] offset:41472
	v_mfma_f32_32x32x16_bf16 v[0:15], v[148:151], v[156:159], v[0:15]
	ds_read_b128 v[148:151], v144 offset:18528
	ds_read_b128 v[152:155], v145 offset:55392
	ds_read_b128 v[156:159], v145 offset:60000
	s_waitcnt lgkmcnt(1)
	v_mfma_f32_32x32x16_bf16 v[48:63], v[148:151], v[152:155], v[48:63]
	s_waitcnt vmcnt(9)
	ds_write_b128 v146, v[120:123] offset:46080
	s_waitcnt lgkmcnt(1)
	v_mfma_f32_32x32x16_bf16 v[32:47], v[148:151], v[156:159], v[32:47]
	ds_read_b128 v[148:151], v144 offset:23136
	s_waitcnt lgkmcnt(0)
	v_mfma_f32_32x32x16_bf16 v[16:31], v[148:151], v[152:155], v[16:31]
	s_waitcnt vmcnt(8)
	ds_write_b128 v146, v[124:127] offset:50688
	v_mfma_f32_32x32x16_bf16 v[0:15], v[148:151], v[156:159], v[0:15]
	s_setprio 0
	s_waitcnt lgkmcnt(0)
	s_barrier
	s_cbranch_scc1 .LBB0_1745
	s_setprio 1
	ds_read_b128 v[96:99], v144
	ds_read_b128 v[100:103], v145 offset:36864
	ds_read_b128 v[104:107], v145 offset:41472
	s_waitcnt lgkmcnt(1)
	v_mfma_f32_32x32x16_bf16 v[48:63], v[96:99], v[100:103], v[48:63]
	s_waitcnt vmcnt(7)
	ds_write_b128 v146, v[64:67] offset:18432
	s_waitcnt lgkmcnt(1)
	v_mfma_f32_32x32x16_bf16 v[32:47], v[96:99], v[104:107], v[32:47]
	ds_read_b128 v[96:99], v144 offset:4608
	s_waitcnt lgkmcnt(0)
	v_mfma_f32_32x32x16_bf16 v[16:31], v[96:99], v[100:103], v[16:31]
	s_waitcnt vmcnt(6)
	ds_write_b128 v146, v[68:71] offset:23040
	v_mfma_f32_32x32x16_bf16 v[0:15], v[96:99], v[104:107], v[0:15]
	ds_read_b128 v[96:99], v144 offset:32
	ds_read_b128 v[100:103], v145 offset:36896
	ds_read_b128 v[104:107], v145 offset:41504
	s_waitcnt lgkmcnt(1)
	v_mfma_f32_32x32x16_bf16 v[48:63], v[96:99], v[100:103], v[48:63]
	s_waitcnt vmcnt(5)
	ds_write_b128 v146, v[72:75] offset:27648
	s_waitcnt lgkmcnt(1)
	v_mfma_f32_32x32x16_bf16 v[32:47], v[96:99], v[104:107], v[32:47]
	ds_read_b128 v[96:99], v144 offset:4640
	s_waitcnt lgkmcnt(0)
	v_mfma_f32_32x32x16_bf16 v[16:31], v[96:99], v[100:103], v[16:31]
	s_waitcnt vmcnt(4)
	ds_write_b128 v146, v[76:79] offset:32256
	v_mfma_f32_32x32x16_bf16 v[0:15], v[96:99], v[104:107], v[0:15]
	ds_read_b128 v[96:99], v144 offset:64
	ds_read_b128 v[100:103], v145 offset:36928
	ds_read_b128 v[104:107], v145 offset:41536
	s_waitcnt lgkmcnt(1)
	v_mfma_f32_32x32x16_bf16 v[48:63], v[96:99], v[100:103], v[48:63]
	s_waitcnt vmcnt(3)
	ds_write_b128 v146, v[80:83] offset:55296
	s_waitcnt lgkmcnt(1)
	v_mfma_f32_32x32x16_bf16 v[32:47], v[96:99], v[104:107], v[32:47]
	ds_read_b128 v[96:99], v144 offset:4672
	s_waitcnt lgkmcnt(0)
	v_mfma_f32_32x32x16_bf16 v[16:31], v[96:99], v[100:103], v[16:31]
	s_waitcnt vmcnt(2)
	ds_write_b128 v146, v[84:87] offset:59904
	v_mfma_f32_32x32x16_bf16 v[0:15], v[96:99], v[104:107], v[0:15]
	ds_read_b128 v[96:99], v144 offset:96
	ds_read_b128 v[100:103], v145 offset:36960
	ds_read_b128 v[104:107], v145 offset:41568
	s_waitcnt lgkmcnt(1)
	v_mfma_f32_32x32x16_bf16 v[48:63], v[96:99], v[100:103], v[48:63]
	s_waitcnt vmcnt(1)
	ds_write_b128 v146, v[88:91] offset:64512
	s_waitcnt lgkmcnt(1)
	v_mfma_f32_32x32x16_bf16 v[32:47], v[96:99], v[104:107], v[32:47]
	ds_read_b128 v[96:99], v144 offset:4704
	s_waitcnt lgkmcnt(0)
	v_mfma_f32_32x32x16_bf16 v[16:31], v[96:99], v[100:103], v[16:31]
	s_waitcnt vmcnt(0)
	ds_write_b128 v147, v[92:95] offset:13824
	v_mfma_f32_32x32x16_bf16 v[0:15], v[96:99], v[104:107], v[0:15]
	s_setprio 0
	s_waitcnt lgkmcnt(0)
	s_barrier
	s_setprio 1
	ds_read_b128 v[64:67], v144 offset:18432
	ds_read_b128 v[68:71], v145 offset:55296
	ds_read_b128 v[72:75], v145 offset:59904
	s_waitcnt lgkmcnt(1)
	v_mfma_f32_32x32x16_bf16 v[48:63], v[64:67], v[68:71], v[48:63]
	s_waitcnt lgkmcnt(0)
	v_mfma_f32_32x32x16_bf16 v[32:47], v[64:67], v[72:75], v[32:47]
	ds_read_b128 v[64:67], v144 offset:23040
	s_waitcnt lgkmcnt(0)
	v_mfma_f32_32x32x16_bf16 v[16:31], v[64:67], v[68:71], v[16:31]
	v_mfma_f32_32x32x16_bf16 v[0:15], v[64:67], v[72:75], v[0:15]
	ds_read_b128 v[64:67], v144 offset:18464
	ds_read_b128 v[68:71], v145 offset:55328
	ds_read_b128 v[72:75], v145 offset:59936
	s_waitcnt lgkmcnt(1)
	v_mfma_f32_32x32x16_bf16 v[48:63], v[64:67], v[68:71], v[48:63]
	s_waitcnt lgkmcnt(0)
	v_mfma_f32_32x32x16_bf16 v[32:47], v[64:67], v[72:75], v[32:47]
	ds_read_b128 v[64:67], v144 offset:23072
	s_waitcnt lgkmcnt(0)
	v_mfma_f32_32x32x16_bf16 v[16:31], v[64:67], v[68:71], v[16:31]
	v_mfma_f32_32x32x16_bf16 v[0:15], v[64:67], v[72:75], v[0:15]
	ds_read_b128 v[64:67], v144 offset:18496
	ds_read_b128 v[68:71], v145 offset:55360
	ds_read_b128 v[72:75], v145 offset:59968
	s_waitcnt lgkmcnt(1)
	v_mfma_f32_32x32x16_bf16 v[48:63], v[64:67], v[68:71], v[48:63]
	s_waitcnt lgkmcnt(0)
	v_mfma_f32_32x32x16_bf16 v[32:47], v[64:67], v[72:75], v[32:47]
	ds_read_b128 v[64:67], v144 offset:23104
	s_waitcnt lgkmcnt(0)
	v_mfma_f32_32x32x16_bf16 v[16:31], v[64:67], v[68:71], v[16:31]
	v_mfma_f32_32x32x16_bf16 v[0:15], v[64:67], v[72:75], v[0:15]
	ds_read_b128 v[64:67], v144 offset:18528
	ds_read_b128 v[68:71], v145 offset:55392
	ds_read_b128 v[72:75], v145 offset:60000
	s_waitcnt lgkmcnt(1)
	v_mfma_f32_32x32x16_bf16 v[48:63], v[64:67], v[68:71], v[48:63]
	s_waitcnt lgkmcnt(0)
	v_mfma_f32_32x32x16_bf16 v[32:47], v[64:67], v[72:75], v[32:47]
	ds_read_b128 v[64:67], v144 offset:23136
	s_waitcnt lgkmcnt(0)
	v_mfma_f32_32x32x16_bf16 v[16:31], v[64:67], v[68:71], v[16:31]
	v_mfma_f32_32x32x16_bf16 v[0:15], v[64:67], v[72:75], v[0:15]
	s_setprio 0
	s_nop 6
	v_cvt_pk_bf16_f32 v32, v32, s0
	s_nop 2
	v_cvt_pk_bf16_f32 v0, v0, s0
	s_barrier
	ds_write_b16 v143, v32 offset:64
	v_cvt_pk_bf16_f32 v32, v49, s0
	ds_write_b16 v143, v0 offset:8768
	v_cvt_pk_bf16_f32 v0, v17, s0
	ds_write_b16 v143, v32 offset:272
	v_cvt_pk_bf16_f32 v32, v33, s0
	ds_write_b16 v143, v0 offset:8976
	v_cvt_pk_bf16_f32 v0, v1, s0
	ds_write_b16 v143, v32 offset:336
	v_cvt_pk_bf16_f32 v32, v50, s0
	ds_write_b16 v143, v0 offset:9040
	v_cvt_pk_bf16_f32 v0, v18, s0
	ds_write_b16 v143, v32 offset:544
	v_cvt_pk_bf16_f32 v32, v34, s0
	ds_write_b16 v143, v0 offset:9248
	v_cvt_pk_bf16_f32 v0, v2, s0
	ds_write_b16 v143, v32 offset:608
	v_cvt_pk_bf16_f32 v32, v51, s0
	ds_write_b16 v143, v0 offset:9312
	v_cvt_pk_bf16_f32 v0, v19, s0
	ds_write_b16 v143, v32 offset:816
	v_cvt_pk_bf16_f32 v32, v35, s0
	ds_write_b16 v143, v0 offset:9520
	v_cvt_pk_bf16_f32 v0, v3, s0
	ds_write_b16 v143, v32 offset:880
	v_cvt_pk_bf16_f32 v32, v52, s0
	ds_write_b16 v143, v0 offset:9584
	v_cvt_pk_bf16_f32 v0, v20, s0
	ds_write_b16 v143, v32 offset:2176
	v_cvt_pk_bf16_f32 v32, v36, s0
	ds_write_b16 v143, v0 offset:10880
	v_cvt_pk_bf16_f32 v0, v4, s0
	ds_write_b16 v143, v32 offset:2240
	v_cvt_pk_bf16_f32 v32, v53, s0
	ds_write_b16 v143, v0 offset:10944
	v_cvt_pk_bf16_f32 v0, v21, s0
	ds_write_b16 v143, v32 offset:2448
	v_cvt_pk_bf16_f32 v32, v37, s0
	ds_write_b16 v143, v0 offset:11152
	v_cvt_pk_bf16_f32 v0, v5, s0
	ds_write_b16 v143, v32 offset:2512
	v_cvt_pk_bf16_f32 v32, v54, s0
	ds_write_b16 v143, v0 offset:11216
	v_cvt_pk_bf16_f32 v0, v22, s0
	ds_write_b16 v143, v32 offset:2720
	v_cvt_pk_bf16_f32 v32, v38, s0
	ds_write_b16 v143, v0 offset:11424
	v_cvt_pk_bf16_f32 v0, v6, s0
	ds_write_b16 v143, v32 offset:2784
	v_cvt_pk_bf16_f32 v32, v55, s0
	ds_write_b16 v143, v0 offset:11488
	v_cvt_pk_bf16_f32 v0, v23, s0
	ds_write_b16 v143, v32 offset:2992
	v_cvt_pk_bf16_f32 v32, v39, s0
	ds_write_b16 v143, v0 offset:11696
	v_cvt_pk_bf16_f32 v0, v7, s0
	ds_write_b16 v143, v32 offset:3056
	v_cvt_pk_bf16_f32 v32, v56, s0
	ds_write_b16 v143, v0 offset:11760
	v_cvt_pk_bf16_f32 v0, v24, s0
	ds_write_b16 v143, v32 offset:4352
	v_cvt_pk_bf16_f32 v32, v40, s0
	ds_write_b16 v143, v0 offset:13056
	v_cvt_pk_bf16_f32 v0, v8, s0
	ds_write_b16 v143, v32 offset:4416
	v_cvt_pk_bf16_f32 v32, v57, s0
	ds_write_b16 v143, v0 offset:13120
	v_cvt_pk_bf16_f32 v0, v25, s0
	ds_write_b16 v143, v32 offset:4624
	v_cvt_pk_bf16_f32 v32, v41, s0
	ds_write_b16 v143, v0 offset:13328
	v_cvt_pk_bf16_f32 v0, v9, s0
	ds_write_b16 v143, v32 offset:4688
	v_cvt_pk_bf16_f32 v32, v58, s0
	ds_write_b16 v143, v0 offset:13392
	v_cvt_pk_bf16_f32 v0, v26, s0
	ds_write_b16 v143, v32 offset:4896
	v_cvt_pk_bf16_f32 v32, v42, s0
	ds_write_b16 v143, v0 offset:13600
	v_cvt_pk_bf16_f32 v0, v10, s0
	ds_write_b16 v143, v32 offset:4960
	v_cvt_pk_bf16_f32 v32, v59, s0
	ds_write_b16 v143, v0 offset:13664
	v_cvt_pk_bf16_f32 v0, v27, s0
	ds_write_b16 v143, v32 offset:5168
	v_cvt_pk_bf16_f32 v32, v43, s0
	ds_write_b16 v143, v0 offset:13872
	v_cvt_pk_bf16_f32 v0, v11, s0
	ds_write_b16 v143, v32 offset:5232
	v_cvt_pk_bf16_f32 v32, v60, s0
	ds_write_b16 v143, v0 offset:13936
	v_cvt_pk_bf16_f32 v0, v28, s0
	ds_write_b16 v143, v32 offset:6528
	v_cvt_pk_bf16_f32 v32, v44, s0
	ds_write_b16 v143, v0 offset:15232
	v_cvt_pk_bf16_f32 v0, v12, s0
	ds_write_b16 v143, v32 offset:6592
	v_cvt_pk_bf16_f32 v32, v61, s0
	ds_write_b16 v143, v0 offset:15296
	v_cvt_pk_bf16_f32 v0, v29, s0
	ds_write_b16 v143, v32 offset:6800
	v_cvt_pk_bf16_f32 v32, v45, s0
	ds_write_b16 v143, v0 offset:15504
	v_cvt_pk_bf16_f32 v0, v13, s0
	ds_write_b16 v143, v32 offset:6864
	v_cvt_pk_bf16_f32 v32, v62, s0
	ds_write_b16 v143, v0 offset:15568
	v_cvt_pk_bf16_f32 v0, v30, s0
	ds_write_b16 v143, v32 offset:7072
	v_cvt_pk_bf16_f32 v32, v46, s0
	ds_write_b16 v143, v0 offset:15776
	v_cvt_pk_bf16_f32 v0, v14, s0
	ds_write_b16 v143, v32 offset:7136
	v_cvt_pk_bf16_f32 v32, v63, s0
	ds_write_b16 v143, v0 offset:15840
	v_cvt_pk_bf16_f32 v0, v31, s0
	v_cvt_pk_bf16_f32 v48, v48, s0
	ds_write_b16 v143, v32 offset:7344
	v_cvt_pk_bf16_f32 v32, v47, s0
	v_cvt_pk_bf16_f32 v16, v16, s0
	ds_write_b16 v143, v0 offset:16048
	v_cvt_pk_bf16_f32 v0, v15, s0
	v_mov_b32_e32 v15, v142
	ds_write_b16 v143, v48
	ds_write_b16 v143, v32 offset:7408
	ds_write_b16 v143, v16 offset:8704
	ds_write_b16 v143, v0 offset:16112
	s_waitcnt lgkmcnt(0)
	s_barrier
	v_mov_b64_e32 v[2:3], s[4:5]
	v_lshlrev_b32_e32 v0, 3, v15
	v_and_b32_e32 v0, 0x78, v0
	v_ashrrev_i32_e32 v1, 4, v15
	v_lshlrev_b32_e32 v128, 1, v0
	v_add_u32_e32 v0, s69, v1
	s_lshl_b32 s16, s26, 10
	v_mad_i64_i32 v[2:3], s[0:1], v0, s66, v[2:3]
	v_lshl_add_u64 v[2:3], s[16:17], 1, v[2:3]
	v_lshl_add_u64 v[2:3], s[22:23], 1, v[2:3]
	v_lshl_add_u64 v[2:3], v[2:3], 0, v[128:129]
	global_load_dwordx4 v[6:9], v[2:3], off
	v_add_co_u32_e32 v80, vcc, 0x18000, v2
	s_nop 1
	v_addc_co_u32_e32 v81, vcc, 0, v3, vcc
	global_load_dwordx4 v[24:27], v[80:81], off
	v_add_co_u32_e32 v80, vcc, 0x30000, v2
	s_nop 1
	v_addc_co_u32_e32 v81, vcc, 0, v3, vcc
	global_load_dwordx4 v[28:31], v[80:81], off
	v_add_co_u32_e32 v80, vcc, 0x48000, v2
	s_nop 1
	v_addc_co_u32_e32 v81, vcc, 0, v3, vcc
	global_load_dwordx4 v[32:35], v[80:81], off
	v_add_co_u32_e32 v80, vcc, 0x60000, v2
	s_nop 1
	v_addc_co_u32_e32 v81, vcc, 0, v3, vcc
	global_load_dwordx4 v[36:39], v[80:81], off
	v_add_co_u32_e32 v80, vcc, 0x78000, v2
	s_nop 1
	v_addc_co_u32_e32 v81, vcc, 0, v3, vcc
	global_load_dwordx4 v[40:43], v[80:81], off
	v_add_co_u32_e32 v80, vcc, 0x90000, v2
	s_nop 1
	v_addc_co_u32_e32 v81, vcc, 0, v3, vcc
	global_load_dwordx4 v[44:47], v[80:81], off
	v_add_co_u32_e32 v80, vcc, 0xa8000, v2
	s_nop 1
	v_addc_co_u32_e32 v81, vcc, 0, v3, vcc
	global_load_dwordx4 v[48:51], v[80:81], off
	v_add_u32_e32 v14, 32, v128
	v_mad_u64_u32 v[2:3], s[0:1], v1, s60, v[14:15]
	ds_read_b128 v[2:5], v2
	v_ashrrev_i32_e32 v1, 31, v0
	v_lshlrev_b64 v[0:1], 11, v[0:1]
	v_lshl_add_u64 v[0:1], s[24:25], 0, v[0:1]
	v_lshl_add_u64 v[16:17], v[0:1], 0, v[128:129]
	v_cndmask_b32_e64 v1, 0, 1, s[50:51]
	v_mov_b32_e32 v0, 0
	v_cmp_ne_u32_e64 s[0:1], 1, v1
	s_andn2_b64 vcc, exec, s[50:51]
	v_mov_b32_e32 v10, 0
	v_mov_b32_e32 v11, 0
	v_mov_b32_e32 v12, 0
	v_mov_b32_e32 v13, 0
	s_cbranch_vccnz .LBB0_1748
	global_load_dwordx4 v[10:13], v[16:17], off
	v_add_co_u32_e32 v80, vcc, 0x8000, v16
	s_nop 1
	v_addc_co_u32_e32 v81, vcc, 0, v17, vcc
	global_load_dwordx4 v[52:55], v[80:81], off
	v_add_co_u32_e32 v80, vcc, 0x10000, v16
	s_nop 1
	v_addc_co_u32_e32 v81, vcc, 0, v17, vcc
	global_load_dwordx4 v[56:59], v[80:81], off
	v_add_co_u32_e32 v80, vcc, 0x18000, v16
	s_nop 1
	v_addc_co_u32_e32 v81, vcc, 0, v17, vcc
	global_load_dwordx4 v[60:63], v[80:81], off
	v_add_co_u32_e32 v80, vcc, 0x20000, v16
	s_nop 1
	v_addc_co_u32_e32 v81, vcc, 0, v17, vcc
	global_load_dwordx4 v[64:67], v[80:81], off
	v_add_co_u32_e32 v80, vcc, 0x28000, v16
	s_nop 1
	v_addc_co_u32_e32 v81, vcc, 0, v17, vcc
	global_load_dwordx4 v[68:71], v[80:81], off
	v_add_co_u32_e32 v80, vcc, 0x30000, v16
	s_nop 1
	v_addc_co_u32_e32 v81, vcc, 0, v17, vcc
	global_load_dwordx4 v[72:75], v[80:81], off
	v_add_co_u32_e32 v80, vcc, 0x38000, v16
	s_nop 1
	v_addc_co_u32_e32 v81, vcc, 0, v17, vcc
	global_load_dwordx4 v[76:79], v[80:81], off

.LBB0_1817:
	s_setprio 1
	ds_read_b128 v[140:143], v103
	ds_read_b128 v[144:147], v104 offset:36864
	ds_read_b128 v[148:151], v103 offset:32
	ds_read_b128 v[152:155], v104 offset:36896
	ds_read_b128 v[156:159], v104 offset:41472
	ds_read_b128 v[160:163], v104 offset:41504
	s_waitcnt lgkmcnt(4)
	v_mfma_f32_32x32x16_bf16 v[48:63], v[140:143], v[144:147], v[48:63]
	global_load_dwordx4 v[108:111], v168, s[98:99] offset:3840
	global_load_dwordx4 v[112:115], v170, s[98:99] offset:3840
	s_waitcnt vmcnt(9)
	ds_write_b128 v105, v[68:71] offset:18432
	s_waitcnt lgkmcnt(2)
	v_mfma_f32_32x32x16_bf16 v[32:47], v[140:143], v[156:159], v[32:47]
	global_load_dwordx4 v[116:119], v172, s[98:99] offset:3840
	global_load_dwordx4 v[120:123], v174, s[98:99] offset:3840
	ds_read_b128 v[140:143], v103 offset:4608
	ds_read_b128 v[164:167], v103 offset:4640
	s_waitcnt lgkmcnt(1)
	v_mfma_f32_32x32x16_bf16 v[16:31], v[140:143], v[144:147], v[16:31]
	global_load_dwordx4 v[124:127], v176, s[98:99] offset:3840
	global_load_dwordx4 v[128:131], v178, s[98:99] offset:3840
	s_waitcnt vmcnt(11)
	ds_write_b128 v105, v[84:87] offset:23040
	v_mfma_f32_32x32x16_bf16 v[0:15], v[140:143], v[156:159], v[0:15]
	global_load_dwordx4 v[132:135], v180, s[98:99] offset:3840
	global_load_dwordx4 v[136:139], v182, s[98:99] offset:3840
	v_mfma_f32_32x32x16_bf16 v[48:63], v[148:151], v[152:155], v[48:63]
	s_waitcnt vmcnt(12)
	ds_write_b128 v105, v[88:91] offset:27648
	v_mfma_f32_32x32x16_bf16 v[32:47], v[148:151], v[160:163], v[32:47]
	s_waitcnt lgkmcnt(2)
	v_mfma_f32_32x32x16_bf16 v[16:31], v[164:167], v[152:155], v[16:31]
	s_waitcnt vmcnt(11)
	ds_write_b128 v105, v[92:95] offset:32256
	ds_read_b128 v[140:143], v103 offset:64
	ds_read_b128 v[144:147], v104 offset:36928
	ds_read_b128 v[148:151], v103 offset:96
	ds_read_b128 v[152:155], v104 offset:36960
	v_mfma_f32_32x32x16_bf16 v[0:15], v[164:167], v[160:163], v[0:15]
	ds_read_b128 v[156:159], v104 offset:41536
	ds_read_b128 v[160:163], v104 offset:41568
	s_waitcnt lgkmcnt(4)
	v_mfma_f32_32x32x16_bf16 v[48:63], v[140:143], v[144:147], v[48:63]
	ds_write_b128 v105, v[64:67] offset:55296
	s_waitcnt lgkmcnt(2)
	v_mfma_f32_32x32x16_bf16 v[32:47], v[140:143], v[156:159], v[32:47]
	ds_read_b128 v[140:143], v103 offset:4672
	ds_read_b128 v[164:167], v103 offset:4704
	s_waitcnt lgkmcnt(1)
	v_mfma_f32_32x32x16_bf16 v[16:31], v[140:143], v[144:147], v[16:31]
	s_waitcnt vmcnt(10)
	ds_write_b128 v105, v[72:75] offset:59904
	v_mfma_f32_32x32x16_bf16 v[0:15], v[140:143], v[156:159], v[0:15]
	v_mfma_f32_32x32x16_bf16 v[48:63], v[148:151], v[152:155], v[48:63]
	s_waitcnt vmcnt(9)
	ds_write_b128 v105, v[76:79] offset:64512
	v_mfma_f32_32x32x16_bf16 v[32:47], v[148:151], v[160:163], v[32:47]
	s_waitcnt lgkmcnt(2)
	v_mfma_f32_32x32x16_bf16 v[16:31], v[164:167], v[152:155], v[16:31]
	s_waitcnt vmcnt(8)
	ds_write_b128 v106, v[80:83] offset:13824
	v_mfma_f32_32x32x16_bf16 v[0:15], v[164:167], v[160:163], v[0:15]
	s_setprio 0
	s_waitcnt lgkmcnt(0)
	s_barrier
	s_setprio 1
	ds_read_b128 v[140:143], v103 offset:18432
	ds_read_b128 v[144:147], v104 offset:55296
	ds_read_b128 v[148:151], v103 offset:18464
	ds_read_b128 v[152:155], v104 offset:55328
	ds_read_b128 v[156:159], v104 offset:59904
	ds_read_b128 v[160:163], v104 offset:59936
	s_waitcnt lgkmcnt(4)
	v_mfma_f32_32x32x16_bf16 v[48:63], v[140:143], v[144:147], v[48:63]
	global_load_dwordx4 v[68:71], v168, s[98:99] offset:3968
	global_load_dwordx4 v[84:87], v170, s[98:99] offset:3968
	s_waitcnt vmcnt(9)
	ds_write_b128 v105, v[108:111]
	s_waitcnt lgkmcnt(2)
	v_mfma_f32_32x32x16_bf16 v[32:47], v[140:143], v[156:159], v[32:47]
	global_load_dwordx4 v[88:91], v172, s[98:99] offset:3968
	global_load_dwordx4 v[92:95], v174, s[98:99] offset:3968
	ds_read_b128 v[140:143], v103 offset:23040
	ds_read_b128 v[164:167], v103 offset:23072
	s_waitcnt lgkmcnt(1)
	v_mfma_f32_32x32x16_bf16 v[16:31], v[140:143], v[144:147], v[16:31]
	global_load_dwordx4 v[64:67], v176, s[98:99] offset:3968
	global_load_dwordx4 v[72:75], v178, s[98:99] offset:3968
	s_waitcnt vmcnt(12)
	ds_write_b128 v105, v[112:115] offset:4608
	v_mfma_f32_32x32x16_bf16 v[0:15], v[140:143], v[156:159], v[0:15]
	global_load_dwordx4 v[76:79], v180, s[98:99] offset:3968
	global_load_dwordx4 v[80:83], v182, s[98:99] offset:3968
	v_mfma_f32_32x32x16_bf16 v[48:63], v[148:151], v[152:155], v[48:63]
	s_add_u32 s98, s98, 0x100
	s_addc_u32 s99, s99, 0
	s_add_i32 s10, s10, 2
	s_cmp_lt_u32 s10, 11
	s_waitcnt vmcnt(13)
	ds_write_b128 v105, v[116:119] offset:9216
	v_mfma_f32_32x32x16_bf16 v[32:47], v[148:151], v[160:163], v[32:47]
	s_waitcnt lgkmcnt(2)
	v_mfma_f32_32x32x16_bf16 v[16:31], v[164:167], v[152:155], v[16:31]
	s_waitcnt vmcnt(12)
	ds_write_b128 v105, v[120:123] offset:13824
	ds_read_b128 v[140:143], v103 offset:18496
	ds_read_b128 v[144:147], v104 offset:55360
	ds_read_b128 v[148:151], v103 offset:18528
	ds_read_b128 v[152:155], v104 offset:55392
	v_mfma_f32_32x32x16_bf16 v[0:15], v[164:167], v[160:163], v[0:15]
	ds_read_b128 v[156:159], v104 offset:59968
	ds_read_b128 v[160:163], v104 offset:60000
	s_waitcnt lgkmcnt(4)
	v_mfma_f32_32x32x16_bf16 v[48:63], v[140:143], v[144:147], v[48:63]
	s_waitcnt vmcnt(11)
	ds_write_b128 v105, v[124:127] offset:36864
	s_waitcnt lgkmcnt(2)
	v_mfma_f32_32x32x16_bf16 v[32:47], v[140:143], v[156:159], v[32:47]
	ds_read_b128 v[140:143], v103 offset:23104
	ds_read_b128 v[164:167], v103 offset:23136
	s_waitcnt lgkmcnt(1)
	v_mfma_f32_32x32x16_bf16 v[16:31], v[140:143], v[144:147], v[16:31]
	s_waitcnt vmcnt(10)
	ds_write_b128 v105, v[128:131] offset:41472
	v_mfma_f32_32x32x16_bf16 v[0:15], v[140:143], v[156:159], v[0:15]
	v_mfma_f32_32x32x16_bf16 v[48:63], v[148:151], v[152:155], v[48:63]
	s_waitcnt vmcnt(9)
	ds_write_b128 v105, v[132:135] offset:46080
	v_mfma_f32_32x32x16_bf16 v[32:47], v[148:151], v[160:163], v[32:47]
	s_waitcnt lgkmcnt(2)
	v_mfma_f32_32x32x16_bf16 v[16:31], v[164:167], v[152:155], v[16:31]
	s_waitcnt vmcnt(8)
	ds_write_b128 v105, v[136:139] offset:50688
	v_mfma_f32_32x32x16_bf16 v[0:15], v[164:167], v[160:163], v[0:15]
	s_setprio 0
	s_waitcnt lgkmcnt(0)
	s_barrier
	s_cbranch_scc1 .LBB0_1817
	s_setprio 1
	ds_read_b128 v[98:101], v103
	ds_read_b128 v[108:111], v104 offset:36864
	ds_read_b128 v[112:115], v103 offset:32
	ds_read_b128 v[116:119], v104 offset:36896
	ds_read_b128 v[120:123], v104 offset:41472
	ds_read_b128 v[124:127], v104 offset:41504
	s_waitcnt lgkmcnt(4)
	v_mfma_f32_32x32x16_bf16 v[48:63], v[98:101], v[108:111], v[48:63]
	s_waitcnt vmcnt(7)
	ds_write_b128 v105, v[68:71] offset:18432
	s_waitcnt lgkmcnt(2)
	v_mfma_f32_32x32x16_bf16 v[32:47], v[98:101], v[120:123], v[32:47]
	ds_read_b128 v[98:101], v103 offset:4608
	ds_read_b128 v[128:131], v103 offset:4640
	s_waitcnt lgkmcnt(1)
	v_mfma_f32_32x32x16_bf16 v[16:31], v[98:101], v[108:111], v[16:31]
	s_waitcnt vmcnt(6)
	ds_write_b128 v105, v[84:87] offset:23040
	v_mfma_f32_32x32x16_bf16 v[0:15], v[98:101], v[120:123], v[0:15]
	v_mfma_f32_32x32x16_bf16 v[48:63], v[112:115], v[116:119], v[48:63]
	s_waitcnt vmcnt(5)
	ds_write_b128 v105, v[88:91] offset:27648
	v_mfma_f32_32x32x16_bf16 v[32:47], v[112:115], v[124:127], v[32:47]
	s_waitcnt lgkmcnt(2)
	v_mfma_f32_32x32x16_bf16 v[16:31], v[128:131], v[116:119], v[16:31]
	s_waitcnt vmcnt(4)
	ds_write_b128 v105, v[92:95] offset:32256
	ds_read_b128 v[98:101], v103 offset:64
	ds_read_b128 v[108:111], v104 offset:36928
	ds_read_b128 v[112:115], v103 offset:96
	ds_read_b128 v[116:119], v104 offset:36960
	v_mfma_f32_32x32x16_bf16 v[0:15], v[128:131], v[124:127], v[0:15]
	ds_read_b128 v[120:123], v104 offset:41536
	ds_read_b128 v[124:127], v104 offset:41568
	s_waitcnt lgkmcnt(4)
	v_mfma_f32_32x32x16_bf16 v[48:63], v[98:101], v[108:111], v[48:63]
	s_waitcnt vmcnt(3)
	ds_write_b128 v105, v[64:67] offset:55296
	s_waitcnt lgkmcnt(2)
	v_mfma_f32_32x32x16_bf16 v[32:47], v[98:101], v[120:123], v[32:47]
	ds_read_b128 v[98:101], v103 offset:4672
	ds_read_b128 v[128:131], v103 offset:4704
	s_waitcnt lgkmcnt(1)
	v_mfma_f32_32x32x16_bf16 v[16:31], v[98:101], v[108:111], v[16:31]
	s_waitcnt vmcnt(2)
	ds_write_b128 v105, v[72:75] offset:59904
	v_mfma_f32_32x32x16_bf16 v[0:15], v[98:101], v[120:123], v[0:15]
	s_waitcnt lgkmcnt(1)
	v_mfma_f32_32x32x16_bf16 v[16:31], v[128:131], v[116:119], v[16:31]
	s_waitcnt vmcnt(1)
	ds_write_b128 v105, v[76:79] offset:64512
	v_mfma_f32_32x32x16_bf16 v[0:15], v[128:131], v[124:127], v[0:15]
	v_mfma_f32_32x32x16_bf16 v[48:63], v[112:115], v[116:119], v[48:63]
	s_waitcnt vmcnt(0)
	ds_write_b128 v106, v[80:83] offset:13824
	v_mfma_f32_32x32x16_bf16 v[32:47], v[112:115], v[124:127], v[32:47]
	s_setprio 0
	s_waitcnt lgkmcnt(0)
	s_barrier
	s_setprio 1
	ds_read_b128 v[64:67], v103 offset:18432
	ds_read_b128 v[68:71], v104 offset:55296
	ds_read_b128 v[72:75], v103 offset:18464
	ds_read_b128 v[76:79], v104 offset:55328
	ds_read_b128 v[80:83], v104 offset:59904
	ds_read_b128 v[84:87], v104 offset:59936
	s_waitcnt lgkmcnt(4)
	v_mfma_f32_32x32x16_bf16 v[48:63], v[64:67], v[68:71], v[48:63]
	s_waitcnt lgkmcnt(1)
	v_mfma_f32_32x32x16_bf16 v[32:47], v[64:67], v[80:83], v[32:47]
	ds_read_b128 v[64:67], v103 offset:23040
	ds_read_b128 v[88:91], v103 offset:23072
	s_waitcnt lgkmcnt(1)
	v_mfma_f32_32x32x16_bf16 v[16:31], v[64:67], v[68:71], v[16:31]
	v_mfma_f32_32x32x16_bf16 v[0:15], v[64:67], v[80:83], v[0:15]
	v_mfma_f32_32x32x16_bf16 v[48:63], v[72:75], v[76:79], v[48:63]
	v_mfma_f32_32x32x16_bf16 v[32:47], v[72:75], v[84:87], v[32:47]
	s_waitcnt lgkmcnt(0)
	v_mfma_f32_32x32x16_bf16 v[16:31], v[88:91], v[76:79], v[16:31]
	ds_read_b128 v[64:67], v103 offset:18496
	ds_read_b128 v[68:71], v104 offset:55360
	ds_read_b128 v[72:75], v103 offset:18528
	ds_read_b128 v[76:79], v104 offset:55392
	v_mfma_f32_32x32x16_bf16 v[0:15], v[88:91], v[84:87], v[0:15]
	ds_read_b128 v[80:83], v104 offset:59968
	ds_read_b128 v[84:87], v104 offset:60000
	s_waitcnt lgkmcnt(4)
	v_mfma_f32_32x32x16_bf16 v[48:63], v[64:67], v[68:71], v[48:63]
	s_waitcnt lgkmcnt(1)
	v_mfma_f32_32x32x16_bf16 v[32:47], v[64:67], v[80:83], v[32:47]
	ds_read_b128 v[64:67], v103 offset:23104
	ds_read_b128 v[88:91], v103 offset:23136
	s_waitcnt lgkmcnt(1)
	v_mfma_f32_32x32x16_bf16 v[16:31], v[64:67], v[68:71], v[16:31]
	v_mfma_f32_32x32x16_bf16 v[0:15], v[64:67], v[80:83], v[0:15]
	s_waitcnt lgkmcnt(0)
	v_mfma_f32_32x32x16_bf16 v[16:31], v[88:91], v[76:79], v[16:31]
	v_mfma_f32_32x32x16_bf16 v[0:15], v[88:91], v[84:87], v[0:15]
	v_mfma_f32_32x32x16_bf16 v[48:63], v[72:75], v[76:79], v[48:63]
	v_mfma_f32_32x32x16_bf16 v[32:47], v[72:75], v[84:87], v[32:47]
	s_setprio 0
	s_addk_i32 s0, 0xf000
	s_lshr_b32 s10, s0, 10
	s_mulk_i32 s10, 0x1800
	s_addk_i32 s10, 0x1800
	s_and_b64 s[22:23], s[8:9], exec
	s_cselect_b32 s10, 0, s10
	v_mov_b32_e32 v68, v234
	s_barrier
	s_lshl_b64 s[22:23], s[10:11], 2
	s_add_u32 s22, s30, s22
	v_and_b32_e32 v69, 0x5f, v68
	v_or_b32_e32 v64, s21, v69
	s_addc_u32 s23, s31, s23
	v_ashrrev_i32_e32 v65, 31, v64
	v_lshl_add_u64 v[64:65], v[64:65], 2, s[22:23]
	v_lshl_add_u64 v[66:67], v[64:65], 0, s[14:15]
	v_add_co_u32_e32 v64, vcc, s54, v64
	v_lshlrev_b32_e32 v69, 2, v69
	s_nop 0
	v_addc_co_u32_e32 v65, vcc, 0, v65, vcc
	global_load_dword v64, v[64:65], off
	s_nop 0
	global_load_dword v65, v[66:67], off offset:128
	v_lshrrev_b32_e32 v67, 3, v68
	v_lshrrev_b32_e32 v66, 1, v68
	v_and_b32_e32 v67, 4, v67
	v_and_or_b32 v66, v66, s45, v67
	v_mul_lo_u32 v66, v66, s55
	v_add3_u32 v66, 32, v69, v66
	v_add_u32_e32 v67, 0x400, v66
	v_add_u32_e32 v69, 0x1000, v66
	v_add_u32_e32 v70, 0x1400, v66
	v_add_u32_e32 v71, 0x2000, v66
	v_add_u32_e32 v72, 0x2400, v66
	v_add_u32_e32 v73, 0x3000, v66
	v_add_u32_e32 v74, 0x3200, v66
	v_add_u32_e32 v75, 0x3400, v66
	v_add_u32_e32 v76, 0x3600, v66
	v_add_u32_e32 v77, 0x4000, v66
	v_readlane_b32 s80, v251, 39
	v_readlane_b32 s81, v251, 40
	s_lshl_b32 s1, s1, 19
	v_readlane_b32 s82, v251, 41
	v_readlane_b32 s83, v251, 42
	s_mov_b64 s[36:37], s[80:81]
	s_add_u32 s10, s36, s1
	s_mov_b32 s1, s11
	s_mov_b64 s[38:39], s[82:83]
	s_addc_u32 s21, s37, 0
	s_lshl_b64 s[0:1], s[0:1], 12
	s_add_u32 s22, s38, s0
	s_addc_u32 s23, s39, s1
	s_and_b64 s[0:1], s[8:9], exec
	s_cselect_b32 s23, s21, s23
	s_cselect_b32 s22, s10, s22
	s_add_i32 s10, s20, s27
	v_readlane_b32 s84, v251, 43
	v_readlane_b32 s85, v251, 44
	v_readlane_b32 s86, v251, 45
	v_readlane_b32 s87, v251, 46
	v_readlane_b32 s88, v251, 47
	v_readlane_b32 s89, v251, 48
	v_readlane_b32 s90, v251, 49
	v_readlane_b32 s91, v251, 50
	v_readlane_b32 s92, v251, 51
	v_readlane_b32 s93, v251, 52
	v_readlane_b32 s94, v251, 53
	v_readlane_b32 s95, v251, 54
	s_waitcnt vmcnt(1)
	v_mul_f32_e32 v48, v48, v64
	s_waitcnt vmcnt(0)
	v_mul_f32_e32 v32, v32, v65
	v_mul_f32_e32 v16, v16, v64
	v_mul_f32_e32 v0, v0, v65
	v_mul_f32_e32 v49, v49, v64
	v_mul_f32_e32 v33, v33, v65
	v_mul_f32_e32 v50, v50, v64
	v_mul_f32_e32 v34, v34, v65
	v_mul_f32_e32 v51, v51, v64
	v_mul_f32_e32 v35, v35, v65
	v_mul_f32_e32 v52, v52, v64
	v_mul_f32_e32 v36, v36, v65
	v_mul_f32_e32 v53, v53, v64
	v_mul_f32_e32 v37, v37, v65
	v_mul_f32_e32 v54, v54, v64
	v_mul_f32_e32 v38, v38, v65
	v_mul_f32_e32 v55, v55, v64
	v_mul_f32_e32 v39, v39, v65
	v_mul_f32_e32 v56, v56, v64
	v_mul_f32_e32 v40, v40, v65
	v_mul_f32_e32 v57, v57, v64
	v_mul_f32_e32 v41, v41, v65
	v_mul_f32_e32 v58, v58, v64
	v_mul_f32_e32 v42, v42, v65
	v_mul_f32_e32 v59, v59, v64
	v_mul_f32_e32 v43, v43, v65
	v_mul_f32_e32 v60, v60, v64
	v_mul_f32_e32 v44, v44, v65
	v_mul_f32_e32 v61, v61, v64
	v_mul_f32_e32 v45, v45, v65
	v_mul_f32_e32 v62, v62, v64
	v_mul_f32_e32 v46, v46, v65
	v_mul_f32_e32 v63, v63, v64
	v_mul_f32_e32 v47, v47, v65
	ds_write2_b32 v66, v48, v32 offset1:32
	ds_write2_b32 v66, v49, v33 offset0:132 offset1:164
	ds_write2_b32 v67, v50, v34 offset0:8 offset1:40
	ds_write2_b32 v67, v51, v35 offset0:140 offset1:172
	ds_write2_b32 v69, v52, v36 offset0:32 offset1:64
	ds_write2_b32 v69, v53, v37 offset0:164 offset1:196
	ds_write2_b32 v70, v54, v38 offset0:40 offset1:72
	ds_write2_b32 v70, v55, v39 offset0:172 offset1:204
	ds_write2_b32 v71, v56, v40 offset0:64 offset1:96
	ds_write2_b32 v71, v57, v41 offset0:196 offset1:228
	ds_write2_b32 v72, v58, v42 offset0:72 offset1:104
	ds_write2_b32 v72, v59, v43 offset0:204 offset1:236
	ds_write2_b32 v73, v60, v44 offset0:96 offset1:128
	ds_write2_b32 v74, v61, v45 offset0:100 offset1:132
	ds_write2_b32 v75, v62, v46 offset0:104 offset1:136
	ds_write2_b32 v76, v63, v47 offset0:108 offset1:140
	ds_write2_b32 v77, v16, v0 offset0:128 offset1:160
	v_mul_f32_e32 v0, v17, v64
	v_mul_f32_e32 v1, v1, v65
	v_add_u32_e32 v16, 0x4400, v66
	ds_write2_b32 v16, v0, v1 offset0:4 offset1:36
	v_mul_f32_e32 v0, v18, v64
	v_mul_f32_e32 v1, v2, v65
	ds_write2_b32 v16, v0, v1 offset0:136 offset1:168
	v_mul_f32_e32 v0, v19, v64
	v_mul_f32_e32 v1, v3, v65
	v_add_u32_e32 v2, 0x4800, v66
	ds_write2_b32 v2, v0, v1 offset0:12 offset1:44
	v_mul_f32_e32 v0, v20, v64
	v_mul_f32_e32 v1, v4, v65
	v_add_u32_e32 v2, 0x5000, v66
	ds_write2_b32 v2, v0, v1 offset0:160 offset1:192
	v_mul_f32_e32 v0, v21, v64
	v_mul_f32_e32 v1, v5, v65
	v_add_u32_e32 v2, 0x5400, v66
	ds_write2_b32 v2, v0, v1 offset0:36 offset1:68
	v_mul_f32_e32 v0, v22, v64
	v_mul_f32_e32 v1, v6, v65
	ds_write2_b32 v2, v0, v1 offset0:168 offset1:200
	v_mul_f32_e32 v0, v23, v64
	v_mul_f32_e32 v1, v7, v65
	v_add_u32_e32 v2, 0x5800, v66
	ds_write2_b32 v2, v0, v1 offset0:44 offset1:76
	v_mul_f32_e32 v0, v24, v64
	v_mul_f32_e32 v1, v8, v65
	v_add_u32_e32 v2, 0x6000, v66
	ds_write2_b32 v2, v0, v1 offset0:192 offset1:224
	v_mul_f32_e32 v0, v25, v64
	v_mul_f32_e32 v1, v9, v65
	v_add_u32_e32 v2, 0x6400, v66
	ds_write2_b32 v2, v0, v1 offset0:68 offset1:100
	v_mul_f32_e32 v0, v26, v64
	v_mul_f32_e32 v1, v10, v65
	ds_write2_b32 v2, v0, v1 offset0:200 offset1:232
	v_mul_f32_e32 v0, v27, v64
	v_mul_f32_e32 v1, v11, v65
	v_add_u32_e32 v2, 0x6800, v66
	ds_write2_b32 v2, v0, v1 offset0:76 offset1:108
	v_mul_f32_e32 v0, v28, v64
	v_mul_f32_e32 v1, v12, v65
	v_add_u32_e32 v2, 0x7200, v66
	ds_write2_b32 v2, v0, v1 offset0:96 offset1:128
	v_mul_f32_e32 v0, v29, v64
	v_mul_f32_e32 v1, v13, v65
	v_add_u32_e32 v2, 0x7400, v66
	ds_write2_b32 v2, v0, v1 offset0:100 offset1:132
	v_mul_f32_e32 v0, v30, v64
	v_mul_f32_e32 v1, v14, v65
	v_add_u32_e32 v2, 0x7600, v66
	ds_write2_b32 v2, v0, v1 offset0:104 offset1:136
	v_mul_f32_e32 v0, v31, v64
	v_mul_f32_e32 v1, v15, v65
	v_add_u32_e32 v2, 0x7800, v66
	ds_write2_b32 v2, v0, v1 offset0:108 offset1:140
	v_and_b32_e32 v0, 64, v102
	v_add_u32_e32 v0, 64, v0
	v_xor_b32_e32 v1, 1, v102
	v_cmp_lt_i32_e32 vcc, v1, v0
	v_and_b32_e32 v4, 31, v68
	v_lshl_add_u32 v2, v4, 2, s18
	v_cndmask_b32_e32 v1, v102, v1, vcc
	v_lshlrev_b32_e32 v20, 2, v1
	v_xor_b32_e32 v1, 2, v102
	v_cmp_lt_i32_e32 vcc, v1, v0
	v_ashrrev_i32_e32 v14, 5, v68
	v_ashrrev_i32_e32 v3, 31, v2
	v_cndmask_b32_e32 v1, v102, v1, vcc
	v_lshlrev_b32_e32 v21, 2, v1
	v_xor_b32_e32 v1, 4, v102
	v_cmp_lt_i32_e32 vcc, v1, v0
	v_cmp_eq_u32_e64 s[0:1], 0, v4
	v_lshlrev_b64 v[16:17], 2, v[2:3]
	v_cndmask_b32_e32 v1, v102, v1, vcc
	v_lshlrev_b32_e32 v22, 2, v1
	v_xor_b32_e32 v1, 8, v102
	v_cmp_lt_i32_e32 vcc, v1, v0
	v_lshlrev_b32_e32 v3, 4, v4
	v_add_u32_e32 v4, s10, v14
	v_cndmask_b32_e32 v1, v102, v1, vcc
	v_lshlrev_b32_e32 v23, 2, v1
	v_xor_b32_e32 v1, 16, v102
	s_add_i32 s10, s20, s33
	s_add_i32 s20, s20, s34
	v_cmp_lt_i32_e32 vcc, v1, v0
	v_add_u32_e32 v8, s10, v14
	v_add_u32_e32 v12, s20, v14
	v_add_u32_e32 v18, s19, v14
	v_cndmask_b32_e32 v0, v102, v1, vcc
	v_ashrrev_i32_e32 v15, 31, v14
	v_mul_lo_u32 v2, v14, s55
	v_ashrrev_i32_e32 v5, 31, v4
	v_ashrrev_i32_e32 v9, 31, v8
	v_ashrrev_i32_e32 v13, 31, v12
	v_ashrrev_i32_e32 v19, 31, v18
	v_lshlrev_b32_e32 v24, 2, v0
	v_lshlrev_b64 v[0:1], 12, v[14:15]
	v_add3_u32 v25, v2, v3, 32
	v_lshlrev_b32_e32 v2, 1, v4
	v_lshlrev_b64 v[4:5], 12, v[4:5]
	v_lshlrev_b32_e32 v6, 1, v8
	v_lshlrev_b64 v[8:9], 12, v[8:9]
	v_lshlrev_b32_e32 v10, 1, v12
	v_lshlrev_b64 v[12:13], 12, v[12:13]
	v_lshlrev_b64 v[14:15], 12, v[18:19]
	v_lshl_add_u64 v[0:1], v[0:1], 0, v[16:17]
	v_lshl_add_u64 v[4:5], v[4:5], 0, v[16:17]
	v_lshl_add_u64 v[8:9], v[8:9], 0, v[16:17]
	v_lshl_add_u64 v[12:13], v[12:13], 0, v[16:17]
	v_lshl_add_u64 v[14:15], v[14:15], 0, v[16:17]
	v_lshlrev_b32_e32 v16, 1, v18
	v_ashrrev_i32_e32 v3, 31, v2
	v_ashrrev_i32_e32 v7, 31, v6
	v_ashrrev_i32_e32 v11, 31, v10
	v_ashrrev_i32_e32 v17, 31, v16
	v_lshl_add_u64 v[0:1], s[22:23], 0, v[0:1]
	v_lshlrev_b64 v[2:3], 2, v[2:3]
	v_lshl_add_u64 v[4:5], s[30:31], 0, v[4:5]
	v_lshlrev_b64 v[6:7], 2, v[6:7]
	v_lshl_add_u64 v[8:9], s[30:31], 0, v[8:9]
	v_lshlrev_b64 v[10:11], 2, v[10:11]
	v_lshl_add_u64 v[12:13], s[30:31], 0, v[12:13]
	v_lshl_add_u64 v[14:15], s[30:31], 0, v[14:15]
	v_lshlrev_b64 v[16:17], 2, v[16:17]
	s_mov_b64 s[18:19], 0
	s_mov_b64 s[20:21], s[30:31]
	s_waitcnt lgkmcnt(0)
	s_barrier
	s_branch .LBB0_1820

.LBB0_1940:
	s_setprio 1
	ds_read_b128 v[140:143], v103
	ds_read_b128 v[144:147], v104 offset:36864
	ds_read_b128 v[148:151], v103 offset:32
	ds_read_b128 v[152:155], v104 offset:36896
	ds_read_b128 v[156:159], v104 offset:41472
	ds_read_b128 v[160:163], v104 offset:41504
	s_waitcnt lgkmcnt(4)
	v_mfma_f32_32x32x16_bf16 v[48:63], v[140:143], v[144:147], v[48:63]
	global_load_dwordx4 v[108:111], v168, s[98:99] offset:3840
	global_load_dwordx4 v[112:115], v170, s[98:99] offset:3840
	s_waitcnt vmcnt(9)
	ds_write_b128 v105, v[68:71] offset:18432
	s_waitcnt lgkmcnt(2)
	v_mfma_f32_32x32x16_bf16 v[32:47], v[140:143], v[156:159], v[32:47]
	global_load_dwordx4 v[116:119], v172, s[98:99] offset:3840
	global_load_dwordx4 v[120:123], v174, s[98:99] offset:3840
	ds_read_b128 v[140:143], v103 offset:4608
	ds_read_b128 v[164:167], v103 offset:4640
	s_waitcnt lgkmcnt(1)
	v_mfma_f32_32x32x16_bf16 v[16:31], v[140:143], v[144:147], v[16:31]
	global_load_dwordx4 v[124:127], v176, s[98:99] offset:3840
	global_load_dwordx4 v[128:131], v178, s[98:99] offset:3840
	s_waitcnt vmcnt(11)
	ds_write_b128 v105, v[84:87] offset:23040
	v_mfma_f32_32x32x16_bf16 v[0:15], v[140:143], v[156:159], v[0:15]
	global_load_dwordx4 v[132:135], v180, s[98:99] offset:3840
	global_load_dwordx4 v[136:139], v182, s[98:99] offset:3840
	v_mfma_f32_32x32x16_bf16 v[48:63], v[148:151], v[152:155], v[48:63]
	s_waitcnt vmcnt(12)
	ds_write_b128 v105, v[88:91] offset:27648
	v_mfma_f32_32x32x16_bf16 v[32:47], v[148:151], v[160:163], v[32:47]
	s_waitcnt lgkmcnt(2)
	v_mfma_f32_32x32x16_bf16 v[16:31], v[164:167], v[152:155], v[16:31]
	s_waitcnt vmcnt(11)
	ds_write_b128 v105, v[92:95] offset:32256
	ds_read_b128 v[140:143], v103 offset:64
	ds_read_b128 v[144:147], v104 offset:36928
	ds_read_b128 v[148:151], v103 offset:96
	ds_read_b128 v[152:155], v104 offset:36960
	v_mfma_f32_32x32x16_bf16 v[0:15], v[164:167], v[160:163], v[0:15]
	ds_read_b128 v[156:159], v104 offset:41536
	ds_read_b128 v[160:163], v104 offset:41568
	s_waitcnt lgkmcnt(4)
	v_mfma_f32_32x32x16_bf16 v[48:63], v[140:143], v[144:147], v[48:63]
	ds_write_b128 v105, v[64:67] offset:55296
	s_waitcnt lgkmcnt(2)
	v_mfma_f32_32x32x16_bf16 v[32:47], v[140:143], v[156:159], v[32:47]
	ds_read_b128 v[140:143], v103 offset:4672
	ds_read_b128 v[164:167], v103 offset:4704
	s_waitcnt lgkmcnt(1)
	v_mfma_f32_32x32x16_bf16 v[16:31], v[140:143], v[144:147], v[16:31]
	s_waitcnt vmcnt(10)
	ds_write_b128 v105, v[72:75] offset:59904
	v_mfma_f32_32x32x16_bf16 v[0:15], v[140:143], v[156:159], v[0:15]
	v_mfma_f32_32x32x16_bf16 v[48:63], v[148:151], v[152:155], v[48:63]
	s_waitcnt vmcnt(9)
	ds_write_b128 v105, v[76:79] offset:64512
	v_mfma_f32_32x32x16_bf16 v[32:47], v[148:151], v[160:163], v[32:47]
	s_waitcnt lgkmcnt(2)
	v_mfma_f32_32x32x16_bf16 v[16:31], v[164:167], v[152:155], v[16:31]
	s_waitcnt vmcnt(8)
	ds_write_b128 v106, v[80:83] offset:13824
	v_mfma_f32_32x32x16_bf16 v[0:15], v[164:167], v[160:163], v[0:15]
	s_setprio 0
	s_waitcnt lgkmcnt(0)
	s_barrier
	s_setprio 1
	ds_read_b128 v[140:143], v103 offset:18432
	ds_read_b128 v[144:147], v104 offset:55296
	ds_read_b128 v[148:151], v103 offset:18464
	ds_read_b128 v[152:155], v104 offset:55328
	ds_read_b128 v[156:159], v104 offset:59904
	ds_read_b128 v[160:163], v104 offset:59936
	s_waitcnt lgkmcnt(4)
	v_mfma_f32_32x32x16_bf16 v[48:63], v[140:143], v[144:147], v[48:63]
	global_load_dwordx4 v[68:71], v168, s[98:99] offset:3968
	global_load_dwordx4 v[84:87], v170, s[98:99] offset:3968
	s_waitcnt vmcnt(9)
	ds_write_b128 v105, v[108:111]
	s_waitcnt lgkmcnt(2)
	v_mfma_f32_32x32x16_bf16 v[32:47], v[140:143], v[156:159], v[32:47]
	global_load_dwordx4 v[88:91], v172, s[98:99] offset:3968
	global_load_dwordx4 v[92:95], v174, s[98:99] offset:3968
	ds_read_b128 v[140:143], v103 offset:23040
	ds_read_b128 v[164:167], v103 offset:23072
	s_waitcnt lgkmcnt(1)
	v_mfma_f32_32x32x16_bf16 v[16:31], v[140:143], v[144:147], v[16:31]
	global_load_dwordx4 v[64:67], v176, s[98:99] offset:3968
	global_load_dwordx4 v[72:75], v178, s[98:99] offset:3968
	s_waitcnt vmcnt(12)
	ds_write_b128 v105, v[112:115] offset:4608
	v_mfma_f32_32x32x16_bf16 v[0:15], v[140:143], v[156:159], v[0:15]
	global_load_dwordx4 v[76:79], v180, s[98:99] offset:3968
	global_load_dwordx4 v[80:83], v182, s[98:99] offset:3968
	v_mfma_f32_32x32x16_bf16 v[48:63], v[148:151], v[152:155], v[48:63]
	s_add_u32 s98, s98, 0x100
	s_addc_u32 s99, s99, 0
	s_add_i32 s41, s41, 2
	s_cmp_lt_u32 s41, 11
	s_waitcnt vmcnt(13)
	ds_write_b128 v105, v[116:119] offset:9216
	v_mfma_f32_32x32x16_bf16 v[32:47], v[148:151], v[160:163], v[32:47]
	s_waitcnt lgkmcnt(2)
	v_mfma_f32_32x32x16_bf16 v[16:31], v[164:167], v[152:155], v[16:31]
	s_waitcnt vmcnt(12)
	ds_write_b128 v105, v[120:123] offset:13824
	ds_read_b128 v[140:143], v103 offset:18496
	ds_read_b128 v[144:147], v104 offset:55360
	ds_read_b128 v[148:151], v103 offset:18528
	ds_read_b128 v[152:155], v104 offset:55392
	v_mfma_f32_32x32x16_bf16 v[0:15], v[164:167], v[160:163], v[0:15]
	ds_read_b128 v[156:159], v104 offset:59968
	ds_read_b128 v[160:163], v104 offset:60000
	s_waitcnt lgkmcnt(4)
	v_mfma_f32_32x32x16_bf16 v[48:63], v[140:143], v[144:147], v[48:63]
	s_waitcnt vmcnt(11)
	ds_write_b128 v105, v[124:127] offset:36864
	s_waitcnt lgkmcnt(2)
	v_mfma_f32_32x32x16_bf16 v[32:47], v[140:143], v[156:159], v[32:47]
	ds_read_b128 v[140:143], v103 offset:23104
	ds_read_b128 v[164:167], v103 offset:23136
	s_waitcnt lgkmcnt(1)
	v_mfma_f32_32x32x16_bf16 v[16:31], v[140:143], v[144:147], v[16:31]
	s_waitcnt vmcnt(10)
	ds_write_b128 v105, v[128:131] offset:41472
	v_mfma_f32_32x32x16_bf16 v[0:15], v[140:143], v[156:159], v[0:15]
	v_mfma_f32_32x32x16_bf16 v[48:63], v[148:151], v[152:155], v[48:63]
	s_waitcnt vmcnt(9)
	ds_write_b128 v105, v[132:135] offset:46080
	v_mfma_f32_32x32x16_bf16 v[32:47], v[148:151], v[160:163], v[32:47]
	s_waitcnt lgkmcnt(2)
	v_mfma_f32_32x32x16_bf16 v[16:31], v[164:167], v[152:155], v[16:31]
	s_waitcnt vmcnt(8)
	ds_write_b128 v105, v[136:139] offset:50688
	v_mfma_f32_32x32x16_bf16 v[0:15], v[164:167], v[160:163], v[0:15]
	s_setprio 0
	s_waitcnt lgkmcnt(0)
	s_barrier
	s_cbranch_scc1 .LBB0_1940
	s_setprio 1
	ds_read_b128 v[98:101], v103
	ds_read_b128 v[108:111], v104 offset:36864
	ds_read_b128 v[112:115], v103 offset:32
	ds_read_b128 v[116:119], v104 offset:36896
	ds_read_b128 v[120:123], v104 offset:41472
	ds_read_b128 v[124:127], v104 offset:41504
	s_waitcnt lgkmcnt(4)
	v_mfma_f32_32x32x16_bf16 v[48:63], v[98:101], v[108:111], v[48:63]
	s_waitcnt vmcnt(7)
	ds_write_b128 v105, v[68:71] offset:18432
	s_waitcnt lgkmcnt(2)
	v_mfma_f32_32x32x16_bf16 v[32:47], v[98:101], v[120:123], v[32:47]
	ds_read_b128 v[98:101], v103 offset:4608
	ds_read_b128 v[128:131], v103 offset:4640
	s_waitcnt lgkmcnt(1)
	v_mfma_f32_32x32x16_bf16 v[16:31], v[98:101], v[108:111], v[16:31]
	s_waitcnt vmcnt(6)
	ds_write_b128 v105, v[84:87] offset:23040
	v_mfma_f32_32x32x16_bf16 v[0:15], v[98:101], v[120:123], v[0:15]
	v_mfma_f32_32x32x16_bf16 v[48:63], v[112:115], v[116:119], v[48:63]
	s_waitcnt vmcnt(5)
	ds_write_b128 v105, v[88:91] offset:27648
	v_mfma_f32_32x32x16_bf16 v[32:47], v[112:115], v[124:127], v[32:47]
	s_waitcnt lgkmcnt(2)
	v_mfma_f32_32x32x16_bf16 v[16:31], v[128:131], v[116:119], v[16:31]
	s_waitcnt vmcnt(4)
	ds_write_b128 v105, v[92:95] offset:32256
	ds_read_b128 v[98:101], v103 offset:64
	ds_read_b128 v[108:111], v104 offset:36928
	ds_read_b128 v[112:115], v103 offset:96
	ds_read_b128 v[116:119], v104 offset:36960
	v_mfma_f32_32x32x16_bf16 v[0:15], v[128:131], v[124:127], v[0:15]
	ds_read_b128 v[120:123], v104 offset:41536
	ds_read_b128 v[124:127], v104 offset:41568
	s_waitcnt lgkmcnt(4)
	v_mfma_f32_32x32x16_bf16 v[48:63], v[98:101], v[108:111], v[48:63]
	s_waitcnt vmcnt(3)
	ds_write_b128 v105, v[64:67] offset:55296
	s_waitcnt lgkmcnt(2)
	v_mfma_f32_32x32x16_bf16 v[32:47], v[98:101], v[120:123], v[32:47]
	ds_read_b128 v[98:101], v103 offset:4672
	ds_read_b128 v[128:131], v103 offset:4704
	s_waitcnt lgkmcnt(1)
	v_mfma_f32_32x32x16_bf16 v[16:31], v[98:101], v[108:111], v[16:31]
	s_waitcnt vmcnt(2)
	ds_write_b128 v105, v[72:75] offset:59904
	v_mfma_f32_32x32x16_bf16 v[0:15], v[98:101], v[120:123], v[0:15]
	v_mfma_f32_32x32x16_bf16 v[48:63], v[112:115], v[116:119], v[48:63]
	s_waitcnt vmcnt(1)
	ds_write_b128 v105, v[76:79] offset:64512
	v_mfma_f32_32x32x16_bf16 v[32:47], v[112:115], v[124:127], v[32:47]
	s_waitcnt lgkmcnt(2)
	v_mfma_f32_32x32x16_bf16 v[16:31], v[128:131], v[116:119], v[16:31]
	s_waitcnt vmcnt(0)
	ds_write_b128 v106, v[80:83] offset:13824
	v_mfma_f32_32x32x16_bf16 v[0:15], v[128:131], v[124:127], v[0:15]
	s_setprio 0
	s_waitcnt lgkmcnt(0)
	s_barrier
	s_setprio 1
	ds_read_b128 v[64:67], v103 offset:18432
	ds_read_b128 v[68:71], v104 offset:55296
	ds_read_b128 v[72:75], v103 offset:18464
	ds_read_b128 v[76:79], v104 offset:55328
	ds_read_b128 v[80:83], v104 offset:59904
	ds_read_b128 v[84:87], v104 offset:59936
	s_waitcnt lgkmcnt(4)
	v_mfma_f32_32x32x16_bf16 v[48:63], v[64:67], v[68:71], v[48:63]
	s_waitcnt lgkmcnt(1)
	v_mfma_f32_32x32x16_bf16 v[32:47], v[64:67], v[80:83], v[32:47]
	ds_read_b128 v[64:67], v103 offset:23040
	ds_read_b128 v[88:91], v103 offset:23072
	s_waitcnt lgkmcnt(1)
	v_mfma_f32_32x32x16_bf16 v[16:31], v[64:67], v[68:71], v[16:31]
	v_mfma_f32_32x32x16_bf16 v[0:15], v[64:67], v[80:83], v[0:15]
	v_mfma_f32_32x32x16_bf16 v[48:63], v[72:75], v[76:79], v[48:63]
	v_mfma_f32_32x32x16_bf16 v[32:47], v[72:75], v[84:87], v[32:47]
	s_waitcnt lgkmcnt(0)
	v_mfma_f32_32x32x16_bf16 v[16:31], v[88:91], v[76:79], v[16:31]
	ds_read_b128 v[64:67], v103 offset:18496
	ds_read_b128 v[68:71], v104 offset:55360
	ds_read_b128 v[72:75], v103 offset:18528
	ds_read_b128 v[76:79], v104 offset:55392
	v_mfma_f32_32x32x16_bf16 v[0:15], v[88:91], v[84:87], v[0:15]
	ds_read_b128 v[80:83], v104 offset:59968
	ds_read_b128 v[84:87], v104 offset:60000
	s_waitcnt lgkmcnt(4)
	v_mfma_f32_32x32x16_bf16 v[48:63], v[64:67], v[68:71], v[48:63]
	s_waitcnt lgkmcnt(1)
	v_mfma_f32_32x32x16_bf16 v[32:47], v[64:67], v[80:83], v[32:47]
	ds_read_b128 v[64:67], v103 offset:23104
	ds_read_b128 v[88:91], v103 offset:23136
	s_waitcnt lgkmcnt(1)
	v_mfma_f32_32x32x16_bf16 v[16:31], v[64:67], v[68:71], v[16:31]
	v_mfma_f32_32x32x16_bf16 v[0:15], v[64:67], v[80:83], v[0:15]
	v_mfma_f32_32x32x16_bf16 v[48:63], v[72:75], v[76:79], v[48:63]
	v_mfma_f32_32x32x16_bf16 v[32:47], v[72:75], v[84:87], v[32:47]
	s_waitcnt lgkmcnt(0)
	v_mfma_f32_32x32x16_bf16 v[16:31], v[88:91], v[76:79], v[16:31]
	v_mfma_f32_32x32x16_bf16 v[0:15], v[88:91], v[84:87], v[0:15]
	s_setprio 0
	v_lshrrev_b32_e32 v65, 3, v102
	v_lshrrev_b32_e32 v64, 1, v102
	v_and_b32_e32 v65, 4, v65
	v_and_or_b32 v64, v64, s22, v65
	v_and_b32_e32 v65, 0x5f, v102
	v_lshlrev_b32_e32 v65, 1, v65
	v_mul_lo_u32 v64, v64, s36
	v_add3_u32 v64, 32, v65, v64
	s_nop 2
	v_cvt_pk_bf16_f32 v0, v0, s0
	s_barrier
	ds_write_b16 v64, v0 offset:8768
	v_cvt_pk_bf16_f32 v0, v17, s0
	ds_write_b16 v64, v0 offset:8976
	v_cvt_pk_bf16_f32 v0, v1, s0
	ds_write_b16 v64, v0 offset:9040
	v_cvt_pk_bf16_f32 v0, v18, s0
	v_cvt_pk_bf16_f32 v32, v32, s0
	ds_write_b16 v64, v0 offset:9248
	v_cvt_pk_bf16_f32 v0, v2, s0
	ds_write_b16 v64, v32 offset:64
	v_cvt_pk_bf16_f32 v32, v49, s0
	ds_write_b16 v64, v0 offset:9312
	v_cvt_pk_bf16_f32 v0, v19, s0
	ds_write_b16 v64, v32 offset:272
	v_cvt_pk_bf16_f32 v32, v33, s0
	ds_write_b16 v64, v0 offset:9520
	v_cvt_pk_bf16_f32 v0, v3, s0
	ds_write_b16 v64, v32 offset:336
	v_cvt_pk_bf16_f32 v32, v50, s0
	ds_write_b16 v64, v0 offset:9584
	v_cvt_pk_bf16_f32 v0, v20, s0
	ds_write_b16 v64, v32 offset:544
	v_cvt_pk_bf16_f32 v32, v34, s0
	ds_write_b16 v64, v0 offset:10880
	v_cvt_pk_bf16_f32 v0, v4, s0
	ds_write_b16 v64, v32 offset:608
	v_cvt_pk_bf16_f32 v32, v51, s0
	ds_write_b16 v64, v0 offset:10944
	v_cvt_pk_bf16_f32 v0, v21, s0
	ds_write_b16 v64, v32 offset:816
	v_cvt_pk_bf16_f32 v32, v35, s0
	ds_write_b16 v64, v0 offset:11152
	v_cvt_pk_bf16_f32 v0, v5, s0
	ds_write_b16 v64, v32 offset:880
	v_cvt_pk_bf16_f32 v32, v52, s0
	ds_write_b16 v64, v0 offset:11216
	v_cvt_pk_bf16_f32 v0, v22, s0
	ds_write_b16 v64, v32 offset:2176
	v_cvt_pk_bf16_f32 v32, v36, s0
	ds_write_b16 v64, v0 offset:11424
	v_cvt_pk_bf16_f32 v0, v6, s0
	ds_write_b16 v64, v32 offset:2240
	v_cvt_pk_bf16_f32 v32, v53, s0
	ds_write_b16 v64, v0 offset:11488
	v_cvt_pk_bf16_f32 v0, v23, s0
	ds_write_b16 v64, v32 offset:2448
	v_cvt_pk_bf16_f32 v32, v37, s0
	ds_write_b16 v64, v0 offset:11696
	v_cvt_pk_bf16_f32 v0, v7, s0
	ds_write_b16 v64, v32 offset:2512
	v_cvt_pk_bf16_f32 v32, v54, s0
	ds_write_b16 v64, v0 offset:11760
	v_cvt_pk_bf16_f32 v0, v24, s0
	ds_write_b16 v64, v32 offset:2720
	v_cvt_pk_bf16_f32 v32, v38, s0
	ds_write_b16 v64, v0 offset:13056
	v_cvt_pk_bf16_f32 v0, v8, s0
	ds_write_b16 v64, v32 offset:2784
	v_cvt_pk_bf16_f32 v32, v55, s0
	ds_write_b16 v64, v0 offset:13120
	v_cvt_pk_bf16_f32 v0, v25, s0
	ds_write_b16 v64, v32 offset:2992
	v_cvt_pk_bf16_f32 v32, v39, s0
	ds_write_b16 v64, v0 offset:13328
	v_cvt_pk_bf16_f32 v0, v9, s0
	ds_write_b16 v64, v32 offset:3056
	v_cvt_pk_bf16_f32 v32, v56, s0
	ds_write_b16 v64, v0 offset:13392
	v_cvt_pk_bf16_f32 v0, v26, s0
	ds_write_b16 v64, v32 offset:4352
	v_cvt_pk_bf16_f32 v32, v40, s0
	ds_write_b16 v64, v0 offset:13600
	v_cvt_pk_bf16_f32 v0, v10, s0
	ds_write_b16 v64, v32 offset:4416
	v_cvt_pk_bf16_f32 v32, v57, s0
	ds_write_b16 v64, v0 offset:13664
	v_cvt_pk_bf16_f32 v0, v27, s0
	ds_write_b16 v64, v32 offset:4624
	v_cvt_pk_bf16_f32 v32, v41, s0
	ds_write_b16 v64, v0 offset:13872
	v_cvt_pk_bf16_f32 v0, v11, s0
	ds_write_b16 v64, v32 offset:4688
	v_cvt_pk_bf16_f32 v32, v58, s0
	ds_write_b16 v64, v0 offset:13936
	v_cvt_pk_bf16_f32 v0, v28, s0
	ds_write_b16 v64, v32 offset:4896
	v_cvt_pk_bf16_f32 v32, v42, s0
	ds_write_b16 v64, v0 offset:15232
	v_cvt_pk_bf16_f32 v0, v12, s0
	ds_write_b16 v64, v32 offset:4960
	v_cvt_pk_bf16_f32 v32, v59, s0
	ds_write_b16 v64, v0 offset:15296
	v_cvt_pk_bf16_f32 v0, v29, s0
	ds_write_b16 v64, v32 offset:5168
	v_cvt_pk_bf16_f32 v32, v43, s0
	ds_write_b16 v64, v0 offset:15504
	v_cvt_pk_bf16_f32 v0, v13, s0
	ds_write_b16 v64, v32 offset:5232
	v_cvt_pk_bf16_f32 v32, v60, s0
	ds_write_b16 v64, v0 offset:15568
	v_cvt_pk_bf16_f32 v0, v30, s0
	ds_write_b16 v64, v32 offset:6528
	v_cvt_pk_bf16_f32 v32, v44, s0
	ds_write_b16 v64, v0 offset:15776
	v_cvt_pk_bf16_f32 v0, v14, s0
	s_mul_i32 s11, s11, 0x160000
	ds_write_b16 v64, v32 offset:6592
	v_cvt_pk_bf16_f32 v32, v61, s0
	ds_write_b16 v64, v0 offset:15840
	v_cvt_pk_bf16_f32 v0, v31, s0
	s_add_u32 s41, s13, s11
	ds_write_b16 v64, v32 offset:6800
	v_cvt_pk_bf16_f32 v32, v45, s0
	ds_write_b16 v64, v0 offset:16048
	v_cvt_pk_bf16_f32 v0, v15, s0
	s_addc_u32 s44, s14, 0
	s_ashr_i32 s11, s10, 31
	ds_write_b16 v64, v32 offset:6864
	v_cvt_pk_bf16_f32 v32, v62, s0
	ds_write_b16 v64, v0 offset:16112
	s_lshl_b64 s[10:11], s[10:11], 1
	v_lshlrev_b32_e32 v0, 4, v102
	ds_write_b16 v64, v32 offset:7072
	v_cvt_pk_bf16_f32 v32, v46, s0
	s_add_u32 s10, s41, s10
	v_and_b32_e32 v96, 0xf0, v0
	ds_write_b16 v64, v32 offset:7136
	v_cvt_pk_bf16_f32 v32, v63, s0
	s_addc_u32 s11, s44, s11
	v_add_u32_e32 v8, 32, v96
	v_ashrrev_i32_e32 v9, 4, v102
	v_add_u32_e32 v4, 0x100, v102
	v_cvt_pk_bf16_f32 v48, v48, s0
	ds_write_b16 v64, v32 offset:7344
	v_cvt_pk_bf16_f32 v32, v47, s0
	v_cvt_pk_bf16_f32 v16, v16, s0
	v_lshl_add_u64 v[10:11], s[10:11], 0, v[96:97]
	v_mad_u64_u32 v[0:1], s[10:11], v9, s36, v[8:9]
	v_ashrrev_i32_e32 v14, 4, v4
	ds_write_b16 v64, v48
	ds_write_b16 v64, v32 offset:7408
	ds_write_b16 v64, v16 offset:8704
	s_waitcnt lgkmcnt(0)
	s_barrier
	ds_read_b128 v[0:3], v0
	v_mad_u64_u32 v[4:5], s[10:11], v14, s36, v[8:9]
	ds_read_b128 v[4:7], v4
	v_mad_i64_i32 v[12:13], s[10:11], v9, s37, v[10:11]
	s_waitcnt lgkmcnt(1)
	global_store_dwordx4 v[12:13], v[0:3], off
	s_nop 1
	v_mad_i64_i32 v[0:1], s[10:11], v14, s37, v[10:11]
	s_waitcnt lgkmcnt(0)
	global_store_dwordx4 v[0:1], v[4:7], off
	v_add_u32_e32 v0, 0x200, v102
	v_ashrrev_i32_e32 v9, 4, v0
	v_add_u32_e32 v4, 0x300, v102
	v_mad_u64_u32 v[0:1], s[10:11], v9, s36, v[8:9]
	v_ashrrev_i32_e32 v14, 4, v4
	ds_read_b128 v[0:3], v0
	v_mad_u64_u32 v[4:5], s[10:11], v14, s36, v[8:9]
	ds_read_b128 v[4:7], v4
	v_mad_i64_i32 v[12:13], s[10:11], v9, s37, v[10:11]
	s_waitcnt lgkmcnt(1)
	global_store_dwordx4 v[12:13], v[0:3], off
	s_nop 1
	v_mad_i64_i32 v[0:1], s[10:11], v14, s37, v[10:11]
	s_waitcnt lgkmcnt(0)
	global_store_dwordx4 v[0:1], v[4:7], off
	v_add_u32_e32 v0, 0x400, v102
	v_ashrrev_i32_e32 v9, 4, v0
	v_add_u32_e32 v4, 0x500, v102
	v_mad_u64_u32 v[0:1], s[10:11], v9, s36, v[8:9]
	v_ashrrev_i32_e32 v14, 4, v4
	ds_read_b128 v[0:3], v0
	v_mad_u64_u32 v[4:5], s[10:11], v14, s36, v[8:9]
	ds_read_b128 v[4:7], v4
	v_mad_i64_i32 v[12:13], s[10:11], v9, s37, v[10:11]
	s_waitcnt lgkmcnt(1)
	global_store_dwordx4 v[12:13], v[0:3], off
	s_nop 1
	v_mad_i64_i32 v[0:1], s[10:11], v14, s37, v[10:11]
	s_waitcnt lgkmcnt(0)
	global_store_dwordx4 v[0:1], v[4:7], off
	v_add_u32_e32 v0, 0x600, v102
	v_ashrrev_i32_e32 v9, 4, v0
	v_add_u32_e32 v4, 0x700, v102
	v_mad_u64_u32 v[0:1], s[10:11], v9, s36, v[8:9]
	v_ashrrev_i32_e32 v12, 4, v4
	ds_read_b128 v[0:3], v0
	v_mad_u64_u32 v[4:5], s[10:11], v12, s36, v[8:9]
	ds_read_b128 v[4:7], v4
	v_mad_i64_i32 v[8:9], s[10:11], v9, s37, v[10:11]
	s_waitcnt lgkmcnt(1)
	global_store_dwordx4 v[8:9], v[0:3], off
	s_nop 1
	v_mad_i64_i32 v[0:1], s[10:11], v12, s37, v[10:11]
	s_waitcnt lgkmcnt(0)
	global_store_dwordx4 v[0:1], v[4:7], off
	s_branch .LBB0_1937

.LBB0_2062:
	s_setprio 1
	ds_read_b128 v[146:149], v109
	ds_read_b128 v[150:153], v110 offset:36864
	ds_read_b128 v[154:157], v109 offset:32
	ds_read_b128 v[158:161], v110 offset:36896
	ds_read_b128 v[162:165], v110 offset:41472
	ds_read_b128 v[166:169], v110 offset:41504
	s_waitcnt lgkmcnt(4)
	v_mfma_f32_32x32x16_bf16 v[32:47], v[146:149], v[150:153], v[32:47]
	global_load_dwordx4 v[114:117], v174, s[98:99] offset:3840
	global_load_dwordx4 v[118:121], v176, s[98:99] offset:3840
	s_waitcnt vmcnt(9)
	ds_write_b128 v111, v[68:71] offset:18432
	s_waitcnt lgkmcnt(2)
	v_mfma_f32_32x32x16_bf16 v[48:63], v[146:149], v[162:165], v[48:63]
	global_load_dwordx4 v[122:125], v178, s[98:99] offset:3840
	global_load_dwordx4 v[126:129], v180, s[98:99] offset:3840
	ds_read_b128 v[146:149], v109 offset:4608
	ds_read_b128 v[170:173], v109 offset:4640
	s_waitcnt lgkmcnt(1)
	v_mfma_f32_32x32x16_bf16 v[16:31], v[146:149], v[150:153], v[16:31]
	global_load_dwordx4 v[130:133], v182, s[98:99] offset:3840
	global_load_dwordx4 v[134:137], v184, s[98:99] offset:3840
	s_waitcnt vmcnt(11)
	ds_write_b128 v111, v[84:87] offset:23040
	v_mfma_f32_32x32x16_bf16 v[0:15], v[146:149], v[162:165], v[0:15]
	global_load_dwordx4 v[138:141], v186, s[98:99] offset:3840
	global_load_dwordx4 v[142:145], v188, s[98:99] offset:3840
	v_mfma_f32_32x32x16_bf16 v[32:47], v[154:157], v[158:161], v[32:47]
	s_waitcnt vmcnt(12)
	ds_write_b128 v111, v[88:91] offset:27648
	v_mfma_f32_32x32x16_bf16 v[48:63], v[154:157], v[166:169], v[48:63]
	s_waitcnt lgkmcnt(2)
	v_mfma_f32_32x32x16_bf16 v[16:31], v[170:173], v[158:161], v[16:31]
	s_waitcnt vmcnt(11)
	ds_write_b128 v111, v[92:95] offset:32256
	ds_read_b128 v[146:149], v109 offset:64
	ds_read_b128 v[150:153], v110 offset:36928
	ds_read_b128 v[154:157], v109 offset:96
	ds_read_b128 v[158:161], v110 offset:36960
	v_mfma_f32_32x32x16_bf16 v[0:15], v[170:173], v[166:169], v[0:15]
	ds_read_b128 v[162:165], v110 offset:41536
	ds_read_b128 v[166:169], v110 offset:41568
	s_waitcnt lgkmcnt(4)
	v_mfma_f32_32x32x16_bf16 v[32:47], v[146:149], v[150:153], v[32:47]
	ds_write_b128 v111, v[64:67] offset:55296
	s_waitcnt lgkmcnt(2)
	v_mfma_f32_32x32x16_bf16 v[48:63], v[146:149], v[162:165], v[48:63]
	ds_read_b128 v[146:149], v109 offset:4672
	ds_read_b128 v[170:173], v109 offset:4704
	s_waitcnt lgkmcnt(1)
	v_mfma_f32_32x32x16_bf16 v[16:31], v[146:149], v[150:153], v[16:31]
	s_waitcnt vmcnt(10)
	ds_write_b128 v111, v[72:75] offset:59904
	v_mfma_f32_32x32x16_bf16 v[0:15], v[146:149], v[162:165], v[0:15]
	v_mfma_f32_32x32x16_bf16 v[32:47], v[154:157], v[158:161], v[32:47]
	s_waitcnt vmcnt(9)
	ds_write_b128 v111, v[76:79] offset:64512
	v_mfma_f32_32x32x16_bf16 v[48:63], v[154:157], v[166:169], v[48:63]
	s_waitcnt lgkmcnt(2)
	v_mfma_f32_32x32x16_bf16 v[16:31], v[170:173], v[158:161], v[16:31]
	s_waitcnt vmcnt(8)
	ds_write_b128 v112, v[80:83] offset:13824
	v_mfma_f32_32x32x16_bf16 v[0:15], v[170:173], v[166:169], v[0:15]
	s_setprio 0
	s_waitcnt lgkmcnt(0)
	s_barrier
	s_setprio 1
	ds_read_b128 v[146:149], v109 offset:18432
	ds_read_b128 v[150:153], v110 offset:55296
	ds_read_b128 v[154:157], v109 offset:18464
	ds_read_b128 v[158:161], v110 offset:55328
	ds_read_b128 v[162:165], v110 offset:59904
	ds_read_b128 v[166:169], v110 offset:59936
	s_waitcnt lgkmcnt(4)
	v_mfma_f32_32x32x16_bf16 v[32:47], v[146:149], v[150:153], v[32:47]
	global_load_dwordx4 v[68:71], v174, s[98:99] offset:3968
	global_load_dwordx4 v[84:87], v176, s[98:99] offset:3968
	s_waitcnt vmcnt(9)
	ds_write_b128 v111, v[114:117]
	s_waitcnt lgkmcnt(2)
	v_mfma_f32_32x32x16_bf16 v[48:63], v[146:149], v[162:165], v[48:63]
	global_load_dwordx4 v[88:91], v178, s[98:99] offset:3968
	global_load_dwordx4 v[92:95], v180, s[98:99] offset:3968
	ds_read_b128 v[146:149], v109 offset:23040
	ds_read_b128 v[170:173], v109 offset:23072
	s_waitcnt lgkmcnt(1)
	v_mfma_f32_32x32x16_bf16 v[16:31], v[146:149], v[150:153], v[16:31]
	global_load_dwordx4 v[64:67], v182, s[98:99] offset:3968
	global_load_dwordx4 v[72:75], v184, s[98:99] offset:3968
	s_waitcnt vmcnt(12)
	ds_write_b128 v111, v[118:121] offset:4608
	v_mfma_f32_32x32x16_bf16 v[0:15], v[146:149], v[162:165], v[0:15]
	global_load_dwordx4 v[76:79], v186, s[98:99] offset:3968
	global_load_dwordx4 v[80:83], v188, s[98:99] offset:3968
	v_mfma_f32_32x32x16_bf16 v[32:47], v[154:157], v[158:161], v[32:47]
	s_add_u32 s98, s98, 0x100
	s_addc_u32 s99, s99, 0
	s_add_i32 s8, s8, 2
	s_cmp_lt_u32 s8, 39
	s_waitcnt vmcnt(13)
	ds_write_b128 v111, v[122:125] offset:9216
	v_mfma_f32_32x32x16_bf16 v[48:63], v[154:157], v[166:169], v[48:63]
	s_waitcnt lgkmcnt(2)
	v_mfma_f32_32x32x16_bf16 v[16:31], v[170:173], v[158:161], v[16:31]
	s_waitcnt vmcnt(12)
	ds_write_b128 v111, v[126:129] offset:13824
	ds_read_b128 v[146:149], v109 offset:18496
	ds_read_b128 v[150:153], v110 offset:55360
	ds_read_b128 v[154:157], v109 offset:18528
	ds_read_b128 v[158:161], v110 offset:55392
	v_mfma_f32_32x32x16_bf16 v[0:15], v[170:173], v[166:169], v[0:15]
	ds_read_b128 v[162:165], v110 offset:59968
	ds_read_b128 v[166:169], v110 offset:60000
	s_waitcnt lgkmcnt(4)
	v_mfma_f32_32x32x16_bf16 v[32:47], v[146:149], v[150:153], v[32:47]
	s_waitcnt vmcnt(11)
	ds_write_b128 v111, v[130:133] offset:36864
	s_waitcnt lgkmcnt(2)
	v_mfma_f32_32x32x16_bf16 v[48:63], v[146:149], v[162:165], v[48:63]
	ds_read_b128 v[146:149], v109 offset:23104
	ds_read_b128 v[170:173], v109 offset:23136
	s_waitcnt lgkmcnt(1)
	v_mfma_f32_32x32x16_bf16 v[16:31], v[146:149], v[150:153], v[16:31]
	s_waitcnt vmcnt(10)
	ds_write_b128 v111, v[134:137] offset:41472
	v_mfma_f32_32x32x16_bf16 v[0:15], v[146:149], v[162:165], v[0:15]
	v_mfma_f32_32x32x16_bf16 v[32:47], v[154:157], v[158:161], v[32:47]
	s_waitcnt vmcnt(9)
	ds_write_b128 v111, v[138:141] offset:46080
	v_mfma_f32_32x32x16_bf16 v[48:63], v[154:157], v[166:169], v[48:63]
	s_waitcnt lgkmcnt(2)
	v_mfma_f32_32x32x16_bf16 v[16:31], v[170:173], v[158:161], v[16:31]
	s_waitcnt vmcnt(8)
	ds_write_b128 v111, v[142:145] offset:50688
	v_mfma_f32_32x32x16_bf16 v[0:15], v[170:173], v[166:169], v[0:15]
	s_setprio 0
	s_waitcnt lgkmcnt(0)
	s_barrier
	s_cbranch_scc1 .LBB0_2062
	s_setprio 1
	ds_read_b128 v[104:107], v109
	ds_read_b128 v[114:117], v110 offset:36864
	ds_read_b128 v[118:121], v109 offset:32
	ds_read_b128 v[122:125], v110 offset:36896
	ds_read_b128 v[126:129], v110 offset:41472
	ds_read_b128 v[130:133], v110 offset:41504
	s_waitcnt lgkmcnt(4)
	v_mfma_f32_32x32x16_bf16 v[32:47], v[104:107], v[114:117], v[32:47]
	s_waitcnt vmcnt(7)
	ds_write_b128 v111, v[68:71] offset:18432
	s_waitcnt lgkmcnt(2)
	v_mfma_f32_32x32x16_bf16 v[48:63], v[104:107], v[126:129], v[48:63]
	ds_read_b128 v[104:107], v109 offset:4608
	ds_read_b128 v[134:137], v109 offset:4640
	s_waitcnt lgkmcnt(1)
	v_mfma_f32_32x32x16_bf16 v[16:31], v[104:107], v[114:117], v[16:31]
	s_waitcnt vmcnt(6)
	ds_write_b128 v111, v[84:87] offset:23040
	v_mfma_f32_32x32x16_bf16 v[0:15], v[104:107], v[126:129], v[0:15]
	v_mfma_f32_32x32x16_bf16 v[32:47], v[118:121], v[122:125], v[32:47]
	s_waitcnt vmcnt(5)
	ds_write_b128 v111, v[88:91] offset:27648
	v_mfma_f32_32x32x16_bf16 v[48:63], v[118:121], v[130:133], v[48:63]
	s_waitcnt lgkmcnt(2)
	v_mfma_f32_32x32x16_bf16 v[16:31], v[134:137], v[122:125], v[16:31]
	s_waitcnt vmcnt(4)
	ds_write_b128 v111, v[92:95] offset:32256
	ds_read_b128 v[104:107], v109 offset:64
	ds_read_b128 v[114:117], v110 offset:36928
	ds_read_b128 v[118:121], v109 offset:96
	ds_read_b128 v[122:125], v110 offset:36960
	v_mfma_f32_32x32x16_bf16 v[0:15], v[134:137], v[130:133], v[0:15]
	ds_read_b128 v[126:129], v110 offset:41536
	ds_read_b128 v[130:133], v110 offset:41568
	s_waitcnt lgkmcnt(4)
	v_mfma_f32_32x32x16_bf16 v[32:47], v[104:107], v[114:117], v[32:47]
	s_waitcnt vmcnt(3)
	ds_write_b128 v111, v[64:67] offset:55296
	s_waitcnt lgkmcnt(2)
	v_mfma_f32_32x32x16_bf16 v[48:63], v[104:107], v[126:129], v[48:63]
	ds_read_b128 v[104:107], v109 offset:4672
	ds_read_b128 v[134:137], v109 offset:4704
	s_waitcnt lgkmcnt(1)
	v_mfma_f32_32x32x16_bf16 v[16:31], v[104:107], v[114:117], v[16:31]
	s_waitcnt vmcnt(2)
	ds_write_b128 v111, v[72:75] offset:59904
	v_mfma_f32_32x32x16_bf16 v[0:15], v[104:107], v[126:129], v[0:15]
	v_mfma_f32_32x32x16_bf16 v[32:47], v[118:121], v[122:125], v[32:47]
	s_waitcnt vmcnt(1)
	ds_write_b128 v111, v[76:79] offset:64512
	s_waitcnt lgkmcnt(2)
	v_mfma_f32_32x32x16_bf16 v[16:31], v[134:137], v[122:125], v[16:31]
	v_mfma_f32_32x32x16_bf16 v[0:15], v[134:137], v[130:133], v[0:15]
	s_waitcnt vmcnt(0)
	ds_write_b128 v112, v[80:83] offset:13824
	v_mfma_f32_32x32x16_bf16 v[48:63], v[118:121], v[130:133], v[48:63]
	s_setprio 0
	s_waitcnt lgkmcnt(0)
	s_barrier
	s_setprio 1
	ds_read_b128 v[64:67], v109 offset:18432
	ds_read_b128 v[68:71], v110 offset:55296
	ds_read_b128 v[72:75], v109 offset:18464
	ds_read_b128 v[76:79], v110 offset:55328
	ds_read_b128 v[80:83], v110 offset:59904
	ds_read_b128 v[84:87], v110 offset:59936
	s_waitcnt lgkmcnt(4)
	v_mfma_f32_32x32x16_bf16 v[32:47], v[64:67], v[68:71], v[32:47]
	s_waitcnt lgkmcnt(1)
	v_mfma_f32_32x32x16_bf16 v[48:63], v[64:67], v[80:83], v[48:63]
	ds_read_b128 v[64:67], v109 offset:23040
	ds_read_b128 v[88:91], v109 offset:23072
	s_waitcnt lgkmcnt(1)
	v_mfma_f32_32x32x16_bf16 v[16:31], v[64:67], v[68:71], v[16:31]
	v_mfma_f32_32x32x16_bf16 v[0:15], v[64:67], v[80:83], v[0:15]
	v_mfma_f32_32x32x16_bf16 v[32:47], v[72:75], v[76:79], v[32:47]
	v_mfma_f32_32x32x16_bf16 v[48:63], v[72:75], v[84:87], v[48:63]
	s_waitcnt lgkmcnt(0)
	v_mfma_f32_32x32x16_bf16 v[16:31], v[88:91], v[76:79], v[16:31]
	ds_read_b128 v[64:67], v109 offset:18496
	ds_read_b128 v[68:71], v110 offset:55360
	ds_read_b128 v[72:75], v109 offset:18528
	ds_read_b128 v[76:79], v110 offset:55392
	v_mfma_f32_32x32x16_bf16 v[0:15], v[88:91], v[84:87], v[0:15]
	ds_read_b128 v[80:83], v110 offset:59968
	ds_read_b128 v[84:87], v110 offset:60000
	s_waitcnt lgkmcnt(4)
	v_mfma_f32_32x32x16_bf16 v[32:47], v[64:67], v[68:71], v[32:47]
	s_waitcnt lgkmcnt(1)
	v_mfma_f32_32x32x16_bf16 v[48:63], v[64:67], v[80:83], v[48:63]
	ds_read_b128 v[64:67], v109 offset:23104
	ds_read_b128 v[88:91], v109 offset:23136
	s_waitcnt lgkmcnt(1)
	v_mfma_f32_32x32x16_bf16 v[16:31], v[64:67], v[68:71], v[16:31]
	v_mfma_f32_32x32x16_bf16 v[0:15], v[64:67], v[80:83], v[0:15]
	v_mfma_f32_32x32x16_bf16 v[32:47], v[72:75], v[76:79], v[32:47]
	s_waitcnt lgkmcnt(0)
	v_mfma_f32_32x32x16_bf16 v[16:31], v[88:91], v[76:79], v[16:31]
	v_mfma_f32_32x32x16_bf16 v[0:15], v[88:91], v[84:87], v[0:15]
	v_mfma_f32_32x32x16_bf16 v[48:63], v[72:75], v[84:87], v[48:63]
	s_setprio 0
	s_addk_i32 s0, 0xf000
	s_lshr_b32 s8, s0, 10
	s_mulk_i32 s8, 0x1800
	s_addk_i32 s8, 0x1800
	s_and_b64 s[58:59], s[4:5], exec
	s_cselect_b32 s8, 0, s8
	v_mov_b32_e32 v68, v234
	s_barrier
	s_lshl_b64 s[58:59], s[8:9], 2
	s_add_u32 s58, s30, s58
	v_and_b32_e32 v69, 0x5f, v68
	v_or_b32_e32 v64, s23, v69
	s_addc_u32 s59, s31, s59
	v_ashrrev_i32_e32 v65, 31, v64
	v_lshl_add_u64 v[64:65], v[64:65], 2, s[58:59]
	v_lshl_add_u64 v[66:67], v[64:65], 0, s[12:13]
	v_add_co_u32_e32 v64, vcc, s51, v64
	global_load_dword v66, v[66:67], off offset:128
	s_nop 0
	v_addc_co_u32_e32 v65, vcc, 0, v65, vcc
	global_load_dword v64, v[64:65], off
	v_lshrrev_b32_e32 v67, 3, v68
	v_lshrrev_b32_e32 v65, 1, v68
	v_and_b32_e32 v67, 4, v67
	v_and_or_b32 v65, v65, s45, v67
	v_lshlrev_b32_e32 v69, 2, v69
	v_mul_lo_u32 v65, v65, s52
	v_add3_u32 v65, 32, v69, v65
	v_add_u32_e32 v67, 0x400, v65
	v_add_u32_e32 v69, 0x1000, v65
	v_add_u32_e32 v70, 0x1400, v65
	v_add_u32_e32 v71, 0x2000, v65
	v_add_u32_e32 v72, 0x2400, v65
	v_add_u32_e32 v73, 0x3000, v65
	v_add_u32_e32 v74, 0x3200, v65
	v_add_u32_e32 v75, 0x3400, v65
	v_add_u32_e32 v76, 0x3600, v65
	v_add_u32_e32 v77, 0x4000, v65
	v_readlane_b32 s80, v250, 6
	v_readlane_b32 s81, v250, 7
	v_readlane_b32 s82, v250, 8
	v_readlane_b32 s83, v250, 9
	s_lshl_b32 s1, s1, 19
	s_add_u32 s8, s15, s1
	s_mov_b32 s1, s9
	v_readlane_b32 s84, v250, 10
	v_readlane_b32 s85, v250, 11
	v_readlane_b32 s86, v250, 12
	v_readlane_b32 s87, v250, 13
	v_readlane_b32 s88, v250, 14
	v_readlane_b32 s89, v250, 15
	v_readlane_b32 s90, v250, 16
	v_readlane_b32 s91, v250, 17
	v_readlane_b32 s92, v250, 18
	v_readlane_b32 s93, v250, 19
	v_readlane_b32 s94, v250, 20
	v_readlane_b32 s95, v250, 21
	s_waitcnt vmcnt(1)
	v_mul_f32_e32 v48, v48, v66
	v_mul_f32_e32 v0, v0, v66
	v_mul_f32_e32 v49, v49, v66
	s_waitcnt vmcnt(0)
	v_mul_f32_e32 v32, v32, v64
	v_mul_f32_e32 v50, v50, v66
	v_mul_f32_e32 v51, v51, v66
	v_mul_f32_e32 v52, v52, v66
	v_mul_f32_e32 v53, v53, v66
	v_mul_f32_e32 v54, v54, v66
	v_mul_f32_e32 v55, v55, v66
	v_mul_f32_e32 v56, v56, v66
	v_mul_f32_e32 v57, v57, v66
	v_mul_f32_e32 v58, v58, v66
	v_mul_f32_e32 v59, v59, v66
	v_mul_f32_e32 v60, v60, v66
	v_mul_f32_e32 v61, v61, v66
	v_mul_f32_e32 v62, v62, v66
	v_mul_f32_e32 v63, v63, v66
	v_mul_f32_e32 v33, v33, v64
	v_mul_f32_e32 v34, v34, v64
	v_mul_f32_e32 v35, v35, v64
	v_mul_f32_e32 v36, v36, v64
	v_mul_f32_e32 v37, v37, v64
	v_mul_f32_e32 v38, v38, v64
	v_mul_f32_e32 v39, v39, v64
	v_mul_f32_e32 v40, v40, v64
	v_mul_f32_e32 v41, v41, v64
	v_mul_f32_e32 v42, v42, v64
	v_mul_f32_e32 v43, v43, v64
	v_mul_f32_e32 v44, v44, v64
	v_mul_f32_e32 v45, v45, v64
	v_mul_f32_e32 v46, v46, v64
	v_mul_f32_e32 v47, v47, v64
	v_mul_f32_e32 v16, v16, v64
	v_mul_f32_e32 v17, v17, v64
	ds_write2_b32 v65, v32, v48 offset1:32
	ds_write2_b32 v65, v33, v49 offset0:132 offset1:164
	ds_write2_b32 v67, v34, v50 offset0:8 offset1:40
	ds_write2_b32 v67, v35, v51 offset0:140 offset1:172
	ds_write2_b32 v69, v36, v52 offset0:32 offset1:64
	ds_write2_b32 v69, v37, v53 offset0:164 offset1:196
	ds_write2_b32 v70, v38, v54 offset0:40 offset1:72
	ds_write2_b32 v70, v39, v55 offset0:172 offset1:204
	ds_write2_b32 v71, v40, v56 offset0:64 offset1:96
	ds_write2_b32 v71, v41, v57 offset0:196 offset1:228
	ds_write2_b32 v72, v42, v58 offset0:72 offset1:104
	ds_write2_b32 v72, v43, v59 offset0:204 offset1:236
	ds_write2_b32 v73, v44, v60 offset0:96 offset1:128
	ds_write2_b32 v74, v45, v61 offset0:100 offset1:132
	ds_write2_b32 v75, v46, v62 offset0:104 offset1:136
	ds_write2_b32 v76, v47, v63 offset0:108 offset1:140
	ds_write2_b32 v77, v16, v0 offset0:128 offset1:160
	v_mul_f32_e32 v0, v1, v66
	v_add_u32_e32 v1, 0x4400, v65
	ds_write2_b32 v1, v17, v0 offset0:4 offset1:36
	v_mul_f32_e32 v0, v18, v64
	v_mul_f32_e32 v2, v2, v66
	ds_write2_b32 v1, v0, v2 offset0:136 offset1:168
	v_mul_f32_e32 v0, v19, v64
	v_mul_f32_e32 v1, v3, v66
	v_add_u32_e32 v2, 0x4800, v65
	ds_write2_b32 v2, v0, v1 offset0:12 offset1:44
	v_mul_f32_e32 v0, v20, v64
	v_mul_f32_e32 v1, v4, v66
	v_add_u32_e32 v2, 0x5000, v65
	ds_write2_b32 v2, v0, v1 offset0:160 offset1:192
	v_mul_f32_e32 v0, v21, v64
	v_mul_f32_e32 v1, v5, v66
	v_add_u32_e32 v2, 0x5400, v65
	ds_write2_b32 v2, v0, v1 offset0:36 offset1:68
	v_mul_f32_e32 v0, v22, v64
	v_mul_f32_e32 v1, v6, v66
	ds_write2_b32 v2, v0, v1 offset0:168 offset1:200
	v_mul_f32_e32 v0, v23, v64
	v_mul_f32_e32 v1, v7, v66
	v_add_u32_e32 v2, 0x5800, v65
	ds_write2_b32 v2, v0, v1 offset0:44 offset1:76
	v_mul_f32_e32 v0, v24, v64
	v_mul_f32_e32 v1, v8, v66
	v_add_u32_e32 v2, 0x6000, v65
	ds_write2_b32 v2, v0, v1 offset0:192 offset1:224
	v_mul_f32_e32 v0, v25, v64
	v_mul_f32_e32 v1, v9, v66
	v_add_u32_e32 v2, 0x6400, v65
	ds_write2_b32 v2, v0, v1 offset0:68 offset1:100
	v_mul_f32_e32 v0, v26, v64
	v_mul_f32_e32 v1, v10, v66
	ds_write2_b32 v2, v0, v1 offset0:200 offset1:232
	v_mul_f32_e32 v0, v27, v64
	v_mul_f32_e32 v1, v11, v66
	v_add_u32_e32 v2, 0x6800, v65
	ds_write2_b32 v2, v0, v1 offset0:76 offset1:108
	v_mul_f32_e32 v0, v28, v64
	v_mul_f32_e32 v1, v12, v66
	v_add_u32_e32 v2, 0x7200, v65
	ds_write2_b32 v2, v0, v1 offset0:96 offset1:128
	v_mul_f32_e32 v0, v29, v64
	v_mul_f32_e32 v1, v13, v66
	v_add_u32_e32 v2, 0x7400, v65
	ds_write2_b32 v2, v0, v1 offset0:100 offset1:132
	v_mul_f32_e32 v0, v30, v64
	v_mul_f32_e32 v1, v14, v66
	v_add_u32_e32 v2, 0x7600, v65
	v_and_b32_e32 v12, 31, v68
	ds_write2_b32 v2, v0, v1 offset0:104 offset1:136
	v_mul_f32_e32 v0, v31, v64
	v_mul_f32_e32 v1, v15, v66
	v_add_u32_e32 v2, 0x7800, v65
	v_lshlrev_b32_e32 v8, 2, v12
	ds_write2_b32 v2, v0, v1 offset0:108 offset1:140
	v_or_b32_e32 v0, s23, v8
	v_ashrrev_i32_e32 v1, 31, v0
	v_lshlrev_b64 v[0:1], 2, v[0:1]
	v_lshl_add_u64 v[2:3], s[80:81], 0, v[0:1]
	v_lshl_add_u64 v[4:5], s[82:83], 0, v[0:1]
	s_waitcnt lgkmcnt(0)
	s_barrier
	global_load_dwordx4 v[0:3], v[2:3], off
	s_nop 0
	global_load_dwordx4 v[4:7], v[4:5], off
	v_and_b32_e32 v9, 64, v108
	v_add_u32_e32 v9, 64, v9
	v_xor_b32_e32 v10, 1, v108
	v_cmp_lt_i32_e32 vcc, v10, v9
	s_addc_u32 s23, s17, 0
	s_lshl_b64 s[0:1], s[0:1], 12
	v_cndmask_b32_e32 v10, v108, v10, vcc
	v_lshlrev_b32_e32 v32, 2, v10
	v_xor_b32_e32 v10, 2, v108
	v_cmp_lt_i32_e32 vcc, v10, v9
	s_add_u32 s58, s24, s0
	s_addc_u32 s59, s25, s1
	v_cndmask_b32_e32 v10, v108, v10, vcc
	v_lshlrev_b32_e32 v33, 2, v10
	v_xor_b32_e32 v10, 4, v108
	v_cmp_lt_i32_e32 vcc, v10, v9
	s_and_b64 s[0:1], s[4:5], exec
	v_ashrrev_i32_e32 v22, 5, v68
	v_cndmask_b32_e32 v10, v108, v10, vcc
	v_lshlrev_b32_e32 v34, 2, v10
	v_xor_b32_e32 v10, 8, v108
	s_cselect_b32 s59, s23, s59
	s_cselect_b32 s58, s8, s58
	v_cmp_lt_i32_e32 vcc, v10, v9
	s_add_i32 s8, s22, s35
	v_add_u32_e32 v16, s8, v22
	v_cndmask_b32_e32 v10, v108, v10, vcc
	s_add_i32 s8, s22, s36
	s_add_i32 s22, s22, s37
	v_lshlrev_b32_e32 v35, 2, v10
	v_xor_b32_e32 v10, 16, v108
	v_add_u32_e32 v20, s8, v22
	v_add_u32_e32 v24, s22, v22
	v_cmp_eq_u32_e64 s[0:1], 0, v12
	v_cmp_lt_i32_e32 vcc, v10, v9
	v_ashrrev_i32_e32 v23, 31, v22
	v_mul_lo_u32 v13, v22, s52
	v_lshlrev_b32_e32 v12, 4, v12
	v_add_u32_e32 v26, s21, v22
	v_ashrrev_i32_e32 v17, 31, v16
	v_ashrrev_i32_e32 v21, 31, v20
	v_ashrrev_i32_e32 v25, 31, v24
	v_cndmask_b32_e32 v9, v108, v10, vcc
	v_add_u32_e32 v8, s20, v8
	v_lshlrev_b64 v[10:11], 12, v[22:23]
	v_add3_u32 v37, v13, v12, 32
	v_lshlrev_b32_e32 v12, 1, v26
	v_lshlrev_b64 v[14:15], 12, v[16:17]
	v_lshlrev_b32_e32 v16, 1, v16
	v_lshlrev_b64 v[18:19], 12, v[20:21]
	v_lshlrev_b32_e32 v20, 1, v20
	v_lshlrev_b64 v[22:23], 12, v[24:25]
	v_lshlrev_b32_e32 v24, 1, v24
	v_ashrrev_i32_e32 v27, 31, v26
	v_lshlrev_b32_e32 v36, 2, v9
	v_ashrrev_i32_e32 v9, 31, v8
	v_ashrrev_i32_e32 v13, 31, v12
	v_ashrrev_i32_e32 v17, 31, v16
	v_ashrrev_i32_e32 v21, 31, v20
	v_ashrrev_i32_e32 v25, 31, v24
	v_lshlrev_b64 v[26:27], 12, v[26:27]
	v_lshlrev_b64 v[8:9], 2, v[8:9]
	v_lshl_add_u64 v[10:11], s[58:59], 0, v[10:11]
	v_lshl_add_u64 v[12:13], v[12:13], 2, s[30:31]
	v_lshl_add_u64 v[14:15], s[28:29], 0, v[14:15]
	v_lshl_add_u64 v[16:17], v[16:17], 2, s[30:31]
	v_lshl_add_u64 v[18:19], s[28:29], 0, v[18:19]
	v_lshl_add_u64 v[20:21], v[20:21], 2, s[30:31]
	v_lshl_add_u64 v[22:23], s[28:29], 0, v[22:23]
	v_lshl_add_u64 v[24:25], v[24:25], 2, s[30:31]
	v_lshl_add_u64 v[26:27], s[6:7], 0, v[26:27]
	s_mov_b64 s[20:21], 0
	s_branch .LBB0_2065

.LBB0_2186:
	s_setprio 1
	ds_read_b128 v[140:143], v103
	ds_read_b128 v[144:147], v104 offset:36864
	ds_read_b128 v[148:151], v103 offset:32
	ds_read_b128 v[152:155], v104 offset:36896
	ds_read_b128 v[156:159], v104 offset:41472
	ds_read_b128 v[160:163], v104 offset:41504
	s_waitcnt lgkmcnt(4)
	v_mfma_f32_32x32x16_bf16 v[48:63], v[140:143], v[144:147], v[48:63]
	global_load_dwordx4 v[108:111], v168, s[98:99] offset:3840
	global_load_dwordx4 v[112:115], v170, s[98:99] offset:3840
	s_waitcnt vmcnt(9)
	ds_write_b128 v105, v[68:71] offset:18432
	s_waitcnt lgkmcnt(2)
	v_mfma_f32_32x32x16_bf16 v[32:47], v[140:143], v[156:159], v[32:47]
	global_load_dwordx4 v[116:119], v172, s[98:99] offset:3840
	global_load_dwordx4 v[120:123], v174, s[98:99] offset:3840
	ds_read_b128 v[140:143], v103 offset:4608
	ds_read_b128 v[164:167], v103 offset:4640
	s_waitcnt lgkmcnt(1)
	v_mfma_f32_32x32x16_bf16 v[16:31], v[140:143], v[144:147], v[16:31]
	global_load_dwordx4 v[124:127], v176, s[98:99] offset:3840
	global_load_dwordx4 v[128:131], v178, s[98:99] offset:3840
	s_waitcnt vmcnt(11)
	ds_write_b128 v105, v[84:87] offset:23040
	v_mfma_f32_32x32x16_bf16 v[0:15], v[140:143], v[156:159], v[0:15]
	global_load_dwordx4 v[132:135], v180, s[98:99] offset:3840
	global_load_dwordx4 v[136:139], v182, s[98:99] offset:3840
	v_mfma_f32_32x32x16_bf16 v[48:63], v[148:151], v[152:155], v[48:63]
	s_waitcnt vmcnt(12)
	ds_write_b128 v105, v[88:91] offset:27648
	v_mfma_f32_32x32x16_bf16 v[32:47], v[148:151], v[160:163], v[32:47]
	s_waitcnt lgkmcnt(2)
	v_mfma_f32_32x32x16_bf16 v[16:31], v[164:167], v[152:155], v[16:31]
	s_waitcnt vmcnt(11)
	ds_write_b128 v105, v[92:95] offset:32256
	ds_read_b128 v[140:143], v103 offset:64
	ds_read_b128 v[144:147], v104 offset:36928
	ds_read_b128 v[148:151], v103 offset:96
	ds_read_b128 v[152:155], v104 offset:36960
	v_mfma_f32_32x32x16_bf16 v[0:15], v[164:167], v[160:163], v[0:15]
	ds_read_b128 v[156:159], v104 offset:41536
	ds_read_b128 v[160:163], v104 offset:41568
	s_waitcnt lgkmcnt(4)
	v_mfma_f32_32x32x16_bf16 v[48:63], v[140:143], v[144:147], v[48:63]
	ds_write_b128 v105, v[64:67] offset:55296
	s_waitcnt lgkmcnt(2)
	v_mfma_f32_32x32x16_bf16 v[32:47], v[140:143], v[156:159], v[32:47]
	ds_read_b128 v[140:143], v103 offset:4672
	ds_read_b128 v[164:167], v103 offset:4704
	s_waitcnt lgkmcnt(1)
	v_mfma_f32_32x32x16_bf16 v[16:31], v[140:143], v[144:147], v[16:31]
	s_waitcnt vmcnt(10)
	ds_write_b128 v105, v[72:75] offset:59904
	v_mfma_f32_32x32x16_bf16 v[0:15], v[140:143], v[156:159], v[0:15]
	v_mfma_f32_32x32x16_bf16 v[48:63], v[148:151], v[152:155], v[48:63]
	s_waitcnt vmcnt(9)
	ds_write_b128 v105, v[76:79] offset:64512
	v_mfma_f32_32x32x16_bf16 v[32:47], v[148:151], v[160:163], v[32:47]
	s_waitcnt lgkmcnt(2)
	v_mfma_f32_32x32x16_bf16 v[16:31], v[164:167], v[152:155], v[16:31]
	s_waitcnt vmcnt(8)
	ds_write_b128 v106, v[80:83] offset:13824
	v_mfma_f32_32x32x16_bf16 v[0:15], v[164:167], v[160:163], v[0:15]
	s_setprio 0
	s_waitcnt lgkmcnt(0)
	s_barrier
	s_setprio 1
	ds_read_b128 v[140:143], v103 offset:18432
	ds_read_b128 v[144:147], v104 offset:55296
	ds_read_b128 v[148:151], v103 offset:18464
	ds_read_b128 v[152:155], v104 offset:55328
	ds_read_b128 v[156:159], v104 offset:59904
	ds_read_b128 v[160:163], v104 offset:59936
	s_waitcnt lgkmcnt(4)
	v_mfma_f32_32x32x16_bf16 v[48:63], v[140:143], v[144:147], v[48:63]
	global_load_dwordx4 v[68:71], v168, s[98:99] offset:3968
	global_load_dwordx4 v[84:87], v170, s[98:99] offset:3968
	s_waitcnt vmcnt(9)
	ds_write_b128 v105, v[108:111]
	s_waitcnt lgkmcnt(2)
	v_mfma_f32_32x32x16_bf16 v[32:47], v[140:143], v[156:159], v[32:47]
	global_load_dwordx4 v[88:91], v172, s[98:99] offset:3968
	global_load_dwordx4 v[92:95], v174, s[98:99] offset:3968
	ds_read_b128 v[140:143], v103 offset:23040
	ds_read_b128 v[164:167], v103 offset:23072
	s_waitcnt lgkmcnt(1)
	v_mfma_f32_32x32x16_bf16 v[16:31], v[140:143], v[144:147], v[16:31]
	global_load_dwordx4 v[64:67], v176, s[98:99] offset:3968
	global_load_dwordx4 v[72:75], v178, s[98:99] offset:3968
	s_waitcnt vmcnt(12)
	ds_write_b128 v105, v[112:115] offset:4608
	v_mfma_f32_32x32x16_bf16 v[0:15], v[140:143], v[156:159], v[0:15]
	global_load_dwordx4 v[76:79], v180, s[98:99] offset:3968
	global_load_dwordx4 v[80:83], v182, s[98:99] offset:3968
	v_mfma_f32_32x32x16_bf16 v[48:63], v[148:151], v[152:155], v[48:63]
	s_add_u32 s98, s98, 0x100
	s_addc_u32 s99, s99, 0
	s_add_i32 s4, s4, 2
	s_cmp_lt_u32 s4, 11
	s_waitcnt vmcnt(13)
	ds_write_b128 v105, v[116:119] offset:9216
	v_mfma_f32_32x32x16_bf16 v[32:47], v[148:151], v[160:163], v[32:47]
	s_waitcnt lgkmcnt(2)
	v_mfma_f32_32x32x16_bf16 v[16:31], v[164:167], v[152:155], v[16:31]
	s_waitcnt vmcnt(12)
	ds_write_b128 v105, v[120:123] offset:13824
	ds_read_b128 v[140:143], v103 offset:18496
	ds_read_b128 v[144:147], v104 offset:55360
	ds_read_b128 v[148:151], v103 offset:18528
	ds_read_b128 v[152:155], v104 offset:55392
	v_mfma_f32_32x32x16_bf16 v[0:15], v[164:167], v[160:163], v[0:15]
	ds_read_b128 v[156:159], v104 offset:59968
	ds_read_b128 v[160:163], v104 offset:60000
	s_waitcnt lgkmcnt(4)
	v_mfma_f32_32x32x16_bf16 v[48:63], v[140:143], v[144:147], v[48:63]
	s_waitcnt vmcnt(11)
	ds_write_b128 v105, v[124:127] offset:36864
	s_waitcnt lgkmcnt(2)
	v_mfma_f32_32x32x16_bf16 v[32:47], v[140:143], v[156:159], v[32:47]
	ds_read_b128 v[140:143], v103 offset:23104
	ds_read_b128 v[164:167], v103 offset:23136
	s_waitcnt lgkmcnt(1)
	v_mfma_f32_32x32x16_bf16 v[16:31], v[140:143], v[144:147], v[16:31]
	s_waitcnt vmcnt(10)
	ds_write_b128 v105, v[128:131] offset:41472
	v_mfma_f32_32x32x16_bf16 v[0:15], v[140:143], v[156:159], v[0:15]
	v_mfma_f32_32x32x16_bf16 v[48:63], v[148:151], v[152:155], v[48:63]
	s_waitcnt vmcnt(9)
	ds_write_b128 v105, v[132:135] offset:46080
	v_mfma_f32_32x32x16_bf16 v[32:47], v[148:151], v[160:163], v[32:47]
	s_waitcnt lgkmcnt(2)
	v_mfma_f32_32x32x16_bf16 v[16:31], v[164:167], v[152:155], v[16:31]
	s_waitcnt vmcnt(8)
	ds_write_b128 v105, v[136:139] offset:50688
	v_mfma_f32_32x32x16_bf16 v[0:15], v[164:167], v[160:163], v[0:15]
	s_setprio 0
	s_waitcnt lgkmcnt(0)
	s_barrier
	s_cbranch_scc1 .LBB0_2186
	s_setprio 1
	ds_read_b128 v[98:101], v103
	ds_read_b128 v[108:111], v104 offset:36864
	ds_read_b128 v[112:115], v103 offset:32
	ds_read_b128 v[116:119], v104 offset:36896
	ds_read_b128 v[120:123], v104 offset:41472
	ds_read_b128 v[124:127], v104 offset:41504
	s_waitcnt lgkmcnt(4)
	v_mfma_f32_32x32x16_bf16 v[48:63], v[98:101], v[108:111], v[48:63]
	s_waitcnt vmcnt(7)
	ds_write_b128 v105, v[68:71] offset:18432
	s_waitcnt lgkmcnt(2)
	v_mfma_f32_32x32x16_bf16 v[32:47], v[98:101], v[120:123], v[32:47]
	ds_read_b128 v[98:101], v103 offset:4608
	ds_read_b128 v[128:131], v103 offset:4640
	s_waitcnt lgkmcnt(1)
	v_mfma_f32_32x32x16_bf16 v[16:31], v[98:101], v[108:111], v[16:31]
	s_waitcnt vmcnt(6)
	ds_write_b128 v105, v[84:87] offset:23040
	v_mfma_f32_32x32x16_bf16 v[0:15], v[98:101], v[120:123], v[0:15]
	v_mfma_f32_32x32x16_bf16 v[48:63], v[112:115], v[116:119], v[48:63]
	s_waitcnt vmcnt(5)
	ds_write_b128 v105, v[88:91] offset:27648
	v_mfma_f32_32x32x16_bf16 v[32:47], v[112:115], v[124:127], v[32:47]
	s_waitcnt lgkmcnt(2)
	v_mfma_f32_32x32x16_bf16 v[16:31], v[128:131], v[116:119], v[16:31]
	s_waitcnt vmcnt(4)
	ds_write_b128 v105, v[92:95] offset:32256
	ds_read_b128 v[98:101], v103 offset:64
	ds_read_b128 v[108:111], v104 offset:36928
	ds_read_b128 v[112:115], v103 offset:96
	ds_read_b128 v[116:119], v104 offset:36960
	v_mfma_f32_32x32x16_bf16 v[0:15], v[128:131], v[124:127], v[0:15]
	ds_read_b128 v[120:123], v104 offset:41536
	ds_read_b128 v[124:127], v104 offset:41568
	s_waitcnt lgkmcnt(4)
	v_mfma_f32_32x32x16_bf16 v[48:63], v[98:101], v[108:111], v[48:63]
	s_waitcnt vmcnt(3)
	ds_write_b128 v105, v[64:67] offset:55296
	s_waitcnt lgkmcnt(2)
	v_mfma_f32_32x32x16_bf16 v[32:47], v[98:101], v[120:123], v[32:47]
	ds_read_b128 v[98:101], v103 offset:4672
	ds_read_b128 v[128:131], v103 offset:4704
	s_waitcnt lgkmcnt(1)
	v_mfma_f32_32x32x16_bf16 v[16:31], v[98:101], v[108:111], v[16:31]
	s_waitcnt vmcnt(2)
	ds_write_b128 v105, v[72:75] offset:59904
	v_mfma_f32_32x32x16_bf16 v[0:15], v[98:101], v[120:123], v[0:15]
	v_mfma_f32_32x32x16_bf16 v[48:63], v[112:115], v[116:119], v[48:63]
	s_waitcnt vmcnt(1)
	ds_write_b128 v105, v[76:79] offset:64512
	v_mfma_f32_32x32x16_bf16 v[32:47], v[112:115], v[124:127], v[32:47]
	s_waitcnt lgkmcnt(2)
	v_mfma_f32_32x32x16_bf16 v[16:31], v[128:131], v[116:119], v[16:31]
	s_waitcnt vmcnt(0)
	ds_write_b128 v106, v[80:83] offset:13824
	v_mfma_f32_32x32x16_bf16 v[0:15], v[128:131], v[124:127], v[0:15]
	s_setprio 0
	s_waitcnt lgkmcnt(0)
	s_barrier
	s_setprio 1
	ds_read_b128 v[64:67], v103 offset:18432
	ds_read_b128 v[68:71], v104 offset:55296
	ds_read_b128 v[72:75], v103 offset:18464
	ds_read_b128 v[76:79], v104 offset:55328
	ds_read_b128 v[80:83], v104 offset:59904
	ds_read_b128 v[84:87], v104 offset:59936
	s_waitcnt lgkmcnt(4)
	v_mfma_f32_32x32x16_bf16 v[48:63], v[64:67], v[68:71], v[48:63]
	s_waitcnt lgkmcnt(1)
	v_mfma_f32_32x32x16_bf16 v[32:47], v[64:67], v[80:83], v[32:47]
	ds_read_b128 v[64:67], v103 offset:23040
	ds_read_b128 v[88:91], v103 offset:23072
	s_waitcnt lgkmcnt(1)
	v_mfma_f32_32x32x16_bf16 v[16:31], v[64:67], v[68:71], v[16:31]
	v_mfma_f32_32x32x16_bf16 v[0:15], v[64:67], v[80:83], v[0:15]
	v_mfma_f32_32x32x16_bf16 v[48:63], v[72:75], v[76:79], v[48:63]
	v_mfma_f32_32x32x16_bf16 v[32:47], v[72:75], v[84:87], v[32:47]
	s_waitcnt lgkmcnt(0)
	v_mfma_f32_32x32x16_bf16 v[16:31], v[88:91], v[76:79], v[16:31]
	ds_read_b128 v[64:67], v103 offset:18496
	ds_read_b128 v[68:71], v104 offset:55360
	ds_read_b128 v[72:75], v103 offset:18528
	ds_read_b128 v[76:79], v104 offset:55392
	v_mfma_f32_32x32x16_bf16 v[0:15], v[88:91], v[84:87], v[0:15]
	ds_read_b128 v[80:83], v104 offset:59968
	ds_read_b128 v[84:87], v104 offset:60000
	s_waitcnt lgkmcnt(4)
	v_mfma_f32_32x32x16_bf16 v[48:63], v[64:67], v[68:71], v[48:63]
	s_waitcnt lgkmcnt(1)
	v_mfma_f32_32x32x16_bf16 v[32:47], v[64:67], v[80:83], v[32:47]
	ds_read_b128 v[64:67], v103 offset:23104
	ds_read_b128 v[88:91], v103 offset:23136
	s_waitcnt lgkmcnt(1)
	v_mfma_f32_32x32x16_bf16 v[16:31], v[64:67], v[68:71], v[16:31]
	v_mfma_f32_32x32x16_bf16 v[0:15], v[64:67], v[80:83], v[0:15]
	v_mfma_f32_32x32x16_bf16 v[48:63], v[72:75], v[76:79], v[48:63]
	v_mfma_f32_32x32x16_bf16 v[32:47], v[72:75], v[84:87], v[32:47]
	s_waitcnt lgkmcnt(0)
	v_mfma_f32_32x32x16_bf16 v[16:31], v[88:91], v[76:79], v[16:31]
	v_mfma_f32_32x32x16_bf16 v[0:15], v[88:91], v[84:87], v[0:15]
	s_setprio 0
	s_cmpk_gt_u32 s22, 0xfff
	s_cselect_b64 s[10:11], -1, 0
	s_cmpk_lt_u32 s22, 0x1000
	s_cselect_b64 s[40:41], -1, 0
	s_ashr_i32 s61, s2, 2
	s_cmp_lt_i32 s61, 7
	s_barrier
	s_cbranch_scc1 .LBB0_2189
	s_cmp_lg_u32 s61, 7
	s_cselect_b64 s[4:5], -1, 0
	s_cbranch_execz .LBB0_2190
	s_branch .LBB0_2191

.LBB0_2206:
	v_ashrrev_i32_e32 v66, 1, v102
	v_lshrrev_b32_e32 v64, 3, v102
	v_and_b32_e32 v72, 4, v64
	v_add_u32_e32 v64, s60, v66
	v_bfe_u32 v73, v64, 6, 4
	v_lshlrev_b32_e32 v64, 1, v102
	v_and_b32_e32 v74, 62, v64
	v_cndmask_b32_e64 v64, 0, 1, s[10:11]
	s_and_b64 vcc, exec, s[8:9]
	v_cmp_ne_u32_e64 s[8:9], 1, v64
	s_cbranch_vccz .LBB0_2211
	s_and_b64 vcc, exec, s[8:9]
	s_cbranch_vccnz .LBB0_2209
	v_lshlrev_b32_e32 v175, 2, v74
	v_mov_b32_e32 v174, v72
	v_cndmask_b32_e64 v174, v174, v73, s[6:7]
	v_lshl_or_b32 v174, v174, 8, v175
	global_load_dwordx2 v[110:111], v174, s[20:21]
	v_or_b32_e32 v174, 1, v72
	v_cndmask_b32_e64 v174, v174, v73, s[6:7]
	v_lshl_or_b32 v174, v174, 8, v175
	global_load_dwordx2 v[112:113], v174, s[20:21]
	v_or_b32_e32 v174, 2, v72
	v_cndmask_b32_e64 v174, v174, v73, s[6:7]
	v_lshl_or_b32 v174, v174, 8, v175
	global_load_dwordx2 v[114:115], v174, s[20:21]
	v_or_b32_e32 v174, 3, v72
	v_cndmask_b32_e64 v174, v174, v73, s[6:7]
	v_lshl_or_b32 v174, v174, 8, v175
	global_load_dwordx2 v[116:117], v174, s[20:21]
	v_or_b32_e32 v174, 8, v72
	v_cndmask_b32_e64 v174, v174, v73, s[6:7]
	v_lshl_or_b32 v174, v174, 8, v175
	global_load_dwordx2 v[118:119], v174, s[20:21]
	v_or_b32_e32 v174, 9, v72
	v_cndmask_b32_e64 v174, v174, v73, s[6:7]
	v_lshl_or_b32 v174, v174, 8, v175
	global_load_dwordx2 v[120:121], v174, s[20:21]
	v_or_b32_e32 v174, 10, v72
	v_cndmask_b32_e64 v174, v174, v73, s[6:7]
	v_lshl_or_b32 v174, v174, 8, v175
	global_load_dwordx2 v[122:123], v174, s[20:21]
	v_or_b32_e32 v174, 11, v72
	v_cndmask_b32_e64 v174, v174, v73, s[6:7]
	v_lshl_or_b32 v174, v174, 8, v175
	global_load_dwordx2 v[124:125], v174, s[20:21]
	v_or_b32_e32 v174, 16, v72
	v_cndmask_b32_e64 v174, v174, v73, s[6:7]
	v_lshl_or_b32 v174, v174, 8, v175
	global_load_dwordx2 v[126:127], v174, s[20:21]
	v_or_b32_e32 v174, 17, v72
	v_cndmask_b32_e64 v174, v174, v73, s[6:7]
	v_lshl_or_b32 v174, v174, 8, v175
	global_load_dwordx2 v[128:129], v174, s[20:21]
	v_or_b32_e32 v174, 18, v72
	v_cndmask_b32_e64 v174, v174, v73, s[6:7]
	v_lshl_or_b32 v174, v174, 8, v175
	global_load_dwordx2 v[130:131], v174, s[20:21]
	v_or_b32_e32 v174, 19, v72
	v_cndmask_b32_e64 v174, v174, v73, s[6:7]
	v_lshl_or_b32 v174, v174, 8, v175
	global_load_dwordx2 v[132:133], v174, s[20:21]
	v_or_b32_e32 v174, 24, v72
	v_cndmask_b32_e64 v174, v174, v73, s[6:7]
	v_lshl_or_b32 v174, v174, 8, v175
	global_load_dwordx2 v[134:135], v174, s[20:21]
	v_or_b32_e32 v174, 25, v72
	v_cndmask_b32_e64 v174, v174, v73, s[6:7]
	v_lshl_or_b32 v174, v174, 8, v175
	global_load_dwordx2 v[136:137], v174, s[20:21]
	v_or_b32_e32 v174, 26, v72
	v_cndmask_b32_e64 v174, v174, v73, s[6:7]
	v_lshl_or_b32 v174, v174, 8, v175
	global_load_dwordx2 v[138:139], v174, s[20:21]
	v_or_b32_e32 v174, 27, v72
	v_cndmask_b32_e64 v174, v174, v73, s[6:7]
	v_lshl_or_b32 v174, v174, 8, v175
	global_load_dwordx2 v[140:141], v174, s[20:21]
	v_or_b32_e32 v174, 32, v72
	v_cndmask_b32_e64 v174, v174, v73, s[6:7]
	v_lshl_or_b32 v174, v174, 8, v175
	global_load_dwordx2 v[142:143], v174, s[20:21]
	v_or_b32_e32 v174, 33, v72
	v_cndmask_b32_e64 v174, v174, v73, s[6:7]
	v_lshl_or_b32 v174, v174, 8, v175
	global_load_dwordx2 v[144:145], v174, s[20:21]
	v_or_b32_e32 v174, 34, v72
	v_cndmask_b32_e64 v174, v174, v73, s[6:7]
	v_lshl_or_b32 v174, v174, 8, v175
	global_load_dwordx2 v[146:147], v174, s[20:21]
	v_or_b32_e32 v174, 35, v72
	v_cndmask_b32_e64 v174, v174, v73, s[6:7]
	v_lshl_or_b32 v174, v174, 8, v175
	global_load_dwordx2 v[148:149], v174, s[20:21]
	v_or_b32_e32 v174, 40, v72
	v_cndmask_b32_e64 v174, v174, v73, s[6:7]
	v_lshl_or_b32 v174, v174, 8, v175
	global_load_dwordx2 v[150:151], v174, s[20:21]
	v_or_b32_e32 v174, 41, v72
	v_cndmask_b32_e64 v174, v174, v73, s[6:7]
	v_lshl_or_b32 v174, v174, 8, v175
	global_load_dwordx2 v[152:153], v174, s[20:21]
	v_or_b32_e32 v174, 42, v72
	v_cndmask_b32_e64 v174, v174, v73, s[6:7]
	v_lshl_or_b32 v174, v174, 8, v175
	global_load_dwordx2 v[154:155], v174, s[20:21]
	v_or_b32_e32 v174, 43, v72
	v_cndmask_b32_e64 v174, v174, v73, s[6:7]
	v_lshl_or_b32 v174, v174, 8, v175
	global_load_dwordx2 v[156:157], v174, s[20:21]
	v_or_b32_e32 v174, 48, v72
	v_cndmask_b32_e64 v174, v174, v73, s[6:7]
	v_lshl_or_b32 v174, v174, 8, v175
	global_load_dwordx2 v[158:159], v174, s[20:21]
	v_or_b32_e32 v174, 49, v72
	v_cndmask_b32_e64 v174, v174, v73, s[6:7]
	v_lshl_or_b32 v174, v174, 8, v175
	global_load_dwordx2 v[160:161], v174, s[20:21]
	v_or_b32_e32 v174, 50, v72
	v_cndmask_b32_e64 v174, v174, v73, s[6:7]
	v_lshl_or_b32 v174, v174, 8, v175
	global_load_dwordx2 v[162:163], v174, s[20:21]
	v_or_b32_e32 v174, 51, v72
	v_cndmask_b32_e64 v174, v174, v73, s[6:7]
	v_lshl_or_b32 v174, v174, 8, v175
	global_load_dwordx2 v[164:165], v174, s[20:21]
	v_or_b32_e32 v174, 56, v72
	v_cndmask_b32_e64 v174, v174, v73, s[6:7]
	v_lshl_or_b32 v174, v174, 8, v175
	global_load_dwordx2 v[166:167], v174, s[20:21]
	v_or_b32_e32 v174, 57, v72
	v_cndmask_b32_e64 v174, v174, v73, s[6:7]
	v_lshl_or_b32 v174, v174, 8, v175
	global_load_dwordx2 v[168:169], v174, s[20:21]
	v_or_b32_e32 v174, 58, v72
	v_cndmask_b32_e64 v174, v174, v73, s[6:7]
	v_lshl_or_b32 v174, v174, 8, v175
	global_load_dwordx2 v[170:171], v174, s[20:21]
	v_or_b32_e32 v174, 59, v72
	v_cndmask_b32_e64 v174, v174, v73, s[6:7]
	v_lshl_or_b32 v174, v174, 8, v175
	global_load_dwordx2 v[172:173], v174, s[20:21]
	s_waitcnt vmcnt(0)
	v_mov_b64_e32 v[64:65], v[110:111]
	v_pk_mul_f32 v[70:71], v[32:33], v[64:65] op_sel:[0,1] op_sel_hi:[0,0]
	v_pk_mul_f32 v[68:69], v[48:49], v[64:65]
	v_pk_fma_f32 v[64:65], v[48:49], v[64:65], v[70:71] op_sel_hi:[0,1,1]
	v_sub_f32_e32 v64, v68, v70
	s_branch .LBB0_2210

.LBB0_2227:
	s_and_b64 vcc, exec, s[14:15]
	s_cbranch_vccz .LBB0_2235
	s_and_b64 vcc, exec, s[8:9]
	s_cbranch_vccnz .LBB0_2237
	v_mov_b64_e32 v[70:71], v[112:113]
	v_pk_mul_f32 v[78:79], v[32:33], v[70:71] op_sel:[1,1] op_sel_hi:[1,0]
	v_pk_mul_f32 v[76:77], v[48:49], v[70:71] op_sel:[1,0]
	v_pk_fma_f32 v[70:71], v[48:49], v[70:71], v[78:79] op_sel:[1,0,0]
	s_nop 0
	v_sub_f32_e32 v70, v76, v78
	s_branch .LBB0_2238

.LBB0_2253:
	s_and_b64 vcc, exec, s[14:15]
	s_cbranch_vccz .LBB0_2261
	s_and_b64 vcc, exec, s[8:9]
	s_cbranch_vccnz .LBB0_2263
	v_mov_b64_e32 v[32:33], v[114:115]
	v_pk_mul_f32 v[76:77], v[34:35], v[32:33] op_sel:[0,1] op_sel_hi:[0,0]
	v_pk_mul_f32 v[48:49], v[50:51], v[32:33]
	v_pk_fma_f32 v[32:33], v[50:51], v[32:33], v[76:77] op_sel_hi:[0,1,1]
	v_sub_f32_e32 v32, v48, v76
	s_branch .LBB0_2264

.LBB0_2279:
	s_and_b64 vcc, exec, s[14:15]
	s_cbranch_vccz .LBB0_2287
	s_and_b64 vcc, exec, s[8:9]
	s_cbranch_vccnz .LBB0_2289
	v_mov_b64_e32 v[48:49], v[116:117]
	v_mov_b32_e32 v50, v35
	v_mov_b32_e32 v34, v51
	v_pk_mul_f32 v[78:79], v[50:51], v[48:49] op_sel:[0,1] op_sel_hi:[0,0]
	v_pk_mul_f32 v[76:77], v[34:35], v[48:49] op_sel_hi:[0,1]
	v_pk_fma_f32 v[48:49], v[34:35], v[48:49], v[78:79] op_sel_hi:[0,1,1]
	v_sub_f32_e32 v48, v76, v78
	s_branch .LBB0_2290

.LBB0_2299:
	s_and_b64 vcc, exec, s[34:35]
	s_cbranch_vccz .LBB0_2315
	s_and_b64 vcc, exec, s[8:9]
	s_cbranch_vccnz .LBB0_2317
	v_mov_b64_e32 v[32:33], v[118:119]
	v_pk_mul_f32 v[48:49], v[36:37], v[32:33] op_sel:[0,1] op_sel_hi:[0,0]
	v_pk_mul_f32 v[34:35], v[52:53], v[32:33]
	v_pk_fma_f32 v[32:33], v[52:53], v[32:33], v[48:49] op_sel_hi:[0,1,1]
	v_sub_f32_e32 v32, v34, v48
	s_branch .LBB0_2318

.LBB0_2333:
	s_and_b64 vcc, exec, s[34:35]
	s_cbranch_vccz .LBB0_2341
	s_and_b64 vcc, exec, s[8:9]
	s_cbranch_vccnz .LBB0_2343
	v_mov_b64_e32 v[34:35], v[120:121]
	v_mov_b32_e32 v48, v37
	v_mov_b32_e32 v36, v53
	v_pk_mul_f32 v[48:49], v[48:49], v[34:35] op_sel:[0,1] op_sel_hi:[0,0]
	v_pk_mul_f32 v[68:69], v[36:37], v[34:35] op_sel_hi:[0,1]
	v_pk_fma_f32 v[34:35], v[36:37], v[34:35], v[48:49] op_sel_hi:[0,1,1]
	v_sub_f32_e32 v34, v68, v48
	s_branch .LBB0_2344

.LBB0_2359:
	s_and_b64 vcc, exec, s[34:35]
	s_cbranch_vccz .LBB0_2367
	s_and_b64 vcc, exec, s[8:9]
	s_cbranch_vccnz .LBB0_2369
	v_mov_b64_e32 v[36:37], v[122:123]
	v_pk_mul_f32 v[52:53], v[38:39], v[36:37] op_sel:[0,1] op_sel_hi:[0,0]
	v_pk_mul_f32 v[48:49], v[54:55], v[36:37]
	v_pk_fma_f32 v[36:37], v[54:55], v[36:37], v[52:53] op_sel_hi:[0,1,1]
	v_sub_f32_e32 v36, v48, v52
	s_branch .LBB0_2370

.LBB0_2385:
	s_and_b64 vcc, exec, s[34:35]
	s_cbranch_vccz .LBB0_2393
	s_and_b64 vcc, exec, s[8:9]
	s_cbranch_vccnz .LBB0_2395
	v_mov_b64_e32 v[48:49], v[124:125]
	v_mov_b32_e32 v52, v39
	v_mov_b32_e32 v38, v55
	v_pk_mul_f32 v[52:53], v[52:53], v[48:49] op_sel:[0,1] op_sel_hi:[0,0]
	v_pk_mul_f32 v[68:69], v[38:39], v[48:49] op_sel_hi:[0,1]
	v_pk_fma_f32 v[48:49], v[38:39], v[48:49], v[52:53] op_sel_hi:[0,1,1]
	v_sub_f32_e32 v48, v68, v52
	s_branch .LBB0_2396

.LBB0_2403:
	s_and_b64 vcc, exec, s[34:35]
	s_cbranch_vccz .LBB0_2421
	s_and_b64 vcc, exec, s[8:9]
	s_cbranch_vccnz .LBB0_2423
	v_mov_b64_e32 v[32:33], v[126:127]
	v_pk_mul_f32 v[36:37], v[40:41], v[32:33] op_sel:[0,1] op_sel_hi:[0,0]
	v_pk_mul_f32 v[34:35], v[56:57], v[32:33]
	v_pk_fma_f32 v[32:33], v[56:57], v[32:33], v[36:37] op_sel_hi:[0,1,1]
	v_sub_f32_e32 v32, v34, v36
	s_branch .LBB0_2424

.LBB0_2439:
	s_and_b64 vcc, exec, s[34:35]
	s_cbranch_vccz .LBB0_2447
	s_and_b64 vcc, exec, s[8:9]
	s_cbranch_vccnz .LBB0_2449
	v_mov_b64_e32 v[34:35], v[128:129]
	v_mov_b32_e32 v38, v41
	v_mov_b32_e32 v36, v57
	v_pk_mul_f32 v[38:39], v[38:39], v[34:35] op_sel:[0,1] op_sel_hi:[0,0]
	v_pk_mul_f32 v[48:49], v[36:37], v[34:35] op_sel_hi:[0,1]
	v_pk_fma_f32 v[34:35], v[36:37], v[34:35], v[38:39] op_sel_hi:[0,1,1]
	v_sub_f32_e32 v34, v48, v38
	s_branch .LBB0_2450

.LBB0_2465:
	s_and_b64 vcc, exec, s[34:35]
	s_cbranch_vccz .LBB0_2473
	s_and_b64 vcc, exec, s[8:9]
	s_cbranch_vccnz .LBB0_2475
	v_mov_b64_e32 v[36:37], v[130:131]
	v_pk_mul_f32 v[40:41], v[42:43], v[36:37] op_sel:[0,1] op_sel_hi:[0,0]
	v_pk_mul_f32 v[38:39], v[58:59], v[36:37]
	v_pk_fma_f32 v[36:37], v[58:59], v[36:37], v[40:41] op_sel_hi:[0,1,1]
	v_sub_f32_e32 v36, v38, v40
	s_branch .LBB0_2476

.LBB0_2491:
	s_and_b64 vcc, exec, s[34:35]
	s_cbranch_vccz .LBB0_2499
	s_and_b64 vcc, exec, s[8:9]
	s_cbranch_vccnz .LBB0_2501
	v_mov_b64_e32 v[38:39], v[132:133]
	v_mov_b32_e32 v42, v43
	v_mov_b32_e32 v40, v59
	v_pk_mul_f32 v[52:53], v[42:43], v[38:39] op_sel:[0,1] op_sel_hi:[0,0]
	v_pk_mul_f32 v[48:49], v[40:41], v[38:39] op_sel_hi:[0,1]
	v_pk_fma_f32 v[38:39], v[40:41], v[38:39], v[52:53] op_sel_hi:[0,1,1]
	v_sub_f32_e32 v38, v48, v52
	s_branch .LBB0_2502

.LBB0_2509:
	s_and_b64 vcc, exec, s[34:35]
	s_cbranch_vccz .LBB0_2527
	s_and_b64 vcc, exec, s[8:9]
	s_cbranch_vccnz .LBB0_2529
	v_mov_b64_e32 v[32:33], v[134:135]
	v_pk_mul_f32 v[36:37], v[44:45], v[32:33] op_sel:[0,1] op_sel_hi:[0,0]
	v_pk_mul_f32 v[34:35], v[60:61], v[32:33]
	v_pk_fma_f32 v[32:33], v[60:61], v[32:33], v[36:37] op_sel_hi:[0,1,1]
	v_sub_f32_e32 v32, v34, v36
	s_branch .LBB0_2530

.LBB0_2545:
	s_and_b64 vcc, exec, s[34:35]
	s_cbranch_vccz .LBB0_2553
	s_and_b64 vcc, exec, s[8:9]
	s_cbranch_vccnz .LBB0_2555
	v_mov_b64_e32 v[34:35], v[136:137]
	v_mov_b32_e32 v38, v45
	v_mov_b32_e32 v36, v61
	v_pk_mul_f32 v[38:39], v[38:39], v[34:35] op_sel:[0,1] op_sel_hi:[0,0]
	v_pk_mul_f32 v[40:41], v[36:37], v[34:35] op_sel_hi:[0,1]
	v_pk_fma_f32 v[34:35], v[36:37], v[34:35], v[38:39] op_sel_hi:[0,1,1]
	v_sub_f32_e32 v34, v40, v38
	s_branch .LBB0_2556

.LBB0_2571:
	s_and_b64 vcc, exec, s[34:35]
	s_cbranch_vccz .LBB0_2579
	s_and_b64 vcc, exec, s[8:9]
	s_cbranch_vccnz .LBB0_2581
	v_mov_b64_e32 v[36:37], v[138:139]
	v_pk_mul_f32 v[40:41], v[46:47], v[36:37] op_sel:[0,1] op_sel_hi:[0,0]
	v_pk_mul_f32 v[38:39], v[62:63], v[36:37]
	v_pk_fma_f32 v[36:37], v[62:63], v[36:37], v[40:41] op_sel_hi:[0,1,1]
	v_sub_f32_e32 v36, v38, v40
	s_branch .LBB0_2582

.LBB0_2597:
	s_and_b64 vcc, exec, s[34:35]
	s_cbranch_vccz .LBB0_2605
	s_and_b64 vcc, exec, s[8:9]
	s_cbranch_vccnz .LBB0_2607
	v_mov_b64_e32 v[38:39], v[140:141]
	v_mov_b32_e32 v42, v47
	v_mov_b32_e32 v40, v63
	v_pk_mul_f32 v[42:43], v[42:43], v[38:39] op_sel:[0,1] op_sel_hi:[0,0]
	v_pk_mul_f32 v[44:45], v[40:41], v[38:39] op_sel_hi:[0,1]
	v_pk_fma_f32 v[38:39], v[40:41], v[38:39], v[42:43] op_sel_hi:[0,1,1]
	v_sub_f32_e32 v38, v44, v42
	s_branch .LBB0_2608

.LBB0_2615:
	s_and_b64 vcc, exec, s[34:35]
	s_cbranch_vccz .LBB0_2633
	s_and_b64 vcc, exec, s[8:9]
	s_cbranch_vccnz .LBB0_2635
	v_mov_b64_e32 v[32:33], v[142:143]
	v_pk_mul_f32 v[36:37], v[0:1], v[32:33] op_sel:[0,1] op_sel_hi:[0,0]
	v_pk_mul_f32 v[34:35], v[16:17], v[32:33]
	v_pk_fma_f32 v[32:33], v[16:17], v[32:33], v[36:37] op_sel_hi:[0,1,1]
	v_sub_f32_e32 v32, v34, v36
	s_branch .LBB0_2636

.LBB0_2651:
	s_and_b64 vcc, exec, s[34:35]
	s_cbranch_vccz .LBB0_2659
	s_and_b64 vcc, exec, s[8:9]
	s_cbranch_vccnz .LBB0_2661
	v_mov_b64_e32 v[34:35], v[144:145]
	v_pk_mul_f32 v[38:39], v[0:1], v[34:35] op_sel:[1,1] op_sel_hi:[1,0]
	v_pk_mul_f32 v[36:37], v[16:17], v[34:35] op_sel:[1,0]
	v_pk_fma_f32 v[34:35], v[16:17], v[34:35], v[38:39] op_sel:[1,0,0]
	s_nop 0
	v_sub_f32_e32 v34, v36, v38
	s_branch .LBB0_2662

.LBB0_2677:
	s_and_b64 vcc, exec, s[34:35]
	s_cbranch_vccz .LBB0_2685
	s_and_b64 vcc, exec, s[8:9]
	s_cbranch_vccnz .LBB0_2687
	v_mov_b64_e32 v[0:1], v[146:147]
	v_pk_mul_f32 v[36:37], v[2:3], v[0:1] op_sel:[0,1] op_sel_hi:[0,0]
	v_pk_mul_f32 v[16:17], v[18:19], v[0:1]
	v_pk_fma_f32 v[0:1], v[18:19], v[0:1], v[36:37] op_sel_hi:[0,1,1]
	v_sub_f32_e32 v0, v16, v36
	s_branch .LBB0_2688

.LBB0_2703:
	s_and_b64 vcc, exec, s[34:35]
	s_cbranch_vccz .LBB0_2711
	s_and_b64 vcc, exec, s[8:9]
	s_cbranch_vccnz .LBB0_2713
	v_mov_b64_e32 v[16:17], v[148:149]
	v_mov_b32_e32 v18, v3
	v_mov_b32_e32 v2, v19
	v_pk_mul_f32 v[38:39], v[18:19], v[16:17] op_sel:[0,1] op_sel_hi:[0,0]
	v_pk_mul_f32 v[36:37], v[2:3], v[16:17] op_sel_hi:[0,1]
	v_pk_fma_f32 v[16:17], v[2:3], v[16:17], v[38:39] op_sel_hi:[0,1,1]
	v_sub_f32_e32 v16, v36, v38
	s_branch .LBB0_2714

.LBB0_2721:
	s_and_b64 vcc, exec, s[34:35]
	s_cbranch_vccz .LBB0_2739
	s_and_b64 vcc, exec, s[8:9]
	s_cbranch_vccnz .LBB0_2741
	v_mov_b64_e32 v[0:1], v[150:151]
	v_pk_mul_f32 v[16:17], v[4:5], v[0:1] op_sel:[0,1] op_sel_hi:[0,0]
	v_pk_mul_f32 v[2:3], v[20:21], v[0:1]
	v_pk_fma_f32 v[0:1], v[20:21], v[0:1], v[16:17] op_sel_hi:[0,1,1]
	v_sub_f32_e32 v0, v2, v16
	s_branch .LBB0_2742

.LBB0_2757:
	s_and_b64 vcc, exec, s[34:35]
	s_cbranch_vccz .LBB0_2765
	s_and_b64 vcc, exec, s[8:9]
	s_cbranch_vccnz .LBB0_2767
	v_mov_b64_e32 v[2:3], v[152:153]
	v_mov_b32_e32 v16, v5
	v_mov_b32_e32 v4, v21
	v_pk_mul_f32 v[16:17], v[16:17], v[2:3] op_sel:[0,1] op_sel_hi:[0,0]
	v_pk_mul_f32 v[18:19], v[4:5], v[2:3] op_sel_hi:[0,1]
	v_pk_fma_f32 v[2:3], v[4:5], v[2:3], v[16:17] op_sel_hi:[0,1,1]
	v_sub_f32_e32 v2, v18, v16
	s_branch .LBB0_2768

.LBB0_2783:
	s_and_b64 vcc, exec, s[34:35]
	s_cbranch_vccz .LBB0_2791
	s_and_b64 vcc, exec, s[8:9]
	s_cbranch_vccnz .LBB0_2793
	v_mov_b64_e32 v[4:5], v[154:155]
	v_pk_mul_f32 v[18:19], v[6:7], v[4:5] op_sel:[0,1] op_sel_hi:[0,0]
	v_pk_mul_f32 v[16:17], v[22:23], v[4:5]
	v_pk_fma_f32 v[4:5], v[22:23], v[4:5], v[18:19] op_sel_hi:[0,1,1]
	v_sub_f32_e32 v4, v16, v18
	s_branch .LBB0_2794

.LBB0_2809:
	s_and_b64 vcc, exec, s[34:35]
	s_cbranch_vccz .LBB0_2817
	s_and_b64 vcc, exec, s[8:9]
	s_cbranch_vccnz .LBB0_2819
	v_mov_b64_e32 v[16:17], v[156:157]
	v_mov_b32_e32 v18, v7
	v_mov_b32_e32 v6, v23
	v_pk_mul_f32 v[18:19], v[18:19], v[16:17] op_sel:[0,1] op_sel_hi:[0,0]
	v_pk_mul_f32 v[20:21], v[6:7], v[16:17] op_sel_hi:[0,1]
	v_pk_fma_f32 v[16:17], v[6:7], v[16:17], v[18:19] op_sel_hi:[0,1,1]
	v_sub_f32_e32 v16, v20, v18
	s_branch .LBB0_2820

.LBB0_2827:
	s_and_b64 vcc, exec, s[34:35]
	s_cbranch_vccz .LBB0_2845
	s_and_b64 vcc, exec, s[8:9]
	s_cbranch_vccnz .LBB0_2847
	v_mov_b64_e32 v[0:1], v[158:159]
	v_pk_mul_f32 v[4:5], v[8:9], v[0:1] op_sel:[0,1] op_sel_hi:[0,0]
	v_pk_mul_f32 v[2:3], v[24:25], v[0:1]
	v_pk_fma_f32 v[0:1], v[24:25], v[0:1], v[4:5] op_sel_hi:[0,1,1]
	v_sub_f32_e32 v0, v2, v4
	s_branch .LBB0_2848

.LBB0_2863:
	s_and_b64 vcc, exec, s[34:35]
	s_cbranch_vccz .LBB0_2871
	s_and_b64 vcc, exec, s[8:9]
	s_cbranch_vccnz .LBB0_2873
	v_mov_b64_e32 v[2:3], v[160:161]
	v_mov_b32_e32 v6, v9
	v_mov_b32_e32 v4, v25
	v_pk_mul_f32 v[6:7], v[6:7], v[2:3] op_sel:[0,1] op_sel_hi:[0,0]
	v_pk_mul_f32 v[16:17], v[4:5], v[2:3] op_sel_hi:[0,1]
	v_pk_fma_f32 v[2:3], v[4:5], v[2:3], v[6:7] op_sel_hi:[0,1,1]
	v_sub_f32_e32 v2, v16, v6
	s_branch .LBB0_2874

.LBB0_2889:
	s_and_b64 vcc, exec, s[34:35]
	s_cbranch_vccz .LBB0_2897
	s_and_b64 vcc, exec, s[8:9]
	s_cbranch_vccnz .LBB0_2899
	v_mov_b64_e32 v[4:5], v[162:163]
	v_pk_mul_f32 v[8:9], v[10:11], v[4:5] op_sel:[0,1] op_sel_hi:[0,0]
	v_pk_mul_f32 v[6:7], v[26:27], v[4:5]
	v_pk_fma_f32 v[4:5], v[26:27], v[4:5], v[8:9] op_sel_hi:[0,1,1]
	v_sub_f32_e32 v4, v6, v8
	s_branch .LBB0_2900

.LBB0_2915:
	s_and_b64 vcc, exec, s[34:35]
	s_cbranch_vccz .LBB0_2923
	s_and_b64 vcc, exec, s[8:9]
	s_cbranch_vccnz .LBB0_2925
	v_mov_b64_e32 v[6:7], v[164:165]
	v_mov_b32_e32 v10, v11
	v_mov_b32_e32 v8, v27
	v_pk_mul_f32 v[18:19], v[10:11], v[6:7] op_sel:[0,1] op_sel_hi:[0,0]
	v_pk_mul_f32 v[16:17], v[8:9], v[6:7] op_sel_hi:[0,1]
	v_pk_fma_f32 v[6:7], v[8:9], v[6:7], v[18:19] op_sel_hi:[0,1,1]
	v_sub_f32_e32 v6, v16, v18
	s_branch .LBB0_2926

.LBB0_2933:
	s_and_b64 vcc, exec, s[34:35]
	s_cbranch_vccz .LBB0_2951
	s_and_b64 vcc, exec, s[8:9]
	s_cbranch_vccnz .LBB0_2953
	v_mov_b64_e32 v[0:1], v[166:167]
	v_pk_mul_f32 v[4:5], v[12:13], v[0:1] op_sel:[0,1] op_sel_hi:[0,0]
	v_pk_mul_f32 v[2:3], v[28:29], v[0:1]
	v_pk_fma_f32 v[0:1], v[28:29], v[0:1], v[4:5] op_sel_hi:[0,1,1]
	v_sub_f32_e32 v0, v2, v4
	s_branch .LBB0_2954

.LBB0_2969:
	s_and_b64 vcc, exec, s[34:35]
	s_cbranch_vccz .LBB0_2977
	s_and_b64 vcc, exec, s[8:9]
	s_cbranch_vccnz .LBB0_2979
	v_mov_b64_e32 v[2:3], v[168:169]
	v_mov_b32_e32 v6, v13
	v_mov_b32_e32 v4, v29
	v_pk_mul_f32 v[6:7], v[6:7], v[2:3] op_sel:[0,1] op_sel_hi:[0,0]
	v_pk_mul_f32 v[8:9], v[4:5], v[2:3] op_sel_hi:[0,1]
	v_pk_fma_f32 v[2:3], v[4:5], v[2:3], v[6:7] op_sel_hi:[0,1,1]
	v_sub_f32_e32 v2, v8, v6
	s_branch .LBB0_2980

.LBB0_2995:
	s_and_b64 vcc, exec, s[34:35]
	s_cbranch_vccz .LBB0_3003
	s_and_b64 vcc, exec, s[8:9]
	s_cbranch_vccnz .LBB0_3005
	v_mov_b64_e32 v[4:5], v[170:171]
	v_pk_mul_f32 v[8:9], v[14:15], v[4:5] op_sel:[0,1] op_sel_hi:[0,0]
	v_pk_mul_f32 v[6:7], v[30:31], v[4:5]
	v_pk_fma_f32 v[4:5], v[30:31], v[4:5], v[8:9] op_sel_hi:[0,1,1]
	v_sub_f32_e32 v4, v6, v8
	s_branch .LBB0_3006

.LBB0_3021:
	s_and_b64 vcc, exec, s[12:13]
	s_cbranch_vccz .LBB0_3029
	s_and_b64 vcc, exec, s[8:9]
	s_cbranch_vccnz .LBB0_3031
	v_mov_b64_e32 v[6:7], v[172:173]
	v_mov_b32_e32 v10, v15
	v_mov_b32_e32 v8, v31
	v_pk_mul_f32 v[10:11], v[10:11], v[6:7] op_sel:[0,1] op_sel_hi:[0,0]
	v_pk_mul_f32 v[12:13], v[8:9], v[6:7] op_sel_hi:[0,1]
	v_pk_fma_f32 v[6:7], v[8:9], v[6:7], v[10:11] op_sel_hi:[0,1,1]
	v_sub_f32_e32 v6, v12, v10
	s_branch .LBB0_3032

.LBB0_3171:
	v_lshl_add_u64 v[0:1], v[74:75], 0, s[4:5]
	s_mov_b32 s0, 0xab93000
	v_add_co_u32_e64 v82, s[0:1], s0, v0
	s_nop 1
	v_addc_co_u32_e64 v83, s[0:1], 0, v1, s[0:1]
	v_lshl_add_u64 v[0:1], v[76:77], 0, s[4:5]
	s_mov_b32 s0, 0xdf93000
	v_add_co_u32_e64 v78, s[0:1], s0, v0
	s_nop 1
	v_addc_co_u32_e64 v79, s[0:1], 0, v1, s[0:1]
	s_mov_b32 s0, 0xdf97000
	v_add_co_u32_e64 v80, s[0:1], s0, v0
	s_nop 1
	v_addc_co_u32_e64 v81, s[0:1], 0, v1, s[0:1]
	s_mov_b32 s0, 0xdf9b000
	v_add_co_u32_e64 v90, s[0:1], s0, v0
	s_nop 1
	v_addc_co_u32_e64 v91, s[0:1], 0, v1, s[0:1]
	s_mov_b32 s0, 0xdf9f000
	v_add_co_u32_e64 v92, s[0:1], s0, v0
	s_nop 1
	v_addc_co_u32_e64 v93, s[0:1], 0, v1, s[0:1]
	global_load_dwordx4 v[112:115], v[82:83], off offset:3584
	global_load_dwordx4 v[116:119], v[82:83], off offset:3616
	global_load_dwordx4 v[120:123], v[78:79], off offset:3584
	global_load_dwordx4 v[124:127], v[80:81], off offset:3584
	global_load_dwordx4 v[128:131], v[90:91], off offset:3584
	global_load_dwordx4 v[132:135], v[92:93], off offset:3584
	global_load_dwordx4 v[136:139], v[78:79], off offset:3616
	global_load_dwordx4 v[140:143], v[80:81], off offset:3616
	global_load_dwordx4 v[144:147], v[90:91], off offset:3616
	global_load_dwordx4 v[148:151], v[92:93], off offset:3616
	global_load_dwordx4 v[152:155], v[82:83], off offset:3648
	global_load_dwordx4 v[156:159], v[82:83], off offset:3680
	global_load_dwordx4 v[160:163], v[78:79], off offset:3648
	global_load_dwordx4 v[168:171], v[80:81], off offset:3648
	global_load_dwordx4 v[172:175], v[90:91], off offset:3648
	global_load_dwordx4 v[176:179], v[92:93], off offset:3648
	global_load_dwordx4 v[180:183], v[78:79], off offset:3680
	global_load_dwordx4 v[184:187], v[80:81], off offset:3680
	global_load_dwordx4 v[188:191], v[90:91], off offset:3680
	global_load_dwordx4 v[192:195], v[92:93], off offset:3680
	v_add_u32_e32 v70, 0xfffffff0, v89
	v_add_u32_e32 v72, 0xff, v88
	v_add_u32_e32 v71, 0xfffffff1, v89
	v_cndmask_b32_e32 v70, v70, v72, vcc
	v_add_u32_e32 v72, 0xfe, v88
	v_cndmask_b32_e32 v71, v71, v72, vcc
	v_cvt_f32_u32_e32 v70, v70
	v_cvt_f32_u32_e32 v71, v71
	v_mul_f32_e32 v70, v87, v70
	v_mul_f32_e32 v71, v87, v71
	v_exp_f32_e32 v70, v70
	v_exp_f32_e32 v71, v71
	s_waitcnt vmcnt(19)
	v_lshlrev_b32_e32 v72, 16, v112
	v_and_b32_e32 v73, 0xffff0000, v112
	v_pk_mul_f32 v[70:71], v[70:71], v[72:73]
	s_nop 0
	v_cvt_pk_bf16_f32 v112, v70, v71
	v_add_u32_e32 v70, 0xfffffff2, v89
	v_add_u32_e32 v72, 0xfd, v88
	v_add_u32_e32 v71, 0xfffffff3, v89
	v_cndmask_b32_e32 v70, v70, v72, vcc
	v_add_u32_e32 v72, 0xfc, v88
	v_cndmask_b32_e32 v71, v71, v72, vcc
	v_cvt_f32_u32_e32 v70, v70
	v_cvt_f32_u32_e32 v71, v71
	v_mul_f32_e32 v70, v87, v70
	v_mul_f32_e32 v71, v87, v71
	v_exp_f32_e32 v70, v70
	v_exp_f32_e32 v71, v71
	v_lshlrev_b32_e32 v72, 16, v113
	v_and_b32_e32 v73, 0xffff0000, v113
	v_pk_mul_f32 v[70:71], v[70:71], v[72:73]
	s_nop 0
	v_cvt_pk_bf16_f32 v113, v70, v71
	v_add_u32_e32 v70, 0xfffffff4, v89
	v_add_u32_e32 v72, 0xfb, v88
	v_add_u32_e32 v71, 0xfffffff5, v89
	v_cndmask_b32_e32 v70, v70, v72, vcc
	v_add_u32_e32 v72, 0xfa, v88
	v_cndmask_b32_e32 v71, v71, v72, vcc
	v_cvt_f32_u32_e32 v70, v70
	v_cvt_f32_u32_e32 v71, v71
	v_mul_f32_e32 v70, v87, v70
	v_mul_f32_e32 v71, v87, v71
	v_exp_f32_e32 v70, v70
	v_exp_f32_e32 v71, v71
	v_lshlrev_b32_e32 v72, 16, v114
	v_and_b32_e32 v73, 0xffff0000, v114
	v_pk_mul_f32 v[70:71], v[70:71], v[72:73]
	s_nop 0
	v_cvt_pk_bf16_f32 v114, v70, v71
	v_add_u32_e32 v70, 0xfffffff6, v89
	v_add_u32_e32 v72, 0xf9, v88
	v_add_u32_e32 v71, 0xfffffff7, v89
	v_cndmask_b32_e32 v70, v70, v72, vcc
	v_add_u32_e32 v72, 0xf8, v88
	v_cndmask_b32_e32 v71, v71, v72, vcc
	v_cvt_f32_u32_e32 v70, v70
	v_cvt_f32_u32_e32 v71, v71
	v_mul_f32_e32 v70, v87, v70
	v_mul_f32_e32 v71, v87, v71
	v_exp_f32_e32 v70, v70
	v_exp_f32_e32 v71, v71
	v_lshlrev_b32_e32 v72, 16, v115
	v_and_b32_e32 v73, 0xffff0000, v115
	v_pk_mul_f32 v[70:71], v[70:71], v[72:73]
	s_nop 0
	v_cvt_pk_bf16_f32 v115, v70, v71
	s_waitcnt vmcnt(17)
	v_mfma_f32_32x32x16_bf16 v[54:69], v[112:115], v[120:123], v[54:69]
	s_waitcnt vmcnt(16)
	v_mfma_f32_32x32x16_bf16 v[38:53], v[112:115], v[124:127], v[38:53]
	s_waitcnt vmcnt(15)
	v_mfma_f32_32x32x16_bf16 v[22:37], v[112:115], v[128:131], v[22:37]
	s_waitcnt vmcnt(14)
	v_mfma_f32_32x32x16_bf16 v[6:21], v[112:115], v[132:135], v[6:21]
	v_add_u32_e32 v70, 0x0, v89
	v_add_u32_e32 v72, 0xef, v88
	v_add_u32_e32 v71, 0x1, v89
	v_cndmask_b32_e32 v70, v70, v72, vcc
	v_add_u32_e32 v72, 0xee, v88
	v_cndmask_b32_e32 v71, v71, v72, vcc
	v_cvt_f32_u32_e32 v70, v70
	v_cvt_f32_u32_e32 v71, v71
	v_mul_f32_e32 v70, v87, v70
	v_mul_f32_e32 v71, v87, v71
	v_exp_f32_e32 v70, v70
	v_exp_f32_e32 v71, v71
	v_lshlrev_b32_e32 v72, 16, v116
	v_and_b32_e32 v73, 0xffff0000, v116
	v_pk_mul_f32 v[70:71], v[70:71], v[72:73]
	s_nop 0
	v_cvt_pk_bf16_f32 v116, v70, v71
	v_add_u32_e32 v70, 0x2, v89
	v_add_u32_e32 v72, 0xed, v88
	v_add_u32_e32 v71, 0x3, v89
	v_cndmask_b32_e32 v70, v70, v72, vcc
	v_add_u32_e32 v72, 0xec, v88
	v_cndmask_b32_e32 v71, v71, v72, vcc
	v_cvt_f32_u32_e32 v70, v70
	v_cvt_f32_u32_e32 v71, v71
	v_mul_f32_e32 v70, v87, v70
	v_mul_f32_e32 v71, v87, v71
	v_exp_f32_e32 v70, v70
	v_exp_f32_e32 v71, v71
	v_lshlrev_b32_e32 v72, 16, v117
	v_and_b32_e32 v73, 0xffff0000, v117
	v_pk_mul_f32 v[70:71], v[70:71], v[72:73]
	s_nop 0
	v_cvt_pk_bf16_f32 v117, v70, v71
	v_add_u32_e32 v70, 0x4, v89
	v_add_u32_e32 v72, 0xeb, v88
	v_add_u32_e32 v71, 0x5, v89
	v_cndmask_b32_e32 v70, v70, v72, vcc
	v_add_u32_e32 v72, 0xea, v88
	v_cndmask_b32_e32 v71, v71, v72, vcc
	v_cvt_f32_u32_e32 v70, v70
	v_cvt_f32_u32_e32 v71, v71
	v_mul_f32_e32 v70, v87, v70
	v_mul_f32_e32 v71, v87, v71
	v_exp_f32_e32 v70, v70
	v_exp_f32_e32 v71, v71
	v_lshlrev_b32_e32 v72, 16, v118
	v_and_b32_e32 v73, 0xffff0000, v118
	v_pk_mul_f32 v[70:71], v[70:71], v[72:73]
	s_nop 0
	v_cvt_pk_bf16_f32 v118, v70, v71
	v_add_u32_e32 v70, 0x6, v89
	v_add_u32_e32 v72, 0xe9, v88
	v_add_u32_e32 v71, 0x7, v89
	v_cndmask_b32_e32 v70, v70, v72, vcc
	v_add_u32_e32 v72, 0xe8, v88
	v_cndmask_b32_e32 v71, v71, v72, vcc
	v_cvt_f32_u32_e32 v70, v70
	v_cvt_f32_u32_e32 v71, v71
	v_mul_f32_e32 v70, v87, v70
	v_mul_f32_e32 v71, v87, v71
	v_exp_f32_e32 v70, v70
	v_exp_f32_e32 v71, v71
	v_lshlrev_b32_e32 v72, 16, v119
	v_and_b32_e32 v73, 0xffff0000, v119
	v_pk_mul_f32 v[70:71], v[70:71], v[72:73]
	s_nop 0
	v_cvt_pk_bf16_f32 v119, v70, v71
	s_waitcnt vmcnt(13)
	v_mfma_f32_32x32x16_bf16 v[54:69], v[116:119], v[136:139], v[54:69]
	s_waitcnt vmcnt(11)
	v_mfma_f32_32x32x16_bf16 v[22:37], v[116:119], v[144:147], v[22:37]
	v_mfma_f32_32x32x16_bf16 v[38:53], v[116:119], v[140:143], v[38:53]
	s_waitcnt vmcnt(10)
	v_mfma_f32_32x32x16_bf16 v[6:21], v[116:119], v[148:151], v[6:21]
	global_load_dwordx4 v[112:115], v[82:83], off offset:3712
	global_load_dwordx4 v[116:119], v[82:83], off offset:3744
	global_load_dwordx4 v[120:123], v[78:79], off offset:3712
	global_load_dwordx4 v[124:127], v[80:81], off offset:3712
	global_load_dwordx4 v[128:131], v[90:91], off offset:3712
	global_load_dwordx4 v[132:135], v[92:93], off offset:3712
	global_load_dwordx4 v[136:139], v[78:79], off offset:3744
	global_load_dwordx4 v[140:143], v[80:81], off offset:3744
	global_load_dwordx4 v[144:147], v[90:91], off offset:3744
	global_load_dwordx4 v[148:151], v[92:93], off offset:3744
	v_add_u32_e32 v70, 0x10, v89
	v_add_u32_e32 v72, 0xdf, v88
	v_add_u32_e32 v71, 0x11, v89
	v_cndmask_b32_e32 v70, v70, v72, vcc
	v_add_u32_e32 v72, 0xde, v88
	v_cndmask_b32_e32 v71, v71, v72, vcc
	v_cvt_f32_u32_e32 v70, v70
	v_cvt_f32_u32_e32 v71, v71
	v_mul_f32_e32 v70, v87, v70
	v_mul_f32_e32 v71, v87, v71
	v_exp_f32_e32 v70, v70
	v_exp_f32_e32 v71, v71
	s_waitcnt vmcnt(19)
	v_lshlrev_b32_e32 v72, 16, v152
	v_and_b32_e32 v73, 0xffff0000, v152
	v_pk_mul_f32 v[70:71], v[70:71], v[72:73]
	s_nop 0
	v_cvt_pk_bf16_f32 v152, v70, v71
	v_add_u32_e32 v70, 0x12, v89
	v_add_u32_e32 v72, 0xdd, v88
	v_add_u32_e32 v71, 0x13, v89
	v_cndmask_b32_e32 v70, v70, v72, vcc
	v_add_u32_e32 v72, 0xdc, v88
	v_cndmask_b32_e32 v71, v71, v72, vcc
	v_cvt_f32_u32_e32 v70, v70
	v_cvt_f32_u32_e32 v71, v71
	v_mul_f32_e32 v70, v87, v70
	v_mul_f32_e32 v71, v87, v71
	v_exp_f32_e32 v70, v70
	v_exp_f32_e32 v71, v71
	v_lshlrev_b32_e32 v72, 16, v153
	v_and_b32_e32 v73, 0xffff0000, v153
	v_pk_mul_f32 v[70:71], v[70:71], v[72:73]
	s_nop 0
	v_cvt_pk_bf16_f32 v153, v70, v71
	v_add_u32_e32 v70, 0x14, v89
	v_add_u32_e32 v72, 0xdb, v88
	v_add_u32_e32 v71, 0x15, v89
	v_cndmask_b32_e32 v70, v70, v72, vcc
	v_add_u32_e32 v72, 0xda, v88
	v_cndmask_b32_e32 v71, v71, v72, vcc
	v_cvt_f32_u32_e32 v70, v70
	v_cvt_f32_u32_e32 v71, v71
	v_mul_f32_e32 v70, v87, v70
	v_mul_f32_e32 v71, v87, v71
	v_exp_f32_e32 v70, v70
	v_exp_f32_e32 v71, v71
	v_lshlrev_b32_e32 v72, 16, v154
	v_and_b32_e32 v73, 0xffff0000, v154
	v_pk_mul_f32 v[70:71], v[70:71], v[72:73]
	s_nop 0
	v_cvt_pk_bf16_f32 v154, v70, v71
	v_add_u32_e32 v70, 0x16, v89
	v_add_u32_e32 v72, 0xd9, v88
	v_add_u32_e32 v71, 0x17, v89
	v_cndmask_b32_e32 v70, v70, v72, vcc
	v_add_u32_e32 v72, 0xd8, v88
	v_cndmask_b32_e32 v71, v71, v72, vcc
	v_cvt_f32_u32_e32 v70, v70
	v_cvt_f32_u32_e32 v71, v71
	v_mul_f32_e32 v70, v87, v70
	v_mul_f32_e32 v71, v87, v71
	v_exp_f32_e32 v70, v70
	v_exp_f32_e32 v71, v71
	v_lshlrev_b32_e32 v72, 16, v155
	v_and_b32_e32 v73, 0xffff0000, v155
	v_pk_mul_f32 v[70:71], v[70:71], v[72:73]
	s_nop 0
	v_cvt_pk_bf16_f32 v155, v70, v71
	s_waitcnt vmcnt(17)
	v_mfma_f32_32x32x16_bf16 v[54:69], v[152:155], v[160:163], v[54:69]
	s_waitcnt vmcnt(16)
	v_mfma_f32_32x32x16_bf16 v[38:53], v[152:155], v[168:171], v[38:53]
	s_waitcnt vmcnt(15)
	v_mfma_f32_32x32x16_bf16 v[22:37], v[152:155], v[172:175], v[22:37]
	s_waitcnt vmcnt(14)
	v_mfma_f32_32x32x16_bf16 v[6:21], v[152:155], v[176:179], v[6:21]
	v_add_u32_e32 v70, 0x20, v89
	v_add_u32_e32 v72, 0xcf, v88
	v_add_u32_e32 v71, 0x21, v89
	v_cndmask_b32_e32 v70, v70, v72, vcc
	v_add_u32_e32 v72, 0xce, v88
	v_cndmask_b32_e32 v71, v71, v72, vcc
	v_cvt_f32_u32_e32 v70, v70
	v_cvt_f32_u32_e32 v71, v71
	v_mul_f32_e32 v70, v87, v70
	v_mul_f32_e32 v71, v87, v71
	v_exp_f32_e32 v70, v70
	v_exp_f32_e32 v71, v71
	v_lshlrev_b32_e32 v72, 16, v156
	v_and_b32_e32 v73, 0xffff0000, v156
	v_pk_mul_f32 v[70:71], v[70:71], v[72:73]
	s_nop 0
	v_cvt_pk_bf16_f32 v156, v70, v71
	v_add_u32_e32 v70, 0x22, v89
	v_add_u32_e32 v72, 0xcd, v88
	v_add_u32_e32 v71, 0x23, v89
	v_cndmask_b32_e32 v70, v70, v72, vcc
	v_add_u32_e32 v72, 0xcc, v88
	v_cndmask_b32_e32 v71, v71, v72, vcc
	v_cvt_f32_u32_e32 v70, v70
	v_cvt_f32_u32_e32 v71, v71
	v_mul_f32_e32 v70, v87, v70
	v_mul_f32_e32 v71, v87, v71
	v_exp_f32_e32 v70, v70
	v_exp_f32_e32 v71, v71
	v_lshlrev_b32_e32 v72, 16, v157
	v_and_b32_e32 v73, 0xffff0000, v157
	v_pk_mul_f32 v[70:71], v[70:71], v[72:73]
	s_nop 0
	v_cvt_pk_bf16_f32 v157, v70, v71
	v_add_u32_e32 v70, 0x24, v89
	v_add_u32_e32 v72, 0xcb, v88
	v_add_u32_e32 v71, 0x25, v89
	v_cndmask_b32_e32 v70, v70, v72, vcc
	v_add_u32_e32 v72, 0xca, v88
	v_cndmask_b32_e32 v71, v71, v72, vcc
	v_cvt_f32_u32_e32 v70, v70
	v_cvt_f32_u32_e32 v71, v71
	v_mul_f32_e32 v70, v87, v70
	v_mul_f32_e32 v71, v87, v71
	v_exp_f32_e32 v70, v70
	v_exp_f32_e32 v71, v71
	v_lshlrev_b32_e32 v72, 16, v158
	v_and_b32_e32 v73, 0xffff0000, v158
	v_pk_mul_f32 v[70:71], v[70:71], v[72:73]
	s_nop 0
	v_cvt_pk_bf16_f32 v158, v70, v71
	v_add_u32_e32 v70, 0x26, v89
	v_add_u32_e32 v72, 0xc9, v88
	v_add_u32_e32 v71, 0x27, v89
	v_cndmask_b32_e32 v70, v70, v72, vcc
	v_add_u32_e32 v72, 0xc8, v88
	v_cndmask_b32_e32 v71, v71, v72, vcc
	v_cvt_f32_u32_e32 v70, v70
	v_cvt_f32_u32_e32 v71, v71
	v_mul_f32_e32 v70, v87, v70
	v_mul_f32_e32 v71, v87, v71
	v_exp_f32_e32 v70, v70
	v_exp_f32_e32 v71, v71
	v_lshlrev_b32_e32 v72, 16, v159
	v_and_b32_e32 v73, 0xffff0000, v159
	v_pk_mul_f32 v[70:71], v[70:71], v[72:73]
	s_nop 0
	v_cvt_pk_bf16_f32 v159, v70, v71
	s_waitcnt vmcnt(13)
	v_mfma_f32_32x32x16_bf16 v[54:69], v[156:159], v[180:183], v[54:69]
	s_waitcnt vmcnt(11)
	v_mfma_f32_32x32x16_bf16 v[22:37], v[156:159], v[188:191], v[22:37]
	v_mfma_f32_32x32x16_bf16 v[38:53], v[156:159], v[184:187], v[38:53]
	s_waitcnt vmcnt(10)
	v_mfma_f32_32x32x16_bf16 v[6:21], v[156:159], v[192:195], v[6:21]
	global_load_dwordx4 v[152:155], v[82:83], off offset:3776
	global_load_dwordx4 v[156:159], v[82:83], off offset:3808
	global_load_dwordx4 v[160:163], v[78:79], off offset:3776
	global_load_dwordx4 v[168:171], v[80:81], off offset:3776
	global_load_dwordx4 v[172:175], v[90:91], off offset:3776
	global_load_dwordx4 v[176:179], v[92:93], off offset:3776
	global_load_dwordx4 v[180:183], v[78:79], off offset:3808
	global_load_dwordx4 v[184:187], v[80:81], off offset:3808
	global_load_dwordx4 v[188:191], v[90:91], off offset:3808
	global_load_dwordx4 v[192:195], v[92:93], off offset:3808
	v_add_u32_e32 v70, 0x30, v89
	v_add_u32_e32 v72, 0xbf, v88
	v_add_u32_e32 v71, 0x31, v89
	v_cndmask_b32_e32 v70, v70, v72, vcc
	v_add_u32_e32 v72, 0xbe, v88
	v_cndmask_b32_e32 v71, v71, v72, vcc
	v_cvt_f32_u32_e32 v70, v70
	v_cvt_f32_u32_e32 v71, v71
	v_mul_f32_e32 v70, v87, v70
	v_mul_f32_e32 v71, v87, v71
	v_exp_f32_e32 v70, v70
	v_exp_f32_e32 v71, v71
	s_waitcnt vmcnt(19)
	v_lshlrev_b32_e32 v72, 16, v112
	v_and_b32_e32 v73, 0xffff0000, v112
	v_pk_mul_f32 v[70:71], v[70:71], v[72:73]
	s_nop 0
	v_cvt_pk_bf16_f32 v112, v70, v71
	v_add_u32_e32 v70, 0x32, v89
	v_add_u32_e32 v72, 0xbd, v88
	v_add_u32_e32 v71, 0x33, v89
	v_cndmask_b32_e32 v70, v70, v72, vcc
	v_add_u32_e32 v72, 0xbc, v88
	v_cndmask_b32_e32 v71, v71, v72, vcc
	v_cvt_f32_u32_e32 v70, v70
	v_cvt_f32_u32_e32 v71, v71
	v_mul_f32_e32 v70, v87, v70
	v_mul_f32_e32 v71, v87, v71
	v_exp_f32_e32 v70, v70
	v_exp_f32_e32 v71, v71
	v_lshlrev_b32_e32 v72, 16, v113
	v_and_b32_e32 v73, 0xffff0000, v113
	v_pk_mul_f32 v[70:71], v[70:71], v[72:73]
	s_nop 0
	v_cvt_pk_bf16_f32 v113, v70, v71
	v_add_u32_e32 v70, 0x34, v89
	v_add_u32_e32 v72, 0xbb, v88
	v_add_u32_e32 v71, 0x35, v89
	v_cndmask_b32_e32 v70, v70, v72, vcc
	v_add_u32_e32 v72, 0xba, v88
	v_cndmask_b32_e32 v71, v71, v72, vcc
	v_cvt_f32_u32_e32 v70, v70
	v_cvt_f32_u32_e32 v71, v71
	v_mul_f32_e32 v70, v87, v70
	v_mul_f32_e32 v71, v87, v71
	v_exp_f32_e32 v70, v70
	v_exp_f32_e32 v71, v71
	v_lshlrev_b32_e32 v72, 16, v114
	v_and_b32_e32 v73, 0xffff0000, v114
	v_pk_mul_f32 v[70:71], v[70:71], v[72:73]
	s_nop 0
	v_cvt_pk_bf16_f32 v114, v70, v71
	v_add_u32_e32 v70, 0x36, v89
	v_add_u32_e32 v72, 0xb9, v88
	v_add_u32_e32 v71, 0x37, v89
	v_cndmask_b32_e32 v70, v70, v72, vcc
	v_add_u32_e32 v72, 0xb8, v88
	v_cndmask_b32_e32 v71, v71, v72, vcc
	v_cvt_f32_u32_e32 v70, v70
	v_cvt_f32_u32_e32 v71, v71
	v_mul_f32_e32 v70, v87, v70
	v_mul_f32_e32 v71, v87, v71
	v_exp_f32_e32 v70, v70
	v_exp_f32_e32 v71, v71
	v_lshlrev_b32_e32 v72, 16, v115
	v_and_b32_e32 v73, 0xffff0000, v115
	v_pk_mul_f32 v[70:71], v[70:71], v[72:73]
	s_nop 0
	v_cvt_pk_bf16_f32 v115, v70, v71
	s_waitcnt vmcnt(17)
	v_mfma_f32_32x32x16_bf16 v[54:69], v[112:115], v[120:123], v[54:69]
	s_waitcnt vmcnt(16)
	v_mfma_f32_32x32x16_bf16 v[38:53], v[112:115], v[124:127], v[38:53]
	s_waitcnt vmcnt(15)
	v_mfma_f32_32x32x16_bf16 v[22:37], v[112:115], v[128:131], v[22:37]
	s_waitcnt vmcnt(14)
	v_mfma_f32_32x32x16_bf16 v[6:21], v[112:115], v[132:135], v[6:21]
	v_add_u32_e32 v70, 0x40, v89
	v_add_u32_e32 v72, 0xaf, v88
	v_add_u32_e32 v71, 0x41, v89
	v_cndmask_b32_e32 v70, v70, v72, vcc
	v_add_u32_e32 v72, 0xae, v88
	v_cndmask_b32_e32 v71, v71, v72, vcc
	v_cvt_f32_u32_e32 v70, v70
	v_cvt_f32_u32_e32 v71, v71
	v_mul_f32_e32 v70, v87, v70
	v_mul_f32_e32 v71, v87, v71
	v_exp_f32_e32 v70, v70
	v_exp_f32_e32 v71, v71
	v_lshlrev_b32_e32 v72, 16, v116
	v_and_b32_e32 v73, 0xffff0000, v116
	v_pk_mul_f32 v[70:71], v[70:71], v[72:73]
	s_nop 0
	v_cvt_pk_bf16_f32 v116, v70, v71
	v_add_u32_e32 v70, 0x42, v89
	v_add_u32_e32 v72, 0xad, v88
	v_add_u32_e32 v71, 0x43, v89
	v_cndmask_b32_e32 v70, v70, v72, vcc
	v_add_u32_e32 v72, 0xac, v88
	v_cndmask_b32_e32 v71, v71, v72, vcc
	v_cvt_f32_u32_e32 v70, v70
	v_cvt_f32_u32_e32 v71, v71
	v_mul_f32_e32 v70, v87, v70
	v_mul_f32_e32 v71, v87, v71
	v_exp_f32_e32 v70, v70
	v_exp_f32_e32 v71, v71
	v_lshlrev_b32_e32 v72, 16, v117
	v_and_b32_e32 v73, 0xffff0000, v117
	v_pk_mul_f32 v[70:71], v[70:71], v[72:73]
	s_nop 0
	v_cvt_pk_bf16_f32 v117, v70, v71
	v_add_u32_e32 v70, 0x44, v89
	v_add_u32_e32 v72, 0xab, v88
	v_add_u32_e32 v71, 0x45, v89
	v_cndmask_b32_e32 v70, v70, v72, vcc
	v_add_u32_e32 v72, 0xaa, v88
	v_cndmask_b32_e32 v71, v71, v72, vcc
	v_cvt_f32_u32_e32 v70, v70
	v_cvt_f32_u32_e32 v71, v71
	v_mul_f32_e32 v70, v87, v70
	v_mul_f32_e32 v71, v87, v71
	v_exp_f32_e32 v70, v70
	v_exp_f32_e32 v71, v71
	v_lshlrev_b32_e32 v72, 16, v118
	v_and_b32_e32 v73, 0xffff0000, v118
	v_pk_mul_f32 v[70:71], v[70:71], v[72:73]
	s_nop 0
	v_cvt_pk_bf16_f32 v118, v70, v71
	v_add_u32_e32 v70, 0x46, v89
	v_add_u32_e32 v72, 0xa9, v88
	v_add_u32_e32 v71, 0x47, v89
	v_cndmask_b32_e32 v70, v70, v72, vcc
	v_add_u32_e32 v72, 0xa8, v88
	v_cndmask_b32_e32 v71, v71, v72, vcc
	v_cvt_f32_u32_e32 v70, v70
	v_cvt_f32_u32_e32 v71, v71
	v_mul_f32_e32 v70, v87, v70
	v_mul_f32_e32 v71, v87, v71
	v_exp_f32_e32 v70, v70
	v_exp_f32_e32 v71, v71
	v_lshlrev_b32_e32 v72, 16, v119
	v_and_b32_e32 v73, 0xffff0000, v119
	v_pk_mul_f32 v[70:71], v[70:71], v[72:73]
	s_nop 0
	v_cvt_pk_bf16_f32 v119, v70, v71
	s_waitcnt vmcnt(13)
	v_mfma_f32_32x32x16_bf16 v[54:69], v[116:119], v[136:139], v[54:69]
	s_waitcnt vmcnt(11)
	v_mfma_f32_32x32x16_bf16 v[22:37], v[116:119], v[144:147], v[22:37]
	v_mfma_f32_32x32x16_bf16 v[38:53], v[116:119], v[140:143], v[38:53]
	s_waitcnt vmcnt(10)
	v_mfma_f32_32x32x16_bf16 v[6:21], v[116:119], v[148:151], v[6:21]
	global_load_dwordx4 v[112:115], v[82:83], off offset:3840
	global_load_dwordx4 v[116:119], v[82:83], off offset:3872
	global_load_dwordx4 v[120:123], v[78:79], off offset:3840
	global_load_dwordx4 v[124:127], v[80:81], off offset:3840
	global_load_dwordx4 v[128:131], v[90:91], off offset:3840
	global_load_dwordx4 v[132:135], v[92:93], off offset:3840
	global_load_dwordx4 v[136:139], v[78:79], off offset:3872
	global_load_dwordx4 v[140:143], v[80:81], off offset:3872
	global_load_dwordx4 v[144:147], v[90:91], off offset:3872
	global_load_dwordx4 v[148:151], v[92:93], off offset:3872
	v_add_u32_e32 v70, 0x50, v89
	v_add_u32_e32 v72, 0x9f, v88
	v_add_u32_e32 v71, 0x51, v89
	v_cndmask_b32_e32 v70, v70, v72, vcc
	v_add_u32_e32 v72, 0x9e, v88
	v_cndmask_b32_e32 v71, v71, v72, vcc
	v_cvt_f32_u32_e32 v70, v70
	v_cvt_f32_u32_e32 v71, v71
	v_mul_f32_e32 v70, v87, v70
	v_mul_f32_e32 v71, v87, v71
	v_exp_f32_e32 v70, v70
	v_exp_f32_e32 v71, v71
	s_waitcnt vmcnt(19)
	v_lshlrev_b32_e32 v72, 16, v152
	v_and_b32_e32 v73, 0xffff0000, v152
	v_pk_mul_f32 v[70:71], v[70:71], v[72:73]
	s_nop 0
	v_cvt_pk_bf16_f32 v152, v70, v71
	v_add_u32_e32 v70, 0x52, v89
	v_add_u32_e32 v72, 0x9d, v88
	v_add_u32_e32 v71, 0x53, v89
	v_cndmask_b32_e32 v70, v70, v72, vcc
	v_add_u32_e32 v72, 0x9c, v88
	v_cndmask_b32_e32 v71, v71, v72, vcc
	v_cvt_f32_u32_e32 v70, v70
	v_cvt_f32_u32_e32 v71, v71
	v_mul_f32_e32 v70, v87, v70
	v_mul_f32_e32 v71, v87, v71
	v_exp_f32_e32 v70, v70
	v_exp_f32_e32 v71, v71
	v_lshlrev_b32_e32 v72, 16, v153
	v_and_b32_e32 v73, 0xffff0000, v153
	v_pk_mul_f32 v[70:71], v[70:71], v[72:73]
	s_nop 0
	v_cvt_pk_bf16_f32 v153, v70, v71
	v_add_u32_e32 v70, 0x54, v89
	v_add_u32_e32 v72, 0x9b, v88
	v_add_u32_e32 v71, 0x55, v89
	v_cndmask_b32_e32 v70, v70, v72, vcc
	v_add_u32_e32 v72, 0x9a, v88
	v_cndmask_b32_e32 v71, v71, v72, vcc
	v_cvt_f32_u32_e32 v70, v70
	v_cvt_f32_u32_e32 v71, v71
	v_mul_f32_e32 v70, v87, v70
	v_mul_f32_e32 v71, v87, v71
	v_exp_f32_e32 v70, v70
	v_exp_f32_e32 v71, v71
	v_lshlrev_b32_e32 v72, 16, v154
	v_and_b32_e32 v73, 0xffff0000, v154
	v_pk_mul_f32 v[70:71], v[70:71], v[72:73]
	s_nop 0
	v_cvt_pk_bf16_f32 v154, v70, v71
	v_add_u32_e32 v70, 0x56, v89
	v_add_u32_e32 v72, 0x99, v88
	v_add_u32_e32 v71, 0x57, v89
	v_cndmask_b32_e32 v70, v70, v72, vcc
	v_add_u32_e32 v72, 0x98, v88
	v_cndmask_b32_e32 v71, v71, v72, vcc
	v_cvt_f32_u32_e32 v70, v70
	v_cvt_f32_u32_e32 v71, v71
	v_mul_f32_e32 v70, v87, v70
	v_mul_f32_e32 v71, v87, v71
	v_exp_f32_e32 v70, v70
	v_exp_f32_e32 v71, v71
	v_lshlrev_b32_e32 v72, 16, v155
	v_and_b32_e32 v73, 0xffff0000, v155
	v_pk_mul_f32 v[70:71], v[70:71], v[72:73]
	s_nop 0
	v_cvt_pk_bf16_f32 v155, v70, v71
	s_waitcnt vmcnt(17)
	v_mfma_f32_32x32x16_bf16 v[54:69], v[152:155], v[160:163], v[54:69]
	s_waitcnt vmcnt(16)
	v_mfma_f32_32x32x16_bf16 v[38:53], v[152:155], v[168:171], v[38:53]
	s_waitcnt vmcnt(15)
	v_mfma_f32_32x32x16_bf16 v[22:37], v[152:155], v[172:175], v[22:37]
	s_waitcnt vmcnt(14)
	v_mfma_f32_32x32x16_bf16 v[6:21], v[152:155], v[176:179], v[6:21]
	v_add_u32_e32 v70, 0x60, v89
	v_add_u32_e32 v72, 0x8f, v88
	v_add_u32_e32 v71, 0x61, v89
	v_cndmask_b32_e32 v70, v70, v72, vcc
	v_add_u32_e32 v72, 0x8e, v88
	v_cndmask_b32_e32 v71, v71, v72, vcc
	v_cvt_f32_u32_e32 v70, v70
	v_cvt_f32_u32_e32 v71, v71
	v_mul_f32_e32 v70, v87, v70
	v_mul_f32_e32 v71, v87, v71
	v_exp_f32_e32 v70, v70
	v_exp_f32_e32 v71, v71
	v_lshlrev_b32_e32 v72, 16, v156
	v_and_b32_e32 v73, 0xffff0000, v156
	v_pk_mul_f32 v[70:71], v[70:71], v[72:73]
	s_nop 0
	v_cvt_pk_bf16_f32 v156, v70, v71
	v_add_u32_e32 v70, 0x62, v89
	v_add_u32_e32 v72, 0x8d, v88
	v_add_u32_e32 v71, 0x63, v89
	v_cndmask_b32_e32 v70, v70, v72, vcc
	v_add_u32_e32 v72, 0x8c, v88
	v_cndmask_b32_e32 v71, v71, v72, vcc
	v_cvt_f32_u32_e32 v70, v70
	v_cvt_f32_u32_e32 v71, v71
	v_mul_f32_e32 v70, v87, v70
	v_mul_f32_e32 v71, v87, v71
	v_exp_f32_e32 v70, v70
	v_exp_f32_e32 v71, v71
	v_lshlrev_b32_e32 v72, 16, v157
	v_and_b32_e32 v73, 0xffff0000, v157
	v_pk_mul_f32 v[70:71], v[70:71], v[72:73]
	s_nop 0
	v_cvt_pk_bf16_f32 v157, v70, v71
	v_add_u32_e32 v70, 0x64, v89
	v_add_u32_e32 v72, 0x8b, v88
	v_add_u32_e32 v71, 0x65, v89
	v_cndmask_b32_e32 v70, v70, v72, vcc
	v_add_u32_e32 v72, 0x8a, v88
	v_cndmask_b32_e32 v71, v71, v72, vcc
	v_cvt_f32_u32_e32 v70, v70
	v_cvt_f32_u32_e32 v71, v71
	v_mul_f32_e32 v70, v87, v70
	v_mul_f32_e32 v71, v87, v71
	v_exp_f32_e32 v70, v70
	v_exp_f32_e32 v71, v71
	v_lshlrev_b32_e32 v72, 16, v158
	v_and_b32_e32 v73, 0xffff0000, v158
	v_pk_mul_f32 v[70:71], v[70:71], v[72:73]
	s_nop 0
	v_cvt_pk_bf16_f32 v158, v70, v71
	v_add_u32_e32 v70, 0x66, v89
	v_add_u32_e32 v72, 0x89, v88
	v_add_u32_e32 v71, 0x67, v89
	v_cndmask_b32_e32 v70, v70, v72, vcc
	v_add_u32_e32 v72, 0x88, v88
	v_cndmask_b32_e32 v71, v71, v72, vcc
	v_cvt_f32_u32_e32 v70, v70
	v_cvt_f32_u32_e32 v71, v71
	v_mul_f32_e32 v70, v87, v70
	v_mul_f32_e32 v71, v87, v71
	v_exp_f32_e32 v70, v70
	v_exp_f32_e32 v71, v71
	v_lshlrev_b32_e32 v72, 16, v159
	v_and_b32_e32 v73, 0xffff0000, v159
	v_pk_mul_f32 v[70:71], v[70:71], v[72:73]
	s_nop 0
	v_cvt_pk_bf16_f32 v159, v70, v71
	s_waitcnt vmcnt(13)
	v_mfma_f32_32x32x16_bf16 v[54:69], v[156:159], v[180:183], v[54:69]
	s_waitcnt vmcnt(11)
	v_mfma_f32_32x32x16_bf16 v[22:37], v[156:159], v[188:191], v[22:37]
	v_mfma_f32_32x32x16_bf16 v[38:53], v[156:159], v[184:187], v[38:53]
	s_waitcnt vmcnt(10)
	v_mfma_f32_32x32x16_bf16 v[6:21], v[156:159], v[192:195], v[6:21]
	global_load_dwordx4 v[152:155], v[82:83], off offset:3904
	global_load_dwordx4 v[156:159], v[82:83], off offset:3936
	global_load_dwordx4 v[160:163], v[78:79], off offset:3904
	global_load_dwordx4 v[168:171], v[80:81], off offset:3904
	global_load_dwordx4 v[172:175], v[90:91], off offset:3904
	global_load_dwordx4 v[176:179], v[92:93], off offset:3904
	global_load_dwordx4 v[180:183], v[78:79], off offset:3936
	global_load_dwordx4 v[184:187], v[80:81], off offset:3936
	global_load_dwordx4 v[188:191], v[90:91], off offset:3936
	global_load_dwordx4 v[192:195], v[92:93], off offset:3936
	v_add_u32_e32 v70, 0x70, v89
	v_add_u32_e32 v72, 0x7f, v88
	v_add_u32_e32 v71, 0x71, v89
	v_cndmask_b32_e32 v70, v70, v72, vcc
	v_add_u32_e32 v72, 0x7e, v88
	v_cndmask_b32_e32 v71, v71, v72, vcc
	v_cvt_f32_u32_e32 v70, v70
	v_cvt_f32_u32_e32 v71, v71
	v_mul_f32_e32 v70, v87, v70
	v_mul_f32_e32 v71, v87, v71
	v_exp_f32_e32 v70, v70
	v_exp_f32_e32 v71, v71
	s_waitcnt vmcnt(19)
	v_lshlrev_b32_e32 v72, 16, v112
	v_and_b32_e32 v73, 0xffff0000, v112
	v_pk_mul_f32 v[70:71], v[70:71], v[72:73]
	s_nop 0
	v_cvt_pk_bf16_f32 v112, v70, v71
	v_add_u32_e32 v70, 0x72, v89
	v_add_u32_e32 v72, 0x7d, v88
	v_add_u32_e32 v71, 0x73, v89
	v_cndmask_b32_e32 v70, v70, v72, vcc
	v_add_u32_e32 v72, 0x7c, v88
	v_cndmask_b32_e32 v71, v71, v72, vcc
	v_cvt_f32_u32_e32 v70, v70
	v_cvt_f32_u32_e32 v71, v71
	v_mul_f32_e32 v70, v87, v70
	v_mul_f32_e32 v71, v87, v71
	v_exp_f32_e32 v70, v70
	v_exp_f32_e32 v71, v71
	v_lshlrev_b32_e32 v72, 16, v113
	v_and_b32_e32 v73, 0xffff0000, v113
	v_pk_mul_f32 v[70:71], v[70:71], v[72:73]
	s_nop 0
	v_cvt_pk_bf16_f32 v113, v70, v71
	v_add_u32_e32 v70, 0x74, v89
	v_add_u32_e32 v72, 0x7b, v88
	v_add_u32_e32 v71, 0x75, v89
	v_cndmask_b32_e32 v70, v70, v72, vcc
	v_add_u32_e32 v72, 0x7a, v88
	v_cndmask_b32_e32 v71, v71, v72, vcc
	v_cvt_f32_u32_e32 v70, v70
	v_cvt_f32_u32_e32 v71, v71
	v_mul_f32_e32 v70, v87, v70
	v_mul_f32_e32 v71, v87, v71
	v_exp_f32_e32 v70, v70
	v_exp_f32_e32 v71, v71
	v_lshlrev_b32_e32 v72, 16, v114
	v_and_b32_e32 v73, 0xffff0000, v114
	v_pk_mul_f32 v[70:71], v[70:71], v[72:73]
	s_nop 0
	v_cvt_pk_bf16_f32 v114, v70, v71
	v_add_u32_e32 v70, 0x76, v89
	v_add_u32_e32 v72, 0x79, v88
	v_add_u32_e32 v71, 0x77, v89
	v_cndmask_b32_e32 v70, v70, v72, vcc
	v_add_u32_e32 v72, 0x78, v88
	v_cndmask_b32_e32 v71, v71, v72, vcc
	v_cvt_f32_u32_e32 v70, v70
	v_cvt_f32_u32_e32 v71, v71
	v_mul_f32_e32 v70, v87, v70
	v_mul_f32_e32 v71, v87, v71
	v_exp_f32_e32 v70, v70
	v_exp_f32_e32 v71, v71
	v_lshlrev_b32_e32 v72, 16, v115
	v_and_b32_e32 v73, 0xffff0000, v115
	v_pk_mul_f32 v[70:71], v[70:71], v[72:73]
	s_nop 0
	v_cvt_pk_bf16_f32 v115, v70, v71
	s_waitcnt vmcnt(17)
	v_mfma_f32_32x32x16_bf16 v[54:69], v[112:115], v[120:123], v[54:69]
	s_waitcnt vmcnt(16)
	v_mfma_f32_32x32x16_bf16 v[38:53], v[112:115], v[124:127], v[38:53]
	s_waitcnt vmcnt(15)
	v_mfma_f32_32x32x16_bf16 v[22:37], v[112:115], v[128:131], v[22:37]
	s_waitcnt vmcnt(14)
	v_mfma_f32_32x32x16_bf16 v[6:21], v[112:115], v[132:135], v[6:21]
	v_add_u32_e32 v70, 0x80, v89
	v_add_u32_e32 v72, 0x6f, v88
	v_add_u32_e32 v71, 0x81, v89
	v_cndmask_b32_e32 v70, v70, v72, vcc
	v_add_u32_e32 v72, 0x6e, v88
	v_cndmask_b32_e32 v71, v71, v72, vcc
	v_cvt_f32_u32_e32 v70, v70
	v_cvt_f32_u32_e32 v71, v71
	v_mul_f32_e32 v70, v87, v70
	v_mul_f32_e32 v71, v87, v71
	v_exp_f32_e32 v70, v70
	v_exp_f32_e32 v71, v71
	v_lshlrev_b32_e32 v72, 16, v116
	v_and_b32_e32 v73, 0xffff0000, v116
	v_pk_mul_f32 v[70:71], v[70:71], v[72:73]
	s_nop 0
	v_cvt_pk_bf16_f32 v116, v70, v71
	v_add_u32_e32 v70, 0x82, v89
	v_add_u32_e32 v72, 0x6d, v88
	v_add_u32_e32 v71, 0x83, v89
	v_cndmask_b32_e32 v70, v70, v72, vcc
	v_add_u32_e32 v72, 0x6c, v88
	v_cndmask_b32_e32 v71, v71, v72, vcc
	v_cvt_f32_u32_e32 v70, v70
	v_cvt_f32_u32_e32 v71, v71
	v_mul_f32_e32 v70, v87, v70
	v_mul_f32_e32 v71, v87, v71
	v_exp_f32_e32 v70, v70
	v_exp_f32_e32 v71, v71
	v_lshlrev_b32_e32 v72, 16, v117
	v_and_b32_e32 v73, 0xffff0000, v117
	v_pk_mul_f32 v[70:71], v[70:71], v[72:73]
	s_nop 0
	v_cvt_pk_bf16_f32 v117, v70, v71
	v_add_u32_e32 v70, 0x84, v89
	v_add_u32_e32 v72, 0x6b, v88
	v_add_u32_e32 v71, 0x85, v89
	v_cndmask_b32_e32 v70, v70, v72, vcc
	v_add_u32_e32 v72, 0x6a, v88
	v_cndmask_b32_e32 v71, v71, v72, vcc
	v_cvt_f32_u32_e32 v70, v70
	v_cvt_f32_u32_e32 v71, v71
	v_mul_f32_e32 v70, v87, v70
	v_mul_f32_e32 v71, v87, v71
	v_exp_f32_e32 v70, v70
	v_exp_f32_e32 v71, v71
	v_lshlrev_b32_e32 v72, 16, v118
	v_and_b32_e32 v73, 0xffff0000, v118
	v_pk_mul_f32 v[70:71], v[70:71], v[72:73]
	s_nop 0
	v_cvt_pk_bf16_f32 v118, v70, v71
	v_add_u32_e32 v70, 0x86, v89
	v_add_u32_e32 v72, 0x69, v88
	v_add_u32_e32 v71, 0x87, v89
	v_cndmask_b32_e32 v70, v70, v72, vcc
	v_add_u32_e32 v72, 0x68, v88
	v_cndmask_b32_e32 v71, v71, v72, vcc
	v_cvt_f32_u32_e32 v70, v70
	v_cvt_f32_u32_e32 v71, v71
	v_mul_f32_e32 v70, v87, v70
	v_mul_f32_e32 v71, v87, v71
	v_exp_f32_e32 v70, v70
	v_exp_f32_e32 v71, v71
	v_lshlrev_b32_e32 v72, 16, v119
	v_and_b32_e32 v73, 0xffff0000, v119
	v_pk_mul_f32 v[70:71], v[70:71], v[72:73]
	s_nop 0
	v_cvt_pk_bf16_f32 v119, v70, v71
	s_waitcnt vmcnt(13)
	v_mfma_f32_32x32x16_bf16 v[54:69], v[116:119], v[136:139], v[54:69]
	s_waitcnt vmcnt(11)
	v_mfma_f32_32x32x16_bf16 v[22:37], v[116:119], v[144:147], v[22:37]
	v_mfma_f32_32x32x16_bf16 v[38:53], v[116:119], v[140:143], v[38:53]
	s_waitcnt vmcnt(10)
	v_mfma_f32_32x32x16_bf16 v[6:21], v[116:119], v[148:151], v[6:21]
	global_load_dwordx4 v[112:115], v[82:83], off offset:3968
	global_load_dwordx4 v[116:119], v[82:83], off offset:4000
	global_load_dwordx4 v[120:123], v[78:79], off offset:3968
	global_load_dwordx4 v[124:127], v[80:81], off offset:3968
	global_load_dwordx4 v[128:131], v[90:91], off offset:3968
	global_load_dwordx4 v[132:135], v[92:93], off offset:3968
	global_load_dwordx4 v[136:139], v[78:79], off offset:4000
	global_load_dwordx4 v[140:143], v[80:81], off offset:4000
	global_load_dwordx4 v[144:147], v[90:91], off offset:4000
	global_load_dwordx4 v[148:151], v[92:93], off offset:4000
	v_add_u32_e32 v70, 0x90, v89
	v_add_u32_e32 v72, 0x5f, v88
	v_add_u32_e32 v71, 0x91, v89
	v_cndmask_b32_e32 v70, v70, v72, vcc
	v_add_u32_e32 v72, 0x5e, v88
	v_cndmask_b32_e32 v71, v71, v72, vcc
	v_cvt_f32_u32_e32 v70, v70
	v_cvt_f32_u32_e32 v71, v71
	v_mul_f32_e32 v70, v87, v70
	v_mul_f32_e32 v71, v87, v71
	v_exp_f32_e32 v70, v70
	v_exp_f32_e32 v71, v71
	s_waitcnt vmcnt(19)
	v_lshlrev_b32_e32 v72, 16, v152
	v_and_b32_e32 v73, 0xffff0000, v152
	v_pk_mul_f32 v[70:71], v[70:71], v[72:73]
	s_nop 0
	v_cvt_pk_bf16_f32 v152, v70, v71
	v_add_u32_e32 v70, 0x92, v89
	v_add_u32_e32 v72, 0x5d, v88
	v_add_u32_e32 v71, 0x93, v89
	v_cndmask_b32_e32 v70, v70, v72, vcc
	v_add_u32_e32 v72, 0x5c, v88
	v_cndmask_b32_e32 v71, v71, v72, vcc
	v_cvt_f32_u32_e32 v70, v70
	v_cvt_f32_u32_e32 v71, v71
	v_mul_f32_e32 v70, v87, v70
	v_mul_f32_e32 v71, v87, v71
	v_exp_f32_e32 v70, v70
	v_exp_f32_e32 v71, v71
	v_lshlrev_b32_e32 v72, 16, v153
	v_and_b32_e32 v73, 0xffff0000, v153
	v_pk_mul_f32 v[70:71], v[70:71], v[72:73]
	s_nop 0
	v_cvt_pk_bf16_f32 v153, v70, v71
	v_add_u32_e32 v70, 0x94, v89
	v_add_u32_e32 v72, 0x5b, v88
	v_add_u32_e32 v71, 0x95, v89
	v_cndmask_b32_e32 v70, v70, v72, vcc
	v_add_u32_e32 v72, 0x5a, v88
	v_cndmask_b32_e32 v71, v71, v72, vcc
	v_cvt_f32_u32_e32 v70, v70
	v_cvt_f32_u32_e32 v71, v71
	v_mul_f32_e32 v70, v87, v70
	v_mul_f32_e32 v71, v87, v71
	v_exp_f32_e32 v70, v70
	v_exp_f32_e32 v71, v71
	v_lshlrev_b32_e32 v72, 16, v154
	v_and_b32_e32 v73, 0xffff0000, v154
	v_pk_mul_f32 v[70:71], v[70:71], v[72:73]
	s_nop 0
	v_cvt_pk_bf16_f32 v154, v70, v71
	v_add_u32_e32 v70, 0x96, v89
	v_add_u32_e32 v72, 0x59, v88
	v_add_u32_e32 v71, 0x97, v89
	v_cndmask_b32_e32 v70, v70, v72, vcc
	v_add_u32_e32 v72, 0x58, v88
	v_cndmask_b32_e32 v71, v71, v72, vcc
	v_cvt_f32_u32_e32 v70, v70
	v_cvt_f32_u32_e32 v71, v71
	v_mul_f32_e32 v70, v87, v70
	v_mul_f32_e32 v71, v87, v71
	v_exp_f32_e32 v70, v70
	v_exp_f32_e32 v71, v71
	v_lshlrev_b32_e32 v72, 16, v155
	v_and_b32_e32 v73, 0xffff0000, v155
	v_pk_mul_f32 v[70:71], v[70:71], v[72:73]
	s_nop 0
	v_cvt_pk_bf16_f32 v155, v70, v71
	s_waitcnt vmcnt(17)
	v_mfma_f32_32x32x16_bf16 v[54:69], v[152:155], v[160:163], v[54:69]
	s_waitcnt vmcnt(16)
	v_mfma_f32_32x32x16_bf16 v[38:53], v[152:155], v[168:171], v[38:53]
	s_waitcnt vmcnt(15)
	v_mfma_f32_32x32x16_bf16 v[22:37], v[152:155], v[172:175], v[22:37]
	s_waitcnt vmcnt(14)
	v_mfma_f32_32x32x16_bf16 v[6:21], v[152:155], v[176:179], v[6:21]
	v_add_u32_e32 v70, 0xa0, v89
	v_add_u32_e32 v72, 0x4f, v88
	v_add_u32_e32 v71, 0xa1, v89
	v_cndmask_b32_e32 v70, v70, v72, vcc
	v_add_u32_e32 v72, 0x4e, v88
	v_cndmask_b32_e32 v71, v71, v72, vcc
	v_cvt_f32_u32_e32 v70, v70
	v_cvt_f32_u32_e32 v71, v71
	v_mul_f32_e32 v70, v87, v70
	v_mul_f32_e32 v71, v87, v71
	v_exp_f32_e32 v70, v70
	v_exp_f32_e32 v71, v71
	v_lshlrev_b32_e32 v72, 16, v156
	v_and_b32_e32 v73, 0xffff0000, v156
	v_pk_mul_f32 v[70:71], v[70:71], v[72:73]
	s_nop 0
	v_cvt_pk_bf16_f32 v156, v70, v71
	v_add_u32_e32 v70, 0xa2, v89
	v_add_u32_e32 v72, 0x4d, v88
	v_add_u32_e32 v71, 0xa3, v89
	v_cndmask_b32_e32 v70, v70, v72, vcc
	v_add_u32_e32 v72, 0x4c, v88
	v_cndmask_b32_e32 v71, v71, v72, vcc
	v_cvt_f32_u32_e32 v70, v70
	v_cvt_f32_u32_e32 v71, v71
	v_mul_f32_e32 v70, v87, v70
	v_mul_f32_e32 v71, v87, v71
	v_exp_f32_e32 v70, v70
	v_exp_f32_e32 v71, v71
	v_lshlrev_b32_e32 v72, 16, v157
	v_and_b32_e32 v73, 0xffff0000, v157
	v_pk_mul_f32 v[70:71], v[70:71], v[72:73]
	s_nop 0
	v_cvt_pk_bf16_f32 v157, v70, v71
	v_add_u32_e32 v70, 0xa4, v89
	v_add_u32_e32 v72, 0x4b, v88
	v_add_u32_e32 v71, 0xa5, v89
	v_cndmask_b32_e32 v70, v70, v72, vcc
	v_add_u32_e32 v72, 0x4a, v88
	v_cndmask_b32_e32 v71, v71, v72, vcc
	v_cvt_f32_u32_e32 v70, v70
	v_cvt_f32_u32_e32 v71, v71
	v_mul_f32_e32 v70, v87, v70
	v_mul_f32_e32 v71, v87, v71
	v_exp_f32_e32 v70, v70
	v_exp_f32_e32 v71, v71
	v_lshlrev_b32_e32 v72, 16, v158
	v_and_b32_e32 v73, 0xffff0000, v158
	v_pk_mul_f32 v[70:71], v[70:71], v[72:73]
	s_nop 0
	v_cvt_pk_bf16_f32 v158, v70, v71
	v_add_u32_e32 v70, 0xa6, v89
	v_add_u32_e32 v72, 0x49, v88
	v_add_u32_e32 v71, 0xa7, v89
	v_cndmask_b32_e32 v70, v70, v72, vcc
	v_add_u32_e32 v72, 0x48, v88
	v_cndmask_b32_e32 v71, v71, v72, vcc
	v_cvt_f32_u32_e32 v70, v70
	v_cvt_f32_u32_e32 v71, v71
	v_mul_f32_e32 v70, v87, v70
	v_mul_f32_e32 v71, v87, v71
	v_exp_f32_e32 v70, v70
	v_exp_f32_e32 v71, v71
	v_lshlrev_b32_e32 v72, 16, v159
	v_and_b32_e32 v73, 0xffff0000, v159
	v_pk_mul_f32 v[70:71], v[70:71], v[72:73]
	s_nop 0
	v_cvt_pk_bf16_f32 v159, v70, v71
	s_waitcnt vmcnt(13)
	v_mfma_f32_32x32x16_bf16 v[54:69], v[156:159], v[180:183], v[54:69]
	s_waitcnt vmcnt(11)
	v_mfma_f32_32x32x16_bf16 v[22:37], v[156:159], v[188:191], v[22:37]
	v_mfma_f32_32x32x16_bf16 v[38:53], v[156:159], v[184:187], v[38:53]
	s_waitcnt vmcnt(10)
	v_mfma_f32_32x32x16_bf16 v[6:21], v[156:159], v[192:195], v[6:21]
	global_load_dwordx4 v[152:155], v[82:83], off offset:4032
	global_load_dwordx4 v[156:159], v[82:83], off offset:4064
	global_load_dwordx4 v[160:163], v[78:79], off offset:4032
	global_load_dwordx4 v[168:171], v[80:81], off offset:4032
	global_load_dwordx4 v[172:175], v[90:91], off offset:4032
	global_load_dwordx4 v[176:179], v[92:93], off offset:4032
	global_load_dwordx4 v[180:183], v[78:79], off offset:4064
	global_load_dwordx4 v[184:187], v[80:81], off offset:4064
	global_load_dwordx4 v[188:191], v[90:91], off offset:4064
	global_load_dwordx4 v[192:195], v[92:93], off offset:4064
	v_add_u32_e32 v70, 0xb0, v89
	v_add_u32_e32 v72, 0x3f, v88
	v_add_u32_e32 v71, 0xb1, v89
	v_cndmask_b32_e32 v70, v70, v72, vcc
	v_add_u32_e32 v72, 0x3e, v88
	v_cndmask_b32_e32 v71, v71, v72, vcc
	v_cvt_f32_u32_e32 v70, v70
	v_cvt_f32_u32_e32 v71, v71
	v_mul_f32_e32 v70, v87, v70
	v_mul_f32_e32 v71, v87, v71
	v_exp_f32_e32 v70, v70
	v_exp_f32_e32 v71, v71
	s_waitcnt vmcnt(19)
	v_lshlrev_b32_e32 v72, 16, v112
	v_and_b32_e32 v73, 0xffff0000, v112
	v_pk_mul_f32 v[70:71], v[70:71], v[72:73]
	s_nop 0
	v_cvt_pk_bf16_f32 v112, v70, v71
	v_add_u32_e32 v70, 0xb2, v89
	v_add_u32_e32 v72, 0x3d, v88
	v_add_u32_e32 v71, 0xb3, v89
	v_cndmask_b32_e32 v70, v70, v72, vcc
	v_add_u32_e32 v72, 0x3c, v88
	v_cndmask_b32_e32 v71, v71, v72, vcc
	v_cvt_f32_u32_e32 v70, v70
	v_cvt_f32_u32_e32 v71, v71
	v_mul_f32_e32 v70, v87, v70
	v_mul_f32_e32 v71, v87, v71
	v_exp_f32_e32 v70, v70
	v_exp_f32_e32 v71, v71
	v_lshlrev_b32_e32 v72, 16, v113
	v_and_b32_e32 v73, 0xffff0000, v113
	v_pk_mul_f32 v[70:71], v[70:71], v[72:73]
	s_nop 0
	v_cvt_pk_bf16_f32 v113, v70, v71
	v_add_u32_e32 v70, 0xb4, v89
	v_add_u32_e32 v72, 0x3b, v88
	v_add_u32_e32 v71, 0xb5, v89
	v_cndmask_b32_e32 v70, v70, v72, vcc
	v_add_u32_e32 v72, 0x3a, v88
	v_cndmask_b32_e32 v71, v71, v72, vcc
	v_cvt_f32_u32_e32 v70, v70
	v_cvt_f32_u32_e32 v71, v71
	v_mul_f32_e32 v70, v87, v70
	v_mul_f32_e32 v71, v87, v71
	v_exp_f32_e32 v70, v70
	v_exp_f32_e32 v71, v71
	v_lshlrev_b32_e32 v72, 16, v114
	v_and_b32_e32 v73, 0xffff0000, v114
	v_pk_mul_f32 v[70:71], v[70:71], v[72:73]
	s_nop 0
	v_cvt_pk_bf16_f32 v114, v70, v71
	v_add_u32_e32 v70, 0xb6, v89
	v_add_u32_e32 v72, 0x39, v88
	v_add_u32_e32 v71, 0xb7, v89
	v_cndmask_b32_e32 v70, v70, v72, vcc
	v_add_u32_e32 v72, 0x38, v88
	v_cndmask_b32_e32 v71, v71, v72, vcc
	v_cvt_f32_u32_e32 v70, v70
	v_cvt_f32_u32_e32 v71, v71
	v_mul_f32_e32 v70, v87, v70
	v_mul_f32_e32 v71, v87, v71
	v_exp_f32_e32 v70, v70
	v_exp_f32_e32 v71, v71
	v_lshlrev_b32_e32 v72, 16, v115
	v_and_b32_e32 v73, 0xffff0000, v115
	v_pk_mul_f32 v[70:71], v[70:71], v[72:73]
	s_nop 0
	v_cvt_pk_bf16_f32 v115, v70, v71
	s_waitcnt vmcnt(17)
	v_mfma_f32_32x32x16_bf16 v[54:69], v[112:115], v[120:123], v[54:69]
	s_waitcnt vmcnt(16)
	v_mfma_f32_32x32x16_bf16 v[38:53], v[112:115], v[124:127], v[38:53]
	s_waitcnt vmcnt(15)
	v_mfma_f32_32x32x16_bf16 v[22:37], v[112:115], v[128:131], v[22:37]
	s_waitcnt vmcnt(14)
	v_mfma_f32_32x32x16_bf16 v[6:21], v[112:115], v[132:135], v[6:21]
	v_add_u32_e32 v70, 0xc0, v89
	v_add_u32_e32 v72, 0x2f, v88
	v_add_u32_e32 v71, 0xc1, v89
	v_cndmask_b32_e32 v70, v70, v72, vcc
	v_add_u32_e32 v72, 0x2e, v88
	v_cndmask_b32_e32 v71, v71, v72, vcc
	v_cvt_f32_u32_e32 v70, v70
	v_cvt_f32_u32_e32 v71, v71
	v_mul_f32_e32 v70, v87, v70
	v_mul_f32_e32 v71, v87, v71
	v_exp_f32_e32 v70, v70
	v_exp_f32_e32 v71, v71
	v_lshlrev_b32_e32 v72, 16, v116
	v_and_b32_e32 v73, 0xffff0000, v116
	v_pk_mul_f32 v[70:71], v[70:71], v[72:73]
	s_nop 0
	v_cvt_pk_bf16_f32 v116, v70, v71
	v_add_u32_e32 v70, 0xc2, v89
	v_add_u32_e32 v72, 0x2d, v88
	v_add_u32_e32 v71, 0xc3, v89
	v_cndmask_b32_e32 v70, v70, v72, vcc
	v_add_u32_e32 v72, 0x2c, v88
	v_cndmask_b32_e32 v71, v71, v72, vcc
	v_cvt_f32_u32_e32 v70, v70
	v_cvt_f32_u32_e32 v71, v71
	v_mul_f32_e32 v70, v87, v70
	v_mul_f32_e32 v71, v87, v71
	v_exp_f32_e32 v70, v70
	v_exp_f32_e32 v71, v71
	v_lshlrev_b32_e32 v72, 16, v117
	v_and_b32_e32 v73, 0xffff0000, v117
	v_pk_mul_f32 v[70:71], v[70:71], v[72:73]
	s_nop 0
	v_cvt_pk_bf16_f32 v117, v70, v71
	v_add_u32_e32 v70, 0xc4, v89
	v_add_u32_e32 v72, 0x2b, v88
	v_add_u32_e32 v71, 0xc5, v89
	v_cndmask_b32_e32 v70, v70, v72, vcc
	v_add_u32_e32 v72, 0x2a, v88
	v_cndmask_b32_e32 v71, v71, v72, vcc
	v_cvt_f32_u32_e32 v70, v70
	v_cvt_f32_u32_e32 v71, v71
	v_mul_f32_e32 v70, v87, v70
	v_mul_f32_e32 v71, v87, v71
	v_exp_f32_e32 v70, v70
	v_exp_f32_e32 v71, v71
	v_lshlrev_b32_e32 v72, 16, v118
	v_and_b32_e32 v73, 0xffff0000, v118
	v_pk_mul_f32 v[70:71], v[70:71], v[72:73]
	s_nop 0
	v_cvt_pk_bf16_f32 v118, v70, v71
	v_add_u32_e32 v70, 0xc6, v89
	v_add_u32_e32 v72, 0x29, v88
	v_add_u32_e32 v71, 0xc7, v89
	v_cndmask_b32_e32 v70, v70, v72, vcc
	v_add_u32_e32 v72, 0x28, v88
	v_cndmask_b32_e32 v71, v71, v72, vcc
	v_cvt_f32_u32_e32 v70, v70
	v_cvt_f32_u32_e32 v71, v71
	v_mul_f32_e32 v70, v87, v70
	v_mul_f32_e32 v71, v87, v71
	v_exp_f32_e32 v70, v70
	v_exp_f32_e32 v71, v71
	v_lshlrev_b32_e32 v72, 16, v119
	v_and_b32_e32 v73, 0xffff0000, v119
	v_pk_mul_f32 v[70:71], v[70:71], v[72:73]
	s_nop 0
	v_cvt_pk_bf16_f32 v119, v70, v71
	s_waitcnt vmcnt(13)
	v_mfma_f32_32x32x16_bf16 v[54:69], v[116:119], v[136:139], v[54:69]
	s_waitcnt vmcnt(11)
	v_mfma_f32_32x32x16_bf16 v[22:37], v[116:119], v[144:147], v[22:37]
	v_mfma_f32_32x32x16_bf16 v[38:53], v[116:119], v[140:143], v[38:53]
	s_waitcnt vmcnt(10)
	v_mfma_f32_32x32x16_bf16 v[6:21], v[116:119], v[148:151], v[6:21]
	v_add_u32_e32 v70, 0xd0, v89
	v_add_u32_e32 v72, 0x1f, v88
	v_add_u32_e32 v71, 0xd1, v89
	v_cndmask_b32_e32 v70, v70, v72, vcc
	v_add_u32_e32 v72, 0x1e, v88
	v_cndmask_b32_e32 v71, v71, v72, vcc
	v_cvt_f32_u32_e32 v70, v70
	v_cvt_f32_u32_e32 v71, v71
	v_mul_f32_e32 v70, v87, v70
	v_mul_f32_e32 v71, v87, v71
	v_exp_f32_e32 v70, v70
	v_exp_f32_e32 v71, v71
	s_waitcnt vmcnt(9)
	v_lshlrev_b32_e32 v72, 16, v152
	v_and_b32_e32 v73, 0xffff0000, v152
	v_pk_mul_f32 v[70:71], v[70:71], v[72:73]
	s_nop 0
	v_cvt_pk_bf16_f32 v152, v70, v71
	v_add_u32_e32 v70, 0xd2, v89
	v_add_u32_e32 v72, 0x1d, v88
	v_add_u32_e32 v71, 0xd3, v89
	v_cndmask_b32_e32 v70, v70, v72, vcc
	v_add_u32_e32 v72, 0x1c, v88
	v_cndmask_b32_e32 v71, v71, v72, vcc
	v_cvt_f32_u32_e32 v70, v70
	v_cvt_f32_u32_e32 v71, v71
	v_mul_f32_e32 v70, v87, v70
	v_mul_f32_e32 v71, v87, v71
	v_exp_f32_e32 v70, v70
	v_exp_f32_e32 v71, v71
	v_lshlrev_b32_e32 v72, 16, v153
	v_and_b32_e32 v73, 0xffff0000, v153
	v_pk_mul_f32 v[70:71], v[70:71], v[72:73]
	s_nop 0
	v_cvt_pk_bf16_f32 v153, v70, v71
	v_add_u32_e32 v70, 0xd4, v89
	v_add_u32_e32 v72, 0x1b, v88
	v_add_u32_e32 v71, 0xd5, v89
	v_cndmask_b32_e32 v70, v70, v72, vcc
	v_add_u32_e32 v72, 0x1a, v88
	v_cndmask_b32_e32 v71, v71, v72, vcc
	v_cvt_f32_u32_e32 v70, v70
	v_cvt_f32_u32_e32 v71, v71
	v_mul_f32_e32 v70, v87, v70
	v_mul_f32_e32 v71, v87, v71
	v_exp_f32_e32 v70, v70
	v_exp_f32_e32 v71, v71
	v_lshlrev_b32_e32 v72, 16, v154
	v_and_b32_e32 v73, 0xffff0000, v154
	v_pk_mul_f32 v[70:71], v[70:71], v[72:73]
	s_nop 0
	v_cvt_pk_bf16_f32 v154, v70, v71
	v_add_u32_e32 v70, 0xd6, v89
	v_add_u32_e32 v72, 0x19, v88
	v_add_u32_e32 v71, 0xd7, v89
	v_cndmask_b32_e32 v70, v70, v72, vcc
	v_add_u32_e32 v72, 0x18, v88
	v_cndmask_b32_e32 v71, v71, v72, vcc
	v_cvt_f32_u32_e32 v70, v70
	v_cvt_f32_u32_e32 v71, v71
	v_mul_f32_e32 v70, v87, v70
	v_mul_f32_e32 v71, v87, v71
	v_exp_f32_e32 v70, v70
	v_exp_f32_e32 v71, v71
	v_lshlrev_b32_e32 v72, 16, v155
	v_and_b32_e32 v73, 0xffff0000, v155
	v_pk_mul_f32 v[70:71], v[70:71], v[72:73]
	s_nop 0
	v_cvt_pk_bf16_f32 v155, v70, v71
	s_waitcnt vmcnt(7)
	v_mfma_f32_32x32x16_bf16 v[54:69], v[152:155], v[160:163], v[54:69]
	s_waitcnt vmcnt(6)
	v_mfma_f32_32x32x16_bf16 v[38:53], v[152:155], v[168:171], v[38:53]
	s_waitcnt vmcnt(5)
	v_mfma_f32_32x32x16_bf16 v[22:37], v[152:155], v[172:175], v[22:37]
	s_waitcnt vmcnt(4)
	v_mfma_f32_32x32x16_bf16 v[6:21], v[152:155], v[176:179], v[6:21]
	v_add_u32_e32 v70, 0xe0, v89
	v_add_u32_e32 v72, 0xf, v88
	v_add_u32_e32 v71, 0xe1, v89
	v_cndmask_b32_e32 v70, v70, v72, vcc
	v_add_u32_e32 v72, 0xe, v88
	v_cndmask_b32_e32 v71, v71, v72, vcc
	v_cvt_f32_u32_e32 v70, v70
	v_cvt_f32_u32_e32 v71, v71
	v_mul_f32_e32 v70, v87, v70
	v_mul_f32_e32 v71, v87, v71
	v_exp_f32_e32 v70, v70
	v_exp_f32_e32 v71, v71
	v_lshlrev_b32_e32 v72, 16, v156
	v_and_b32_e32 v73, 0xffff0000, v156
	v_pk_mul_f32 v[70:71], v[70:71], v[72:73]
	s_nop 0
	v_cvt_pk_bf16_f32 v156, v70, v71
	v_add_u32_e32 v70, 0xe2, v89
	v_add_u32_e32 v72, 0xd, v88
	v_add_u32_e32 v71, 0xe3, v89
	v_cndmask_b32_e32 v70, v70, v72, vcc
	v_add_u32_e32 v72, 0xc, v88
	v_cndmask_b32_e32 v71, v71, v72, vcc
	v_cvt_f32_u32_e32 v70, v70
	v_cvt_f32_u32_e32 v71, v71
	v_mul_f32_e32 v70, v87, v70
	v_mul_f32_e32 v71, v87, v71
	v_exp_f32_e32 v70, v70
	v_exp_f32_e32 v71, v71
	v_lshlrev_b32_e32 v72, 16, v157
	v_and_b32_e32 v73, 0xffff0000, v157
	v_pk_mul_f32 v[70:71], v[70:71], v[72:73]
	s_nop 0
	v_cvt_pk_bf16_f32 v157, v70, v71
	v_add_u32_e32 v70, 0xe4, v89
	v_add_u32_e32 v72, 0xb, v88
	v_add_u32_e32 v71, 0xe5, v89
	v_cndmask_b32_e32 v70, v70, v72, vcc
	v_add_u32_e32 v72, 0xa, v88
	v_cndmask_b32_e32 v71, v71, v72, vcc
	v_cvt_f32_u32_e32 v70, v70
	v_cvt_f32_u32_e32 v71, v71
	v_mul_f32_e32 v70, v87, v70
	v_mul_f32_e32 v71, v87, v71
	v_exp_f32_e32 v70, v70
	v_exp_f32_e32 v71, v71
	v_lshlrev_b32_e32 v72, 16, v158
	v_and_b32_e32 v73, 0xffff0000, v158
	v_pk_mul_f32 v[70:71], v[70:71], v[72:73]
	s_nop 0
	v_cvt_pk_bf16_f32 v158, v70, v71
	v_add_u32_e32 v70, 0xe6, v89
	v_add_u32_e32 v72, 0x9, v88
	v_add_u32_e32 v71, 0xe7, v89
	v_cndmask_b32_e32 v70, v70, v72, vcc
	v_add_u32_e32 v72, 0x8, v88
	v_cndmask_b32_e32 v71, v71, v72, vcc
	v_cvt_f32_u32_e32 v70, v70
	v_cvt_f32_u32_e32 v71, v71
	v_mul_f32_e32 v70, v87, v70
	v_mul_f32_e32 v71, v87, v71
	v_exp_f32_e32 v70, v70
	v_exp_f32_e32 v71, v71
	v_lshlrev_b32_e32 v72, 16, v159
	v_and_b32_e32 v73, 0xffff0000, v159
	v_pk_mul_f32 v[70:71], v[70:71], v[72:73]
	s_nop 0
	v_cvt_pk_bf16_f32 v159, v70, v71
	s_waitcnt vmcnt(3)
	v_mfma_f32_32x32x16_bf16 v[54:69], v[156:159], v[180:183], v[54:69]
	s_waitcnt vmcnt(1)
	v_mfma_f32_32x32x16_bf16 v[22:37], v[156:159], v[188:191], v[22:37]
	v_mfma_f32_32x32x16_bf16 v[38:53], v[156:159], v[184:187], v[38:53]
	s_waitcnt vmcnt(0)
	v_mfma_f32_32x32x16_bf16 v[6:21], v[156:159], v[192:195], v[6:21]
	v_add_u32_e32 v89, 0x100, v89
	s_movk_i32 s8, 0xff00
	s_lshl_b32 s0, s7, 18
	s_lshl_b32 s1, s6, 16
	s_or_b32 s0, s0, s1
	s_lshl_b32 s1, s2, 14
	s_or_b32 s94, s0, s1
	s_lshl_b64 s[0:1], s[94:95], 2
	s_add_u32 s0, s28, s0
	s_addc_u32 s1, s29, s1
	v_lshlrev_b32_e32 v4, 2, v86
	v_lshl_or_b32 v2, v84, 2, v85
	v_lshl_add_u64 v[0:1], s[0:1], 0, v[4:5]
	s_mov_b64 s[0:1], 0x2080000
	v_ashrrev_i32_e32 v3, 31, v2
	v_or_b32_e32 v72, 1, v2
	v_lshl_add_u64 v[0:1], v[0:1], 0, s[0:1]
	v_lshlrev_b64 v[70:71], 9, v[2:3]
	v_ashrrev_i32_e32 v73, 31, v72
	v_lshl_add_u64 v[70:71], v[0:1], 0, v[70:71]
	v_lshlrev_b64 v[72:73], 9, v[72:73]
	global_store_dword v[70:71], v54, off
	v_lshl_add_u64 v[72:73], v[0:1], 0, v[72:73]
	v_or_b32_e32 v54, 2, v2
	global_store_dword v[72:73], v55, off
	v_ashrrev_i32_e32 v55, 31, v54
	v_or_b32_e32 v74, 3, v2
	v_lshlrev_b64 v[54:55], 9, v[54:55]
	v_ashrrev_i32_e32 v75, 31, v74
	v_lshl_add_u64 v[54:55], v[0:1], 0, v[54:55]
	v_lshlrev_b64 v[74:75], 9, v[74:75]
	global_store_dword v[54:55], v56, off
	v_lshl_add_u64 v[74:75], v[0:1], 0, v[74:75]
	v_or_b32_e32 v56, 8, v2
	global_store_dword v[74:75], v57, off
	v_ashrrev_i32_e32 v57, 31, v56
	v_or_b32_e32 v76, 9, v2
	v_lshlrev_b64 v[56:57], 9, v[56:57]
	v_ashrrev_i32_e32 v77, 31, v76
	v_lshl_add_u64 v[56:57], v[0:1], 0, v[56:57]
	v_lshlrev_b64 v[76:77], 9, v[76:77]
	global_store_dword v[56:57], v58, off
	v_lshl_add_u64 v[76:77], v[0:1], 0, v[76:77]
	v_or_b32_e32 v58, 10, v2
	global_store_dword v[76:77], v59, off
	v_ashrrev_i32_e32 v59, 31, v58
	v_or_b32_e32 v78, 11, v2
	v_lshlrev_b64 v[58:59], 9, v[58:59]
	v_ashrrev_i32_e32 v79, 31, v78
	v_lshl_add_u64 v[58:59], v[0:1], 0, v[58:59]
	v_lshlrev_b64 v[78:79], 9, v[78:79]
	global_store_dword v[58:59], v60, off
	v_lshl_add_u64 v[78:79], v[0:1], 0, v[78:79]
	v_or_b32_e32 v60, 16, v2
	global_store_dword v[78:79], v61, off
	v_ashrrev_i32_e32 v61, 31, v60
	v_or_b32_e32 v80, 17, v2
	v_lshlrev_b64 v[60:61], 9, v[60:61]
	v_ashrrev_i32_e32 v81, 31, v80
	v_lshl_add_u64 v[60:61], v[0:1], 0, v[60:61]
	v_lshlrev_b64 v[80:81], 9, v[80:81]
	global_store_dword v[60:61], v62, off
	v_lshl_add_u64 v[80:81], v[0:1], 0, v[80:81]
	v_or_b32_e32 v62, 18, v2
	global_store_dword v[80:81], v63, off
	v_ashrrev_i32_e32 v63, 31, v62
	v_or_b32_e32 v82, 19, v2
	v_lshlrev_b64 v[62:63], 9, v[62:63]
	v_ashrrev_i32_e32 v83, 31, v82
	v_lshl_add_u64 v[62:63], v[0:1], 0, v[62:63]
	v_lshlrev_b64 v[82:83], 9, v[82:83]
	global_store_dword v[62:63], v64, off
	v_lshl_add_u64 v[82:83], v[0:1], 0, v[82:83]
	v_or_b32_e32 v64, 24, v2
	global_store_dword v[82:83], v65, off
	v_ashrrev_i32_e32 v65, 31, v64
	v_or_b32_e32 v84, 25, v2
	v_lshlrev_b64 v[64:65], 9, v[64:65]
	v_ashrrev_i32_e32 v85, 31, v84
	v_lshl_add_u64 v[64:65], v[0:1], 0, v[64:65]
	v_lshlrev_b64 v[84:85], 9, v[84:85]
	global_store_dword v[64:65], v66, off
	v_lshl_add_u64 v[84:85], v[0:1], 0, v[84:85]
	v_or_b32_e32 v66, 26, v2
	v_or_b32_e32 v2, 27, v2
	global_store_dword v[84:85], v67, off
	v_ashrrev_i32_e32 v67, 31, v66
	v_ashrrev_i32_e32 v3, 31, v2
	v_lshlrev_b64 v[66:67], 9, v[66:67]
	v_lshlrev_b64 v[2:3], 9, v[2:3]
	v_lshl_add_u64 v[66:67], v[0:1], 0, v[66:67]
	v_lshl_add_u64 v[0:1], v[0:1], 0, v[2:3]
	global_store_dword v[66:67], v68, off
	global_store_dword v[0:1], v69, off
	global_store_dword v[70:71], v38, off offset:128
	global_store_dword v[72:73], v39, off offset:128
	global_store_dword v[54:55], v40, off offset:128
	global_store_dword v[74:75], v41, off offset:128
	global_store_dword v[56:57], v42, off offset:128
	global_store_dword v[76:77], v43, off offset:128
	global_store_dword v[58:59], v44, off offset:128
	global_store_dword v[78:79], v45, off offset:128
	global_store_dword v[60:61], v46, off offset:128
	global_store_dword v[80:81], v47, off offset:128
	global_store_dword v[62:63], v48, off offset:128
	global_store_dword v[82:83], v49, off offset:128
	global_store_dword v[64:65], v50, off offset:128
	global_store_dword v[84:85], v51, off offset:128
	global_store_dword v[66:67], v52, off offset:128
	global_store_dword v[0:1], v53, off offset:128
	global_store_dword v[70:71], v22, off offset:256
	global_store_dword v[72:73], v23, off offset:256
	global_store_dword v[54:55], v24, off offset:256
	global_store_dword v[74:75], v25, off offset:256
	global_store_dword v[56:57], v26, off offset:256
	global_store_dword v[76:77], v27, off offset:256
	global_store_dword v[58:59], v28, off offset:256
	global_store_dword v[78:79], v29, off offset:256
	global_store_dword v[60:61], v30, off offset:256
	global_store_dword v[80:81], v31, off offset:256
	global_store_dword v[62:63], v32, off offset:256
	global_store_dword v[82:83], v33, off offset:256
	global_store_dword v[64:65], v34, off offset:256
	global_store_dword v[84:85], v35, off offset:256
	global_store_dword v[66:67], v36, off offset:256
	global_store_dword v[0:1], v37, off offset:256
	global_store_dword v[70:71], v6, off offset:384
	global_store_dword v[72:73], v7, off offset:384
	global_store_dword v[54:55], v8, off offset:384
	global_store_dword v[74:75], v9, off offset:384
	global_store_dword v[56:57], v10, off offset:384
	global_store_dword v[76:77], v11, off offset:384
	global_store_dword v[58:59], v12, off offset:384
	global_store_dword v[78:79], v13, off offset:384
	global_store_dword v[60:61], v14, off offset:384
	global_store_dword v[80:81], v15, off offset:384
	global_store_dword v[62:63], v16, off offset:384
	global_store_dword v[82:83], v17, off offset:384
	global_store_dword v[64:65], v18, off offset:384
	global_store_dword v[84:85], v19, off offset:384
	global_store_dword v[66:67], v20, off offset:384
	global_store_dword v[0:1], v21, off offset:384
	s_mov_b64 s[0:1], 0

.LBB0_3734:
	s_setprio 1
	ds_read_b128 v[148:151], v112
	ds_read_b128 v[152:155], v113 offset:36864
	ds_read_b128 v[156:159], v112 offset:32
	ds_read_b128 v[160:163], v113 offset:36896
	ds_read_b128 v[164:167], v113 offset:41472
	ds_read_b128 v[168:171], v113 offset:41504
	s_waitcnt lgkmcnt(4)
	v_mfma_f32_32x32x16_bf16 v[48:63], v[148:151], v[152:155], v[48:63]
	global_load_dwordx4 v[116:119], v176, s[98:99] offset:256
	global_load_dwordx4 v[120:123], v180, s[98:99] offset:256
	s_waitcnt vmcnt(9)
	ds_write_b128 v114, v[64:67] offset:18432
	s_waitcnt lgkmcnt(2)
	v_mfma_f32_32x32x16_bf16 v[32:47], v[148:151], v[164:167], v[32:47]
	global_load_dwordx4 v[124:127], v182, s[98:99] offset:256
	global_load_dwordx4 v[128:131], v184, s[98:99] offset:256
	ds_read_b128 v[148:151], v112 offset:4608
	ds_read_b128 v[172:175], v112 offset:4640
	s_waitcnt lgkmcnt(1)
	v_mfma_f32_32x32x16_bf16 v[16:31], v[148:151], v[152:155], v[16:31]
	global_load_dwordx4 v[132:135], v178, s[98:99]
	global_load_dwordx4 v[136:139], v98, s[98:99]
	s_waitcnt vmcnt(12)
	ds_write_b128 v114, v[68:71] offset:23040
	v_mfma_f32_32x32x16_bf16 v[0:15], v[148:151], v[164:167], v[0:15]
	global_load_dwordx4 v[140:143], v186, s[98:99]
	global_load_dwordx4 v[144:147], v188, s[98:99] offset:-128
	v_mfma_f32_32x32x16_bf16 v[48:63], v[156:159], v[160:163], v[48:63]
	s_waitcnt vmcnt(13)
	ds_write_b128 v114, v[72:75] offset:27648
	v_mfma_f32_32x32x16_bf16 v[32:47], v[156:159], v[168:171], v[32:47]
	s_waitcnt lgkmcnt(2)
	v_mfma_f32_32x32x16_bf16 v[16:31], v[172:175], v[160:163], v[16:31]
	s_waitcnt vmcnt(12)
	ds_write_b128 v114, v[76:79] offset:32256
	ds_read_b128 v[148:151], v112 offset:64
	ds_read_b128 v[152:155], v113 offset:36928
	ds_read_b128 v[156:159], v112 offset:96
	ds_read_b128 v[160:163], v113 offset:36960
	v_mfma_f32_32x32x16_bf16 v[0:15], v[172:175], v[168:171], v[0:15]
	ds_read_b128 v[164:167], v113 offset:41536
	ds_read_b128 v[168:171], v113 offset:41568
	s_waitcnt lgkmcnt(4)
	v_mfma_f32_32x32x16_bf16 v[48:63], v[148:151], v[152:155], v[48:63]
	s_waitcnt vmcnt(11)
	ds_write_b128 v114, v[80:83] offset:55296
	s_waitcnt lgkmcnt(2)
	v_mfma_f32_32x32x16_bf16 v[32:47], v[148:151], v[164:167], v[32:47]
	ds_read_b128 v[148:151], v112 offset:4672
	ds_read_b128 v[172:175], v112 offset:4704
	s_waitcnt lgkmcnt(1)
	v_mfma_f32_32x32x16_bf16 v[16:31], v[148:151], v[152:155], v[16:31]
	s_waitcnt vmcnt(10)
	ds_write_b128 v114, v[84:87] offset:59904
	v_mfma_f32_32x32x16_bf16 v[0:15], v[148:151], v[164:167], v[0:15]
	v_mfma_f32_32x32x16_bf16 v[48:63], v[156:159], v[160:163], v[48:63]
	s_waitcnt vmcnt(9)
	ds_write_b128 v114, v[88:91] offset:64512
	v_mfma_f32_32x32x16_bf16 v[32:47], v[156:159], v[168:171], v[32:47]
	s_waitcnt lgkmcnt(2)
	v_mfma_f32_32x32x16_bf16 v[16:31], v[172:175], v[160:163], v[16:31]
	s_waitcnt vmcnt(8)
	ds_write_b128 v115, v[92:95] offset:13824
	v_mfma_f32_32x32x16_bf16 v[0:15], v[172:175], v[168:171], v[0:15]
	s_setprio 0
	s_waitcnt lgkmcnt(0)
	s_barrier
	s_setprio 1
	ds_read_b128 v[148:151], v112 offset:18432
	ds_read_b128 v[152:155], v113 offset:55296
	ds_read_b128 v[156:159], v112 offset:18464
	ds_read_b128 v[160:163], v113 offset:55328
	ds_read_b128 v[164:167], v113 offset:59904
	ds_read_b128 v[168:171], v113 offset:59936
	s_waitcnt lgkmcnt(4)
	v_mfma_f32_32x32x16_bf16 v[48:63], v[148:151], v[152:155], v[48:63]
	global_load_dwordx4 v[64:67], v176, s[98:99] offset:384
	global_load_dwordx4 v[68:71], v180, s[98:99] offset:384
	s_waitcnt vmcnt(9)
	ds_write_b128 v114, v[116:119]
	s_waitcnt lgkmcnt(2)
	v_mfma_f32_32x32x16_bf16 v[32:47], v[148:151], v[164:167], v[32:47]
	global_load_dwordx4 v[72:75], v182, s[98:99] offset:384
	global_load_dwordx4 v[76:79], v184, s[98:99] offset:384
	ds_read_b128 v[148:151], v112 offset:23040
	ds_read_b128 v[172:175], v112 offset:23072
	s_waitcnt lgkmcnt(1)
	v_mfma_f32_32x32x16_bf16 v[16:31], v[148:151], v[152:155], v[16:31]
	global_load_dwordx4 v[80:83], v178, s[98:99] offset:128
	global_load_dwordx4 v[84:87], v99, s[98:99]
	s_waitcnt vmcnt(12)
	ds_write_b128 v114, v[120:123] offset:4608
	v_mfma_f32_32x32x16_bf16 v[0:15], v[148:151], v[164:167], v[0:15]
	global_load_dwordx4 v[88:91], v186, s[98:99] offset:128
	global_load_dwordx4 v[92:95], v188, s[98:99]
	v_mfma_f32_32x32x16_bf16 v[48:63], v[156:159], v[160:163], v[48:63]
	s_add_u32 s98, s98, 0x100
	s_addc_u32 s99, s99, 0
	s_add_i32 s0, s0, 2
	s_cmp_lt_u32 s0, 3
	s_waitcnt vmcnt(13)
	ds_write_b128 v114, v[124:127] offset:9216
	v_mfma_f32_32x32x16_bf16 v[32:47], v[156:159], v[168:171], v[32:47]
	s_waitcnt lgkmcnt(2)
	v_mfma_f32_32x32x16_bf16 v[16:31], v[172:175], v[160:163], v[16:31]
	s_waitcnt vmcnt(12)
	ds_write_b128 v114, v[128:131] offset:13824
	ds_read_b128 v[148:151], v112 offset:18496
	ds_read_b128 v[152:155], v113 offset:55360
	ds_read_b128 v[156:159], v112 offset:18528
	ds_read_b128 v[160:163], v113 offset:55392
	v_mfma_f32_32x32x16_bf16 v[0:15], v[172:175], v[168:171], v[0:15]
	ds_read_b128 v[164:167], v113 offset:59968
	ds_read_b128 v[168:171], v113 offset:60000
	s_waitcnt lgkmcnt(4)
	v_mfma_f32_32x32x16_bf16 v[48:63], v[148:151], v[152:155], v[48:63]
	s_waitcnt vmcnt(11)
	ds_write_b128 v114, v[132:135] offset:36864
	s_waitcnt lgkmcnt(2)
	v_mfma_f32_32x32x16_bf16 v[32:47], v[148:151], v[164:167], v[32:47]
	ds_read_b128 v[148:151], v112 offset:23104
	ds_read_b128 v[172:175], v112 offset:23136
	s_waitcnt lgkmcnt(1)
	v_mfma_f32_32x32x16_bf16 v[16:31], v[148:151], v[152:155], v[16:31]
	s_waitcnt vmcnt(10)
	ds_write_b128 v114, v[136:139] offset:41472
	v_mfma_f32_32x32x16_bf16 v[0:15], v[148:151], v[164:167], v[0:15]
	v_mfma_f32_32x32x16_bf16 v[48:63], v[156:159], v[160:163], v[48:63]
	s_waitcnt vmcnt(9)
	ds_write_b128 v114, v[140:143] offset:46080
	v_mfma_f32_32x32x16_bf16 v[32:47], v[156:159], v[168:171], v[32:47]
	s_waitcnt lgkmcnt(2)
	v_mfma_f32_32x32x16_bf16 v[16:31], v[172:175], v[160:163], v[16:31]
	s_waitcnt vmcnt(8)
	ds_write_b128 v114, v[144:147] offset:50688
	v_mfma_f32_32x32x16_bf16 v[0:15], v[172:175], v[168:171], v[0:15]
	s_setprio 0
	s_waitcnt lgkmcnt(0)
	s_barrier
	s_cbranch_scc1 .LBB0_3734
	s_setprio 1
	ds_read_b128 v[98:101], v112
	ds_read_b128 v[102:105], v113 offset:36864
	ds_read_b128 v[106:109], v112 offset:32
	ds_read_b128 v[116:119], v113 offset:36896
	ds_read_b128 v[120:123], v113 offset:41472
	ds_read_b128 v[124:127], v113 offset:41504
	s_waitcnt lgkmcnt(4)
	v_mfma_f32_32x32x16_bf16 v[48:63], v[98:101], v[102:105], v[48:63]
	s_waitcnt vmcnt(7)
	ds_write_b128 v114, v[64:67] offset:18432
	s_waitcnt lgkmcnt(2)
	v_mfma_f32_32x32x16_bf16 v[32:47], v[98:101], v[120:123], v[32:47]
	ds_read_b128 v[98:101], v112 offset:4608
	ds_read_b128 v[128:131], v112 offset:4640
	s_waitcnt lgkmcnt(1)
	v_mfma_f32_32x32x16_bf16 v[16:31], v[98:101], v[102:105], v[16:31]
	s_waitcnt vmcnt(6)
	ds_write_b128 v114, v[68:71] offset:23040
	v_mfma_f32_32x32x16_bf16 v[0:15], v[98:101], v[120:123], v[0:15]
	v_mfma_f32_32x32x16_bf16 v[48:63], v[106:109], v[116:119], v[48:63]
	s_waitcnt vmcnt(5)
	ds_write_b128 v114, v[72:75] offset:27648
	v_mfma_f32_32x32x16_bf16 v[32:47], v[106:109], v[124:127], v[32:47]
	s_waitcnt lgkmcnt(2)
	v_mfma_f32_32x32x16_bf16 v[16:31], v[128:131], v[116:119], v[16:31]
	s_waitcnt vmcnt(4)
	ds_write_b128 v114, v[76:79] offset:32256
	ds_read_b128 v[98:101], v112 offset:64
	ds_read_b128 v[102:105], v113 offset:36928
	ds_read_b128 v[106:109], v112 offset:96
	ds_read_b128 v[116:119], v113 offset:36960
	v_mfma_f32_32x32x16_bf16 v[0:15], v[128:131], v[124:127], v[0:15]
	ds_read_b128 v[120:123], v113 offset:41536
	ds_read_b128 v[124:127], v113 offset:41568
	s_waitcnt lgkmcnt(4)
	v_mfma_f32_32x32x16_bf16 v[48:63], v[98:101], v[102:105], v[48:63]
	s_waitcnt vmcnt(3)
	ds_write_b128 v114, v[80:83] offset:55296
	s_waitcnt lgkmcnt(2)
	v_mfma_f32_32x32x16_bf16 v[32:47], v[98:101], v[120:123], v[32:47]
	ds_read_b128 v[98:101], v112 offset:4672
	ds_read_b128 v[128:131], v112 offset:4704
	s_waitcnt lgkmcnt(1)
	v_mfma_f32_32x32x16_bf16 v[16:31], v[98:101], v[102:105], v[16:31]
	s_waitcnt vmcnt(2)
	ds_write_b128 v114, v[84:87] offset:59904
	v_mfma_f32_32x32x16_bf16 v[0:15], v[98:101], v[120:123], v[0:15]
	s_waitcnt lgkmcnt(1)
	v_mfma_f32_32x32x16_bf16 v[16:31], v[128:131], v[116:119], v[16:31]
	s_waitcnt vmcnt(1)
	ds_write_b128 v114, v[88:91] offset:64512
	v_mfma_f32_32x32x16_bf16 v[0:15], v[128:131], v[124:127], v[0:15]
	v_mfma_f32_32x32x16_bf16 v[48:63], v[106:109], v[116:119], v[48:63]
	s_waitcnt vmcnt(0)
	ds_write_b128 v115, v[92:95] offset:13824
	v_mfma_f32_32x32x16_bf16 v[32:47], v[106:109], v[124:127], v[32:47]
	s_setprio 0
	s_waitcnt lgkmcnt(0)
	s_barrier
	s_setprio 1
	ds_read_b128 v[64:67], v112 offset:18432
	ds_read_b128 v[68:71], v113 offset:55296
	ds_read_b128 v[72:75], v112 offset:18464
	ds_read_b128 v[76:79], v113 offset:55328
	ds_read_b128 v[80:83], v113 offset:59904
	ds_read_b128 v[84:87], v113 offset:59936
	s_waitcnt lgkmcnt(4)
	v_mfma_f32_32x32x16_bf16 v[48:63], v[64:67], v[68:71], v[48:63]
	s_waitcnt lgkmcnt(1)
	v_mfma_f32_32x32x16_bf16 v[32:47], v[64:67], v[80:83], v[32:47]
	ds_read_b128 v[64:67], v112 offset:23040
	ds_read_b128 v[88:91], v112 offset:23072
	s_waitcnt lgkmcnt(1)
	v_mfma_f32_32x32x16_bf16 v[16:31], v[64:67], v[68:71], v[16:31]
	v_mfma_f32_32x32x16_bf16 v[0:15], v[64:67], v[80:83], v[0:15]
	v_mfma_f32_32x32x16_bf16 v[48:63], v[72:75], v[76:79], v[48:63]
	v_mfma_f32_32x32x16_bf16 v[32:47], v[72:75], v[84:87], v[32:47]
	s_waitcnt lgkmcnt(0)
	v_mfma_f32_32x32x16_bf16 v[16:31], v[88:91], v[76:79], v[16:31]
	ds_read_b128 v[64:67], v112 offset:18496
	ds_read_b128 v[68:71], v113 offset:55360
	ds_read_b128 v[72:75], v112 offset:18528
	ds_read_b128 v[76:79], v113 offset:55392
	v_mfma_f32_32x32x16_bf16 v[0:15], v[88:91], v[84:87], v[0:15]
	ds_read_b128 v[80:83], v113 offset:59968
	ds_read_b128 v[84:87], v113 offset:60000
	s_waitcnt lgkmcnt(4)
	v_mfma_f32_32x32x16_bf16 v[48:63], v[64:67], v[68:71], v[48:63]
	s_waitcnt lgkmcnt(1)
	v_mfma_f32_32x32x16_bf16 v[32:47], v[64:67], v[80:83], v[32:47]
	ds_read_b128 v[64:67], v112 offset:23104
	ds_read_b128 v[88:91], v112 offset:23136
	s_waitcnt lgkmcnt(1)
	v_mfma_f32_32x32x16_bf16 v[16:31], v[64:67], v[68:71], v[16:31]
	v_mfma_f32_32x32x16_bf16 v[0:15], v[64:67], v[80:83], v[0:15]
	s_waitcnt lgkmcnt(0)
	v_mfma_f32_32x32x16_bf16 v[16:31], v[88:91], v[76:79], v[16:31]
	v_mfma_f32_32x32x16_bf16 v[0:15], v[88:91], v[84:87], v[0:15]
	v_mfma_f32_32x32x16_bf16 v[48:63], v[72:75], v[76:79], v[48:63]
	v_mfma_f32_32x32x16_bf16 v[32:47], v[72:75], v[84:87], v[32:47]
	s_setprio 0
	s_nop 10
	v_cvt_pk_bf16_f32 v32, v32, s0
	v_cvt_pk_bf16_f32 v0, v0, s0
	s_barrier
	ds_write_b16 v111, v32 offset:64
	v_cvt_pk_bf16_f32 v32, v49, s0
	ds_write_b16 v111, v0 offset:8768
	v_cvt_pk_bf16_f32 v0, v17, s0
	ds_write_b16 v111, v32 offset:272
	v_cvt_pk_bf16_f32 v32, v33, s0
	ds_write_b16 v111, v0 offset:8976
	v_cvt_pk_bf16_f32 v0, v1, s0
	ds_write_b16 v111, v32 offset:336
	v_cvt_pk_bf16_f32 v32, v50, s0
	ds_write_b16 v111, v0 offset:9040
	v_cvt_pk_bf16_f32 v0, v18, s0
	ds_write_b16 v111, v32 offset:544
	v_cvt_pk_bf16_f32 v32, v34, s0
	ds_write_b16 v111, v0 offset:9248
	v_cvt_pk_bf16_f32 v0, v2, s0
	ds_write_b16 v111, v32 offset:608
	v_cvt_pk_bf16_f32 v32, v51, s0
	ds_write_b16 v111, v0 offset:9312
	v_cvt_pk_bf16_f32 v0, v19, s0
	ds_write_b16 v111, v32 offset:816
	v_cvt_pk_bf16_f32 v32, v35, s0
	ds_write_b16 v111, v0 offset:9520
	v_cvt_pk_bf16_f32 v0, v3, s0
	ds_write_b16 v111, v32 offset:880
	v_cvt_pk_bf16_f32 v32, v52, s0
	ds_write_b16 v111, v0 offset:9584
	v_cvt_pk_bf16_f32 v0, v20, s0
	ds_write_b16 v111, v32 offset:2176
	v_cvt_pk_bf16_f32 v32, v36, s0
	ds_write_b16 v111, v0 offset:10880
	v_cvt_pk_bf16_f32 v0, v4, s0
	ds_write_b16 v111, v32 offset:2240
	v_cvt_pk_bf16_f32 v32, v53, s0
	ds_write_b16 v111, v0 offset:10944
	v_cvt_pk_bf16_f32 v0, v21, s0
	ds_write_b16 v111, v32 offset:2448
	v_cvt_pk_bf16_f32 v32, v37, s0
	ds_write_b16 v111, v0 offset:11152
	v_cvt_pk_bf16_f32 v0, v5, s0
	ds_write_b16 v111, v32 offset:2512
	v_cvt_pk_bf16_f32 v32, v54, s0
	ds_write_b16 v111, v0 offset:11216
	v_cvt_pk_bf16_f32 v0, v22, s0
	ds_write_b16 v111, v32 offset:2720
	v_cvt_pk_bf16_f32 v32, v38, s0
	ds_write_b16 v111, v0 offset:11424
	v_cvt_pk_bf16_f32 v0, v6, s0
	ds_write_b16 v111, v32 offset:2784
	v_cvt_pk_bf16_f32 v32, v55, s0
	ds_write_b16 v111, v0 offset:11488
	v_cvt_pk_bf16_f32 v0, v23, s0
	ds_write_b16 v111, v32 offset:2992
	v_cvt_pk_bf16_f32 v32, v39, s0
	ds_write_b16 v111, v0 offset:11696
	v_cvt_pk_bf16_f32 v0, v7, s0
	ds_write_b16 v111, v32 offset:3056
	v_cvt_pk_bf16_f32 v32, v56, s0
	ds_write_b16 v111, v0 offset:11760
	v_cvt_pk_bf16_f32 v0, v24, s0
	ds_write_b16 v111, v32 offset:4352
	v_cvt_pk_bf16_f32 v32, v40, s0
	ds_write_b16 v111, v0 offset:13056
	v_cvt_pk_bf16_f32 v0, v8, s0
	ds_write_b16 v111, v32 offset:4416
	v_cvt_pk_bf16_f32 v32, v57, s0
	ds_write_b16 v111, v0 offset:13120
	v_cvt_pk_bf16_f32 v0, v25, s0
	ds_write_b16 v111, v32 offset:4624
	v_cvt_pk_bf16_f32 v32, v41, s0
	ds_write_b16 v111, v0 offset:13328
	v_cvt_pk_bf16_f32 v0, v9, s0
	ds_write_b16 v111, v32 offset:4688
	v_cvt_pk_bf16_f32 v32, v58, s0
	ds_write_b16 v111, v0 offset:13392
	v_cvt_pk_bf16_f32 v0, v26, s0
	ds_write_b16 v111, v32 offset:4896
	v_cvt_pk_bf16_f32 v32, v42, s0
	ds_write_b16 v111, v0 offset:13600
	v_cvt_pk_bf16_f32 v0, v10, s0
	ds_write_b16 v111, v32 offset:4960
	v_cvt_pk_bf16_f32 v32, v59, s0
	ds_write_b16 v111, v0 offset:13664
	v_cvt_pk_bf16_f32 v0, v27, s0
	ds_write_b16 v111, v32 offset:5168
	v_cvt_pk_bf16_f32 v32, v43, s0
	ds_write_b16 v111, v0 offset:13872
	v_cvt_pk_bf16_f32 v0, v11, s0
	ds_write_b16 v111, v32 offset:5232
	v_cvt_pk_bf16_f32 v32, v60, s0
	ds_write_b16 v111, v0 offset:13936
	v_cvt_pk_bf16_f32 v0, v28, s0
	ds_write_b16 v111, v32 offset:6528
	v_cvt_pk_bf16_f32 v32, v44, s0
	ds_write_b16 v111, v0 offset:15232
	v_cvt_pk_bf16_f32 v0, v12, s0
	ds_write_b16 v111, v32 offset:6592
	v_cvt_pk_bf16_f32 v32, v61, s0
	ds_write_b16 v111, v0 offset:15296
	v_cvt_pk_bf16_f32 v0, v29, s0
	ds_write_b16 v111, v32 offset:6800
	v_cvt_pk_bf16_f32 v32, v45, s0
	ds_write_b16 v111, v0 offset:15504
	v_cvt_pk_bf16_f32 v0, v13, s0
	ds_write_b16 v111, v32 offset:6864
	v_cvt_pk_bf16_f32 v32, v62, s0
	ds_write_b16 v111, v0 offset:15568
	v_cvt_pk_bf16_f32 v0, v30, s0
	ds_write_b16 v111, v32 offset:7072
	v_cvt_pk_bf16_f32 v32, v46, s0
	ds_write_b16 v111, v0 offset:15776
	v_cvt_pk_bf16_f32 v0, v14, s0
	ds_write_b16 v111, v32 offset:7136
	v_cvt_pk_bf16_f32 v32, v63, s0
	ds_write_b16 v111, v0 offset:15840
	v_cvt_pk_bf16_f32 v0, v31, s0
	v_cvt_pk_bf16_f32 v48, v48, s0
	ds_write_b16 v111, v32 offset:7344
	v_cvt_pk_bf16_f32 v32, v47, s0
	v_cvt_pk_bf16_f32 v16, v16, s0
	ds_write_b16 v111, v0 offset:16048
	v_cvt_pk_bf16_f32 v0, v15, s0
	v_mov_b32_e32 v15, v110
	ds_write_b16 v111, v48
	ds_write_b16 v111, v32 offset:7408
	ds_write_b16 v111, v16 offset:8704
	ds_write_b16 v111, v0 offset:16112
	s_waitcnt lgkmcnt(0)
	s_barrier
	v_mov_b64_e32 v[2:3], s[4:5]
	v_lshlrev_b32_e32 v0, 3, v15
	v_and_b32_e32 v0, 0x78, v0
	v_ashrrev_i32_e32 v1, 4, v15
	v_lshlrev_b32_e32 v96, 1, v0
	v_add_u32_e32 v0, s63, v1
	s_lshl_b32 s16, s26, 10
	v_mad_i64_i32 v[2:3], s[0:1], v0, s60, v[2:3]
	v_lshl_add_u64 v[2:3], s[16:17], 1, v[2:3]
	v_lshl_add_u64 v[2:3], s[22:23], 1, v[2:3]
	v_lshl_add_u64 v[2:3], v[2:3], 0, v[96:97]
	global_load_dwordx4 v[6:9], v[2:3], off
	v_add_co_u32_e32 v80, vcc, 0x18000, v2
	s_nop 1
	v_addc_co_u32_e32 v81, vcc, 0, v3, vcc
	global_load_dwordx4 v[24:27], v[80:81], off
	v_add_co_u32_e32 v80, vcc, 0x30000, v2
	s_nop 1
	v_addc_co_u32_e32 v81, vcc, 0, v3, vcc
	global_load_dwordx4 v[28:31], v[80:81], off
	v_add_co_u32_e32 v80, vcc, 0x48000, v2
	s_nop 1
	v_addc_co_u32_e32 v81, vcc, 0, v3, vcc
	global_load_dwordx4 v[32:35], v[80:81], off
	v_add_co_u32_e32 v80, vcc, 0x60000, v2
	s_nop 1
	v_addc_co_u32_e32 v81, vcc, 0, v3, vcc
	global_load_dwordx4 v[36:39], v[80:81], off
	v_add_co_u32_e32 v80, vcc, 0x78000, v2
	s_nop 1
	v_addc_co_u32_e32 v81, vcc, 0, v3, vcc
	global_load_dwordx4 v[40:43], v[80:81], off
	v_add_co_u32_e32 v80, vcc, 0x90000, v2
	s_nop 1
	v_addc_co_u32_e32 v81, vcc, 0, v3, vcc
	global_load_dwordx4 v[44:47], v[80:81], off
	v_add_co_u32_e32 v80, vcc, 0xa8000, v2
	s_nop 1
	v_addc_co_u32_e32 v81, vcc, 0, v3, vcc
	global_load_dwordx4 v[48:51], v[80:81], off
	v_add_u32_e32 v14, 32, v96
	v_mad_u64_u32 v[2:3], s[0:1], v1, s54, v[14:15]
	ds_read_b128 v[2:5], v2
	v_ashrrev_i32_e32 v1, 31, v0
	v_lshlrev_b64 v[0:1], 11, v[0:1]
	v_lshl_add_u64 v[0:1], s[24:25], 0, v[0:1]
	v_lshl_add_u64 v[16:17], v[0:1], 0, v[96:97]
	v_cndmask_b32_e64 v1, 0, 1, s[44:45]
	v_mov_b32_e32 v0, 0
	v_cmp_ne_u32_e64 s[0:1], 1, v1
	s_andn2_b64 vcc, exec, s[44:45]
	v_mov_b32_e32 v10, 0
	v_mov_b32_e32 v11, 0
	v_mov_b32_e32 v12, 0
	v_mov_b32_e32 v13, 0
	s_cbranch_vccnz .LBB0_3737
	global_load_dwordx4 v[10:13], v[16:17], off
	v_add_co_u32_e32 v80, vcc, 0x8000, v16
	s_nop 1
	v_addc_co_u32_e32 v81, vcc, 0, v17, vcc
	global_load_dwordx4 v[52:55], v[80:81], off
	v_add_co_u32_e32 v80, vcc, 0x10000, v16
	s_nop 1
	v_addc_co_u32_e32 v81, vcc, 0, v17, vcc
	global_load_dwordx4 v[56:59], v[80:81], off
	v_add_co_u32_e32 v80, vcc, 0x18000, v16
	s_nop 1
	v_addc_co_u32_e32 v81, vcc, 0, v17, vcc
	global_load_dwordx4 v[60:63], v[80:81], off
	v_add_co_u32_e32 v80, vcc, 0x20000, v16
	s_nop 1
	v_addc_co_u32_e32 v81, vcc, 0, v17, vcc
	global_load_dwordx4 v[64:67], v[80:81], off
	v_add_co_u32_e32 v80, vcc, 0x28000, v16
	s_nop 1
	v_addc_co_u32_e32 v81, vcc, 0, v17, vcc
	global_load_dwordx4 v[68:71], v[80:81], off
	v_add_co_u32_e32 v80, vcc, 0x30000, v16
	s_nop 1
	v_addc_co_u32_e32 v81, vcc, 0, v17, vcc
	global_load_dwordx4 v[72:75], v[80:81], off
	v_add_co_u32_e32 v80, vcc, 0x38000, v16
	s_nop 1
	v_addc_co_u32_e32 v81, vcc, 0, v17, vcc
	global_load_dwordx4 v[76:79], v[80:81], off

.LBB0_3806:
	s_setprio 1
	ds_read_b128 v[140:143], v103
	ds_read_b128 v[144:147], v104 offset:36864
	ds_read_b128 v[148:151], v103 offset:32
	ds_read_b128 v[152:155], v104 offset:36896
	ds_read_b128 v[156:159], v104 offset:41472
	ds_read_b128 v[160:163], v104 offset:41504
	s_waitcnt lgkmcnt(4)
	v_mfma_f32_32x32x16_bf16 v[48:63], v[140:143], v[144:147], v[48:63]
	global_load_dwordx4 v[108:111], v168, s[98:99] offset:3840
	global_load_dwordx4 v[112:115], v170, s[98:99] offset:3840
	s_waitcnt vmcnt(9)
	ds_write_b128 v105, v[68:71] offset:18432
	s_waitcnt lgkmcnt(2)
	v_mfma_f32_32x32x16_bf16 v[32:47], v[140:143], v[156:159], v[32:47]
	global_load_dwordx4 v[116:119], v172, s[98:99] offset:3840
	global_load_dwordx4 v[120:123], v174, s[98:99] offset:3840
	ds_read_b128 v[140:143], v103 offset:4608
	ds_read_b128 v[164:167], v103 offset:4640
	s_waitcnt lgkmcnt(1)
	v_mfma_f32_32x32x16_bf16 v[16:31], v[140:143], v[144:147], v[16:31]
	global_load_dwordx4 v[124:127], v176, s[98:99] offset:3840
	global_load_dwordx4 v[128:131], v178, s[98:99] offset:3840
	s_waitcnt vmcnt(11)
	ds_write_b128 v105, v[84:87] offset:23040
	v_mfma_f32_32x32x16_bf16 v[0:15], v[140:143], v[156:159], v[0:15]
	global_load_dwordx4 v[132:135], v180, s[98:99] offset:3840
	global_load_dwordx4 v[136:139], v182, s[98:99] offset:3840
	v_mfma_f32_32x32x16_bf16 v[48:63], v[148:151], v[152:155], v[48:63]
	s_waitcnt vmcnt(12)
	ds_write_b128 v105, v[88:91] offset:27648
	v_mfma_f32_32x32x16_bf16 v[32:47], v[148:151], v[160:163], v[32:47]
	s_waitcnt lgkmcnt(2)
	v_mfma_f32_32x32x16_bf16 v[16:31], v[164:167], v[152:155], v[16:31]
	s_waitcnt vmcnt(11)
	ds_write_b128 v105, v[92:95] offset:32256
	ds_read_b128 v[140:143], v103 offset:64
	ds_read_b128 v[144:147], v104 offset:36928
	ds_read_b128 v[148:151], v103 offset:96
	ds_read_b128 v[152:155], v104 offset:36960
	v_mfma_f32_32x32x16_bf16 v[0:15], v[164:167], v[160:163], v[0:15]
	ds_read_b128 v[156:159], v104 offset:41536
	ds_read_b128 v[160:163], v104 offset:41568
	s_waitcnt lgkmcnt(4)
	v_mfma_f32_32x32x16_bf16 v[48:63], v[140:143], v[144:147], v[48:63]
	ds_write_b128 v105, v[64:67] offset:55296
	s_waitcnt lgkmcnt(2)
	v_mfma_f32_32x32x16_bf16 v[32:47], v[140:143], v[156:159], v[32:47]
	ds_read_b128 v[140:143], v103 offset:4672
	ds_read_b128 v[164:167], v103 offset:4704
	s_waitcnt lgkmcnt(1)
	v_mfma_f32_32x32x16_bf16 v[16:31], v[140:143], v[144:147], v[16:31]
	s_waitcnt vmcnt(10)
	ds_write_b128 v105, v[72:75] offset:59904
	v_mfma_f32_32x32x16_bf16 v[0:15], v[140:143], v[156:159], v[0:15]
	v_mfma_f32_32x32x16_bf16 v[48:63], v[148:151], v[152:155], v[48:63]
	s_waitcnt vmcnt(9)
	ds_write_b128 v105, v[76:79] offset:64512
	v_mfma_f32_32x32x16_bf16 v[32:47], v[148:151], v[160:163], v[32:47]
	s_waitcnt lgkmcnt(2)
	v_mfma_f32_32x32x16_bf16 v[16:31], v[164:167], v[152:155], v[16:31]
	s_waitcnt vmcnt(8)
	ds_write_b128 v106, v[80:83] offset:13824
	v_mfma_f32_32x32x16_bf16 v[0:15], v[164:167], v[160:163], v[0:15]
	s_setprio 0
	s_waitcnt lgkmcnt(0)
	s_barrier
	s_setprio 1
	ds_read_b128 v[140:143], v103 offset:18432
	ds_read_b128 v[144:147], v104 offset:55296
	ds_read_b128 v[148:151], v103 offset:18464
	ds_read_b128 v[152:155], v104 offset:55328
	ds_read_b128 v[156:159], v104 offset:59904
	ds_read_b128 v[160:163], v104 offset:59936
	s_waitcnt lgkmcnt(4)
	v_mfma_f32_32x32x16_bf16 v[48:63], v[140:143], v[144:147], v[48:63]
	global_load_dwordx4 v[68:71], v168, s[98:99] offset:3968
	global_load_dwordx4 v[84:87], v170, s[98:99] offset:3968
	s_waitcnt vmcnt(9)
	ds_write_b128 v105, v[108:111]
	s_waitcnt lgkmcnt(2)
	v_mfma_f32_32x32x16_bf16 v[32:47], v[140:143], v[156:159], v[32:47]
	global_load_dwordx4 v[88:91], v172, s[98:99] offset:3968
	global_load_dwordx4 v[92:95], v174, s[98:99] offset:3968
	ds_read_b128 v[140:143], v103 offset:23040
	ds_read_b128 v[164:167], v103 offset:23072
	s_waitcnt lgkmcnt(1)
	v_mfma_f32_32x32x16_bf16 v[16:31], v[140:143], v[144:147], v[16:31]
	global_load_dwordx4 v[64:67], v176, s[98:99] offset:3968
	global_load_dwordx4 v[72:75], v178, s[98:99] offset:3968
	s_waitcnt vmcnt(12)
	ds_write_b128 v105, v[112:115] offset:4608
	v_mfma_f32_32x32x16_bf16 v[0:15], v[140:143], v[156:159], v[0:15]
	global_load_dwordx4 v[76:79], v180, s[98:99] offset:3968
	global_load_dwordx4 v[80:83], v182, s[98:99] offset:3968
	v_mfma_f32_32x32x16_bf16 v[48:63], v[148:151], v[152:155], v[48:63]
	s_add_u32 s98, s98, 0x100
	s_addc_u32 s99, s99, 0
	s_add_i32 s10, s10, 2
	s_cmp_lt_u32 s10, 11
	s_waitcnt vmcnt(13)
	ds_write_b128 v105, v[116:119] offset:9216
	v_mfma_f32_32x32x16_bf16 v[32:47], v[148:151], v[160:163], v[32:47]
	s_waitcnt lgkmcnt(2)
	v_mfma_f32_32x32x16_bf16 v[16:31], v[164:167], v[152:155], v[16:31]
	s_waitcnt vmcnt(12)
	ds_write_b128 v105, v[120:123] offset:13824
	ds_read_b128 v[140:143], v103 offset:18496
	ds_read_b128 v[144:147], v104 offset:55360
	ds_read_b128 v[148:151], v103 offset:18528
	ds_read_b128 v[152:155], v104 offset:55392
	v_mfma_f32_32x32x16_bf16 v[0:15], v[164:167], v[160:163], v[0:15]
	ds_read_b128 v[156:159], v104 offset:59968
	ds_read_b128 v[160:163], v104 offset:60000
	s_waitcnt lgkmcnt(4)
	v_mfma_f32_32x32x16_bf16 v[48:63], v[140:143], v[144:147], v[48:63]
	s_waitcnt vmcnt(11)
	ds_write_b128 v105, v[124:127] offset:36864
	s_waitcnt lgkmcnt(2)
	v_mfma_f32_32x32x16_bf16 v[32:47], v[140:143], v[156:159], v[32:47]
	ds_read_b128 v[140:143], v103 offset:23104
	ds_read_b128 v[164:167], v103 offset:23136
	s_waitcnt lgkmcnt(1)
	v_mfma_f32_32x32x16_bf16 v[16:31], v[140:143], v[144:147], v[16:31]
	s_waitcnt vmcnt(10)
	ds_write_b128 v105, v[128:131] offset:41472
	v_mfma_f32_32x32x16_bf16 v[0:15], v[140:143], v[156:159], v[0:15]
	v_mfma_f32_32x32x16_bf16 v[48:63], v[148:151], v[152:155], v[48:63]
	s_waitcnt vmcnt(9)
	ds_write_b128 v105, v[132:135] offset:46080
	v_mfma_f32_32x32x16_bf16 v[32:47], v[148:151], v[160:163], v[32:47]
	s_waitcnt lgkmcnt(2)
	v_mfma_f32_32x32x16_bf16 v[16:31], v[164:167], v[152:155], v[16:31]
	s_waitcnt vmcnt(8)
	ds_write_b128 v105, v[136:139] offset:50688
	v_mfma_f32_32x32x16_bf16 v[0:15], v[164:167], v[160:163], v[0:15]
	s_setprio 0
	s_waitcnt lgkmcnt(0)
	s_barrier
	s_cbranch_scc1 .LBB0_3806
	s_setprio 1
	ds_read_b128 v[98:101], v103
	ds_read_b128 v[108:111], v104 offset:36864
	ds_read_b128 v[112:115], v103 offset:32
	ds_read_b128 v[116:119], v104 offset:36896
	ds_read_b128 v[120:123], v104 offset:41472
	ds_read_b128 v[124:127], v104 offset:41504
	s_waitcnt lgkmcnt(4)
	v_mfma_f32_32x32x16_bf16 v[48:63], v[98:101], v[108:111], v[48:63]
	s_waitcnt vmcnt(7)
	ds_write_b128 v105, v[68:71] offset:18432
	s_waitcnt lgkmcnt(2)
	v_mfma_f32_32x32x16_bf16 v[32:47], v[98:101], v[120:123], v[32:47]
	ds_read_b128 v[98:101], v103 offset:4608
	ds_read_b128 v[128:131], v103 offset:4640
	s_waitcnt lgkmcnt(1)
	v_mfma_f32_32x32x16_bf16 v[16:31], v[98:101], v[108:111], v[16:31]
	s_waitcnt vmcnt(6)
	ds_write_b128 v105, v[84:87] offset:23040
	v_mfma_f32_32x32x16_bf16 v[0:15], v[98:101], v[120:123], v[0:15]
	v_mfma_f32_32x32x16_bf16 v[48:63], v[112:115], v[116:119], v[48:63]
	s_waitcnt vmcnt(5)
	ds_write_b128 v105, v[88:91] offset:27648
	v_mfma_f32_32x32x16_bf16 v[32:47], v[112:115], v[124:127], v[32:47]
	s_waitcnt lgkmcnt(2)
	v_mfma_f32_32x32x16_bf16 v[16:31], v[128:131], v[116:119], v[16:31]
	s_waitcnt vmcnt(4)
	ds_write_b128 v105, v[92:95] offset:32256
	ds_read_b128 v[98:101], v103 offset:64
	ds_read_b128 v[108:111], v104 offset:36928
	ds_read_b128 v[112:115], v103 offset:96
	ds_read_b128 v[116:119], v104 offset:36960
	v_mfma_f32_32x32x16_bf16 v[0:15], v[128:131], v[124:127], v[0:15]
	ds_read_b128 v[120:123], v104 offset:41536
	ds_read_b128 v[124:127], v104 offset:41568
	s_waitcnt lgkmcnt(4)
	v_mfma_f32_32x32x16_bf16 v[48:63], v[98:101], v[108:111], v[48:63]
	s_waitcnt vmcnt(3)
	ds_write_b128 v105, v[64:67] offset:55296
	s_waitcnt lgkmcnt(2)
	v_mfma_f32_32x32x16_bf16 v[32:47], v[98:101], v[120:123], v[32:47]
	ds_read_b128 v[98:101], v103 offset:4672
	ds_read_b128 v[128:131], v103 offset:4704
	s_waitcnt lgkmcnt(1)
	v_mfma_f32_32x32x16_bf16 v[16:31], v[98:101], v[108:111], v[16:31]
	s_waitcnt vmcnt(2)
	ds_write_b128 v105, v[72:75] offset:59904
	v_mfma_f32_32x32x16_bf16 v[0:15], v[98:101], v[120:123], v[0:15]
	v_mfma_f32_32x32x16_bf16 v[32:47], v[112:115], v[124:127], v[32:47]
	s_waitcnt vmcnt(1)
	ds_write_b128 v105, v[76:79] offset:64512
	s_waitcnt lgkmcnt(2)
	v_mfma_f32_32x32x16_bf16 v[16:31], v[128:131], v[116:119], v[16:31]
	v_mfma_f32_32x32x16_bf16 v[0:15], v[128:131], v[124:127], v[0:15]
	s_waitcnt vmcnt(0)
	ds_write_b128 v106, v[80:83] offset:13824
	v_mfma_f32_32x32x16_bf16 v[48:63], v[112:115], v[116:119], v[48:63]
	s_setprio 0
	s_waitcnt lgkmcnt(0)
	s_barrier
	s_setprio 1
	ds_read_b128 v[64:67], v103 offset:18432
	ds_read_b128 v[68:71], v104 offset:55296
	ds_read_b128 v[72:75], v103 offset:18464
	ds_read_b128 v[76:79], v104 offset:55328
	ds_read_b128 v[80:83], v104 offset:59904
	ds_read_b128 v[84:87], v104 offset:59936
	s_waitcnt lgkmcnt(4)
	v_mfma_f32_32x32x16_bf16 v[48:63], v[64:67], v[68:71], v[48:63]
	s_waitcnt lgkmcnt(1)
	v_mfma_f32_32x32x16_bf16 v[32:47], v[64:67], v[80:83], v[32:47]
	ds_read_b128 v[64:67], v103 offset:23040
	ds_read_b128 v[88:91], v103 offset:23072
	s_waitcnt lgkmcnt(1)
	v_mfma_f32_32x32x16_bf16 v[16:31], v[64:67], v[68:71], v[16:31]
	v_mfma_f32_32x32x16_bf16 v[0:15], v[64:67], v[80:83], v[0:15]
	v_mfma_f32_32x32x16_bf16 v[48:63], v[72:75], v[76:79], v[48:63]
	v_mfma_f32_32x32x16_bf16 v[32:47], v[72:75], v[84:87], v[32:47]
	s_waitcnt lgkmcnt(0)
	v_mfma_f32_32x32x16_bf16 v[16:31], v[88:91], v[76:79], v[16:31]
	ds_read_b128 v[64:67], v103 offset:18496
	ds_read_b128 v[68:71], v104 offset:55360
	ds_read_b128 v[72:75], v103 offset:18528
	ds_read_b128 v[76:79], v104 offset:55392
	v_mfma_f32_32x32x16_bf16 v[0:15], v[88:91], v[84:87], v[0:15]
	ds_read_b128 v[80:83], v104 offset:59968
	ds_read_b128 v[84:87], v104 offset:60000
	s_waitcnt lgkmcnt(4)
	v_mfma_f32_32x32x16_bf16 v[48:63], v[64:67], v[68:71], v[48:63]
	s_waitcnt lgkmcnt(1)
	v_mfma_f32_32x32x16_bf16 v[32:47], v[64:67], v[80:83], v[32:47]
	ds_read_b128 v[64:67], v103 offset:23104
	ds_read_b128 v[88:91], v103 offset:23136
	s_waitcnt lgkmcnt(1)
	v_mfma_f32_32x32x16_bf16 v[16:31], v[64:67], v[68:71], v[16:31]
	v_mfma_f32_32x32x16_bf16 v[0:15], v[64:67], v[80:83], v[0:15]
	v_mfma_f32_32x32x16_bf16 v[32:47], v[72:75], v[84:87], v[32:47]
	s_waitcnt lgkmcnt(0)
	v_mfma_f32_32x32x16_bf16 v[16:31], v[88:91], v[76:79], v[16:31]
	v_mfma_f32_32x32x16_bf16 v[0:15], v[88:91], v[84:87], v[0:15]
	v_mfma_f32_32x32x16_bf16 v[48:63], v[72:75], v[76:79], v[48:63]
	s_setprio 0
	s_addk_i32 s0, 0xf000
	s_lshr_b32 s10, s0, 10
	s_mulk_i32 s10, 0x1800
	s_add_i32 s10, s10, 0x9000
	s_and_b64 s[58:59], s[8:9], exec
	s_cselect_b32 s10, 0x7800, s10
	v_mov_b32_e32 v68, v234
	s_barrier
	s_lshl_b64 s[58:59], s[10:11], 2
	s_add_u32 s58, s30, s58
	v_and_b32_e32 v69, 0x5f, v68
	v_or_b32_e32 v64, s25, v69
	s_addc_u32 s59, s31, s59
	v_ashrrev_i32_e32 v65, 31, v64
	v_lshl_add_u64 v[64:65], v[64:65], 2, s[58:59]
	v_lshl_add_u64 v[66:67], v[64:65], 0, s[14:15]
	v_add_co_u32_e32 v64, vcc, s51, v64
	v_lshlrev_b32_e32 v69, 2, v69
	s_nop 0
	v_addc_co_u32_e32 v65, vcc, 0, v65, vcc
	global_load_dword v64, v[64:65], off
	s_nop 0
	global_load_dword v65, v[66:67], off offset:128
	v_lshrrev_b32_e32 v67, 3, v68
	v_lshrrev_b32_e32 v66, 1, v68
	v_and_b32_e32 v67, 4, v67
	v_and_or_b32 v66, v66, s42, v67
	v_mul_lo_u32 v66, v66, s52
	v_add3_u32 v66, 32, v69, v66
	v_add_u32_e32 v67, 0x400, v66
	v_add_u32_e32 v69, 0x1000, v66
	v_add_u32_e32 v70, 0x1400, v66
	v_add_u32_e32 v71, 0x2000, v66
	v_add_u32_e32 v72, 0x2400, v66
	v_add_u32_e32 v73, 0x3000, v66
	v_add_u32_e32 v74, 0x3200, v66
	v_add_u32_e32 v75, 0x3400, v66
	v_add_u32_e32 v76, 0x3600, v66
	v_add_u32_e32 v77, 0x4000, v66
	v_readlane_b32 s80, v250, 6
	v_readlane_b32 s81, v250, 7
	v_readlane_b32 s82, v250, 8
	v_readlane_b32 s83, v250, 9
	v_readlane_b32 s92, v250, 18
	v_readlane_b32 s93, v250, 19
	v_readlane_b32 s94, v250, 20
	v_readlane_b32 s95, v250, 21
	s_mov_b64 s[80:81], s[92:93]
	s_mov_b64 s[82:83], s[94:95]
	s_lshl_b32 s1, s1, 19
	s_add_u32 s10, s28, s1
	s_mov_b32 s1, s11
	v_readlane_b32 s84, v250, 10
	v_readlane_b32 s85, v250, 11
	v_readlane_b32 s86, v250, 12
	v_readlane_b32 s87, v250, 13
	v_readlane_b32 s88, v250, 14
	v_readlane_b32 s89, v250, 15
	v_readlane_b32 s90, v250, 16
	v_readlane_b32 s91, v250, 17
	s_waitcnt vmcnt(1)
	v_mul_f32_e32 v48, v48, v64
	s_waitcnt vmcnt(0)
	v_mul_f32_e32 v32, v32, v65
	v_mul_f32_e32 v16, v16, v64
	v_mul_f32_e32 v0, v0, v65
	v_mul_f32_e32 v49, v49, v64
	v_mul_f32_e32 v33, v33, v65
	v_mul_f32_e32 v50, v50, v64
	v_mul_f32_e32 v34, v34, v65
	v_mul_f32_e32 v51, v51, v64
	v_mul_f32_e32 v35, v35, v65
	v_mul_f32_e32 v52, v52, v64
	v_mul_f32_e32 v36, v36, v65
	v_mul_f32_e32 v53, v53, v64
	v_mul_f32_e32 v37, v37, v65
	v_mul_f32_e32 v54, v54, v64
	v_mul_f32_e32 v38, v38, v65
	v_mul_f32_e32 v55, v55, v64
	v_mul_f32_e32 v39, v39, v65
	v_mul_f32_e32 v56, v56, v64
	v_mul_f32_e32 v40, v40, v65
	v_mul_f32_e32 v57, v57, v64
	v_mul_f32_e32 v41, v41, v65
	v_mul_f32_e32 v58, v58, v64
	v_mul_f32_e32 v42, v42, v65
	v_mul_f32_e32 v59, v59, v64
	v_mul_f32_e32 v43, v43, v65
	v_mul_f32_e32 v60, v60, v64
	v_mul_f32_e32 v44, v44, v65
	v_mul_f32_e32 v61, v61, v64
	v_mul_f32_e32 v45, v45, v65
	v_mul_f32_e32 v62, v62, v64
	v_mul_f32_e32 v46, v46, v65
	v_mul_f32_e32 v63, v63, v64
	v_mul_f32_e32 v47, v47, v65
	ds_write2_b32 v66, v48, v32 offset1:32
	ds_write2_b32 v66, v49, v33 offset0:132 offset1:164
	ds_write2_b32 v67, v50, v34 offset0:8 offset1:40
	ds_write2_b32 v67, v51, v35 offset0:140 offset1:172
	ds_write2_b32 v69, v52, v36 offset0:32 offset1:64
	ds_write2_b32 v69, v53, v37 offset0:164 offset1:196
	ds_write2_b32 v70, v54, v38 offset0:40 offset1:72
	ds_write2_b32 v70, v55, v39 offset0:172 offset1:204
	ds_write2_b32 v71, v56, v40 offset0:64 offset1:96
	ds_write2_b32 v71, v57, v41 offset0:196 offset1:228
	ds_write2_b32 v72, v58, v42 offset0:72 offset1:104
	ds_write2_b32 v72, v59, v43 offset0:204 offset1:236
	ds_write2_b32 v73, v60, v44 offset0:96 offset1:128
	ds_write2_b32 v74, v61, v45 offset0:100 offset1:132
	ds_write2_b32 v75, v62, v46 offset0:104 offset1:136
	ds_write2_b32 v76, v63, v47 offset0:108 offset1:140
	ds_write2_b32 v77, v16, v0 offset0:128 offset1:160
	v_mul_f32_e32 v0, v17, v64
	v_mul_f32_e32 v1, v1, v65
	v_add_u32_e32 v16, 0x4400, v66
	ds_write2_b32 v16, v0, v1 offset0:4 offset1:36
	v_mul_f32_e32 v0, v18, v64
	v_mul_f32_e32 v1, v2, v65
	ds_write2_b32 v16, v0, v1 offset0:136 offset1:168
	v_mul_f32_e32 v0, v19, v64
	v_mul_f32_e32 v1, v3, v65
	v_add_u32_e32 v2, 0x4800, v66
	ds_write2_b32 v2, v0, v1 offset0:12 offset1:44
	v_mul_f32_e32 v0, v20, v64
	v_mul_f32_e32 v1, v4, v65
	v_add_u32_e32 v2, 0x5000, v66
	ds_write2_b32 v2, v0, v1 offset0:160 offset1:192
	v_mul_f32_e32 v0, v21, v64
	v_mul_f32_e32 v1, v5, v65
	v_add_u32_e32 v2, 0x5400, v66
	ds_write2_b32 v2, v0, v1 offset0:36 offset1:68
	v_mul_f32_e32 v0, v22, v64
	v_mul_f32_e32 v1, v6, v65
	ds_write2_b32 v2, v0, v1 offset0:168 offset1:200
	v_mul_f32_e32 v0, v23, v64
	v_mul_f32_e32 v1, v7, v65
	v_add_u32_e32 v2, 0x5800, v66
	ds_write2_b32 v2, v0, v1 offset0:44 offset1:76
	v_mul_f32_e32 v0, v24, v64
	v_mul_f32_e32 v1, v8, v65
	v_add_u32_e32 v2, 0x6000, v66
	ds_write2_b32 v2, v0, v1 offset0:192 offset1:224
	v_mul_f32_e32 v0, v25, v64
	v_mul_f32_e32 v1, v9, v65
	v_add_u32_e32 v2, 0x6400, v66
	ds_write2_b32 v2, v0, v1 offset0:68 offset1:100
	v_mul_f32_e32 v0, v26, v64
	v_mul_f32_e32 v1, v10, v65
	ds_write2_b32 v2, v0, v1 offset0:200 offset1:232
	v_mul_f32_e32 v0, v27, v64
	v_mul_f32_e32 v1, v11, v65
	v_add_u32_e32 v2, 0x6800, v66
	ds_write2_b32 v2, v0, v1 offset0:76 offset1:108
	v_mul_f32_e32 v0, v28, v64
	v_mul_f32_e32 v1, v12, v65
	v_add_u32_e32 v2, 0x7200, v66
	ds_write2_b32 v2, v0, v1 offset0:96 offset1:128
	v_mul_f32_e32 v0, v29, v64
	v_mul_f32_e32 v1, v13, v65
	v_add_u32_e32 v2, 0x7400, v66
	ds_write2_b32 v2, v0, v1 offset0:100 offset1:132
	v_mul_f32_e32 v0, v30, v64
	v_mul_f32_e32 v1, v14, v65
	v_add_u32_e32 v2, 0x7600, v66
	v_and_b32_e32 v12, 31, v68
	ds_write2_b32 v2, v0, v1 offset0:104 offset1:136
	v_mul_f32_e32 v0, v31, v64
	v_mul_f32_e32 v1, v15, v65
	v_add_u32_e32 v2, 0x7800, v66
	v_lshlrev_b32_e32 v10, 2, v12
	ds_write2_b32 v2, v0, v1 offset0:108 offset1:140
	v_or_b32_e32 v0, s25, v10
	v_ashrrev_i32_e32 v1, 31, v0
	v_lshlrev_b64 v[0:1], 2, v[0:1]
	v_lshl_add_u64 v[2:3], s[80:81], 0, v[0:1]
	v_lshl_add_u64 v[4:5], s[82:83], 0, v[0:1]
	s_waitcnt lgkmcnt(0)
	s_barrier
	global_load_dwordx4 v[0:3], v[2:3], off
	s_nop 0
	global_load_dwordx4 v[4:7], v[4:5], off
	v_and_b32_e32 v8, 64, v102
	v_add_u32_e32 v8, 64, v8
	v_xor_b32_e32 v9, 1, v102
	v_cmp_lt_i32_e32 vcc, v9, v8
	s_addc_u32 s25, s29, 0
	s_lshl_b64 s[0:1], s[0:1], 12
	v_cndmask_b32_e32 v9, v102, v9, vcc
	v_lshlrev_b32_e32 v30, 2, v9
	v_xor_b32_e32 v9, 2, v102
	v_cmp_lt_i32_e32 vcc, v9, v8
	s_add_u32 s58, s17, s0
	s_addc_u32 s59, s19, s1
	v_cndmask_b32_e32 v9, v102, v9, vcc
	v_lshlrev_b32_e32 v31, 2, v9
	v_xor_b32_e32 v9, 4, v102
	v_cmp_lt_i32_e32 vcc, v9, v8
	s_and_b64 s[0:1], s[8:9], exec
	v_add_u32_e32 v10, s22, v10
	v_cndmask_b32_e32 v9, v102, v9, vcc
	v_lshlrev_b32_e32 v32, 2, v9
	v_xor_b32_e32 v9, 8, v102
	v_cmp_lt_i32_e32 vcc, v9, v8
	v_ashrrev_i32_e32 v22, 5, v68
	s_cselect_b32 s59, s25, s59
	s_cselect_b32 s58, s10, s58
	v_cndmask_b32_e32 v9, v102, v9, vcc
	v_ashrrev_i32_e32 v11, 31, v10
	s_add_i32 s10, s24, s35
	v_cmp_eq_u32_e64 s[0:1], 0, v12
	v_lshlrev_b32_e32 v33, 2, v9
	v_xor_b32_e32 v9, 16, v102
	v_lshlrev_b64 v[24:25], 2, v[10:11]
	v_lshlrev_b32_e32 v11, 4, v12
	v_add_u32_e32 v12, s10, v22
	s_add_i32 s10, s24, s36
	s_add_i32 s24, s24, s37
	v_cmp_lt_i32_e32 vcc, v9, v8
	v_add_u32_e32 v16, s10, v22
	v_add_u32_e32 v20, s24, v22
	v_cndmask_b32_e32 v8, v102, v9, vcc
	v_ashrrev_i32_e32 v23, 31, v22
	v_mul_lo_u32 v10, v22, s52
	v_ashrrev_i32_e32 v13, 31, v12
	v_ashrrev_i32_e32 v17, 31, v16
	v_ashrrev_i32_e32 v21, 31, v20
	v_add_u32_e32 v26, s23, v22
	v_lshlrev_b32_e32 v34, 2, v8
	v_lshlrev_b64 v[8:9], 12, v[22:23]
	v_add3_u32 v35, v10, v11, 32
	v_lshlrev_b64 v[10:11], 12, v[12:13]
	v_lshlrev_b32_e32 v12, 1, v12
	v_lshlrev_b64 v[14:15], 12, v[16:17]
	v_lshlrev_b32_e32 v16, 1, v16
	v_lshlrev_b64 v[18:19], 12, v[20:21]
	v_lshlrev_b32_e32 v20, 1, v20
	v_lshlrev_b32_e32 v22, 1, v26
	v_ashrrev_i32_e32 v27, 31, v26
	v_lshl_add_u64 v[8:9], v[8:9], 0, v[24:25]
	v_ashrrev_i32_e32 v13, 31, v12
	v_ashrrev_i32_e32 v17, 31, v16
	v_ashrrev_i32_e32 v21, 31, v20
	v_ashrrev_i32_e32 v23, 31, v22
	v_lshlrev_b64 v[26:27], 12, v[26:27]
	v_lshl_add_u64 v[8:9], s[58:59], 0, v[8:9]
	v_lshl_add_u64 v[10:11], v[10:11], 0, v[24:25]
	v_lshlrev_b64 v[12:13], 2, v[12:13]
	v_lshl_add_u64 v[14:15], v[14:15], 0, v[24:25]
	v_lshlrev_b64 v[16:17], 2, v[16:17]
	v_lshl_add_u64 v[18:19], v[18:19], 0, v[24:25]
	v_lshlrev_b64 v[20:21], 2, v[20:21]
	v_lshlrev_b64 v[22:23], 2, v[22:23]
	v_lshl_add_u64 v[24:25], v[26:27], 0, v[24:25]
	s_mov_b64 s[22:23], 0
	s_branch .LBB0_3809

.LBB0_3929:
	s_setprio 1
	ds_read_b128 v[140:143], v103
	ds_read_b128 v[144:147], v104 offset:36864
	ds_read_b128 v[148:151], v103 offset:32
	ds_read_b128 v[152:155], v104 offset:36896
	ds_read_b128 v[156:159], v104 offset:41472
	ds_read_b128 v[160:163], v104 offset:41504
	s_waitcnt lgkmcnt(4)
	v_mfma_f32_32x32x16_bf16 v[48:63], v[140:143], v[144:147], v[48:63]
	global_load_dwordx4 v[108:111], v168, s[98:99] offset:3840
	global_load_dwordx4 v[112:115], v170, s[98:99] offset:3840
	s_waitcnt vmcnt(9)
	ds_write_b128 v105, v[68:71] offset:18432
	s_waitcnt lgkmcnt(2)
	v_mfma_f32_32x32x16_bf16 v[32:47], v[140:143], v[156:159], v[32:47]
	global_load_dwordx4 v[116:119], v172, s[98:99] offset:3840
	global_load_dwordx4 v[120:123], v174, s[98:99] offset:3840
	ds_read_b128 v[140:143], v103 offset:4608
	ds_read_b128 v[164:167], v103 offset:4640
	s_waitcnt lgkmcnt(1)
	v_mfma_f32_32x32x16_bf16 v[16:31], v[140:143], v[144:147], v[16:31]
	global_load_dwordx4 v[124:127], v176, s[98:99] offset:3840
	global_load_dwordx4 v[128:131], v178, s[98:99] offset:3840
	s_waitcnt vmcnt(11)
	ds_write_b128 v105, v[84:87] offset:23040
	v_mfma_f32_32x32x16_bf16 v[0:15], v[140:143], v[156:159], v[0:15]
	global_load_dwordx4 v[132:135], v180, s[98:99] offset:3840
	global_load_dwordx4 v[136:139], v182, s[98:99] offset:3840
	v_mfma_f32_32x32x16_bf16 v[48:63], v[148:151], v[152:155], v[48:63]
	s_waitcnt vmcnt(12)
	ds_write_b128 v105, v[88:91] offset:27648
	v_mfma_f32_32x32x16_bf16 v[32:47], v[148:151], v[160:163], v[32:47]
	s_waitcnt lgkmcnt(2)
	v_mfma_f32_32x32x16_bf16 v[16:31], v[164:167], v[152:155], v[16:31]
	s_waitcnt vmcnt(11)
	ds_write_b128 v105, v[92:95] offset:32256
	ds_read_b128 v[140:143], v103 offset:64
	ds_read_b128 v[144:147], v104 offset:36928
	ds_read_b128 v[148:151], v103 offset:96
	ds_read_b128 v[152:155], v104 offset:36960
	v_mfma_f32_32x32x16_bf16 v[0:15], v[164:167], v[160:163], v[0:15]
	ds_read_b128 v[156:159], v104 offset:41536
	ds_read_b128 v[160:163], v104 offset:41568
	s_waitcnt lgkmcnt(4)
	v_mfma_f32_32x32x16_bf16 v[48:63], v[140:143], v[144:147], v[48:63]
	ds_write_b128 v105, v[64:67] offset:55296
	s_waitcnt lgkmcnt(2)
	v_mfma_f32_32x32x16_bf16 v[32:47], v[140:143], v[156:159], v[32:47]
	ds_read_b128 v[140:143], v103 offset:4672
	ds_read_b128 v[164:167], v103 offset:4704
	s_waitcnt lgkmcnt(1)
	v_mfma_f32_32x32x16_bf16 v[16:31], v[140:143], v[144:147], v[16:31]
	s_waitcnt vmcnt(10)
	ds_write_b128 v105, v[72:75] offset:59904
	v_mfma_f32_32x32x16_bf16 v[0:15], v[140:143], v[156:159], v[0:15]
	v_mfma_f32_32x32x16_bf16 v[48:63], v[148:151], v[152:155], v[48:63]
	s_waitcnt vmcnt(9)
	ds_write_b128 v105, v[76:79] offset:64512
	v_mfma_f32_32x32x16_bf16 v[32:47], v[148:151], v[160:163], v[32:47]
	s_waitcnt lgkmcnt(2)
	v_mfma_f32_32x32x16_bf16 v[16:31], v[164:167], v[152:155], v[16:31]
	s_waitcnt vmcnt(8)
	ds_write_b128 v106, v[80:83] offset:13824
	v_mfma_f32_32x32x16_bf16 v[0:15], v[164:167], v[160:163], v[0:15]
	s_setprio 0
	s_waitcnt lgkmcnt(0)
	s_barrier
	s_setprio 1
	ds_read_b128 v[140:143], v103 offset:18432
	ds_read_b128 v[144:147], v104 offset:55296
	ds_read_b128 v[148:151], v103 offset:18464
	ds_read_b128 v[152:155], v104 offset:55328
	ds_read_b128 v[156:159], v104 offset:59904
	ds_read_b128 v[160:163], v104 offset:59936
	s_waitcnt lgkmcnt(4)
	v_mfma_f32_32x32x16_bf16 v[48:63], v[140:143], v[144:147], v[48:63]
	global_load_dwordx4 v[68:71], v168, s[98:99] offset:3968
	global_load_dwordx4 v[84:87], v170, s[98:99] offset:3968
	s_waitcnt vmcnt(9)
	ds_write_b128 v105, v[108:111]
	s_waitcnt lgkmcnt(2)
	v_mfma_f32_32x32x16_bf16 v[32:47], v[140:143], v[156:159], v[32:47]
	global_load_dwordx4 v[88:91], v172, s[98:99] offset:3968
	global_load_dwordx4 v[92:95], v174, s[98:99] offset:3968
	ds_read_b128 v[140:143], v103 offset:23040
	ds_read_b128 v[164:167], v103 offset:23072
	s_waitcnt lgkmcnt(1)
	v_mfma_f32_32x32x16_bf16 v[16:31], v[140:143], v[144:147], v[16:31]
	global_load_dwordx4 v[64:67], v176, s[98:99] offset:3968
	global_load_dwordx4 v[72:75], v178, s[98:99] offset:3968
	s_waitcnt vmcnt(12)
	ds_write_b128 v105, v[112:115] offset:4608
	v_mfma_f32_32x32x16_bf16 v[0:15], v[140:143], v[156:159], v[0:15]
	global_load_dwordx4 v[76:79], v180, s[98:99] offset:3968
	global_load_dwordx4 v[80:83], v182, s[98:99] offset:3968
	v_mfma_f32_32x32x16_bf16 v[48:63], v[148:151], v[152:155], v[48:63]
	s_add_u32 s98, s98, 0x100
	s_addc_u32 s99, s99, 0
	s_add_i32 s41, s41, 2
	s_cmp_lt_u32 s41, 11
	s_waitcnt vmcnt(13)
	ds_write_b128 v105, v[116:119] offset:9216
	v_mfma_f32_32x32x16_bf16 v[32:47], v[148:151], v[160:163], v[32:47]
	s_waitcnt lgkmcnt(2)
	v_mfma_f32_32x32x16_bf16 v[16:31], v[164:167], v[152:155], v[16:31]
	s_waitcnt vmcnt(12)
	ds_write_b128 v105, v[120:123] offset:13824
	ds_read_b128 v[140:143], v103 offset:18496
	ds_read_b128 v[144:147], v104 offset:55360
	ds_read_b128 v[148:151], v103 offset:18528
	ds_read_b128 v[152:155], v104 offset:55392
	v_mfma_f32_32x32x16_bf16 v[0:15], v[164:167], v[160:163], v[0:15]
	ds_read_b128 v[156:159], v104 offset:59968
	ds_read_b128 v[160:163], v104 offset:60000
	s_waitcnt lgkmcnt(4)
	v_mfma_f32_32x32x16_bf16 v[48:63], v[140:143], v[144:147], v[48:63]
	s_waitcnt vmcnt(11)
	ds_write_b128 v105, v[124:127] offset:36864
	s_waitcnt lgkmcnt(2)
	v_mfma_f32_32x32x16_bf16 v[32:47], v[140:143], v[156:159], v[32:47]
	ds_read_b128 v[140:143], v103 offset:23104
	ds_read_b128 v[164:167], v103 offset:23136
	s_waitcnt lgkmcnt(1)
	v_mfma_f32_32x32x16_bf16 v[16:31], v[140:143], v[144:147], v[16:31]
	s_waitcnt vmcnt(10)
	ds_write_b128 v105, v[128:131] offset:41472
	v_mfma_f32_32x32x16_bf16 v[0:15], v[140:143], v[156:159], v[0:15]
	v_mfma_f32_32x32x16_bf16 v[48:63], v[148:151], v[152:155], v[48:63]
	s_waitcnt vmcnt(9)
	ds_write_b128 v105, v[132:135] offset:46080
	v_mfma_f32_32x32x16_bf16 v[32:47], v[148:151], v[160:163], v[32:47]
	s_waitcnt lgkmcnt(2)
	v_mfma_f32_32x32x16_bf16 v[16:31], v[164:167], v[152:155], v[16:31]
	s_waitcnt vmcnt(8)
	ds_write_b128 v105, v[136:139] offset:50688
	v_mfma_f32_32x32x16_bf16 v[0:15], v[164:167], v[160:163], v[0:15]
	s_setprio 0
	s_waitcnt lgkmcnt(0)
	s_barrier
	s_cbranch_scc1 .LBB0_3929
	s_setprio 1
	ds_read_b128 v[98:101], v103
	ds_read_b128 v[108:111], v104 offset:36864
	ds_read_b128 v[112:115], v103 offset:32
	ds_read_b128 v[116:119], v104 offset:36896
	ds_read_b128 v[120:123], v104 offset:41472
	ds_read_b128 v[124:127], v104 offset:41504
	s_waitcnt lgkmcnt(4)
	v_mfma_f32_32x32x16_bf16 v[48:63], v[98:101], v[108:111], v[48:63]
	s_waitcnt vmcnt(7)
	ds_write_b128 v105, v[68:71] offset:18432
	s_waitcnt lgkmcnt(2)
	v_mfma_f32_32x32x16_bf16 v[32:47], v[98:101], v[120:123], v[32:47]
	ds_read_b128 v[98:101], v103 offset:4608
	ds_read_b128 v[128:131], v103 offset:4640
	s_waitcnt lgkmcnt(1)
	v_mfma_f32_32x32x16_bf16 v[16:31], v[98:101], v[108:111], v[16:31]
	s_waitcnt vmcnt(6)
	ds_write_b128 v105, v[84:87] offset:23040
	v_mfma_f32_32x32x16_bf16 v[0:15], v[98:101], v[120:123], v[0:15]
	v_mfma_f32_32x32x16_bf16 v[48:63], v[112:115], v[116:119], v[48:63]
	s_waitcnt vmcnt(5)
	ds_write_b128 v105, v[88:91] offset:27648
	v_mfma_f32_32x32x16_bf16 v[32:47], v[112:115], v[124:127], v[32:47]
	s_waitcnt lgkmcnt(2)
	v_mfma_f32_32x32x16_bf16 v[16:31], v[128:131], v[116:119], v[16:31]
	s_waitcnt vmcnt(4)
	ds_write_b128 v105, v[92:95] offset:32256
	ds_read_b128 v[98:101], v103 offset:64
	ds_read_b128 v[108:111], v104 offset:36928
	ds_read_b128 v[112:115], v103 offset:96
	ds_read_b128 v[116:119], v104 offset:36960
	v_mfma_f32_32x32x16_bf16 v[0:15], v[128:131], v[124:127], v[0:15]
	ds_read_b128 v[120:123], v104 offset:41536
	ds_read_b128 v[124:127], v104 offset:41568
	s_waitcnt lgkmcnt(4)
	v_mfma_f32_32x32x16_bf16 v[48:63], v[98:101], v[108:111], v[48:63]
	s_waitcnt vmcnt(3)
	ds_write_b128 v105, v[64:67] offset:55296
	s_waitcnt lgkmcnt(2)
	v_mfma_f32_32x32x16_bf16 v[32:47], v[98:101], v[120:123], v[32:47]
	ds_read_b128 v[98:101], v103 offset:4672
	ds_read_b128 v[128:131], v103 offset:4704
	s_waitcnt lgkmcnt(1)
	v_mfma_f32_32x32x16_bf16 v[16:31], v[98:101], v[108:111], v[16:31]
	s_waitcnt vmcnt(2)
	ds_write_b128 v105, v[72:75] offset:59904
	v_mfma_f32_32x32x16_bf16 v[0:15], v[98:101], v[120:123], v[0:15]
	v_mfma_f32_32x32x16_bf16 v[48:63], v[112:115], v[116:119], v[48:63]
	s_waitcnt vmcnt(1)
	ds_write_b128 v105, v[76:79] offset:64512
	v_mfma_f32_32x32x16_bf16 v[32:47], v[112:115], v[124:127], v[32:47]
	s_waitcnt lgkmcnt(2)
	v_mfma_f32_32x32x16_bf16 v[16:31], v[128:131], v[116:119], v[16:31]
	s_waitcnt vmcnt(0)
	ds_write_b128 v106, v[80:83] offset:13824
	v_mfma_f32_32x32x16_bf16 v[0:15], v[128:131], v[124:127], v[0:15]
	s_setprio 0
	s_waitcnt lgkmcnt(0)
	s_barrier
	s_setprio 1
	ds_read_b128 v[64:67], v103 offset:18432
	ds_read_b128 v[68:71], v104 offset:55296
	ds_read_b128 v[72:75], v103 offset:18464
	ds_read_b128 v[76:79], v104 offset:55328
	ds_read_b128 v[80:83], v104 offset:59904
	ds_read_b128 v[84:87], v104 offset:59936
	s_waitcnt lgkmcnt(4)
	v_mfma_f32_32x32x16_bf16 v[48:63], v[64:67], v[68:71], v[48:63]
	s_waitcnt lgkmcnt(1)
	v_mfma_f32_32x32x16_bf16 v[32:47], v[64:67], v[80:83], v[32:47]
	ds_read_b128 v[64:67], v103 offset:23040
	ds_read_b128 v[88:91], v103 offset:23072
	s_waitcnt lgkmcnt(1)
	v_mfma_f32_32x32x16_bf16 v[16:31], v[64:67], v[68:71], v[16:31]
	v_mfma_f32_32x32x16_bf16 v[0:15], v[64:67], v[80:83], v[0:15]
	v_mfma_f32_32x32x16_bf16 v[48:63], v[72:75], v[76:79], v[48:63]
	v_mfma_f32_32x32x16_bf16 v[32:47], v[72:75], v[84:87], v[32:47]
	s_waitcnt lgkmcnt(0)
	v_mfma_f32_32x32x16_bf16 v[16:31], v[88:91], v[76:79], v[16:31]
	ds_read_b128 v[64:67], v103 offset:18496
	ds_read_b128 v[68:71], v104 offset:55360
	ds_read_b128 v[72:75], v103 offset:18528
	ds_read_b128 v[76:79], v104 offset:55392
	v_mfma_f32_32x32x16_bf16 v[0:15], v[88:91], v[84:87], v[0:15]
	ds_read_b128 v[80:83], v104 offset:59968
	ds_read_b128 v[84:87], v104 offset:60000
	s_waitcnt lgkmcnt(4)
	v_mfma_f32_32x32x16_bf16 v[48:63], v[64:67], v[68:71], v[48:63]
	s_waitcnt lgkmcnt(1)
	v_mfma_f32_32x32x16_bf16 v[32:47], v[64:67], v[80:83], v[32:47]
	ds_read_b128 v[64:67], v103 offset:23104
	ds_read_b128 v[88:91], v103 offset:23136
	s_waitcnt lgkmcnt(1)
	v_mfma_f32_32x32x16_bf16 v[16:31], v[64:67], v[68:71], v[16:31]
	v_mfma_f32_32x32x16_bf16 v[0:15], v[64:67], v[80:83], v[0:15]
	v_mfma_f32_32x32x16_bf16 v[48:63], v[72:75], v[76:79], v[48:63]
	v_mfma_f32_32x32x16_bf16 v[32:47], v[72:75], v[84:87], v[32:47]
	s_waitcnt lgkmcnt(0)
	v_mfma_f32_32x32x16_bf16 v[16:31], v[88:91], v[76:79], v[16:31]
	v_mfma_f32_32x32x16_bf16 v[0:15], v[88:91], v[84:87], v[0:15]
	s_setprio 0
	v_lshrrev_b32_e32 v65, 3, v102
	v_lshrrev_b32_e32 v64, 1, v102
	v_and_b32_e32 v65, 4, v65
	v_and_or_b32 v64, v64, s22, v65
	v_and_b32_e32 v65, 0x5f, v102
	v_lshlrev_b32_e32 v65, 1, v65
	v_mul_lo_u32 v64, v64, s36
	v_add3_u32 v64, 32, v65, v64
	s_nop 2
	v_cvt_pk_bf16_f32 v0, v0, s0
	s_barrier
	ds_write_b16 v64, v0 offset:8768
	v_cvt_pk_bf16_f32 v0, v17, s0
	ds_write_b16 v64, v0 offset:8976
	v_cvt_pk_bf16_f32 v0, v1, s0
	ds_write_b16 v64, v0 offset:9040
	v_cvt_pk_bf16_f32 v0, v18, s0
	v_cvt_pk_bf16_f32 v32, v32, s0
	ds_write_b16 v64, v0 offset:9248
	v_cvt_pk_bf16_f32 v0, v2, s0
	ds_write_b16 v64, v32 offset:64
	v_cvt_pk_bf16_f32 v32, v49, s0
	ds_write_b16 v64, v0 offset:9312
	v_cvt_pk_bf16_f32 v0, v19, s0
	ds_write_b16 v64, v32 offset:272
	v_cvt_pk_bf16_f32 v32, v33, s0
	ds_write_b16 v64, v0 offset:9520
	v_cvt_pk_bf16_f32 v0, v3, s0
	ds_write_b16 v64, v32 offset:336
	v_cvt_pk_bf16_f32 v32, v50, s0
	ds_write_b16 v64, v0 offset:9584
	v_cvt_pk_bf16_f32 v0, v20, s0
	ds_write_b16 v64, v32 offset:544
	v_cvt_pk_bf16_f32 v32, v34, s0
	ds_write_b16 v64, v0 offset:10880
	v_cvt_pk_bf16_f32 v0, v4, s0
	ds_write_b16 v64, v32 offset:608
	v_cvt_pk_bf16_f32 v32, v51, s0
	ds_write_b16 v64, v0 offset:10944
	v_cvt_pk_bf16_f32 v0, v21, s0
	ds_write_b16 v64, v32 offset:816
	v_cvt_pk_bf16_f32 v32, v35, s0
	ds_write_b16 v64, v0 offset:11152
	v_cvt_pk_bf16_f32 v0, v5, s0
	ds_write_b16 v64, v32 offset:880
	v_cvt_pk_bf16_f32 v32, v52, s0
	ds_write_b16 v64, v0 offset:11216
	v_cvt_pk_bf16_f32 v0, v22, s0
	ds_write_b16 v64, v32 offset:2176
	v_cvt_pk_bf16_f32 v32, v36, s0
	ds_write_b16 v64, v0 offset:11424
	v_cvt_pk_bf16_f32 v0, v6, s0
	ds_write_b16 v64, v32 offset:2240
	v_cvt_pk_bf16_f32 v32, v53, s0
	ds_write_b16 v64, v0 offset:11488
	v_cvt_pk_bf16_f32 v0, v23, s0
	ds_write_b16 v64, v32 offset:2448
	v_cvt_pk_bf16_f32 v32, v37, s0
	ds_write_b16 v64, v0 offset:11696
	v_cvt_pk_bf16_f32 v0, v7, s0
	ds_write_b16 v64, v32 offset:2512
	v_cvt_pk_bf16_f32 v32, v54, s0
	ds_write_b16 v64, v0 offset:11760
	v_cvt_pk_bf16_f32 v0, v24, s0
	ds_write_b16 v64, v32 offset:2720
	v_cvt_pk_bf16_f32 v32, v38, s0
	ds_write_b16 v64, v0 offset:13056
	v_cvt_pk_bf16_f32 v0, v8, s0
	ds_write_b16 v64, v32 offset:2784
	v_cvt_pk_bf16_f32 v32, v55, s0
	ds_write_b16 v64, v0 offset:13120
	v_cvt_pk_bf16_f32 v0, v25, s0
	ds_write_b16 v64, v32 offset:2992
	v_cvt_pk_bf16_f32 v32, v39, s0
	ds_write_b16 v64, v0 offset:13328
	v_cvt_pk_bf16_f32 v0, v9, s0
	ds_write_b16 v64, v32 offset:3056
	v_cvt_pk_bf16_f32 v32, v56, s0
	ds_write_b16 v64, v0 offset:13392
	v_cvt_pk_bf16_f32 v0, v26, s0
	ds_write_b16 v64, v32 offset:4352
	v_cvt_pk_bf16_f32 v32, v40, s0
	ds_write_b16 v64, v0 offset:13600
	v_cvt_pk_bf16_f32 v0, v10, s0
	ds_write_b16 v64, v32 offset:4416
	v_cvt_pk_bf16_f32 v32, v57, s0
	ds_write_b16 v64, v0 offset:13664
	v_cvt_pk_bf16_f32 v0, v27, s0
	ds_write_b16 v64, v32 offset:4624
	v_cvt_pk_bf16_f32 v32, v41, s0
	ds_write_b16 v64, v0 offset:13872
	v_cvt_pk_bf16_f32 v0, v11, s0
	ds_write_b16 v64, v32 offset:4688
	v_cvt_pk_bf16_f32 v32, v58, s0
	ds_write_b16 v64, v0 offset:13936
	v_cvt_pk_bf16_f32 v0, v28, s0
	ds_write_b16 v64, v32 offset:4896
	v_cvt_pk_bf16_f32 v32, v42, s0
	ds_write_b16 v64, v0 offset:15232
	v_cvt_pk_bf16_f32 v0, v12, s0
	ds_write_b16 v64, v32 offset:4960
	v_cvt_pk_bf16_f32 v32, v59, s0
	ds_write_b16 v64, v0 offset:15296
	v_cvt_pk_bf16_f32 v0, v29, s0
	ds_write_b16 v64, v32 offset:5168
	v_cvt_pk_bf16_f32 v32, v43, s0
	ds_write_b16 v64, v0 offset:15504
	v_cvt_pk_bf16_f32 v0, v13, s0
	ds_write_b16 v64, v32 offset:5232
	v_cvt_pk_bf16_f32 v32, v60, s0
	ds_write_b16 v64, v0 offset:15568
	v_cvt_pk_bf16_f32 v0, v30, s0
	ds_write_b16 v64, v32 offset:6528
	v_cvt_pk_bf16_f32 v32, v44, s0
	ds_write_b16 v64, v0 offset:15776
	v_cvt_pk_bf16_f32 v0, v14, s0
	s_mul_i32 s11, s11, 0x160000
	ds_write_b16 v64, v32 offset:6592
	v_cvt_pk_bf16_f32 v32, v61, s0
	ds_write_b16 v64, v0 offset:15840
	v_cvt_pk_bf16_f32 v0, v31, s0
	s_add_u32 s41, s13, s11
	ds_write_b16 v64, v32 offset:6800
	v_cvt_pk_bf16_f32 v32, v45, s0
	ds_write_b16 v64, v0 offset:16048
	v_cvt_pk_bf16_f32 v0, v15, s0
	s_addc_u32 s42, s14, 0
	s_ashr_i32 s11, s10, 31
	ds_write_b16 v64, v32 offset:6864
	v_cvt_pk_bf16_f32 v32, v62, s0
	ds_write_b16 v64, v0 offset:16112
	s_lshl_b64 s[10:11], s[10:11], 1
	v_lshlrev_b32_e32 v0, 4, v102
	ds_write_b16 v64, v32 offset:7072
	v_cvt_pk_bf16_f32 v32, v46, s0
	s_add_u32 s10, s41, s10
	v_and_b32_e32 v96, 0xf0, v0
	ds_write_b16 v64, v32 offset:7136
	v_cvt_pk_bf16_f32 v32, v63, s0
	s_addc_u32 s11, s42, s11
	v_add_u32_e32 v8, 32, v96
	v_ashrrev_i32_e32 v9, 4, v102
	v_add_u32_e32 v4, 0x100, v102
	v_cvt_pk_bf16_f32 v48, v48, s0
	ds_write_b16 v64, v32 offset:7344
	v_cvt_pk_bf16_f32 v32, v47, s0
	v_cvt_pk_bf16_f32 v16, v16, s0
	v_lshl_add_u64 v[10:11], s[10:11], 0, v[96:97]
	v_mad_u64_u32 v[0:1], s[10:11], v9, s36, v[8:9]
	v_ashrrev_i32_e32 v14, 4, v4
	ds_write_b16 v64, v48
	ds_write_b16 v64, v32 offset:7408
	ds_write_b16 v64, v16 offset:8704
	s_waitcnt lgkmcnt(0)
	s_barrier
	ds_read_b128 v[0:3], v0
	v_mad_u64_u32 v[4:5], s[10:11], v14, s36, v[8:9]
	ds_read_b128 v[4:7], v4
	v_mad_i64_i32 v[12:13], s[10:11], v9, s37, v[10:11]
	s_waitcnt lgkmcnt(1)
	global_store_dwordx4 v[12:13], v[0:3], off
	s_nop 1
	v_mad_i64_i32 v[0:1], s[10:11], v14, s37, v[10:11]
	s_waitcnt lgkmcnt(0)
	global_store_dwordx4 v[0:1], v[4:7], off
	v_add_u32_e32 v0, 0x200, v102
	v_ashrrev_i32_e32 v9, 4, v0
	v_add_u32_e32 v4, 0x300, v102
	v_mad_u64_u32 v[0:1], s[10:11], v9, s36, v[8:9]
	v_ashrrev_i32_e32 v14, 4, v4
	ds_read_b128 v[0:3], v0
	v_mad_u64_u32 v[4:5], s[10:11], v14, s36, v[8:9]
	ds_read_b128 v[4:7], v4
	v_mad_i64_i32 v[12:13], s[10:11], v9, s37, v[10:11]
	s_waitcnt lgkmcnt(1)
	global_store_dwordx4 v[12:13], v[0:3], off
	s_nop 1
	v_mad_i64_i32 v[0:1], s[10:11], v14, s37, v[10:11]
	s_waitcnt lgkmcnt(0)
	global_store_dwordx4 v[0:1], v[4:7], off
	v_add_u32_e32 v0, 0x400, v102
	v_ashrrev_i32_e32 v9, 4, v0
	v_add_u32_e32 v4, 0x500, v102
	v_mad_u64_u32 v[0:1], s[10:11], v9, s36, v[8:9]
	v_ashrrev_i32_e32 v14, 4, v4
	ds_read_b128 v[0:3], v0
	v_mad_u64_u32 v[4:5], s[10:11], v14, s36, v[8:9]
	ds_read_b128 v[4:7], v4
	v_mad_i64_i32 v[12:13], s[10:11], v9, s37, v[10:11]
	s_waitcnt lgkmcnt(1)
	global_store_dwordx4 v[12:13], v[0:3], off
	s_nop 1
	v_mad_i64_i32 v[0:1], s[10:11], v14, s37, v[10:11]
	s_waitcnt lgkmcnt(0)
	global_store_dwordx4 v[0:1], v[4:7], off
	v_add_u32_e32 v0, 0x600, v102
	v_ashrrev_i32_e32 v9, 4, v0
	v_add_u32_e32 v4, 0x700, v102
	v_mad_u64_u32 v[0:1], s[10:11], v9, s36, v[8:9]
	v_ashrrev_i32_e32 v12, 4, v4
	ds_read_b128 v[0:3], v0
	v_mad_u64_u32 v[4:5], s[10:11], v12, s36, v[8:9]
	ds_read_b128 v[4:7], v4
	v_mad_i64_i32 v[8:9], s[10:11], v9, s37, v[10:11]
	s_waitcnt lgkmcnt(1)
	global_store_dwordx4 v[8:9], v[0:3], off
	s_nop 1
	v_mad_i64_i32 v[0:1], s[10:11], v12, s37, v[10:11]
	s_waitcnt lgkmcnt(0)
	global_store_dwordx4 v[0:1], v[4:7], off
	s_branch .LBB0_3926

.LBB0_4051:
	s_setprio 1
	ds_read_b128 v[146:149], v109
	ds_read_b128 v[150:153], v110 offset:36864
	ds_read_b128 v[154:157], v109 offset:32
	ds_read_b128 v[158:161], v110 offset:36896
	ds_read_b128 v[162:165], v110 offset:41472
	ds_read_b128 v[166:169], v110 offset:41504
	s_waitcnt lgkmcnt(4)
	v_mfma_f32_32x32x16_bf16 v[48:63], v[146:149], v[150:153], v[48:63]
	global_load_dwordx4 v[114:117], v174, s[98:99] offset:3840
	global_load_dwordx4 v[118:121], v176, s[98:99] offset:3840
	s_waitcnt vmcnt(9)
	ds_write_b128 v111, v[68:71] offset:18432
	s_waitcnt lgkmcnt(2)
	v_mfma_f32_32x32x16_bf16 v[32:47], v[146:149], v[162:165], v[32:47]
	global_load_dwordx4 v[122:125], v178, s[98:99] offset:3840
	global_load_dwordx4 v[126:129], v180, s[98:99] offset:3840
	ds_read_b128 v[146:149], v109 offset:4608
	ds_read_b128 v[170:173], v109 offset:4640
	s_waitcnt lgkmcnt(1)
	v_mfma_f32_32x32x16_bf16 v[16:31], v[146:149], v[150:153], v[16:31]
	global_load_dwordx4 v[130:133], v182, s[98:99] offset:3840
	global_load_dwordx4 v[134:137], v184, s[98:99] offset:3840
	s_waitcnt vmcnt(11)
	ds_write_b128 v111, v[84:87] offset:23040
	v_mfma_f32_32x32x16_bf16 v[0:15], v[146:149], v[162:165], v[0:15]
	global_load_dwordx4 v[138:141], v186, s[98:99] offset:3840
	global_load_dwordx4 v[142:145], v188, s[98:99] offset:3840
	v_mfma_f32_32x32x16_bf16 v[48:63], v[154:157], v[158:161], v[48:63]
	s_waitcnt vmcnt(12)
	ds_write_b128 v111, v[88:91] offset:27648
	v_mfma_f32_32x32x16_bf16 v[32:47], v[154:157], v[166:169], v[32:47]
	s_waitcnt lgkmcnt(2)
	v_mfma_f32_32x32x16_bf16 v[16:31], v[170:173], v[158:161], v[16:31]
	s_waitcnt vmcnt(11)
	ds_write_b128 v111, v[92:95] offset:32256
	ds_read_b128 v[146:149], v109 offset:64
	ds_read_b128 v[150:153], v110 offset:36928
	ds_read_b128 v[154:157], v109 offset:96
	ds_read_b128 v[158:161], v110 offset:36960
	v_mfma_f32_32x32x16_bf16 v[0:15], v[170:173], v[166:169], v[0:15]
	ds_read_b128 v[162:165], v110 offset:41536
	ds_read_b128 v[166:169], v110 offset:41568
	s_waitcnt lgkmcnt(4)
	v_mfma_f32_32x32x16_bf16 v[48:63], v[146:149], v[150:153], v[48:63]
	ds_write_b128 v111, v[64:67] offset:55296
	s_waitcnt lgkmcnt(2)
	v_mfma_f32_32x32x16_bf16 v[32:47], v[146:149], v[162:165], v[32:47]
	ds_read_b128 v[146:149], v109 offset:4672
	ds_read_b128 v[170:173], v109 offset:4704
	s_waitcnt lgkmcnt(1)
	v_mfma_f32_32x32x16_bf16 v[16:31], v[146:149], v[150:153], v[16:31]
	s_waitcnt vmcnt(10)
	ds_write_b128 v111, v[72:75] offset:59904
	v_mfma_f32_32x32x16_bf16 v[0:15], v[146:149], v[162:165], v[0:15]
	v_mfma_f32_32x32x16_bf16 v[48:63], v[154:157], v[158:161], v[48:63]
	s_waitcnt vmcnt(9)
	ds_write_b128 v111, v[76:79] offset:64512
	v_mfma_f32_32x32x16_bf16 v[32:47], v[154:157], v[166:169], v[32:47]
	s_waitcnt lgkmcnt(2)
	v_mfma_f32_32x32x16_bf16 v[16:31], v[170:173], v[158:161], v[16:31]
	s_waitcnt vmcnt(8)
	ds_write_b128 v112, v[80:83] offset:13824
	v_mfma_f32_32x32x16_bf16 v[0:15], v[170:173], v[166:169], v[0:15]
	s_setprio 0
	s_waitcnt lgkmcnt(0)
	s_barrier
	s_setprio 1
	ds_read_b128 v[146:149], v109 offset:18432
	ds_read_b128 v[150:153], v110 offset:55296
	ds_read_b128 v[154:157], v109 offset:18464
	ds_read_b128 v[158:161], v110 offset:55328
	ds_read_b128 v[162:165], v110 offset:59904
	ds_read_b128 v[166:169], v110 offset:59936
	s_waitcnt lgkmcnt(4)
	v_mfma_f32_32x32x16_bf16 v[48:63], v[146:149], v[150:153], v[48:63]
	global_load_dwordx4 v[68:71], v174, s[98:99] offset:3968
	global_load_dwordx4 v[84:87], v176, s[98:99] offset:3968
	s_waitcnt vmcnt(9)
	ds_write_b128 v111, v[114:117]
	s_waitcnt lgkmcnt(2)
	v_mfma_f32_32x32x16_bf16 v[32:47], v[146:149], v[162:165], v[32:47]
	global_load_dwordx4 v[88:91], v178, s[98:99] offset:3968
	global_load_dwordx4 v[92:95], v180, s[98:99] offset:3968
	ds_read_b128 v[146:149], v109 offset:23040
	ds_read_b128 v[170:173], v109 offset:23072
	s_waitcnt lgkmcnt(1)
	v_mfma_f32_32x32x16_bf16 v[16:31], v[146:149], v[150:153], v[16:31]
	global_load_dwordx4 v[64:67], v182, s[98:99] offset:3968
	global_load_dwordx4 v[72:75], v184, s[98:99] offset:3968
	s_waitcnt vmcnt(12)
	ds_write_b128 v111, v[118:121] offset:4608
	v_mfma_f32_32x32x16_bf16 v[0:15], v[146:149], v[162:165], v[0:15]
	global_load_dwordx4 v[76:79], v186, s[98:99] offset:3968
	global_load_dwordx4 v[80:83], v188, s[98:99] offset:3968
	v_mfma_f32_32x32x16_bf16 v[48:63], v[154:157], v[158:161], v[48:63]
	s_add_u32 s98, s98, 0x100
	s_addc_u32 s99, s99, 0
	s_add_i32 s12, s12, 2
	s_cmp_lt_u32 s12, 39
	s_waitcnt vmcnt(13)
	ds_write_b128 v111, v[122:125] offset:9216
	v_mfma_f32_32x32x16_bf16 v[32:47], v[154:157], v[166:169], v[32:47]
	s_waitcnt lgkmcnt(2)
	v_mfma_f32_32x32x16_bf16 v[16:31], v[170:173], v[158:161], v[16:31]
	s_waitcnt vmcnt(12)
	ds_write_b128 v111, v[126:129] offset:13824
	ds_read_b128 v[146:149], v109 offset:18496
	ds_read_b128 v[150:153], v110 offset:55360
	ds_read_b128 v[154:157], v109 offset:18528
	ds_read_b128 v[158:161], v110 offset:55392
	v_mfma_f32_32x32x16_bf16 v[0:15], v[170:173], v[166:169], v[0:15]
	ds_read_b128 v[162:165], v110 offset:59968
	ds_read_b128 v[166:169], v110 offset:60000
	s_waitcnt lgkmcnt(4)
	v_mfma_f32_32x32x16_bf16 v[48:63], v[146:149], v[150:153], v[48:63]
	s_waitcnt vmcnt(11)
	ds_write_b128 v111, v[130:133] offset:36864
	s_waitcnt lgkmcnt(2)
	v_mfma_f32_32x32x16_bf16 v[32:47], v[146:149], v[162:165], v[32:47]
	ds_read_b128 v[146:149], v109 offset:23104
	ds_read_b128 v[170:173], v109 offset:23136
	s_waitcnt lgkmcnt(1)
	v_mfma_f32_32x32x16_bf16 v[16:31], v[146:149], v[150:153], v[16:31]
	s_waitcnt vmcnt(10)
	ds_write_b128 v111, v[134:137] offset:41472
	v_mfma_f32_32x32x16_bf16 v[0:15], v[146:149], v[162:165], v[0:15]
	v_mfma_f32_32x32x16_bf16 v[48:63], v[154:157], v[158:161], v[48:63]
	s_waitcnt vmcnt(9)
	ds_write_b128 v111, v[138:141] offset:46080
	v_mfma_f32_32x32x16_bf16 v[32:47], v[154:157], v[166:169], v[32:47]
	s_waitcnt lgkmcnt(2)
	v_mfma_f32_32x32x16_bf16 v[16:31], v[170:173], v[158:161], v[16:31]
	s_waitcnt vmcnt(8)
	ds_write_b128 v111, v[142:145] offset:50688
	v_mfma_f32_32x32x16_bf16 v[0:15], v[170:173], v[166:169], v[0:15]
	s_setprio 0
	s_waitcnt lgkmcnt(0)
	s_barrier
	s_cbranch_scc1 .LBB0_4051
	s_setprio 1
	ds_read_b128 v[104:107], v109
	ds_read_b128 v[114:117], v110 offset:36864
	ds_read_b128 v[118:121], v109 offset:32
	ds_read_b128 v[122:125], v110 offset:36896
	ds_read_b128 v[126:129], v110 offset:41472
	ds_read_b128 v[130:133], v110 offset:41504
	s_waitcnt lgkmcnt(4)
	v_mfma_f32_32x32x16_bf16 v[48:63], v[104:107], v[114:117], v[48:63]
	s_waitcnt vmcnt(7)
	ds_write_b128 v111, v[68:71] offset:18432
	s_waitcnt lgkmcnt(2)
	v_mfma_f32_32x32x16_bf16 v[32:47], v[104:107], v[126:129], v[32:47]
	ds_read_b128 v[104:107], v109 offset:4608
	ds_read_b128 v[134:137], v109 offset:4640
	s_waitcnt lgkmcnt(1)
	v_mfma_f32_32x32x16_bf16 v[16:31], v[104:107], v[114:117], v[16:31]
	s_waitcnt vmcnt(6)
	ds_write_b128 v111, v[84:87] offset:23040
	v_mfma_f32_32x32x16_bf16 v[0:15], v[104:107], v[126:129], v[0:15]
	v_mfma_f32_32x32x16_bf16 v[48:63], v[118:121], v[122:125], v[48:63]
	s_waitcnt vmcnt(5)
	ds_write_b128 v111, v[88:91] offset:27648
	v_mfma_f32_32x32x16_bf16 v[32:47], v[118:121], v[130:133], v[32:47]
	s_waitcnt lgkmcnt(2)
	v_mfma_f32_32x32x16_bf16 v[16:31], v[134:137], v[122:125], v[16:31]
	s_waitcnt vmcnt(4)
	ds_write_b128 v111, v[92:95] offset:32256
	ds_read_b128 v[104:107], v109 offset:64
	ds_read_b128 v[114:117], v110 offset:36928
	ds_read_b128 v[118:121], v109 offset:96
	ds_read_b128 v[122:125], v110 offset:36960
	v_mfma_f32_32x32x16_bf16 v[0:15], v[134:137], v[130:133], v[0:15]
	ds_read_b128 v[126:129], v110 offset:41536
	ds_read_b128 v[130:133], v110 offset:41568
	s_waitcnt lgkmcnt(4)
	v_mfma_f32_32x32x16_bf16 v[48:63], v[104:107], v[114:117], v[48:63]
	s_waitcnt vmcnt(3)
	ds_write_b128 v111, v[64:67] offset:55296
	s_waitcnt lgkmcnt(2)
	v_mfma_f32_32x32x16_bf16 v[32:47], v[104:107], v[126:129], v[32:47]
	ds_read_b128 v[104:107], v109 offset:4672
	ds_read_b128 v[134:137], v109 offset:4704
	s_waitcnt lgkmcnt(1)
	v_mfma_f32_32x32x16_bf16 v[16:31], v[104:107], v[114:117], v[16:31]
	s_waitcnt vmcnt(2)
	ds_write_b128 v111, v[72:75] offset:59904
	v_mfma_f32_32x32x16_bf16 v[0:15], v[104:107], v[126:129], v[0:15]
	v_mfma_f32_32x32x16_bf16 v[32:47], v[118:121], v[130:133], v[32:47]
	s_waitcnt vmcnt(1)
	ds_write_b128 v111, v[76:79] offset:64512
	s_waitcnt lgkmcnt(2)
	v_mfma_f32_32x32x16_bf16 v[16:31], v[134:137], v[122:125], v[16:31]
	v_mfma_f32_32x32x16_bf16 v[0:15], v[134:137], v[130:133], v[0:15]
	s_waitcnt vmcnt(0)
	ds_write_b128 v112, v[80:83] offset:13824
	v_mfma_f32_32x32x16_bf16 v[48:63], v[118:121], v[122:125], v[48:63]
	s_setprio 0
	s_waitcnt lgkmcnt(0)
	s_barrier
	s_setprio 1
	ds_read_b128 v[64:67], v109 offset:18432
	ds_read_b128 v[68:71], v110 offset:55296
	ds_read_b128 v[72:75], v109 offset:18464
	ds_read_b128 v[76:79], v110 offset:55328
	ds_read_b128 v[80:83], v110 offset:59904
	ds_read_b128 v[84:87], v110 offset:59936
	s_waitcnt lgkmcnt(4)
	v_mfma_f32_32x32x16_bf16 v[48:63], v[64:67], v[68:71], v[48:63]
	s_waitcnt lgkmcnt(1)
	v_mfma_f32_32x32x16_bf16 v[32:47], v[64:67], v[80:83], v[32:47]
	ds_read_b128 v[64:67], v109 offset:23040
	ds_read_b128 v[88:91], v109 offset:23072
	s_waitcnt lgkmcnt(1)
	v_mfma_f32_32x32x16_bf16 v[16:31], v[64:67], v[68:71], v[16:31]
	v_mfma_f32_32x32x16_bf16 v[0:15], v[64:67], v[80:83], v[0:15]
	v_mfma_f32_32x32x16_bf16 v[48:63], v[72:75], v[76:79], v[48:63]
	v_mfma_f32_32x32x16_bf16 v[32:47], v[72:75], v[84:87], v[32:47]
	s_waitcnt lgkmcnt(0)
	v_mfma_f32_32x32x16_bf16 v[16:31], v[88:91], v[76:79], v[16:31]
	ds_read_b128 v[64:67], v109 offset:18496
	ds_read_b128 v[68:71], v110 offset:55360
	ds_read_b128 v[72:75], v109 offset:18528
	ds_read_b128 v[76:79], v110 offset:55392
	v_mfma_f32_32x32x16_bf16 v[0:15], v[88:91], v[84:87], v[0:15]
	ds_read_b128 v[80:83], v110 offset:59968
	ds_read_b128 v[84:87], v110 offset:60000
	s_waitcnt lgkmcnt(4)
	v_mfma_f32_32x32x16_bf16 v[48:63], v[64:67], v[68:71], v[48:63]
	s_waitcnt lgkmcnt(1)
	v_mfma_f32_32x32x16_bf16 v[32:47], v[64:67], v[80:83], v[32:47]
	ds_read_b128 v[64:67], v109 offset:23104
	ds_read_b128 v[88:91], v109 offset:23136
	s_waitcnt lgkmcnt(1)
	v_mfma_f32_32x32x16_bf16 v[16:31], v[64:67], v[68:71], v[16:31]
	v_mfma_f32_32x32x16_bf16 v[0:15], v[64:67], v[80:83], v[0:15]
	v_mfma_f32_32x32x16_bf16 v[32:47], v[72:75], v[84:87], v[32:47]
	s_waitcnt lgkmcnt(0)
	v_mfma_f32_32x32x16_bf16 v[16:31], v[88:91], v[76:79], v[16:31]
	v_mfma_f32_32x32x16_bf16 v[0:15], v[88:91], v[84:87], v[0:15]
	v_mfma_f32_32x32x16_bf16 v[48:63], v[72:75], v[76:79], v[48:63]
	s_setprio 0
	s_addk_i32 s0, 0xf000
	s_lshr_b32 s12, s0, 10
	s_mulk_i32 s12, 0x1800
	s_add_i32 s12, s12, 0x9000
	s_and_b64 s[66:67], s[4:5], exec
	s_cselect_b32 s12, 0x7800, s12
	v_mov_b32_e32 v68, v234
	s_barrier
	s_lshl_b64 s[66:67], s[12:13], 2
	s_add_u32 s66, s30, s66
	v_and_b32_e32 v69, 0x5f, v68
	v_or_b32_e32 v64, s27, v69
	s_addc_u32 s67, s31, s67
	v_ashrrev_i32_e32 v65, 31, v64
	v_lshl_add_u64 v[64:65], v[64:65], 2, s[66:67]
	v_lshl_add_u64 v[66:67], v[64:65], 0, s[16:17]
	v_add_co_u32_e32 v64, vcc, s56, v64
	v_lshlrev_b32_e32 v69, 2, v69
	s_nop 0
	v_addc_co_u32_e32 v65, vcc, 0, v65, vcc
	global_load_dword v64, v[64:65], off
	s_nop 0
	global_load_dword v65, v[66:67], off offset:128
	v_lshrrev_b32_e32 v67, 3, v68
	v_lshrrev_b32_e32 v66, 1, v68
	v_and_b32_e32 v67, 4, v67
	v_and_or_b32 v66, v66, s47, v67
	v_mul_lo_u32 v66, v66, s57
	v_add3_u32 v66, 32, v69, v66
	v_add_u32_e32 v67, 0x400, v66
	v_add_u32_e32 v69, 0x1000, v66
	v_add_u32_e32 v70, 0x1400, v66
	v_add_u32_e32 v71, 0x2000, v66
	v_add_u32_e32 v72, 0x2400, v66
	v_add_u32_e32 v73, 0x3000, v66
	v_add_u32_e32 v74, 0x3200, v66
	v_add_u32_e32 v75, 0x3400, v66
	v_add_u32_e32 v76, 0x3600, v66
	v_add_u32_e32 v77, 0x4000, v66
	s_lshl_b32 s1, s1, 19
	s_add_u32 s12, s19, s1
	s_mov_b32 s1, s13
	s_waitcnt vmcnt(1)
	v_mul_f32_e32 v48, v48, v64
	s_waitcnt vmcnt(0)
	v_mul_f32_e32 v32, v32, v65
	v_mul_f32_e32 v16, v16, v64
	v_mul_f32_e32 v0, v0, v65
	v_mul_f32_e32 v49, v49, v64
	v_mul_f32_e32 v33, v33, v65
	v_mul_f32_e32 v50, v50, v64
	v_mul_f32_e32 v34, v34, v65
	v_mul_f32_e32 v51, v51, v64
	v_mul_f32_e32 v35, v35, v65
	v_mul_f32_e32 v52, v52, v64
	v_mul_f32_e32 v36, v36, v65
	v_mul_f32_e32 v53, v53, v64
	v_mul_f32_e32 v37, v37, v65
	v_mul_f32_e32 v54, v54, v64
	v_mul_f32_e32 v38, v38, v65
	v_mul_f32_e32 v55, v55, v64
	v_mul_f32_e32 v39, v39, v65
	v_mul_f32_e32 v56, v56, v64
	v_mul_f32_e32 v40, v40, v65
	v_mul_f32_e32 v57, v57, v64
	v_mul_f32_e32 v41, v41, v65
	v_mul_f32_e32 v58, v58, v64
	v_mul_f32_e32 v42, v42, v65
	v_mul_f32_e32 v59, v59, v64
	v_mul_f32_e32 v43, v43, v65
	v_mul_f32_e32 v60, v60, v64
	v_mul_f32_e32 v44, v44, v65
	v_mul_f32_e32 v61, v61, v64
	v_mul_f32_e32 v45, v45, v65
	v_mul_f32_e32 v62, v62, v64
	v_mul_f32_e32 v46, v46, v65
	v_mul_f32_e32 v63, v63, v64
	v_mul_f32_e32 v47, v47, v65
	ds_write2_b32 v66, v48, v32 offset1:32
	ds_write2_b32 v66, v49, v33 offset0:132 offset1:164
	ds_write2_b32 v67, v50, v34 offset0:8 offset1:40
	ds_write2_b32 v67, v51, v35 offset0:140 offset1:172
	ds_write2_b32 v69, v52, v36 offset0:32 offset1:64
	ds_write2_b32 v69, v53, v37 offset0:164 offset1:196
	ds_write2_b32 v70, v54, v38 offset0:40 offset1:72
	ds_write2_b32 v70, v55, v39 offset0:172 offset1:204
	ds_write2_b32 v71, v56, v40 offset0:64 offset1:96
	ds_write2_b32 v71, v57, v41 offset0:196 offset1:228
	ds_write2_b32 v72, v58, v42 offset0:72 offset1:104
	ds_write2_b32 v72, v59, v43 offset0:204 offset1:236
	ds_write2_b32 v73, v60, v44 offset0:96 offset1:128
	ds_write2_b32 v74, v61, v45 offset0:100 offset1:132
	ds_write2_b32 v75, v62, v46 offset0:104 offset1:136
	ds_write2_b32 v76, v63, v47 offset0:108 offset1:140
	ds_write2_b32 v77, v16, v0 offset0:128 offset1:160
	v_mul_f32_e32 v0, v17, v64
	v_mul_f32_e32 v1, v1, v65
	v_add_u32_e32 v16, 0x4400, v66
	ds_write2_b32 v16, v0, v1 offset0:4 offset1:36
	v_mul_f32_e32 v0, v18, v64
	v_mul_f32_e32 v1, v2, v65
	ds_write2_b32 v16, v0, v1 offset0:136 offset1:168
	v_mul_f32_e32 v0, v19, v64
	v_mul_f32_e32 v1, v3, v65
	v_add_u32_e32 v2, 0x4800, v66
	ds_write2_b32 v2, v0, v1 offset0:12 offset1:44
	v_mul_f32_e32 v0, v20, v64
	v_mul_f32_e32 v1, v4, v65
	v_add_u32_e32 v2, 0x5000, v66
	ds_write2_b32 v2, v0, v1 offset0:160 offset1:192
	v_mul_f32_e32 v0, v21, v64
	v_mul_f32_e32 v1, v5, v65
	v_add_u32_e32 v2, 0x5400, v66
	ds_write2_b32 v2, v0, v1 offset0:36 offset1:68
	v_mul_f32_e32 v0, v22, v64
	v_mul_f32_e32 v1, v6, v65
	ds_write2_b32 v2, v0, v1 offset0:168 offset1:200
	v_mul_f32_e32 v0, v23, v64
	v_mul_f32_e32 v1, v7, v65
	v_add_u32_e32 v2, 0x5800, v66
	ds_write2_b32 v2, v0, v1 offset0:44 offset1:76
	v_mul_f32_e32 v0, v24, v64
	v_mul_f32_e32 v1, v8, v65
	v_add_u32_e32 v2, 0x6000, v66
	ds_write2_b32 v2, v0, v1 offset0:192 offset1:224
	v_mul_f32_e32 v0, v25, v64
	v_mul_f32_e32 v1, v9, v65
	v_add_u32_e32 v2, 0x6400, v66
	ds_write2_b32 v2, v0, v1 offset0:68 offset1:100
	v_mul_f32_e32 v0, v26, v64
	v_mul_f32_e32 v1, v10, v65
	ds_write2_b32 v2, v0, v1 offset0:200 offset1:232
	v_mul_f32_e32 v0, v27, v64
	v_mul_f32_e32 v1, v11, v65
	v_add_u32_e32 v2, 0x6800, v66
	ds_write2_b32 v2, v0, v1 offset0:76 offset1:108
	v_mul_f32_e32 v0, v28, v64
	v_mul_f32_e32 v1, v12, v65
	v_add_u32_e32 v2, 0x7200, v66
	ds_write2_b32 v2, v0, v1 offset0:96 offset1:128
	v_mul_f32_e32 v0, v29, v64
	v_mul_f32_e32 v1, v13, v65
	v_add_u32_e32 v2, 0x7400, v66
	ds_write2_b32 v2, v0, v1 offset0:100 offset1:132
	v_mul_f32_e32 v0, v30, v64
	v_mul_f32_e32 v1, v14, v65
	v_add_u32_e32 v2, 0x7600, v66
	v_and_b32_e32 v12, 31, v68
	ds_write2_b32 v2, v0, v1 offset0:104 offset1:136
	v_mul_f32_e32 v0, v31, v64
	v_mul_f32_e32 v1, v15, v65
	v_add_u32_e32 v2, 0x7800, v66
	v_lshlrev_b32_e32 v8, 2, v12
	ds_write2_b32 v2, v0, v1 offset0:108 offset1:140
	v_or_b32_e32 v0, s27, v8
	v_ashrrev_i32_e32 v1, 31, v0
	v_lshlrev_b64 v[0:1], 2, v[0:1]
	v_lshl_add_u64 v[2:3], s[6:7], 0, v[0:1]
	v_lshl_add_u64 v[4:5], s[8:9], 0, v[0:1]
	s_waitcnt lgkmcnt(0)
	s_barrier
	global_load_dwordx4 v[0:3], v[2:3], off
	s_nop 0
	global_load_dwordx4 v[4:7], v[4:5], off
	v_and_b32_e32 v9, 64, v108
	v_add_u32_e32 v9, 64, v9
	v_xor_b32_e32 v10, 1, v108
	v_cmp_lt_i32_e32 vcc, v10, v9
	s_addc_u32 s27, s21, 0
	s_lshl_b64 s[0:1], s[0:1], 12
	v_cndmask_b32_e32 v10, v108, v10, vcc
	v_lshlrev_b32_e32 v32, 2, v10
	v_xor_b32_e32 v10, 2, v108
	v_cmp_lt_i32_e32 vcc, v10, v9
	s_add_u32 s63, s33, s0
	s_addc_u32 s65, s34, s1
	v_cndmask_b32_e32 v10, v108, v10, vcc
	v_lshlrev_b32_e32 v33, 2, v10
	v_xor_b32_e32 v10, 4, v108
	v_cmp_lt_i32_e32 vcc, v10, v9
	s_and_b64 s[0:1], s[4:5], exec
	v_ashrrev_i32_e32 v22, 5, v68
	v_cndmask_b32_e32 v10, v108, v10, vcc
	v_lshlrev_b32_e32 v34, 2, v10
	v_xor_b32_e32 v10, 8, v108
	s_cselect_b32 s67, s27, s65
	s_cselect_b32 s66, s12, s63
	v_cmp_lt_i32_e32 vcc, v10, v9
	s_add_i32 s12, s26, s39
	v_add_u32_e32 v16, s12, v22
	v_cndmask_b32_e32 v10, v108, v10, vcc
	s_add_i32 s12, s26, s40
	s_add_i32 s26, s26, s41
	v_lshlrev_b32_e32 v35, 2, v10
	v_xor_b32_e32 v10, 16, v108
	v_add_u32_e32 v20, s12, v22
	v_add_u32_e32 v24, s26, v22
	v_cmp_eq_u32_e64 s[0:1], 0, v12
	v_cmp_lt_i32_e32 vcc, v10, v9
	v_ashrrev_i32_e32 v23, 31, v22
	v_mul_lo_u32 v13, v22, s57
	v_lshlrev_b32_e32 v12, 4, v12
	v_add_u32_e32 v26, s25, v22
	v_ashrrev_i32_e32 v17, 31, v16
	v_ashrrev_i32_e32 v21, 31, v20
	v_ashrrev_i32_e32 v25, 31, v24
	v_cndmask_b32_e32 v9, v108, v10, vcc
	v_add_u32_e32 v8, s24, v8
	v_lshlrev_b64 v[10:11], 12, v[22:23]
	v_add3_u32 v37, v13, v12, 32
	v_lshlrev_b32_e32 v12, 1, v26
	v_lshlrev_b64 v[14:15], 12, v[16:17]
	v_lshlrev_b32_e32 v16, 1, v16
	v_lshlrev_b64 v[18:19], 12, v[20:21]
	v_lshlrev_b32_e32 v20, 1, v20
	v_lshlrev_b64 v[22:23], 12, v[24:25]
	v_lshlrev_b32_e32 v24, 1, v24
	v_ashrrev_i32_e32 v27, 31, v26
	v_lshlrev_b32_e32 v36, 2, v9
	v_ashrrev_i32_e32 v9, 31, v8
	v_ashrrev_i32_e32 v13, 31, v12
	v_ashrrev_i32_e32 v17, 31, v16
	v_ashrrev_i32_e32 v21, 31, v20
	v_ashrrev_i32_e32 v25, 31, v24
	v_lshlrev_b64 v[26:27], 12, v[26:27]
	v_lshlrev_b64 v[8:9], 2, v[8:9]
	v_lshl_add_u64 v[10:11], s[66:67], 0, v[10:11]
	v_lshl_add_u64 v[12:13], v[12:13], 2, s[30:31]
	v_lshl_add_u64 v[14:15], s[28:29], 0, v[14:15]
	v_lshl_add_u64 v[16:17], v[16:17], 2, s[30:31]
	v_lshl_add_u64 v[18:19], s[28:29], 0, v[18:19]
	v_lshl_add_u64 v[20:21], v[20:21], 2, s[30:31]
	v_lshl_add_u64 v[22:23], s[28:29], 0, v[22:23]
	v_lshl_add_u64 v[24:25], v[24:25], 2, s[30:31]
	v_lshl_add_u64 v[26:27], s[10:11], 0, v[26:27]
	s_mov_b64 s[24:25], 0
	s_branch .LBB0_4054
